# baseline (speedup 1.0000x reference)
; #define STAGE(P,BASE,LD,br,kt) do{long _g=(long)(br)*(LD)+(long)(kt)*BK; \
;     _Pragma("unroll") for(int _i=0;_i<2;++_i){int _b=tid*16+_i*8192;int _r,_c;stage_rc(_b,_r,_c); \
;       __builtin_amdgcn_global_load_lds((const unsigned*)((BASE)+_g+(long)_r*(LD)+_c), \
;         (unsigned*)((char*)(P)+_b),16,0,0);}}while(0)
; #define STAGE(P,BASE,LD,br,kt) do{long _g=(long)(br)*(LD)+(long)(kt)*BK; \
;     _Pragma("unroll") for(int _i=0;_i<2;++_i){int _b=tid*16+_i*8192;int _r,_c;stage_rc(_b,_r,_c); \
;       __builtin_amdgcn_global_load_lds((const unsigned*)((BASE)+_g+(long)_r*(LD)+_c), \
;         (unsigned*)((char*)(P)+_b),16,0,0);}}while(0)
; #define LDA(dst,b,h) _Pragma("unroll") for(int m=0;m<4;++m) _Pragma("unroll") for(int k=0;k<2;++k) \
;     dst[m][k]=*reinterpret_cast<const bf16x8*>((char*)SA(b,h)+lds_byte(wr*64+m*16+fr,k*32+fq*8))
; #define LDB(dst,b,h) _Pragma("unroll") for(int n=0;n<2;++n) _Pragma("unroll") for(int k=0;k<2;++k) \
;     dst[n][k]=*reinterpret_cast<const bf16x8*>((char*)SB(b,h)+lds_byte(wc*32+n*16+fr,k*32+fq*8))
; #define WAIT_V(n) asm volatile("s_waitcnt vmcnt(" #n ")":::"memory")
; #define WAIT_L(n) asm volatile("s_waitcnt lgkmcnt(" #n ")":::"memory")
; #define BAR __builtin_amdgcn_s_barrier()
; #define SCHED __builtin_amdgcn_sched_barrier(0)
; DEVINL void gemm8_mainloop(const u16* A, long lda, const u16* Bt, long ldb, int K, int brow, int bcol, f32x4 (&acc)[2][2][4][2], char* smem, int tid) {
;     ...
;   for(int t=0;t<nt-2;t+=2){
;     LDB(B0,0,0); SCHED; LDA(At,0,0); STAGE(SA(1,1),A,lda,brow+HALF,t+1);
;     WAIT_L(8); BAR; WAIT_L(0); MMA(0,0,At,B0); BAR; SCHED;
;     LDB(B1,0,1); STAGE(SB(0,0),Bt,ldb,bcol,t+2);
;     BAR; WAIT_L(0); MMA(0,1,At,B1); BAR;
;     LDA(At,0,1); STAGE(SA(0,0),A,lda,brow,t+2);
;     BAR; WAIT_L(0); MMA(1,0,At,B0); BAR; SCHED;
;     STAGE(SB(0,1),Bt,ldb,bcol+HALF,t+2);
;     WAIT_V(6); BAR; MMA(1,1,At,B1); BAR;
;     LDB(B0,1,0); SCHED; LDA(At,1,0); STAGE(SA(0,1),A,lda,brow+HALF,t+2);
;     WAIT_L(8); BAR; WAIT_L(0); MMA(0,0,At,B0); BAR; SCHED;
;     LDB(B1,1,1); STAGE(SB(1,0),Bt,ldb,bcol,t+3);
;     BAR; WAIT_L(0); MMA(0,1,At,B1); BAR;
;     LDA(At,1,1); STAGE(SA(1,0),A,lda,brow,t+3);
;     BAR; WAIT_L(0); MMA(1,0,At,B0); BAR; SCHED;
;     STAGE(SB(1,1),Bt,ldb,bcol+HALF,t+3);
;     WAIT_V(6); BAR; MMA(1,1,At,B1); BAR;
;   }
.LBB0_269:
	ds_read_b128 v[170:173], v161
	ds_read_b128 v[180:183], v161 offset:1024
	ds_read_b128 v[184:187], v161 offset:2048
	ds_read_b128 v[188:191], v161 offset:3072
	v_add_u32_e32 v178, 0xc000, v128
	v_lshl_add_u64 v[244:245], s[94:95], 0, v[148:149]
	v_readfirstlane_b32 s3, v178
	v_add_u32_e32 v179, 0xe000, v128
	v_add_u32_e32 v174, s41, v160
	v_add_u32_e32 v175, s45, v160
	v_add_u32_e32 v177, s47, v160
	v_lshl_add_u64 v[162:163], v[244:245], 0, s[12:13]
	s_mov_b32 m0, s3
	v_lshl_add_u64 v[246:247], s[94:95], 0, v[150:151]
	v_readfirstlane_b32 s3, v179
	ds_read_b128 v[192:195], v131
	ds_read_b128 v[196:199], v131 offset:1024
	ds_read_b128 v[200:203], v174
	ds_read_b128 v[204:207], v174 offset:1024
	ds_read_b128 v[208:211], v175
	ds_read_b128 v[212:215], v175 offset:1024
	ds_read_b128 v[216:219], v177
	ds_read_b128 v[220:223], v177 offset:1024
	global_load_lds_dwordx4 v[162:163], off
	v_lshl_add_u64 v[162:163], v[246:247], 0, s[12:13]
	s_mov_b32 m0, s3
	s_nop 0
	global_load_lds_dwordx4 v[162:163], off
	s_waitcnt lgkmcnt(8)
	s_barrier
	s_waitcnt lgkmcnt(0)
	s_setprio 1
	v_mfma_f32_16x16x32_bf16 v[124:127], v[170:173], v[192:195], v[124:127]
	v_mfma_f32_16x16x32_bf16 v[120:123], v[184:187], v[192:195], v[120:123]
	v_mfma_f32_16x16x32_bf16 v[116:119], v[170:173], v[200:203], v[116:119]
	v_mfma_f32_16x16x32_bf16 v[112:115], v[184:187], v[200:203], v[112:115]
	v_mfma_f32_16x16x32_bf16 v[108:111], v[170:173], v[208:211], v[108:111]
	v_mfma_f32_16x16x32_bf16 v[104:107], v[184:187], v[208:211], v[104:107]
	v_mfma_f32_16x16x32_bf16 v[100:103], v[170:173], v[216:219], v[100:103]
	v_mfma_f32_16x16x32_bf16 v[96:99], v[184:187], v[216:219], v[96:99]
	v_mfma_f32_16x16x32_bf16 v[124:127], v[180:183], v[196:199], v[124:127]
	v_mfma_f32_16x16x32_bf16 v[120:123], v[188:191], v[196:199], v[120:123]
	v_mfma_f32_16x16x32_bf16 v[116:119], v[180:183], v[204:207], v[116:119]
	v_mfma_f32_16x16x32_bf16 v[112:115], v[188:191], v[204:207], v[112:115]
	v_mfma_f32_16x16x32_bf16 v[108:111], v[180:183], v[212:215], v[108:111]
	v_mfma_f32_16x16x32_bf16 v[104:107], v[188:191], v[212:215], v[104:107]
	v_mfma_f32_16x16x32_bf16 v[100:103], v[180:183], v[220:223], v[100:103]
	v_mfma_f32_16x16x32_bf16 v[96:99], v[188:191], v[220:223], v[96:99]
	s_setprio 0
	s_barrier
	v_add_u32_e32 v162, s31, v153
	v_lshl_add_u64 v[248:249], s[94:95], 0, v[144:145]
	v_readfirstlane_b32 s3, v162
	v_add_u32_e32 v163, 0x2000, v162
	v_lshl_add_u64 v[240:241], v[248:249], 0, s[14:15]
	s_mov_b32 m0, s3
	v_lshl_add_u64 v[250:251], s[94:95], 0, v[146:147]
	v_readfirstlane_b32 s3, v163
	ds_read_b128 v[224:227], v158
	ds_read_b128 v[228:231], v158 offset:1024
	ds_read_b128 v[232:235], v158 offset:2048
	ds_read_b128 v[236:239], v158 offset:3072
	global_load_lds_dwordx4 v[240:241], off
	v_lshl_add_u64 v[240:241], v[250:251], 0, s[14:15]
	s_mov_b32 m0, s3
	s_nop 0
	global_load_lds_dwordx4 v[240:241], off
	s_barrier
	s_waitcnt lgkmcnt(0)
	s_setprio 1
	v_mfma_f32_16x16x32_bf16 v[92:95], v[224:227], v[192:195], v[92:95]
	v_mfma_f32_16x16x32_bf16 v[88:91], v[232:235], v[192:195], v[88:91]
	v_mfma_f32_16x16x32_bf16 v[84:87], v[224:227], v[200:203], v[84:87]
	v_mfma_f32_16x16x32_bf16 v[80:83], v[232:235], v[200:203], v[80:83]
	v_mfma_f32_16x16x32_bf16 v[76:79], v[224:227], v[208:211], v[76:79]
	v_mfma_f32_16x16x32_bf16 v[72:75], v[232:235], v[208:211], v[72:75]
	v_mfma_f32_16x16x32_bf16 v[68:71], v[224:227], v[216:219], v[68:71]
	v_mfma_f32_16x16x32_bf16 v[64:67], v[232:235], v[216:219], v[64:67]
	v_mfma_f32_16x16x32_bf16 v[92:95], v[228:231], v[196:199], v[92:95]
	v_mfma_f32_16x16x32_bf16 v[88:91], v[236:239], v[196:199], v[88:91]
	v_mfma_f32_16x16x32_bf16 v[84:87], v[228:231], v[204:207], v[84:87]
	v_mfma_f32_16x16x32_bf16 v[80:83], v[236:239], v[204:207], v[80:83]
	v_mfma_f32_16x16x32_bf16 v[76:79], v[228:231], v[212:215], v[76:79]
	v_mfma_f32_16x16x32_bf16 v[72:75], v[236:239], v[212:215], v[72:75]
	v_mfma_f32_16x16x32_bf16 v[68:71], v[228:231], v[220:223], v[68:71]
	v_mfma_f32_16x16x32_bf16 v[64:67], v[236:239], v[220:223], v[64:67]
	s_setprio 0
	v_readfirstlane_b32 s3, v128
	v_add_u32_e32 v169, 0x2000, v128
	v_lshl_add_u64 v[240:241], v[244:245], 0, s[16:17]
	s_mov_b32 m0, s3
	v_readfirstlane_b32 s3, v169
	s_barrier
	ds_read_b128 v[192:195], v131 offset:16384
	ds_read_b128 v[196:199], v131 offset:17408
	ds_read_b128 v[200:203], v174 offset:16384
	ds_read_b128 v[204:207], v174 offset:17408
	ds_read_b128 v[208:211], v175 offset:16384
	ds_read_b128 v[212:215], v175 offset:17408
	ds_read_b128 v[216:219], v177 offset:16384
	ds_read_b128 v[220:223], v177 offset:17408
	global_load_lds_dwordx4 v[240:241], off
	v_lshl_add_u64 v[240:241], v[246:247], 0, s[16:17]
	s_mov_b32 m0, s3
	s_nop 0
	global_load_lds_dwordx4 v[240:241], off
	s_barrier
	s_waitcnt lgkmcnt(0)
	s_setprio 1
	v_mfma_f32_16x16x32_bf16 v[60:63], v[170:173], v[192:195], v[60:63]
	v_mfma_f32_16x16x32_bf16 v[56:59], v[184:187], v[192:195], v[56:59]
	v_mfma_f32_16x16x32_bf16 v[52:55], v[170:173], v[200:203], v[52:55]
	v_mfma_f32_16x16x32_bf16 v[48:51], v[184:187], v[200:203], v[48:51]
	v_mfma_f32_16x16x32_bf16 v[44:47], v[170:173], v[208:211], v[44:47]
	v_mfma_f32_16x16x32_bf16 v[40:43], v[184:187], v[208:211], v[40:43]
	v_mfma_f32_16x16x32_bf16 v[36:39], v[170:173], v[216:219], v[36:39]
	v_mfma_f32_16x16x32_bf16 v[32:35], v[184:187], v[216:219], v[32:35]
	v_mfma_f32_16x16x32_bf16 v[60:63], v[180:183], v[196:199], v[60:63]
	v_mfma_f32_16x16x32_bf16 v[56:59], v[188:191], v[196:199], v[56:59]
	v_mfma_f32_16x16x32_bf16 v[52:55], v[180:183], v[204:207], v[52:55]
	v_mfma_f32_16x16x32_bf16 v[48:51], v[188:191], v[204:207], v[48:51]
	v_mfma_f32_16x16x32_bf16 v[44:47], v[180:183], v[212:215], v[44:47]
	v_mfma_f32_16x16x32_bf16 v[40:43], v[188:191], v[212:215], v[40:43]
	v_mfma_f32_16x16x32_bf16 v[36:39], v[180:183], v[220:223], v[36:39]
	v_mfma_f32_16x16x32_bf16 v[32:35], v[188:191], v[220:223], v[32:35]
	s_setprio 0
	s_barrier
; #define STAGE(P,BASE,LD,br,kt) do{long _g=(long)(br)*(LD)+(long)(kt)*BK; \
;     _Pragma("unroll") for(int _i=0;_i<2;++_i){int _b=tid*16+_i*8192;int _r,_c;stage_rc(_b,_r,_c); \
;       __builtin_amdgcn_global_load_lds((const unsigned*)((BASE)+_g+(long)_r*(LD)+_c), \
;         (unsigned*)((char*)(P)+_b),16,0,0);}}while(0)
; #define STAGE(P,BASE,LD,br,kt) do{long _g=(long)(br)*(LD)+(long)(kt)*BK; \
;     _Pragma("unroll") for(int _i=0;_i<2;++_i){int _b=tid*16+_i*8192;int _r,_c;stage_rc(_b,_r,_c); \
;       __builtin_amdgcn_global_load_lds((const unsigned*)((BASE)+_g+(long)_r*(LD)+_c), \
;         (unsigned*)((char*)(P)+_b),16,0,0);}}while(0)
; #define LDA(dst,b,h) _Pragma("unroll") for(int m=0;m<4;++m) _Pragma("unroll") for(int k=0;k<2;++k) \
;     dst[m][k]=*reinterpret_cast<const bf16x8*>((char*)SA(b,h)+lds_byte(wr*64+m*16+fr,k*32+fq*8))
; #define LDB(dst,b,h) _Pragma("unroll") for(int n=0;n<2;++n) _Pragma("unroll") for(int k=0;k<2;++k) \
;     dst[n][k]=*reinterpret_cast<const bf16x8*>((char*)SB(b,h)+lds_byte(wc*32+n*16+fr,k*32+fq*8))
; #define WAIT_V(n) asm volatile("s_waitcnt vmcnt(" #n ")":::"memory")
; #define WAIT_L(n) asm volatile("s_waitcnt lgkmcnt(" #n ")":::"memory")
; #define BAR __builtin_amdgcn_s_barrier()
; #define SCHED __builtin_amdgcn_sched_barrier(0)
; DEVINL void gemm8_mainloop(const u16* A, long lda, const u16* Bt, long ldb, int K, int brow, int bcol, f32x4 (&acc)[2][2][4][2], char* smem, int tid) {
;     ...
;   for(int t=0;t<nt-2;t+=2){
;     LDB(B0,0,0); SCHED; LDA(At,0,0); STAGE(SA(1,1),A,lda,brow+HALF,t+1);
;     WAIT_L(8); BAR; WAIT_L(0); MMA(0,0,At,B0); BAR; SCHED;
;     LDB(B1,0,1); STAGE(SB(0,0),Bt,ldb,bcol,t+2);
;     BAR; WAIT_L(0); MMA(0,1,At,B1); BAR;
;     LDA(At,0,1); STAGE(SA(0,0),A,lda,brow,t+2);
;     BAR; WAIT_L(0); MMA(1,0,At,B0); BAR; SCHED;
;     STAGE(SB(0,1),Bt,ldb,bcol+HALF,t+2);
;     WAIT_V(6); BAR; MMA(1,1,At,B1); BAR;
;     LDB(B0,1,0); SCHED; LDA(At,1,0); STAGE(SA(0,1),A,lda,brow+HALF,t+2);
;     WAIT_L(8); BAR; WAIT_L(0); MMA(0,0,At,B0); BAR; SCHED;
;     LDB(B1,1,1); STAGE(SB(1,0),Bt,ldb,bcol,t+3);
;     BAR; WAIT_L(0); MMA(0,1,At,B1); BAR;
;     LDA(At,1,1); STAGE(SA(1,0),A,lda,brow,t+3);
;     BAR; WAIT_L(0); MMA(1,0,At,B0); BAR; SCHED;
;     STAGE(SB(1,1),Bt,ldb,bcol+HALF,t+3);
;     WAIT_V(6); BAR; MMA(1,1,At,B1); BAR;
;   }
	v_add_u32_e32 v170, s33, v153
	v_add_u32_e32 v171, 0x2000, v170
	v_readfirstlane_b32 s3, v170
	v_lshl_add_u64 v[172:173], v[248:249], 0, s[18:19]
	s_mov_b32 m0, s3
	v_readfirstlane_b32 s3, v171
	global_load_lds_dwordx4 v[172:173], off
	v_lshl_add_u64 v[172:173], v[250:251], 0, s[18:19]
	s_mov_b32 m0, s3
	s_nop 0
	global_load_lds_dwordx4 v[172:173], off
	s_waitcnt vmcnt(6)
	s_barrier
	s_setprio 1
	v_mfma_f32_16x16x32_bf16 v[28:31], v[224:227], v[192:195], v[28:31]
	v_mfma_f32_16x16x32_bf16 v[24:27], v[232:235], v[192:195], v[24:27]
	v_mfma_f32_16x16x32_bf16 v[20:23], v[224:227], v[200:203], v[20:23]
	v_mfma_f32_16x16x32_bf16 v[16:19], v[232:235], v[200:203], v[16:19]
	v_mfma_f32_16x16x32_bf16 v[12:15], v[224:227], v[208:211], v[12:15]
	v_mfma_f32_16x16x32_bf16 v[8:11], v[232:235], v[208:211], v[8:11]
	v_mfma_f32_16x16x32_bf16 v[4:7], v[224:227], v[216:219], v[4:7]
	v_mfma_f32_16x16x32_bf16 v[0:3], v[232:235], v[216:219], v[0:3]
	v_mfma_f32_16x16x32_bf16 v[28:31], v[228:231], v[196:199], v[28:31]
	v_mfma_f32_16x16x32_bf16 v[24:27], v[236:239], v[196:199], v[24:27]
	v_mfma_f32_16x16x32_bf16 v[20:23], v[228:231], v[204:207], v[20:23]
	v_mfma_f32_16x16x32_bf16 v[16:19], v[236:239], v[204:207], v[16:19]
	v_mfma_f32_16x16x32_bf16 v[12:15], v[228:231], v[212:215], v[12:15]
	v_mfma_f32_16x16x32_bf16 v[8:11], v[236:239], v[212:215], v[8:11]
	v_mfma_f32_16x16x32_bf16 v[4:7], v[228:231], v[220:223], v[4:7]
	v_mfma_f32_16x16x32_bf16 v[0:3], v[236:239], v[220:223], v[0:3]
	s_setprio 0
	s_barrier
	ds_read_b128 v[180:183], v154
	ds_read_b128 v[184:187], v154 offset:1024
	ds_read_b128 v[188:191], v154 offset:2048
	ds_read_b128 v[192:195], v154 offset:3072
	v_add_u32_e32 v172, 0x4000, v128
	v_add_u32_e32 v173, 0x6000, v128
	v_readfirstlane_b32 s3, v172
	v_lshl_add_u64 v[228:229], v[244:245], 0, s[20:21]
	s_mov_b32 m0, s3
	v_readfirstlane_b32 s3, v173
	ds_read_b128 v[196:199], v131 offset:32768
	ds_read_b128 v[200:203], v131 offset:33792
	ds_read_b128 v[204:207], v174 offset:32768
	ds_read_b128 v[208:211], v174 offset:33792
	ds_read_b128 v[212:215], v175 offset:32768
	ds_read_b128 v[216:219], v175 offset:33792
	ds_read_b128 v[220:223], v177 offset:32768
	ds_read_b128 v[224:227], v177 offset:33792
	global_load_lds_dwordx4 v[228:229], off
	v_lshl_add_u64 v[228:229], v[246:247], 0, s[20:21]
	s_mov_b32 m0, s3
	s_nop 0
	global_load_lds_dwordx4 v[228:229], off
	s_waitcnt lgkmcnt(8)
	s_barrier
	s_waitcnt lgkmcnt(0)
	s_setprio 1
	v_mfma_f32_16x16x32_bf16 v[124:127], v[180:183], v[196:199], v[124:127]
	v_mfma_f32_16x16x32_bf16 v[120:123], v[188:191], v[196:199], v[120:123]
	v_mfma_f32_16x16x32_bf16 v[116:119], v[180:183], v[204:207], v[116:119]
	v_mfma_f32_16x16x32_bf16 v[112:115], v[188:191], v[204:207], v[112:115]
	v_mfma_f32_16x16x32_bf16 v[108:111], v[180:183], v[212:215], v[108:111]
	v_mfma_f32_16x16x32_bf16 v[104:107], v[188:191], v[212:215], v[104:107]
	v_mfma_f32_16x16x32_bf16 v[100:103], v[180:183], v[220:223], v[100:103]
	v_mfma_f32_16x16x32_bf16 v[96:99], v[188:191], v[220:223], v[96:99]
	v_mfma_f32_16x16x32_bf16 v[124:127], v[184:187], v[200:203], v[124:127]
	v_mfma_f32_16x16x32_bf16 v[120:123], v[192:195], v[200:203], v[120:123]
	v_mfma_f32_16x16x32_bf16 v[116:119], v[184:187], v[208:211], v[116:119]
	v_mfma_f32_16x16x32_bf16 v[112:115], v[192:195], v[208:211], v[112:115]
	v_mfma_f32_16x16x32_bf16 v[108:111], v[184:187], v[216:219], v[108:111]
	v_mfma_f32_16x16x32_bf16 v[104:107], v[192:195], v[216:219], v[104:107]
	v_mfma_f32_16x16x32_bf16 v[100:103], v[184:187], v[224:227], v[100:103]
	v_mfma_f32_16x16x32_bf16 v[96:99], v[192:195], v[224:227], v[96:99]
	s_setprio 0
	s_barrier
	v_readfirstlane_b32 s3, v155
	v_add_u32_e32 v165, 0x2000, v155
	v_lshl_add_u64 v[252:253], v[248:249], 0, s[22:23]
	s_mov_b32 m0, s3
	v_readfirstlane_b32 s3, v165
	ds_read_b128 v[228:231], v152
	ds_read_b128 v[232:235], v152 offset:1024
	ds_read_b128 v[236:239], v152 offset:2048
	ds_read_b128 v[240:243], v152 offset:3072
	global_load_lds_dwordx4 v[252:253], off
	v_lshl_add_u64 v[252:253], v[250:251], 0, s[22:23]
	s_mov_b32 m0, s3
	s_nop 0
	global_load_lds_dwordx4 v[252:253], off
	s_barrier
	s_waitcnt lgkmcnt(0)
	s_setprio 1
	v_mfma_f32_16x16x32_bf16 v[92:95], v[228:231], v[196:199], v[92:95]
	v_mfma_f32_16x16x32_bf16 v[88:91], v[236:239], v[196:199], v[88:91]
	v_mfma_f32_16x16x32_bf16 v[84:87], v[228:231], v[204:207], v[84:87]
	v_mfma_f32_16x16x32_bf16 v[80:83], v[236:239], v[204:207], v[80:83]
	v_mfma_f32_16x16x32_bf16 v[76:79], v[228:231], v[212:215], v[76:79]
	v_mfma_f32_16x16x32_bf16 v[72:75], v[236:239], v[212:215], v[72:75]
	v_mfma_f32_16x16x32_bf16 v[68:71], v[228:231], v[220:223], v[68:71]
	v_mfma_f32_16x16x32_bf16 v[64:67], v[236:239], v[220:223], v[64:67]
	v_mfma_f32_16x16x32_bf16 v[92:95], v[232:235], v[200:203], v[92:95]
	v_mfma_f32_16x16x32_bf16 v[88:91], v[240:243], v[200:203], v[88:91]
	v_mfma_f32_16x16x32_bf16 v[84:87], v[232:235], v[208:211], v[84:87]
	v_mfma_f32_16x16x32_bf16 v[80:83], v[240:243], v[208:211], v[80:83]
	v_mfma_f32_16x16x32_bf16 v[76:79], v[232:235], v[216:219], v[76:79]
	v_mfma_f32_16x16x32_bf16 v[72:75], v[240:243], v[216:219], v[72:75]
	v_mfma_f32_16x16x32_bf16 v[68:71], v[232:235], v[224:227], v[68:71]
	v_mfma_f32_16x16x32_bf16 v[64:67], v[240:243], v[224:227], v[64:67]
	s_setprio 0
	v_readfirstlane_b32 s3, v156
	v_lshl_add_u64 v[244:245], v[244:245], 0, s[24:25]
	s_mov_b32 m0, s3
	v_readfirstlane_b32 s3, v157
	s_barrier
; #define STAGE(P,BASE,LD,br,kt) do{long _g=(long)(br)*(LD)+(long)(kt)*BK; \
;     _Pragma("unroll") for(int _i=0;_i<2;++_i){int _b=tid*16+_i*8192;int _r,_c;stage_rc(_b,_r,_c); \
;       __builtin_amdgcn_global_load_lds((const unsigned*)((BASE)+_g+(long)_r*(LD)+_c), \
;         (unsigned*)((char*)(P)+_b),16,0,0);}}while(0)
; #define STAGE(P,BASE,LD,br,kt) do{long _g=(long)(br)*(LD)+(long)(kt)*BK; \
;     _Pragma("unroll") for(int _i=0;_i<2;++_i){int _b=tid*16+_i*8192;int _r,_c;stage_rc(_b,_r,_c); \
;       __builtin_amdgcn_global_load_lds((const unsigned*)((BASE)+_g+(long)_r*(LD)+_c), \
;         (unsigned*)((char*)(P)+_b),16,0,0);}}while(0)
; #define LDA(dst,b,h) _Pragma("unroll") for(int m=0;m<4;++m) _Pragma("unroll") for(int k=0;k<2;++k) \
;     dst[m][k]=*reinterpret_cast<const bf16x8*>((char*)SA(b,h)+lds_byte(wr*64+m*16+fr,k*32+fq*8))
; #define LDB(dst,b,h) _Pragma("unroll") for(int n=0;n<2;++n) _Pragma("unroll") for(int k=0;k<2;++k) \
;     dst[n][k]=*reinterpret_cast<const bf16x8*>((char*)SB(b,h)+lds_byte(wc*32+n*16+fr,k*32+fq*8))
; #define MMA(ai,bj,At_,Bt_) do{__builtin_amdgcn_s_setprio(1); \
;     _Pragma("unroll") for(int m=0;m<4;++m) _Pragma("unroll") for(int n=0;n<2;++n) _Pragma("unroll") for(int k=0;k<2;++k) \
;       acc[ai][bj][m][n]=__builtin_amdgcn_mfma_f32_16x16x32_bf16(Bt_[n][k],At_[m][k],acc[ai][bj][m][n],0,0,0); \
;     __builtin_amdgcn_s_setprio(0);}while(0)
; #define WAIT_V(n) asm volatile("s_waitcnt vmcnt(" #n ")":::"memory")
; #define BAR __builtin_amdgcn_s_barrier()
; DEVINL void gemm8_mainloop(const u16* A, long lda, const u16* Bt, long ldb, int K, int brow, int bcol, f32x4 (&acc)[2][2][4][2], char* smem, int tid) {
;     ...
;     WAIT_V(6); BAR; MMA(1,1,At,B1); BAR;
;     LDB(B0,1,0); SCHED; LDA(At,1,0); STAGE(SA(0,1),A,lda,brow+HALF,t+2);
;     WAIT_L(8); BAR; WAIT_L(0); MMA(0,0,At,B0); BAR; SCHED;
;     LDB(B1,1,1); STAGE(SB(1,0),Bt,ldb,bcol,t+3);
;     BAR; WAIT_L(0); MMA(0,1,At,B1); BAR;
;     LDA(At,1,1); STAGE(SA(1,0),A,lda,brow,t+3);
;     BAR; WAIT_L(0); MMA(1,0,At,B0); BAR; SCHED;
;     STAGE(SB(1,1),Bt,ldb,bcol+HALF,t+3);
;     WAIT_V(6); BAR; MMA(1,1,At,B1); BAR;
;   }
;   { LDB(B0,0,0); LDA(At,0,0); STAGE(SA(1,1),A,lda,brow+HALF,nt-1);
;     BAR; WAIT_L(0); MMA(0,0,At,B0); BAR;
;     LDB(B1,0,1); BAR; WAIT_L(0); MMA(0,1,At,B1); BAR;
;     LDA(At,0,1); WAIT_V(4); BAR; WAIT_L(0); MMA(1,0,At,B0); MMA(1,1,At,B1); BAR; }
	ds_read_b128 v[196:199], v131 offset:49152
	ds_read_b128 v[200:203], v131 offset:50176
	ds_read_b128 v[204:207], v174 offset:49152
	ds_read_b128 v[208:211], v174 offset:50176
	ds_read_b128 v[212:215], v175 offset:49152
	ds_read_b128 v[216:219], v175 offset:50176
	ds_read_b128 v[220:223], v177 offset:49152
	ds_read_b128 v[224:227], v177 offset:50176
	global_load_lds_dwordx4 v[244:245], off
	v_lshl_add_u64 v[244:245], v[246:247], 0, s[24:25]
	s_mov_b32 m0, s3
	s_nop 0
	global_load_lds_dwordx4 v[244:245], off
	s_barrier
	s_waitcnt lgkmcnt(0)
	s_setprio 1
	v_mfma_f32_16x16x32_bf16 v[60:63], v[180:183], v[196:199], v[60:63]
	v_mfma_f32_16x16x32_bf16 v[56:59], v[188:191], v[196:199], v[56:59]
	v_mfma_f32_16x16x32_bf16 v[52:55], v[180:183], v[204:207], v[52:55]
	v_mfma_f32_16x16x32_bf16 v[48:51], v[188:191], v[204:207], v[48:51]
	v_mfma_f32_16x16x32_bf16 v[44:47], v[180:183], v[212:215], v[44:47]
	v_mfma_f32_16x16x32_bf16 v[40:43], v[188:191], v[212:215], v[40:43]
	v_mfma_f32_16x16x32_bf16 v[36:39], v[180:183], v[220:223], v[36:39]
	v_mfma_f32_16x16x32_bf16 v[32:35], v[188:191], v[220:223], v[32:35]
	v_mfma_f32_16x16x32_bf16 v[60:63], v[184:187], v[200:203], v[60:63]
	v_mfma_f32_16x16x32_bf16 v[56:59], v[192:195], v[200:203], v[56:59]
	v_mfma_f32_16x16x32_bf16 v[52:55], v[184:187], v[208:211], v[52:55]
	v_mfma_f32_16x16x32_bf16 v[48:51], v[192:195], v[208:211], v[48:51]
	v_mfma_f32_16x16x32_bf16 v[44:47], v[184:187], v[216:219], v[44:47]
	v_mfma_f32_16x16x32_bf16 v[40:43], v[192:195], v[216:219], v[40:43]
	v_mfma_f32_16x16x32_bf16 v[36:39], v[184:187], v[224:227], v[36:39]
	v_mfma_f32_16x16x32_bf16 v[32:35], v[192:195], v[224:227], v[32:35]
	s_setprio 0
	s_barrier
	v_readfirstlane_b32 s3, v159
	v_add_u32_e32 v165, 0x2000, v159
	v_lshl_add_u64 v[180:181], v[248:249], 0, s[26:27]
	s_mov_b32 m0, s3
	v_readfirstlane_b32 s3, v165
	global_load_lds_dwordx4 v[180:181], off
	v_lshl_add_u64 v[180:181], v[250:251], 0, s[26:27]
	s_mov_b32 m0, s3
	s_nop 0
	global_load_lds_dwordx4 v[180:181], off
	s_waitcnt vmcnt(6)
	s_barrier
	s_setprio 1
	v_mfma_f32_16x16x32_bf16 v[28:31], v[228:231], v[196:199], v[28:31]
	v_mfma_f32_16x16x32_bf16 v[24:27], v[236:239], v[196:199], v[24:27]
	v_mfma_f32_16x16x32_bf16 v[20:23], v[228:231], v[204:207], v[20:23]
	v_mfma_f32_16x16x32_bf16 v[16:19], v[236:239], v[204:207], v[16:19]
	v_mfma_f32_16x16x32_bf16 v[12:15], v[228:231], v[212:215], v[12:15]
	v_mfma_f32_16x16x32_bf16 v[8:11], v[236:239], v[212:215], v[8:11]
	v_mfma_f32_16x16x32_bf16 v[4:7], v[228:231], v[220:223], v[4:7]
	v_mfma_f32_16x16x32_bf16 v[0:3], v[236:239], v[220:223], v[0:3]
	v_mfma_f32_16x16x32_bf16 v[28:31], v[232:235], v[200:203], v[28:31]
	v_mfma_f32_16x16x32_bf16 v[24:27], v[240:243], v[200:203], v[24:27]
	v_mfma_f32_16x16x32_bf16 v[20:23], v[232:235], v[208:211], v[20:23]
	v_mfma_f32_16x16x32_bf16 v[16:19], v[240:243], v[208:211], v[16:19]
	v_mfma_f32_16x16x32_bf16 v[12:15], v[232:235], v[216:219], v[12:15]
	v_mfma_f32_16x16x32_bf16 v[8:11], v[240:243], v[216:219], v[8:11]
	v_mfma_f32_16x16x32_bf16 v[4:7], v[232:235], v[224:227], v[4:7]
	v_mfma_f32_16x16x32_bf16 v[0:3], v[240:243], v[224:227], v[0:3]
	s_setprio 0
	s_add_i32 s2, s2, 2
	v_lshl_add_u64 v[144:145], v[144:145], 0, s[14:15]
	v_lshl_add_u64 v[146:147], v[146:147], 0, s[14:15]
	v_lshl_add_u64 v[148:149], v[148:149], 0, s[14:15]
	s_cmp_lt_u32 s2, 28
	v_lshl_add_u64 v[150:151], v[150:151], 0, s[14:15]
	s_barrier
	s_cbranch_scc1 .LBB0_269
	s_or_b32 s2, s40, 0x80
	s_ashr_i32 s3, s2, 31
	s_lshl_b64 s[2:3], s[2:3], 12
	s_add_u32 s2, s90, s2
	s_addc_u32 s3, s91, s3
	v_lshl_add_u64 v[156:157], v[136:137], 1, s[2:3]
	v_lshl_add_u64 v[140:141], v[140:141], 1, v[156:157]
	v_readfirstlane_b32 s41, v178
	v_lshl_add_u64 v[140:141], v[140:141], 0, s[28:29]
	s_mov_b32 m0, s41
	ds_read_b128 v[144:147], v161
	ds_read_b128 v[148:151], v161 offset:1024
	ds_read_b128 v[180:183], v161 offset:2048
	ds_read_b128 v[184:187], v161 offset:3072
	ds_read_b128 v[188:191], v131
	ds_read_b128 v[192:195], v131 offset:1024
	ds_read_b128 v[196:199], v174
	ds_read_b128 v[200:203], v174 offset:1024
	ds_read_b128 v[204:207], v175
	ds_read_b128 v[208:211], v175 offset:1024
	ds_read_b128 v[212:215], v177
	ds_read_b128 v[216:219], v177 offset:1024
	global_load_lds_dwordx4 v[140:141], off
	v_lshl_add_u64 v[140:141], v[138:139], 1, s[2:3]
	v_lshl_add_u64 v[140:141], v[142:143], 1, v[140:141]
	v_readfirstlane_b32 s2, v179
	v_lshl_add_u64 v[140:141], v[140:141], 0, s[28:29]
	s_mov_b32 m0, s2
	s_nop 0
	global_load_lds_dwordx4 v[140:141], off
	s_barrier
	s_waitcnt lgkmcnt(0)
	s_setprio 1
	v_mfma_f32_16x16x32_bf16 v[124:127], v[144:147], v[188:191], v[124:127]
	v_mfma_f32_16x16x32_bf16 v[120:123], v[180:183], v[188:191], v[120:123]
	v_mfma_f32_16x16x32_bf16 v[108:111], v[144:147], v[204:207], v[108:111]
	v_mfma_f32_16x16x32_bf16 v[104:107], v[180:183], v[204:207], v[104:107]
	v_mfma_f32_16x16x32_bf16 v[124:127], v[148:151], v[192:195], v[124:127]
	v_mfma_f32_16x16x32_bf16 v[120:123], v[184:187], v[192:195], v[120:123]
	v_mfma_f32_16x16x32_bf16 v[116:119], v[144:147], v[196:199], v[116:119]
	v_mfma_f32_16x16x32_bf16 v[112:115], v[180:183], v[196:199], v[112:115]
	v_mfma_f32_16x16x32_bf16 v[108:111], v[148:151], v[208:211], v[108:111]
	v_mfma_f32_16x16x32_bf16 v[104:107], v[184:187], v[208:211], v[104:107]
	v_mfma_f32_16x16x32_bf16 v[100:103], v[144:147], v[212:215], v[100:103]
	v_mfma_f32_16x16x32_bf16 v[96:99], v[180:183], v[212:215], v[96:99]
	v_mfma_f32_16x16x32_bf16 v[140:143], v[148:151], v[200:203], v[116:119]
	v_mfma_f32_16x16x32_bf16 v[220:223], v[184:187], v[200:203], v[112:115]
	v_mfma_f32_16x16x32_bf16 v[224:227], v[148:151], v[216:219], v[100:103]
	v_mfma_f32_16x16x32_bf16 v[228:231], v[184:187], v[216:219], v[96:99]
	s_setprio 0
	s_barrier
; #define STAGE(P,BASE,LD,br,kt) do{long _g=(long)(br)*(LD)+(long)(kt)*BK; \
;     _Pragma("unroll") for(int _i=0;_i<2;++_i){int _b=tid*16+_i*8192;int _r,_c;stage_rc(_b,_r,_c); \
;       __builtin_amdgcn_global_load_lds((const unsigned*)((BASE)+_g+(long)_r*(LD)+_c), \
;         (unsigned*)((char*)(P)+_b),16,0,0);}}while(0)
; #define STAGE(P,BASE,LD,br,kt) do{long _g=(long)(br)*(LD)+(long)(kt)*BK; \
;     _Pragma("unroll") for(int _i=0;_i<2;++_i){int _b=tid*16+_i*8192;int _r,_c;stage_rc(_b,_r,_c); \
;       __builtin_amdgcn_global_load_lds((const unsigned*)((BASE)+_g+(long)_r*(LD)+_c), \
;         (unsigned*)((char*)(P)+_b),16,0,0);}}while(0)
; #define LDA(dst,b,h) _Pragma("unroll") for(int m=0;m<4;++m) _Pragma("unroll") for(int k=0;k<2;++k) \
;     dst[m][k]=*reinterpret_cast<const bf16x8*>((char*)SA(b,h)+lds_byte(wr*64+m*16+fr,k*32+fq*8))
; #define LDB(dst,b,h) _Pragma("unroll") for(int n=0;n<2;++n) _Pragma("unroll") for(int k=0;k<2;++k) \
;     dst[n][k]=*reinterpret_cast<const bf16x8*>((char*)SB(b,h)+lds_byte(wc*32+n*16+fr,k*32+fq*8))
; #define MMA(ai,bj,At_,Bt_) do{__builtin_amdgcn_s_setprio(1); \
;     _Pragma("unroll") for(int m=0;m<4;++m) _Pragma("unroll") for(int n=0;n<2;++n) _Pragma("unroll") for(int k=0;k<2;++k) \
;       acc[ai][bj][m][n]=__builtin_amdgcn_mfma_f32_16x16x32_bf16(Bt_[n][k],At_[m][k],acc[ai][bj][m][n],0,0,0); \
;     __builtin_amdgcn_s_setprio(0);}while(0)
; #define WAIT_V(n) asm volatile("s_waitcnt vmcnt(" #n ")":::"memory")
; #define WAIT_L(n) asm volatile("s_waitcnt lgkmcnt(" #n ")":::"memory")
; #define BAR __builtin_amdgcn_s_barrier()
; DEVINL void gemm8_mainloop(const u16* A, long lda, const u16* Bt, long ldb, int K, int brow, int bcol, f32x4 (&acc)[2][2][4][2], char* smem, int tid) {
;     ...
;   { LDB(B0,0,0); LDA(At,0,0); STAGE(SA(1,1),A,lda,brow+HALF,nt-1);
;     BAR; WAIT_L(0); MMA(0,0,At,B0); BAR;
;     LDB(B1,0,1); BAR; WAIT_L(0); MMA(0,1,At,B1); BAR;
;     LDA(At,0,1); WAIT_V(4); BAR; WAIT_L(0); MMA(1,0,At,B0); MMA(1,1,At,B1); BAR; }
;   { LDB(B0,1,0); LDA(At,1,0); WAIT_V(2); BAR; WAIT_L(0); MMA(0,0,At,B0); BAR;
;     LDB(B1,1,1); WAIT_V(0); BAR; WAIT_L(0); MMA(0,1,At,B1); BAR;
	s_nop 1
	ds_read_b128 v[96:99], v158
	ds_read_b128 v[100:103], v158 offset:1024
	ds_read_b128 v[112:115], v158 offset:2048
	ds_read_b128 v[116:119], v158 offset:3072
	s_barrier
	s_waitcnt lgkmcnt(0)
	s_setprio 1
	v_mfma_f32_16x16x32_bf16 v[92:95], v[96:99], v[188:191], v[92:95]
	v_mfma_f32_16x16x32_bf16 v[88:91], v[112:115], v[188:191], v[88:91]
	v_mfma_f32_16x16x32_bf16 v[76:79], v[96:99], v[204:207], v[76:79]
	v_mfma_f32_16x16x32_bf16 v[72:75], v[112:115], v[204:207], v[72:75]
	v_mfma_f32_16x16x32_bf16 v[92:95], v[100:103], v[192:195], v[92:95]
	v_mfma_f32_16x16x32_bf16 v[88:91], v[116:119], v[192:195], v[88:91]
	v_mfma_f32_16x16x32_bf16 v[84:87], v[96:99], v[196:199], v[84:87]
	v_mfma_f32_16x16x32_bf16 v[80:83], v[112:115], v[196:199], v[80:83]
	v_mfma_f32_16x16x32_bf16 v[76:79], v[100:103], v[208:211], v[76:79]
	v_mfma_f32_16x16x32_bf16 v[72:75], v[116:119], v[208:211], v[72:75]
	v_mfma_f32_16x16x32_bf16 v[68:71], v[96:99], v[212:215], v[68:71]
	v_mfma_f32_16x16x32_bf16 v[64:67], v[112:115], v[212:215], v[64:67]
	v_mfma_f32_16x16x32_bf16 v[156:159], v[100:103], v[200:203], v[84:87]
	v_mfma_f32_16x16x32_bf16 v[188:191], v[116:119], v[200:203], v[80:83]
	v_mfma_f32_16x16x32_bf16 v[192:195], v[100:103], v[216:219], v[68:71]
	v_mfma_f32_16x16x32_bf16 v[196:199], v[116:119], v[216:219], v[64:67]
	s_setprio 0
	s_barrier
	s_nop 1
	ds_read_b128 v[64:67], v131 offset:16384
	ds_read_b128 v[68:71], v131 offset:17408
	ds_read_b128 v[80:83], v174 offset:16384
	ds_read_b128 v[84:87], v174 offset:17408
	ds_read_b128 v[200:203], v175 offset:16384
	ds_read_b128 v[204:207], v175 offset:17408
	ds_read_b128 v[208:211], v177 offset:16384
	ds_read_b128 v[212:215], v177 offset:17408
	s_waitcnt vmcnt(4)
	s_barrier
	s_waitcnt lgkmcnt(0)
	s_setprio 1
	v_mfma_f32_16x16x32_bf16 v[60:63], v[144:147], v[64:67], v[60:63]
	v_mfma_f32_16x16x32_bf16 v[52:55], v[144:147], v[80:83], v[52:55]
	v_mfma_f32_16x16x32_bf16 v[44:47], v[144:147], v[200:203], v[44:47]
	v_mfma_f32_16x16x32_bf16 v[40:43], v[180:183], v[200:203], v[40:43]
	v_mfma_f32_16x16x32_bf16 v[60:63], v[148:151], v[68:71], v[60:63]
	v_mfma_f32_16x16x32_bf16 v[56:59], v[180:183], v[64:67], v[56:59]
	v_mfma_f32_16x16x32_bf16 v[52:55], v[148:151], v[84:87], v[52:55]
	v_mfma_f32_16x16x32_bf16 v[48:51], v[180:183], v[80:83], v[48:51]
	v_mfma_f32_16x16x32_bf16 v[44:47], v[148:151], v[204:207], v[44:47]
	v_mfma_f32_16x16x32_bf16 v[40:43], v[184:187], v[204:207], v[40:43]
	v_mfma_f32_16x16x32_bf16 v[36:39], v[144:147], v[208:211], v[36:39]
	v_mfma_f32_16x16x32_bf16 v[32:35], v[180:183], v[208:211], v[32:35]
	v_mfma_f32_16x16x32_bf16 v[216:219], v[184:187], v[68:71], v[56:59]
	v_mfma_f32_16x16x32_bf16 v[232:235], v[184:187], v[84:87], v[48:51]
	v_mfma_f32_16x16x32_bf16 v[144:147], v[148:151], v[212:215], v[36:39]
	v_mfma_f32_16x16x32_bf16 v[148:151], v[184:187], v[212:215], v[32:35]
	s_setprio 0
	s_setprio 1
	v_mfma_f32_16x16x32_bf16 v[28:31], v[96:99], v[64:67], v[28:31]
	v_mfma_f32_16x16x32_bf16 v[20:23], v[96:99], v[80:83], v[20:23]
	v_mfma_f32_16x16x32_bf16 v[12:15], v[96:99], v[200:203], v[12:15]
	v_mfma_f32_16x16x32_bf16 v[4:7], v[96:99], v[208:211], v[4:7]
	v_mfma_f32_16x16x32_bf16 v[28:31], v[100:103], v[68:71], v[28:31]
	v_mfma_f32_16x16x32_bf16 v[24:27], v[112:115], v[64:67], v[24:27]
	v_mfma_f32_16x16x32_bf16 v[20:23], v[100:103], v[84:87], v[20:23]
	v_mfma_f32_16x16x32_bf16 v[16:19], v[112:115], v[80:83], v[16:19]
	v_mfma_f32_16x16x32_bf16 v[12:15], v[100:103], v[204:207], v[12:15]
	v_mfma_f32_16x16x32_bf16 v[8:11], v[112:115], v[200:203], v[8:11]
	v_mfma_f32_16x16x32_bf16 v[4:7], v[100:103], v[212:215], v[4:7]
	v_mfma_f32_16x16x32_bf16 v[0:3], v[112:115], v[208:211], v[0:3]
	v_mfma_f32_16x16x32_bf16 v[178:181], v[116:119], v[68:71], v[24:27]
	v_mfma_f32_16x16x32_bf16 v[182:185], v[116:119], v[84:87], v[16:19]
	v_mfma_f32_16x16x32_bf16 v[200:203], v[116:119], v[204:207], v[8:11]
	v_mfma_f32_16x16x32_bf16 v[204:207], v[116:119], v[212:215], v[0:3]
	s_setprio 0
	s_barrier
	s_nop 1
	ds_read_b128 v[0:3], v154
	ds_read_b128 v[8:11], v154 offset:1024
	ds_read_b128 v[208:211], v154 offset:2048
	ds_read_b128 v[212:215], v154 offset:3072
	ds_read_b128 v[16:19], v131 offset:32768
	ds_read_b128 v[24:27], v131 offset:33792
	ds_read_b128 v[32:35], v174 offset:32768
	ds_read_b128 v[36:39], v174 offset:33792
	ds_read_b128 v[48:51], v175 offset:32768
	ds_read_b128 v[56:59], v175 offset:33792
	ds_read_b128 v[236:239], v177 offset:32768
	ds_read_b128 v[240:243], v177 offset:33792
	s_waitcnt vmcnt(2)
	s_barrier
; #define LDA(dst,b,h) _Pragma("unroll") for(int m=0;m<4;++m) _Pragma("unroll") for(int k=0;k<2;++k) \
;     dst[m][k]=*reinterpret_cast<const bf16x8*>((char*)SA(b,h)+lds_byte(wr*64+m*16+fr,k*32+fq*8))
; #define LDB(dst,b,h) _Pragma("unroll") for(int n=0;n<2;++n) _Pragma("unroll") for(int k=0;k<2;++k) \
;     dst[n][k]=*reinterpret_cast<const bf16x8*>((char*)SB(b,h)+lds_byte(wc*32+n*16+fr,k*32+fq*8))
; #define MMA(ai,bj,At_,Bt_) do{__builtin_amdgcn_s_setprio(1); \
;     _Pragma("unroll") for(int m=0;m<4;++m) _Pragma("unroll") for(int n=0;n<2;++n) _Pragma("unroll") for(int k=0;k<2;++k) \
;       acc[ai][bj][m][n]=__builtin_amdgcn_mfma_f32_16x16x32_bf16(Bt_[n][k],At_[m][k],acc[ai][bj][m][n],0,0,0); \
;     __builtin_amdgcn_s_setprio(0);}while(0)
; #define WAIT_V(n) asm volatile("s_waitcnt vmcnt(" #n ")":::"memory")
; #define WAIT_L(n) asm volatile("s_waitcnt lgkmcnt(" #n ")":::"memory")
; #define BAR __builtin_amdgcn_s_barrier()
; DEVINL void gemm8_mainloop(const u16* A, long lda, const u16* Bt, long ldb, int K, int brow, int bcol, f32x4 (&acc)[2][2][4][2], char* smem, int tid) {
;     ...
;     LDA(At,0,1); WAIT_V(4); BAR; WAIT_L(0); MMA(1,0,At,B0); MMA(1,1,At,B1); BAR; }
;   { LDB(B0,1,0); LDA(At,1,0); WAIT_V(2); BAR; WAIT_L(0); MMA(0,0,At,B0); BAR;
;     LDB(B1,1,1); WAIT_V(0); BAR; WAIT_L(0); MMA(0,1,At,B1); BAR;
;     LDA(At,1,1); BAR; WAIT_L(0); MMA(1,0,At,B0); MMA(1,1,At,B1); BAR; }
;   if(wr==0)BAR;
	s_waitcnt lgkmcnt(0)
	s_setprio 1
	v_mfma_f32_16x16x32_bf16 v[64:67], v[0:3], v[16:19], v[124:127]
	v_mfma_f32_16x16x32_bf16 v[116:119], v[8:11], v[24:27], v[64:67]
	v_mfma_f32_16x16x32_bf16 v[64:67], v[208:211], v[16:19], v[120:123]
	v_mfma_f32_16x16x32_bf16 v[112:115], v[212:215], v[24:27], v[64:67]
	v_mfma_f32_16x16x32_bf16 v[64:67], v[0:3], v[32:35], v[140:143]
	v_mfma_f32_16x16x32_bf16 v[100:103], v[8:11], v[36:39], v[64:67]
	v_mfma_f32_16x16x32_bf16 v[64:67], v[208:211], v[32:35], v[220:223]
	v_mfma_f32_16x16x32_bf16 v[96:99], v[212:215], v[36:39], v[64:67]
	v_mfma_f32_16x16x32_bf16 v[64:67], v[0:3], v[48:51], v[108:111]
	v_mfma_f32_16x16x32_bf16 v[84:87], v[8:11], v[56:59], v[64:67]
	v_mfma_f32_16x16x32_bf16 v[64:67], v[208:211], v[48:51], v[104:107]
	v_mfma_f32_16x16x32_bf16 v[80:83], v[212:215], v[56:59], v[64:67]
	v_mfma_f32_16x16x32_bf16 v[64:67], v[0:3], v[236:239], v[224:227]
	v_mfma_f32_16x16x32_bf16 v[68:71], v[8:11], v[240:243], v[64:67]
	v_mfma_f32_16x16x32_bf16 v[64:67], v[208:211], v[236:239], v[228:231]
	v_mfma_f32_16x16x32_bf16 v[64:67], v[212:215], v[240:243], v[64:67]
	s_setprio 0
	s_barrier
	ds_read_b128 v[140:143], v152
	ds_read_b128 v[220:223], v152 offset:1024
	ds_read_b128 v[224:227], v152 offset:2048
	ds_read_b128 v[152:155], v152 offset:3072
	s_waitcnt vmcnt(0)
	s_barrier
	s_waitcnt lgkmcnt(0)
	s_setprio 1
	v_mfma_f32_16x16x32_bf16 v[92:95], v[140:143], v[16:19], v[92:95]
	v_mfma_f32_16x16x32_bf16 v[16:19], v[224:227], v[16:19], v[88:91]
	v_mfma_f32_16x16x32_bf16 v[120:123], v[152:155], v[24:27], v[16:19]
	v_mfma_f32_16x16x32_bf16 v[16:19], v[140:143], v[32:35], v[156:159]
	v_mfma_f32_16x16x32_bf16 v[104:107], v[220:223], v[36:39], v[16:19]
	v_mfma_f32_16x16x32_bf16 v[16:19], v[224:227], v[32:35], v[188:191]
	v_mfma_f32_16x16x32_bf16 v[108:111], v[152:155], v[36:39], v[16:19]
	v_mfma_f32_16x16x32_bf16 v[16:19], v[140:143], v[48:51], v[76:79]
	v_mfma_f32_16x16x32_bf16 v[124:127], v[220:223], v[24:27], v[92:95]
	v_mfma_f32_16x16x32_bf16 v[92:95], v[220:223], v[56:59], v[16:19]
	v_mfma_f32_16x16x32_bf16 v[16:19], v[224:227], v[48:51], v[72:75]
	v_mfma_f32_16x16x32_bf16 v[88:91], v[152:155], v[56:59], v[16:19]
	v_mfma_f32_16x16x32_bf16 v[16:19], v[140:143], v[236:239], v[192:195]
	v_mfma_f32_16x16x32_bf16 v[72:75], v[220:223], v[240:243], v[16:19]
	v_mfma_f32_16x16x32_bf16 v[16:19], v[224:227], v[236:239], v[196:199]
	v_mfma_f32_16x16x32_bf16 v[76:79], v[152:155], v[240:243], v[16:19]
	s_setprio 0
	s_barrier
	ds_read_b128 v[156:159], v131 offset:49152
	ds_read_b128 v[186:189], v131 offset:50176
	ds_read_b128 v[190:193], v174 offset:49152
	ds_read_b128 v[194:197], v174 offset:50176
	ds_read_b128 v[228:231], v175 offset:49152
	ds_read_b128 v[236:239], v175 offset:50176
	ds_read_b128 v[240:243], v177 offset:49152
	ds_read_b128 v[244:247], v177 offset:50176
	s_barrier
	s_waitcnt lgkmcnt(0)
	s_setprio 1
	v_mfma_f32_16x16x32_bf16 v[16:19], v[0:3], v[156:159], v[60:63]
	v_mfma_f32_16x16x32_bf16 v[56:59], v[8:11], v[186:189], v[16:19]
	v_mfma_f32_16x16x32_bf16 v[16:19], v[208:211], v[156:159], v[216:219]
	v_mfma_f32_16x16x32_bf16 v[48:51], v[212:215], v[186:189], v[16:19]
	v_mfma_f32_16x16x32_bf16 v[16:19], v[0:3], v[190:193], v[52:55]
	v_mfma_f32_16x16x32_bf16 v[36:39], v[8:11], v[194:197], v[16:19]
	v_mfma_f32_16x16x32_bf16 v[16:19], v[208:211], v[190:193], v[232:235]
	v_mfma_f32_16x16x32_bf16 v[32:35], v[212:215], v[194:197], v[16:19]
	v_mfma_f32_16x16x32_bf16 v[16:19], v[0:3], v[228:231], v[44:47]
	v_mfma_f32_16x16x32_bf16 v[0:3], v[0:3], v[240:243], v[144:147]
	v_mfma_f32_16x16x32_bf16 v[24:27], v[8:11], v[236:239], v[16:19]
	v_mfma_f32_16x16x32_bf16 v[16:19], v[208:211], v[228:231], v[40:43]
	v_mfma_f32_16x16x32_bf16 v[8:11], v[8:11], v[244:247], v[0:3]
	v_mfma_f32_16x16x32_bf16 v[0:3], v[208:211], v[240:243], v[148:151]
	v_mfma_f32_16x16x32_bf16 v[16:19], v[212:215], v[236:239], v[16:19]
	v_mfma_f32_16x16x32_bf16 v[0:3], v[212:215], v[244:247], v[0:3]
	s_setprio 0
	s_setprio 1
	v_mfma_f32_16x16x32_bf16 v[28:31], v[140:143], v[156:159], v[28:31]
	v_mfma_f32_16x16x32_bf16 v[60:63], v[220:223], v[186:189], v[28:31]
	v_mfma_f32_16x16x32_bf16 v[28:31], v[224:227], v[156:159], v[178:181]
	v_mfma_f32_16x16x32_bf16 v[20:23], v[140:143], v[190:193], v[20:23]
	v_mfma_f32_16x16x32_bf16 v[12:15], v[140:143], v[228:231], v[12:15]
	v_mfma_f32_16x16x32_bf16 v[52:55], v[152:155], v[186:189], v[28:31]
	v_mfma_f32_16x16x32_bf16 v[40:43], v[220:223], v[194:197], v[20:23]
	v_mfma_f32_16x16x32_bf16 v[20:23], v[224:227], v[190:193], v[182:185]
	v_mfma_f32_16x16x32_bf16 v[28:31], v[220:223], v[236:239], v[12:15]
	v_mfma_f32_16x16x32_bf16 v[12:15], v[224:227], v[228:231], v[200:203]
	v_mfma_f32_16x16x32_bf16 v[4:7], v[140:143], v[240:243], v[4:7]
	v_mfma_f32_16x16x32_bf16 v[44:47], v[152:155], v[194:197], v[20:23]
	v_mfma_f32_16x16x32_bf16 v[20:23], v[152:155], v[236:239], v[12:15]
	v_mfma_f32_16x16x32_bf16 v[12:15], v[220:223], v[244:247], v[4:7]
	v_mfma_f32_16x16x32_bf16 v[4:7], v[224:227], v[240:243], v[204:207]
	v_mfma_f32_16x16x32_bf16 v[4:7], v[152:155], v[244:247], v[4:7]
	s_setprio 0
	s_cmpk_gt_u32 s44, 0xff
	s_barrier
	s_cbranch_scc1 .LBB0_272
	s_barrier

; #define LDK(DST, KQ) _Pragma("unroll") for (int kc = 0; kc < 4; ++kc) DST[kc] = *(const bf16x8*)(Ks + ((KQ) * 16 + fr) * 136 + kc * 32 + fq * 8)
; DEVINL void attn_item(const Params& p, int item, char* smem, int wv) {
;     ...
;   const size_t qtok = (size_t)b * SEQ + q0 + wid * 16 + fr;
;   bf16x8 qf[2][4];
; #pragma unroll
;   for (int hh = 0; hh < 2; ++hh)
; #pragma unroll
;     for (int kc = 0; kc < 4; ++kc)
;       qf[hh][kc] = *(const bf16x8*)(hb + qtok * HS + 2560 + (kvh * 2 + hh) * 128 + kc * 32 + fq * 8);
;   f32x4 o[2][8];
; #pragma unroll
;   for (int hh = 0; hh < 2; ++hh)
; #pragma unroll
;     for (int dt = 0; dt < 8; ++dt) o[hh][dt] = f32x4{0.f, 0.f, 0.f, 0.f};
;   float mrun[2] = {0.f, 0.f}, lsum[2] = {0.f, 0.f};
;   unsigned long long mw_next = bits[qtok * 64];
;   u32x4 rk[2], rv[2];
;   const u16* kg = hb + ((size_t)b * SEQ + (tid >> 4)) * HS + 3584 + kvh * 128 + (tid & 15) * 8;
;   const u16* vg = vT + ((size_t)(b * 4 + kvh) * 128 + (tid >> 3)) * SEQ + (tid & 7) * 8;
; #pragma unroll
;   for (int i = 0; i < 2; ++i) {
;     rk[i] = *(const u32x4*)(kg + (size_t)(32 * i) * HS);
;     rv[i] = *(const u32x4*)(vg + (size_t)(64 * i) * SEQ);
;   }
;   for (int kt = 0; kt < ntile; ++kt) {
; #pragma unroll
;     for (int i = 0; i < 2; ++i) {
;       *(u32x4*)(Ks + ((tid >> 4) + 32 * i) * 136 + (tid & 15) * 8) = rk[i];
;       *(u32x4*)(Vs + ((tid >> 3) + 64 * i) * 72 + (tid & 7) * 8) = rv[i];
;     }
;     __syncthreads();
;     if (kt + 1 < ntile) {
; #pragma unroll
;       for (int i = 0; i < 2; ++i) {
;         rk[i] = *(const u32x4*)(kg + (size_t)((kt + 1) * 64 + 32 * i) * HS);
;         rv[i] = *(const u32x4*)(vg + (size_t)(64 * i) * SEQ + (kt + 1) * 64);
;       }
;     }
;     const unsigned long long mw = mw_next;
;     if (kt + 1 < ntile) mw_next = bits[qtok * 64 + kt + 1];
;     if (kt * 64 <= qlast) {
;     f32x4 s[2][4];
;     bf16x8 kfa[4], kfb[4];
;     bf16x8 vfa[2], vfb[2];
;     ...
;     LDK(kfa, 0);
;     LDK(kfb, 1); MMS(kfa, 0);
;     LDK(kfa, 2); MMS(kfb, 1);
;     LDK(kfb, 3); MMS(kfa, 2);
;     LDV(vfa, 0); MMS(kfb, 3);
.Lprio_skip_a0:
	s_and_b32 s33, s1, 0x3000
	v_and_b32_e32 v60, 15, v120
	s_and_b32 s0, s31, -16
	s_add_i32 s8, s7, s33
	s_ashr_i32 s1, s0, 31
	v_or_b32_e32 v0, s8, v60
	s_waitcnt vmcnt(1)
	v_lshl_add_u64 v[156:157], v[0:1], 0, s[0:1]
	v_mov_b64_e32 v[2:3], s[62:63]
	v_mad_u64_u32 v[4:5], s[0:1], v156, s19, v[2:3]
	s_and_b32 s6, s5, 3
	v_mad_i32_i24 v5, v157, s19, v5
	v_and_b32_e32 v0, 48, v120
	v_lshl_add_u64 v[4:5], v[4:5], 0, v[0:1]
	s_lshl_b32 s8, s6, 9
	v_ashrrev_i32_e32 v14, 4, v120
	v_lshl_add_u64 v[8:9], v[4:5], 0, s[8:9]
	v_add_u32_e32 v4, s33, v14
	s_lshl_b32 s16, s6, 8
	s_mov_b32 s17, s9
	v_mad_i64_i32 v[2:3], s[0:1], v4, s19, v[2:3]
	v_lshlrev_b32_e32 v6, 4, v120
	v_lshl_add_u64 v[2:3], v[2:3], 0, s[16:17]
	v_and_b32_e32 v10, 0xf0, v6
	v_mov_b32_e32 v11, v1
	v_lshl_add_u64 v[116:117], v[2:3], 0, v[10:11]
	s_lshl_b32 s0, s5, 7
	v_ashrrev_i32_e32 v2, 3, v120
	s_and_b32 s8, s0, 0x780
	v_ashrrev_i32_e32 v3, 31, v2
	v_lshl_add_u64 v[4:5], v[2:3], 0, s[8:9]
	v_lshlrev_b64 v[4:5], 13, v[4:5]
	v_lshl_add_u64 v[4:5], s[82:83], 0, v[4:5]
	v_and_b32_e32 v12, 0x70, v6
	v_mov_b32_e32 v13, v1
	v_lshl_add_u64 v[158:159], v[4:5], 0, v[12:13]
	v_add_co_u32_e32 v4, vcc, s20, v116
	global_load_dwordx4 v[36:39], v[158:159], off
	s_nop 0
	v_addc_co_u32_e32 v5, vcc, 0, v117, vcc
	v_add_co_u32_e32 v6, vcc, s21, v116
	v_mul_lo_u32 v2, v2, s24
	s_nop 0
	v_addc_co_u32_e32 v7, vcc, 0, v117, vcc
	global_load_dwordx4 v[40:43], v[4:5], off offset:3072
	global_load_dwordx4 v[44:47], v[6:7], off offset:3072
	v_add_co_u32_e32 v52, vcc, s22, v158
	v_add_u32_e32 v11, 0, v12
	s_nop 0
	v_addc_co_u32_e32 v53, vcc, 0, v159, vcc
	global_load_dwordx4 v[48:51], v[52:53], off
	v_mul_lo_u32 v3, v14, s23
	v_add_u32_e32 v10, 0, v10
	v_and_b32_e32 v173, 64, v12
	v_bfe_u32 v11, v12, 4, 1
	v_lshl_or_b32 v173, v11, 5, v173
	v_bfe_u32 v11, v12, 5, 1
	v_lshl_or_b32 v173, v11, 3, v173
	v_add_u32_e32 v173, v173, v2
	v_add_co_u32_e64 v2, s[0:1], s20, v8
	v_lshl_add_u64 v[28:29], v[8:9], 0, s[10:11]
	v_add_u32_e32 v172, v10, v3
	v_lshlrev_b64 v[118:119], 9, v[156:157]
	v_add_co_u32_e32 v54, vcc, 0xa1000, v116
	v_addc_co_u32_e64 v3, s[0:1], 0, v9, s[0:1]
	global_load_dwordx4 v[4:7], v[28:29], off offset:64
	v_lshl_add_u64 v[56:57], s[80:81], 0, v[118:119]
	v_addc_co_u32_e32 v55, vcc, 0, v117, vcc
	global_load_dwordx4 v[8:11], v[28:29], off offset:128
	global_load_dwordx4 v[12:15], v[28:29], off offset:192
	global_load_dwordx4 v[16:19], v[28:29], off offset:256
	global_load_dwordx4 v[20:23], v[28:29], off offset:320
	global_load_dwordx4 v[24:27], v[28:29], off offset:384
	s_nop 0
	global_load_dwordx4 v[28:31], v[28:29], off offset:448
	s_nop 0
	global_load_dwordx4 v[32:35], v[2:3], off offset:1024
	s_nop 0
	global_load_dwordx2 v[2:3], v[56:57], off
	v_add_co_u32_e32 v58, vcc, 0xf1000, v116
	s_add_i32 s8, s31, s7
	s_nop 0
	v_addc_co_u32_e32 v59, vcc, 0, v117, vcc
	s_cmp_gt_i32 s8, -1
	s_mov_b64 s[0:1], -1
	s_waitcnt vmcnt(11)
	ds_write_b128 v172, v[40:43]
	ds_write_b64 v173, v[36:37] offset:17408
	ds_write_b64 v173, v[38:39] offset:17424
	s_waitcnt vmcnt(10)
	ds_write_b128 v172, v[44:47] offset:8704
	s_waitcnt vmcnt(9)
	ds_write_b64 v173, v[48:49] offset:26624
	ds_write_b64 v173, v[50:51] offset:26640
	s_waitcnt lgkmcnt(0)
	s_barrier
	global_load_dwordx4 v[44:47], v[58:59], off offset:3072
	global_load_dwordx4 v[36:39], v[54:55], off offset:3072
	global_load_dwordx4 v[48:51], v[52:53], off offset:128
	global_load_dwordx4 v[40:43], v[158:159], off offset:128
	global_load_dwordx2 v[162:163], v[56:57], off offset:8
	v_mad_u32_u24 v52, v60, s23, 0
	v_lshlrev_b32_e32 v53, 7, v60
	v_lshrrev_b32_e32 v54, 2, v120
	v_sub_u32_e32 v53, v52, v53
	v_and_b32_e32 v174, 12, v54
	v_add_u32_e32 v175, v52, v0
	v_lshl_add_u32 v177, v174, 2, v53
	s_cbranch_scc0 .LBB0_704
	ds_read_b128 v[52:55], v175
	ds_read_b128 v[56:59], v175 offset:64
	ds_read_b128 v[60:63], v175 offset:128
	ds_read_b128 v[64:67], v175 offset:192
	ds_read_b128 v[68:71], v175 offset:4352
	ds_read_b128 v[72:75], v175 offset:4416
	ds_read_b128 v[76:79], v175 offset:4480
	ds_read_b128 v[80:83], v175 offset:4544
	s_mov_b32 s6, s4
	s_mov_b32 s7, s4
	s_mov_b32 s5, s4
	v_mov_b64_e32 v[86:87], s[6:7]
	v_mov_b64_e32 v[84:85], s[4:5]
	s_waitcnt vmcnt(6) lgkmcnt(7)
	s_nop 0
	v_mfma_f32_16x16x32_bf16 v[88:91], v[52:55], v[32:35], v[84:87]
	v_mfma_f32_16x16x32_bf16 v[52:55], v[52:55], v[16:19], v[84:87]
	s_waitcnt lgkmcnt(6)
	v_mfma_f32_16x16x32_bf16 v[88:91], v[56:59], v[4:7], v[88:91]
	v_mfma_f32_16x16x32_bf16 v[52:55], v[56:59], v[20:23], v[52:55]
	s_waitcnt lgkmcnt(5)
	v_mfma_f32_16x16x32_bf16 v[56:59], v[60:63], v[8:11], v[88:91]
	v_mfma_f32_16x16x32_bf16 v[52:55], v[60:63], v[24:27], v[52:55]
	s_waitcnt lgkmcnt(4)
	v_mfma_f32_16x16x32_bf16 v[60:63], v[64:67], v[12:15], v[56:59]
	v_mfma_f32_16x16x32_bf16 v[64:67], v[64:67], v[28:31], v[52:55]
	s_nop 3
	s_nop 0
	ds_read_b128 v[52:55], v175 offset:8704
	ds_read_b128 v[56:59], v175 offset:8768
	ds_read_b128 v[88:91], v175 offset:8832
	ds_read_b128 v[92:95], v175 offset:8896
	s_waitcnt lgkmcnt(7)
	v_mfma_f32_16x16x32_bf16 v[96:99], v[68:71], v[32:35], v[84:87]
	v_mfma_f32_16x16x32_bf16 v[68:71], v[68:71], v[16:19], v[84:87]
	s_waitcnt lgkmcnt(6)
	v_mfma_f32_16x16x32_bf16 v[96:99], v[72:75], v[4:7], v[96:99]
	v_mfma_f32_16x16x32_bf16 v[68:71], v[72:75], v[20:23], v[68:71]
	s_waitcnt lgkmcnt(5)
	v_mfma_f32_16x16x32_bf16 v[72:75], v[76:79], v[8:11], v[96:99]
	v_mfma_f32_16x16x32_bf16 v[68:71], v[76:79], v[24:27], v[68:71]
	s_waitcnt lgkmcnt(4)
; DEVINL void attn_item(const Params& p, int item, char* smem, int wv) {
;     ...
;     LDK(kfb, 1); MMS(kfa, 0);
;     LDK(kfa, 2); MMS(kfb, 1);
;     LDK(kfb, 3); MMS(kfa, 2);
;     LDV(vfa, 0); MMS(kfb, 3);
;     bf16x8 pf[2][2];
;     {
;       const unsigned long long msh = mw >> (fq * 4);
;       const int mlo = (int)(unsigned)msh, mhi = (int)(unsigned)(msh >> 32);
;       int mk[4][4];
; #pragma unroll
;       for (int j = 0; j < 4; ++j) {
;         mk[0][j] = __builtin_amdgcn_sbfe(mlo, j, 1); mk[1][j] = __builtin_amdgcn_sbfe(mlo, 16 + j, 1);
;         mk[2][j] = __builtin_amdgcn_sbfe(mhi, j, 1); mk[3][j] = __builtin_amdgcn_sbfe(mhi, 16 + j, 1);
;       }
; #pragma unroll
;       for (int hh = 0; hh < 2; ++hh) {
;         float mx = s[hh][0][0];
; #pragma unroll
;         for (int kq = 0; kq < 4; ++kq)
; #pragma unroll
;           for (int j = 0; j < 4; ++j) mx = fmaxf(mx, s[hh][kq][j]);
;         {
;           auto r1 = __builtin_amdgcn_permlane16_swap(__float_as_uint(mx), __float_as_uint(mx), false, false);
;           mx = fmaxf(__uint_as_float(r1[0]), __uint_as_float(r1[1]));
;           auto r2 = __builtin_amdgcn_permlane32_swap(__float_as_uint(mx), __float_as_uint(mx), false, false);
;           mx = fmaxf(__uint_as_float(r2[0]), __uint_as_float(r2[1]));
;         }
;         if (kt == 0 || __ballot(mx > 8.f)) {
;           const float delta = (kt == 0) ? mx : fmaxf(mx, 0.f);
;           const float alpha = fexp2(-delta);
;           mrun[hh] += delta;
;           lsum[hh] *= alpha;
; #pragma unroll
;           for (int dt = 0; dt < 8; ++dt) o[hh][dt] *= alpha;
; #pragma unroll
;           for (int kq = 0; kq < 4; ++kq)
; #pragma unroll
;             for (int j = 0; j < 4; ++j) s[hh][kq][j] -= delta;
;         }
;         float ps = 0.f;
;         float pv[4][4];
; #pragma unroll
;         for (int kq = 0; kq < 4; ++kq)
; #pragma unroll
;           for (int j = 0; j < 4; ++j) {
;             pv[kq][j] = __uint_as_float(__float_as_uint(fexp2(s[hh][kq][j])) & (unsigned)mk[kq][j]);
;             ps += pv[kq][j];
;           }
; #pragma unroll
;         for (int c2 = 0; c2 < 2; ++c2) {
;           u32x4 pw;
;           pw[0] = pk2(pv[2 * c2][0], pv[2 * c2][1]); pw[1] = pk2(pv[2 * c2][2], pv[2 * c2][3]);
;           pw[2] = pk2(pv[2 * c2 + 1][0], pv[2 * c2 + 1][1]); pw[3] = pk2(pv[2 * c2 + 1][2], pv[2 * c2 + 1][3]);
;           pf[hh][c2] = *(bf16x8*)&pw;
	v_mfma_f32_16x16x32_bf16 v[72:75], v[80:83], v[12:15], v[72:75]
	v_mfma_f32_16x16x32_bf16 v[68:71], v[80:83], v[28:31], v[68:71]
	ds_read_b128 v[76:79], v175 offset:13056
	ds_read_b128 v[80:83], v175 offset:13120
	ds_read_b128 v[96:99], v175 offset:13184
	ds_read_b128 v[100:103], v175 offset:13248
	s_waitcnt lgkmcnt(7)
	v_mfma_f32_16x16x32_bf16 v[104:107], v[52:55], v[32:35], v[84:87]
	v_mfma_f32_16x16x32_bf16 v[52:55], v[52:55], v[16:19], v[84:87]
	s_waitcnt lgkmcnt(6)
	v_mfma_f32_16x16x32_bf16 v[104:107], v[56:59], v[4:7], v[104:107]
	v_mfma_f32_16x16x32_bf16 v[52:55], v[56:59], v[20:23], v[52:55]
	s_waitcnt lgkmcnt(5)
	v_mfma_f32_16x16x32_bf16 v[56:59], v[88:91], v[8:11], v[104:107]
	v_mfma_f32_16x16x32_bf16 v[52:55], v[88:91], v[24:27], v[52:55]
	s_waitcnt lgkmcnt(4)
	v_mfma_f32_16x16x32_bf16 v[88:91], v[92:95], v[12:15], v[56:59]
	v_mfma_f32_16x16x32_bf16 v[92:95], v[92:95], v[28:31], v[52:55]
	s_nop 2
	s_nop 1
	ds_read_b128 v[52:55], v177 offset:17408
	ds_read_b128 v[56:59], v177 offset:17472
	s_waitcnt lgkmcnt(5)
	v_mfma_f32_16x16x32_bf16 v[104:107], v[76:79], v[32:35], v[84:87]
	v_mfma_f32_16x16x32_bf16 v[76:79], v[76:79], v[16:19], v[84:87]
	s_waitcnt lgkmcnt(4)
	v_mfma_f32_16x16x32_bf16 v[84:87], v[80:83], v[4:7], v[104:107]
	v_mfma_f32_16x16x32_bf16 v[76:79], v[80:83], v[20:23], v[76:79]
	s_waitcnt lgkmcnt(3)
	v_mfma_f32_16x16x32_bf16 v[80:83], v[96:99], v[8:11], v[84:87]
	v_mfma_f32_16x16x32_bf16 v[76:79], v[96:99], v[24:27], v[76:79]
	s_waitcnt lgkmcnt(2)
	v_mfma_f32_16x16x32_bf16 v[80:83], v[100:103], v[12:15], v[80:83]
	v_mfma_f32_16x16x32_bf16 v[76:79], v[100:103], v[28:31], v[76:79]
	s_waitcnt vmcnt(5)
	v_lshrrev_b64 v[2:3], v174, v[2:3]
	v_bfe_i32 v0, v2, 0, 1
	v_bfe_i32 v86, v2, 16, 1
	v_bfe_i32 v87, v3, 0, 1
	v_bfe_i32 v96, v3, 16, 1
	v_bfe_i32 v97, v2, 1, 1
	v_bfe_i32 v98, v2, 17, 1
	v_bfe_i32 v99, v3, 1, 1
	v_bfe_i32 v104, v3, 17, 1
	v_bfe_i32 v100, v2, 2, 1
	v_bfe_i32 v101, v2, 18, 1
	v_bfe_i32 v105, v3, 2, 1
	v_bfe_i32 v106, v3, 18, 1
	v_bfe_i32 v102, v2, 3, 1
	v_bfe_i32 v103, v2, 19, 1
	v_bfe_i32 v107, v3, 3, 1
	v_bfe_i32 v108, v3, 19, 1
	v_max_f32_e32 v3, v60, v60
	v_max_f32_e32 v2, v3, v61
	v_max3_f32 v2, v2, v62, v63
	v_max3_f32 v2, v2, v72, v73
	v_max3_f32 v2, v2, v74, v75
	v_max3_f32 v2, v2, v88, v89
	v_max3_f32 v2, v2, v90, v91
	v_max3_f32 v2, v2, v80, v81
	v_max3_f32 v2, v2, v82, v83
	v_mov_b32_e32 v3, v2
	s_nop 1
	v_permlane16_swap_b32_e32 v2, v3
	v_max_f32_e32 v2, v2, v3
	v_mov_b32_e32 v3, v2
	s_nop 1
	v_permlane32_swap_b32_e32 v2, v3
	v_max_f32_e32 v3, v2, v3
	v_sub_f32_e32 v2, v80, v3
	v_sub_f32_e32 v61, v61, v3
	v_sub_f32_e32 v80, v81, v3
	v_sub_f32_e32 v81, v82, v3
	v_sub_f32_e32 v82, v83, v3
	v_sub_f32_e32 v83, v88, v3
	v_sub_f32_e32 v88, v90, v3
	v_exp_f32_e32 v90, v61
	v_exp_f32_e32 v115, v2
	v_max_f32_e32 v61, v64, v64
	v_max_f32_e32 v2, v61, v65
	v_max3_f32 v2, v2, v66, v67
	v_max3_f32 v2, v2, v68, v69
	v_max3_f32 v2, v2, v70, v71
	v_max3_f32 v2, v2, v92, v93
	v_max3_f32 v2, v2, v94, v95
	v_max3_f32 v2, v2, v76, v77
	v_max3_f32 v2, v2, v78, v79
	v_mov_b32_e32 v61, v2
	s_nop 1
	v_permlane16_swap_b32_e32 v2, v61
	v_max_f32_e32 v2, v2, v61
	v_mov_b32_e32 v61, v2
	s_nop 1
	v_permlane32_swap_b32_e32 v2, v61
	v_max_f32_e32 v2, v2, v61
	v_sub_f32_e32 v60, v60, v3
	v_sub_f32_e32 v64, v64, v2
	v_exp_f32_e32 v60, v60
	v_sub_f32_e32 v65, v65, v2
	v_exp_f32_e32 v64, v64
	v_sub_f32_e32 v62, v62, v3
	v_sub_f32_e32 v66, v66, v2
	v_exp_f32_e32 v65, v65
	v_sub_f32_e32 v85, v89, v3
	v_sub_f32_e32 v89, v91, v3
	v_sub_f32_e32 v63, v63, v3
	v_exp_f32_e32 v91, v62
	v_sub_f32_e32 v67, v67, v2
	v_exp_f32_e32 v66, v66
	v_sub_f32_e32 v72, v72, v3
	v_exp_f32_e32 v109, v63
	v_sub_f32_e32 v61, v68, v2
	v_sub_f32_e32 v62, v69, v2
	v_exp_f32_e32 v67, v67
	v_sub_f32_e32 v73, v73, v3
	v_exp_f32_e32 v72, v72
	v_exp_f32_e32 v113, v83
	v_exp_f32_e32 v125, v82
	v_sub_f32_e32 v82, v92, v2
	v_sub_f32_e32 v83, v93, v2
	v_sub_f32_e32 v63, v70, v2
	v_sub_f32_e32 v68, v71, v2
	v_exp_f32_e32 v70, v61
	v_exp_f32_e32 v71, v62
	v_and_b32_e32 v61, v0, v64
	v_and_b32_e32 v60, v0, v60
	v_and_b32_e32 v62, v97, v90
	v_sub_f32_e32 v74, v74, v3
	v_exp_f32_e32 v110, v73
	v_exp_f32_e32 v121, v80
	v_exp_f32_e32 v124, v81
	v_sub_f32_e32 v122, v76, v2
	v_sub_f32_e32 v126, v78, v2
	v_exp_f32_e32 v76, v63
	v_exp_f32_e32 v78, v68
	v_and_b32_e32 v63, v97, v65
	v_cvt_pk_bf16_f32 v68, v60, v62
	v_pk_add_f32 v[80:81], v[60:61], 0 op_sel_hi:[1,0]
	v_exp_f32_e32 v0, v82
	v_exp_f32_e32 v60, v83
	v_sub_f32_e32 v75, v75, v3
	v_exp_f32_e32 v111, v74
	v_and_b32_e32 v65, v100, v66
	v_and_b32_e32 v64, v100, v91
	v_pk_add_f32 v[80:81], v[80:81], v[62:63]
	v_exp_f32_e32 v112, v75
	v_and_b32_e32 v67, v102, v67
	v_and_b32_e32 v66, v102, v109
	v_pk_add_f32 v[80:81], v[80:81], v[64:65]
	v_sub_f32_e32 v93, v95, v2
	v_and_b32_e32 v73, v86, v70
	v_and_b32_e32 v72, v86, v72
	v_pk_add_f32 v[80:81], v[80:81], v[66:67]
	v_exp_f32_e32 v114, v85
	v_sub_f32_e32 v92, v94, v2
	v_and_b32_e32 v75, v98, v71
	v_and_b32_e32 v74, v98, v110
	v_pk_add_f32 v[80:81], v[80:81], v[72:73]
	v_and_b32_e32 v83, v87, v0
	v_and_b32_e32 v82, v87, v113
	v_and_b32_e32 v87, v99, v60
	v_exp_f32_e32 v60, v93
	v_exp_f32_e32 v88, v88
	v_sub_f32_e32 v123, v77, v2
	v_and_b32_e32 v77, v101, v76
	v_and_b32_e32 v76, v101, v111
; DEVINL float fexp2(float x) { return __builtin_amdgcn_exp2f(x); }
; DEVINL uint32_t pk2(float a, float b) { hwf2 v = {a, b}; hwbf2 r = __builtin_convertvector(v, hwbf2); return *(uint32_t*)&r; }
; #define MMV(SRC, DT) do { __builtin_amdgcn_s_setprio(1); _Pragma("unroll") for (int c2 = 0; c2 < 2; ++c2) { o[0][DT] = mfma16(SRC[c2], pf[0][c2], o[0][DT]); o[1][DT] = mfma16(SRC[c2], pf[1][c2], o[1][DT]); } __builtin_amdgcn_s_setprio(0); } while (0)
; DEVINL void attn_item(const Params& p, int item, char* smem, int wv) {
;     ...
;         float ps = 0.f;
;         float pv[4][4];
; #pragma unroll
;         for (int kq = 0; kq < 4; ++kq)
; #pragma unroll
;           for (int j = 0; j < 4; ++j) {
;             pv[kq][j] = __uint_as_float(__float_as_uint(fexp2(s[hh][kq][j])) & (unsigned)mk[kq][j]);
;             ps += pv[kq][j];
;           }
; #pragma unroll
;         for (int c2 = 0; c2 < 2; ++c2) {
;           u32x4 pw;
;           pw[0] = pk2(pv[2 * c2][0], pv[2 * c2][1]); pw[1] = pk2(pv[2 * c2][2], pv[2 * c2][3]);
;           pw[2] = pk2(pv[2 * c2 + 1][0], pv[2 * c2 + 1][1]); pw[3] = pk2(pv[2 * c2 + 1][2], pv[2 * c2 + 1][3]);
;           pf[hh][c2] = *(bf16x8*)&pw;
;         }
;         lsum[hh] += ps;
;       }
;     }
;     LDV(vfb, 1); MMV(vfa, 0);
;     LDV(vfa, 2); MMV(vfb, 1);
;     LDV(vfb, 3); MMV(vfa, 2);
;     LDV(vfa, 4); MMV(vfb, 3);
;     LDV(vfb, 5); MMV(vfa, 4);
;     LDV(vfa, 6); MMV(vfb, 5);
;     LDV(vfb, 7); MMV(vfa, 6);
;     MMV(vfb, 7);
	v_pk_add_f32 v[80:81], v[80:81], v[74:75]
	v_exp_f32_e32 v0, v92
	v_exp_f32_e32 v89, v89
	v_sub_f32_e32 v127, v79, v2
	v_and_b32_e32 v79, v103, v78
	v_and_b32_e32 v78, v103, v112
	v_pk_add_f32 v[80:81], v[80:81], v[76:77]
	v_exp_f32_e32 v62, v122
	v_pk_add_f32 v[80:81], v[80:81], v[78:79]
	v_cvt_pk_bf16_f32 v69, v64, v66
	v_and_b32_e32 v86, v99, v114
	v_exp_f32_e32 v64, v123
	v_cvt_pk_bf16_f32 v100, v61, v63
	v_cvt_pk_bf16_f32 v102, v73, v75
	v_and_b32_e32 v75, v107, v60
	v_pk_add_f32 v[60:61], v[80:81], v[82:83]
	v_cvt_pk_bf16_f32 v70, v72, v74
	v_exp_f32_e32 v66, v126
	v_and_b32_e32 v73, v105, v0
	v_and_b32_e32 v72, v105, v88
	v_pk_add_f32 v[60:61], v[60:61], v[86:87]
	v_exp_f32_e32 v90, v127
	v_and_b32_e32 v74, v107, v89
	v_pk_add_f32 v[60:61], v[60:61], v[72:73]
	v_cvt_pk_bf16_f32 v71, v76, v78
	v_cvt_pk_bf16_f32 v103, v77, v79
	v_and_b32_e32 v77, v96, v62
	v_and_b32_e32 v76, v96, v115
	v_pk_add_f32 v[60:61], v[60:61], v[74:75]
	v_and_b32_e32 v79, v104, v64
	v_and_b32_e32 v78, v104, v121
	v_pk_add_f32 v[60:61], v[60:61], v[76:77]
	v_and_b32_e32 v89, v106, v66
	v_and_b32_e32 v88, v106, v124
	v_pk_add_f32 v[60:61], v[60:61], v[78:79]
	v_and_b32_e32 v91, v108, v90
	v_and_b32_e32 v90, v108, v125
	v_pk_add_f32 v[60:61], v[60:61], v[88:89]
	v_exp_f32_e64 v84, -v3
	v_exp_f32_e64 v85, -v2
	v_cvt_pk_bf16_f32 v101, v65, v67
	v_pk_add_f32 v[80:81], v[60:61], v[90:91]
	ds_read_b128 v[60:63], v177 offset:19712
	ds_read_b128 v[64:67], v177 offset:19776
	v_pk_add_f32 v[2:3], v[2:3], 0 op_sel_hi:[1,0]
	v_pk_mul_f32 v[122:123], v[84:85], 0 op_sel_hi:[1,0]
	v_pk_fma_f32 v[160:161], v[84:85], 0, v[80:81] op_sel_hi:[1,0,1]
	v_mov_b32_e32 v126, v122
	v_mov_b32_e32 v127, v122
	v_mov_b32_e32 v128, v122
	v_mov_b32_e32 v129, v122
	v_cvt_pk_bf16_f32 v130, v82, v86
	v_cvt_pk_bf16_f32 v131, v72, v74
	v_cvt_pk_bf16_f32 v132, v76, v78
	v_cvt_pk_bf16_f32 v133, v88, v90
	v_mov_b32_e32 v122, v123
	v_mov_b32_e32 v124, v123
	v_mov_b32_e32 v125, v123
	v_cvt_pk_bf16_f32 v134, v83, v87
	v_cvt_pk_bf16_f32 v135, v73, v75
	v_cvt_pk_bf16_f32 v136, v77, v79
	v_cvt_pk_bf16_f32 v137, v89, v91
	s_waitcnt lgkmcnt(3)
	v_mfma_f32_16x16x32_bf16 v[72:75], v[52:55], v[68:71], v[126:129]
	v_mfma_f32_16x16x32_bf16 v[52:55], v[52:55], v[100:103], v[122:125]
	s_waitcnt lgkmcnt(2)
	v_mfma_f32_16x16x32_bf16 v[88:91], v[56:59], v[130:133], v[72:75]
	v_mfma_f32_16x16x32_bf16 v[52:55], v[56:59], v[134:137], v[52:55]
	s_nop 1
	s_nop 1
	ds_read_b128 v[72:75], v177 offset:22016
	ds_read_b128 v[76:79], v177 offset:22080
	s_waitcnt lgkmcnt(3)
	v_mfma_f32_16x16x32_bf16 v[56:59], v[60:63], v[68:71], v[126:129]
	v_mfma_f32_16x16x32_bf16 v[60:63], v[60:63], v[100:103], v[122:125]
	s_waitcnt lgkmcnt(2)
	v_mfma_f32_16x16x32_bf16 v[84:87], v[64:67], v[130:133], v[56:59]
	v_mfma_f32_16x16x32_bf16 v[56:59], v[64:67], v[134:137], v[60:63]
	ds_read_b128 v[64:67], v177 offset:24320
	ds_read_b128 v[80:83], v177 offset:24384
	s_waitcnt lgkmcnt(3)
	v_mfma_f32_16x16x32_bf16 v[60:63], v[72:75], v[68:71], v[126:129]
	v_mfma_f32_16x16x32_bf16 v[72:75], v[72:75], v[100:103], v[122:125]
	s_waitcnt lgkmcnt(2)
	v_mfma_f32_16x16x32_bf16 v[92:95], v[76:79], v[130:133], v[60:63]
	v_mfma_f32_16x16x32_bf16 v[60:63], v[76:79], v[134:137], v[72:75]
	s_nop 2
	s_nop 1
	ds_read_b128 v[72:75], v177 offset:26624
	ds_read_b128 v[76:79], v177 offset:26688
	s_waitcnt lgkmcnt(3)
	v_mfma_f32_16x16x32_bf16 v[96:99], v[64:67], v[68:71], v[126:129]
	v_mfma_f32_16x16x32_bf16 v[64:67], v[64:67], v[100:103], v[122:125]
	s_waitcnt lgkmcnt(2)
	v_mfma_f32_16x16x32_bf16 v[96:99], v[80:83], v[130:133], v[96:99]
	v_mfma_f32_16x16x32_bf16 v[64:67], v[80:83], v[134:137], v[64:67]
	ds_read_b128 v[80:83], v177 offset:28928
	ds_read_b128 v[112:115], v177 offset:28992
	s_waitcnt lgkmcnt(3)
	v_mfma_f32_16x16x32_bf16 v[104:107], v[72:75], v[68:71], v[126:129]
	v_mfma_f32_16x16x32_bf16 v[72:75], v[72:75], v[100:103], v[122:125]
	s_waitcnt lgkmcnt(2)
	v_mfma_f32_16x16x32_bf16 v[104:107], v[76:79], v[130:133], v[104:107]
	v_mfma_f32_16x16x32_bf16 v[72:75], v[76:79], v[134:137], v[72:75]
	ds_read_b128 v[138:141], v177 offset:31232
	ds_read_b128 v[142:145], v177 offset:31296
	s_waitcnt lgkmcnt(3)
	v_mfma_f32_16x16x32_bf16 v[76:79], v[80:83], v[68:71], v[126:129]
	v_mfma_f32_16x16x32_bf16 v[80:83], v[80:83], v[100:103], v[122:125]
	s_waitcnt lgkmcnt(2)
	v_mfma_f32_16x16x32_bf16 v[108:111], v[112:115], v[130:133], v[76:79]
	v_mfma_f32_16x16x32_bf16 v[76:79], v[112:115], v[134:137], v[80:83]
	ds_read_b128 v[146:149], v177 offset:33536
	ds_read_b128 v[150:153], v177 offset:33600
	s_waitcnt lgkmcnt(3)
	v_mfma_f32_16x16x32_bf16 v[80:83], v[138:141], v[68:71], v[126:129]
	v_mfma_f32_16x16x32_bf16 v[138:141], v[138:141], v[100:103], v[122:125]
	s_waitcnt lgkmcnt(2)
	v_mfma_f32_16x16x32_bf16 v[112:115], v[142:145], v[130:133], v[80:83]
	v_mfma_f32_16x16x32_bf16 v[80:83], v[142:145], v[134:137], v[138:141]
	s_waitcnt lgkmcnt(1)
	v_mfma_f32_16x16x32_bf16 v[68:71], v[146:149], v[68:71], v[126:129]
	v_mfma_f32_16x16x32_bf16 v[122:125], v[146:149], v[100:103], v[122:125]
	s_waitcnt lgkmcnt(0)
	v_mfma_f32_16x16x32_bf16 v[100:103], v[150:153], v[130:133], v[68:71]
	v_mfma_f32_16x16x32_bf16 v[68:71], v[150:153], v[134:137], v[122:125]
	s_cbranch_execz .LBB0_705
	s_branch .LBB0_706

; DEVINL float fexp2(float x) { return __builtin_amdgcn_exp2f(x); }
; #define LDK(DST, KQ) _Pragma("unroll") for (int kc = 0; kc < 4; ++kc) DST[kc] = *(const bf16x8*)(Ks + ((KQ) * 16 + fr) * 136 + kc * 32 + fq * 8)
; DEVINL void attn_item(const Params& p, int item, char* smem, int wv) {
;     ...
;     if (kt * 64 <= qlast) {
;     f32x4 s[2][4];
;     bf16x8 kfa[4], kfb[4];
;     bf16x8 vfa[2], vfb[2];
;     ...
;     LDK(kfa, 0);
;     LDK(kfb, 1); MMS(kfa, 0);
;     LDK(kfa, 2); MMS(kfb, 1);
;     LDK(kfb, 3); MMS(kfa, 2);
;     LDV(vfa, 0); MMS(kfb, 3);
;     bf16x8 pf[2][2];
;     {
;       const unsigned long long msh = mw >> (fq * 4);
;       const int mlo = (int)(unsigned)msh, mhi = (int)(unsigned)(msh >> 32);
;       int mk[4][4];
; #pragma unroll
;       for (int j = 0; j < 4; ++j) {
;         mk[0][j] = __builtin_amdgcn_sbfe(mlo, j, 1); mk[1][j] = __builtin_amdgcn_sbfe(mlo, 16 + j, 1);
;         mk[2][j] = __builtin_amdgcn_sbfe(mhi, j, 1); mk[3][j] = __builtin_amdgcn_sbfe(mhi, 16 + j, 1);
;       }
; #pragma unroll
;       for (int hh = 0; hh < 2; ++hh) {
;         float mx = s[hh][0][0];
; #pragma unroll
;         for (int kq = 0; kq < 4; ++kq)
; #pragma unroll
;           for (int j = 0; j < 4; ++j) mx = fmaxf(mx, s[hh][kq][j]);
;         {
;           auto r1 = __builtin_amdgcn_permlane16_swap(__float_as_uint(mx), __float_as_uint(mx), false, false);
;           mx = fmaxf(__uint_as_float(r1[0]), __uint_as_float(r1[1]));
;           auto r2 = __builtin_amdgcn_permlane32_swap(__float_as_uint(mx), __float_as_uint(mx), false, false);
;           mx = fmaxf(__uint_as_float(r2[0]), __uint_as_float(r2[1]));
;         }
;         if (kt == 0 || __ballot(mx > 8.f)) {
;           const float delta = (kt == 0) ? mx : fmaxf(mx, 0.f);
;           const float alpha = fexp2(-delta);
;           mrun[hh] += delta;
;           lsum[hh] *= alpha;
; #pragma unroll
;           for (int dt = 0; dt < 8; ++dt) o[hh][dt] *= alpha;
; #pragma unroll
;           for (int kq = 0; kq < 4; ++kq)
; #pragma unroll
;             for (int j = 0; j < 4; ++j) s[hh][kq][j] -= delta;
;         }
.LBB0_709:
	s_add_i32 s8, s6, 0xffffffa0
	s_cmp_gt_i32 s8, s1
	s_cbranch_scc1 .LBB0_715
	ds_read_b128 v[116:119], v175
	ds_read_b128 v[120:123], v175 offset:64
	ds_read_b128 v[124:127], v175 offset:128
	ds_read_b128 v[128:131], v175 offset:192
	ds_read_b128 v[132:135], v175 offset:4352
	ds_read_b128 v[140:143], v175 offset:4416
	ds_read_b128 v[144:147], v175 offset:4480
	ds_read_b128 v[178:181], v175 offset:4544
	v_xor_b32_e32 v182, 0x80000000, v3
	v_xor_b32_e32 v186, 0x80000000, v2
	v_mov_b32_e32 v183, v182
	v_mov_b32_e32 v184, v182
	v_mov_b32_e32 v185, v182
	v_mov_b32_e32 v187, v186
	v_mov_b32_e32 v188, v186
	v_mov_b32_e32 v189, v186
	s_waitcnt lgkmcnt(7)
	v_mfma_f32_16x16x32_bf16 v[136:139], v[116:119], v[32:35], v[182:185]
	v_mfma_f32_16x16x32_bf16 v[116:119], v[116:119], v[16:19], v[186:189]
	s_waitcnt lgkmcnt(6)
	v_mfma_f32_16x16x32_bf16 v[136:139], v[120:123], v[4:7], v[136:139]
	v_mfma_f32_16x16x32_bf16 v[116:119], v[120:123], v[20:23], v[116:119]
	s_waitcnt lgkmcnt(5)
	v_mfma_f32_16x16x32_bf16 v[120:123], v[124:127], v[8:11], v[136:139]
	v_mfma_f32_16x16x32_bf16 v[116:119], v[124:127], v[24:27], v[116:119]
	s_waitcnt lgkmcnt(4)
	v_mfma_f32_16x16x32_bf16 v[152:155], v[128:131], v[12:15], v[120:123]
	v_mfma_f32_16x16x32_bf16 v[136:139], v[128:131], v[28:31], v[116:119]
	s_nop 3
	s_nop 0
	ds_read_b128 v[116:119], v175 offset:8704
	ds_read_b128 v[120:123], v175 offset:8768
	ds_read_b128 v[124:127], v175 offset:8832
	ds_read_b128 v[128:131], v175 offset:8896
	s_waitcnt lgkmcnt(7)
	v_mfma_f32_16x16x32_bf16 v[148:151], v[132:135], v[32:35], v[182:185]
	v_mfma_f32_16x16x32_bf16 v[132:135], v[132:135], v[16:19], v[186:189]
	s_waitcnt lgkmcnt(6)
	v_mfma_f32_16x16x32_bf16 v[148:151], v[140:143], v[4:7], v[148:151]
	v_mfma_f32_16x16x32_bf16 v[132:135], v[140:143], v[20:23], v[132:135]
	s_waitcnt lgkmcnt(5)
	v_mfma_f32_16x16x32_bf16 v[140:143], v[144:147], v[8:11], v[148:151]
	v_mfma_f32_16x16x32_bf16 v[132:135], v[144:147], v[24:27], v[132:135]
	s_waitcnt lgkmcnt(4)
	v_mfma_f32_16x16x32_bf16 v[148:151], v[178:181], v[12:15], v[140:143]
	v_mfma_f32_16x16x32_bf16 v[132:135], v[178:181], v[28:31], v[132:135]
	ds_read_b128 v[144:147], v175 offset:13056
	ds_read_b128 v[178:181], v175 offset:13120
	ds_read_b128 v[190:193], v175 offset:13184
	ds_read_b128 v[194:197], v175 offset:13248
	s_waitcnt lgkmcnt(7)
	v_mfma_f32_16x16x32_bf16 v[140:143], v[116:119], v[32:35], v[182:185]
	v_mfma_f32_16x16x32_bf16 v[116:119], v[116:119], v[16:19], v[186:189]
	s_waitcnt lgkmcnt(6)
	v_mfma_f32_16x16x32_bf16 v[140:143], v[120:123], v[4:7], v[140:143]
	v_mfma_f32_16x16x32_bf16 v[116:119], v[120:123], v[20:23], v[116:119]
	s_waitcnt lgkmcnt(5)
	v_mfma_f32_16x16x32_bf16 v[120:123], v[124:127], v[8:11], v[140:143]
	v_mfma_f32_16x16x32_bf16 v[116:119], v[124:127], v[24:27], v[116:119]
	s_waitcnt lgkmcnt(4)
	v_mfma_f32_16x16x32_bf16 v[140:143], v[128:131], v[12:15], v[120:123]
	v_mfma_f32_16x16x32_bf16 v[124:127], v[128:131], v[28:31], v[116:119]
	s_nop 2
	s_nop 1
	ds_read_b128 v[116:119], v177 offset:17408
	ds_read_b128 v[120:123], v177 offset:17472
	s_waitcnt lgkmcnt(5)
	v_mfma_f32_16x16x32_bf16 v[128:131], v[144:147], v[32:35], v[182:185]
	v_mfma_f32_16x16x32_bf16 v[144:147], v[144:147], v[16:19], v[186:189]
	s_waitcnt lgkmcnt(4)
	v_mfma_f32_16x16x32_bf16 v[128:131], v[178:181], v[4:7], v[128:131]
	v_mfma_f32_16x16x32_bf16 v[144:147], v[178:181], v[20:23], v[144:147]
	s_waitcnt lgkmcnt(3)
	v_mfma_f32_16x16x32_bf16 v[128:131], v[190:193], v[8:11], v[128:131]
	v_mfma_f32_16x16x32_bf16 v[178:181], v[190:193], v[24:27], v[144:147]
	s_waitcnt lgkmcnt(2)
	v_mfma_f32_16x16x32_bf16 v[144:147], v[194:197], v[12:15], v[128:131]
	v_mfma_f32_16x16x32_bf16 v[128:131], v[194:197], v[28:31], v[178:181]
	s_nop 3
	s_nop 0
	v_max_f32_e32 v179, v152, v152
	v_max_f32_e32 v178, v179, v153
	v_max3_f32 v178, v178, v154, v155
	v_max3_f32 v178, v178, v148, v149
	v_max3_f32 v178, v178, v150, v151
	v_max3_f32 v178, v178, v140, v141
	v_max3_f32 v178, v178, v142, v143
	v_max3_f32 v178, v178, v144, v145
	v_max3_f32 v178, v178, v146, v147
	v_mov_b32_e32 v179, v178
	s_nop 1
	v_permlane16_swap_b32_e32 v178, v179
	v_max_f32_e32 v178, v178, v179
	v_mov_b32_e32 v179, v178
	s_nop 1
	v_permlane32_swap_b32_e32 v178, v179
	v_max_f32_e32 v178, v178, v179
	v_cmp_lt_f32_e32 vcc, s25, v178
	s_cbranch_vccz .LBB0_712
	v_max_f32_e32 v178, 0, v178
	v_exp_f32_e64 v180, -v178
	v_add_f32_e32 v3, v3, v178
	v_pk_add_f32 v[152:153], v[152:153], v[178:179] op_sel_hi:[1,0] neg_lo:[0,1] neg_hi:[0,1]
	v_pk_add_f32 v[154:155], v[154:155], v[178:179] op_sel_hi:[1,0] neg_lo:[0,1] neg_hi:[0,1]
	v_mul_f32_e32 v160, v160, v180
	v_pk_mul_f32 v[90:91], v[90:91], v[180:181] op_sel_hi:[1,0]
	v_pk_mul_f32 v[88:89], v[88:89], v[180:181] op_sel_hi:[1,0]
	v_pk_mul_f32 v[86:87], v[86:87], v[180:181] op_sel_hi:[1,0]
	v_pk_mul_f32 v[84:85], v[84:85], v[180:181] op_sel_hi:[1,0]
	v_pk_mul_f32 v[94:95], v[94:95], v[180:181] op_sel_hi:[1,0]
	v_pk_mul_f32 v[92:93], v[92:93], v[180:181] op_sel_hi:[1,0]
	v_pk_mul_f32 v[98:99], v[98:99], v[180:181] op_sel_hi:[1,0]
	v_pk_mul_f32 v[96:97], v[96:97], v[180:181] op_sel_hi:[1,0]
	v_pk_mul_f32 v[106:107], v[106:107], v[180:181] op_sel_hi:[1,0]
	v_pk_mul_f32 v[104:105], v[104:105], v[180:181] op_sel_hi:[1,0]
	v_pk_mul_f32 v[110:111], v[110:111], v[180:181] op_sel_hi:[1,0]
	v_pk_mul_f32 v[108:109], v[108:109], v[180:181] op_sel_hi:[1,0]
	v_pk_mul_f32 v[114:115], v[114:115], v[180:181] op_sel_hi:[1,0]
	v_pk_mul_f32 v[112:113], v[112:113], v[180:181] op_sel_hi:[1,0]
	v_pk_mul_f32 v[102:103], v[102:103], v[180:181] op_sel_hi:[1,0]
	v_pk_mul_f32 v[100:101], v[100:101], v[180:181] op_sel_hi:[1,0]
	v_pk_add_f32 v[148:149], v[148:149], v[178:179] op_sel_hi:[1,0] neg_lo:[0,1] neg_hi:[0,1]
	v_pk_add_f32 v[150:151], v[150:151], v[178:179] op_sel_hi:[1,0] neg_lo:[0,1] neg_hi:[0,1]
	v_pk_add_f32 v[140:141], v[140:141], v[178:179] op_sel_hi:[1,0] neg_lo:[0,1] neg_hi:[0,1]
	v_pk_add_f32 v[142:143], v[142:143], v[178:179] op_sel_hi:[1,0] neg_lo:[0,1] neg_hi:[0,1]
	v_pk_add_f32 v[144:145], v[144:145], v[178:179] op_sel_hi:[1,0] neg_lo:[0,1] neg_hi:[0,1]
	v_pk_add_f32 v[146:147], v[146:147], v[178:179] op_sel_hi:[1,0] neg_lo:[0,1] neg_hi:[0,1]

; DEVINL float fexp2(float x) { return __builtin_amdgcn_exp2f(x); }
; DEVINL uint32_t pk2(float a, float b) { hwf2 v = {a, b}; hwbf2 r = __builtin_convertvector(v, hwbf2); return *(uint32_t*)&r; }
; #define MMV(SRC, DT) do { __builtin_amdgcn_s_setprio(1); _Pragma("unroll") for (int c2 = 0; c2 < 2; ++c2) { o[0][DT] = mfma16(SRC[c2], pf[0][c2], o[0][DT]); o[1][DT] = mfma16(SRC[c2], pf[1][c2], o[1][DT]); } __builtin_amdgcn_s_setprio(0); } while (0)
; DEVINL void attn_item(const Params& p, int item, char* smem, int wv) {
;     ...
;         float ps = 0.f;
;         float pv[4][4];
; #pragma unroll
;         for (int kq = 0; kq < 4; ++kq)
; #pragma unroll
;           for (int j = 0; j < 4; ++j) {
;             pv[kq][j] = __uint_as_float(__float_as_uint(fexp2(s[hh][kq][j])) & (unsigned)mk[kq][j]);
;             ps += pv[kq][j];
;           }
; #pragma unroll
;         for (int c2 = 0; c2 < 2; ++c2) {
;           u32x4 pw;
;           pw[0] = pk2(pv[2 * c2][0], pv[2 * c2][1]); pw[1] = pk2(pv[2 * c2][2], pv[2 * c2][3]);
;           pw[2] = pk2(pv[2 * c2 + 1][0], pv[2 * c2 + 1][1]); pw[3] = pk2(pv[2 * c2 + 1][2], pv[2 * c2 + 1][3]);
;           pf[hh][c2] = *(bf16x8*)&pw;
;         }
;         lsum[hh] += ps;
;       }
;     }
;     LDV(vfb, 1); MMV(vfa, 0);
.LBB0_714:
	v_exp_f32_e32 v152, v152
	v_exp_f32_e32 v153, v153
	v_lshrrev_b64 v[162:163], v174, v[162:163]
	v_exp_f32_e32 v154, v154
	v_bfe_i32 v178, v162, 0, 1
	v_exp_f32_e32 v155, v155
	v_bfe_i32 v180, v162, 1, 1
	v_and_b32_e32 v152, v178, v152
	v_exp_f32_e32 v148, v148
	v_bfe_i32 v187, v162, 2, 1
	v_and_b32_e32 v153, v180, v153
	v_add_f32_e32 v192, 0, v152
	v_exp_f32_e32 v149, v149
	v_bfe_i32 v186, v162, 3, 1
	v_add_f32_e32 v192, v192, v153
	v_and_b32_e32 v154, v187, v154
	v_exp_f32_e32 v150, v150
	v_exp_f32_e32 v141, v141
	v_bfe_i32 v182, v162, 16, 1
	v_and_b32_e32 v155, v186, v155
	v_add_f32_e32 v192, v192, v154
	v_exp_f32_e32 v151, v151
	v_exp_f32_e32 v140, v140
	v_bfe_i32 v181, v162, 17, 1
	v_add_f32_e32 v192, v192, v155
	v_and_b32_e32 v148, v182, v148
	v_bfe_i32 v183, v163, 1, 1
	v_bfe_i32 v188, v162, 19, 1
	v_bfe_i32 v162, v162, 18, 1
	v_and_b32_e32 v149, v181, v149
	v_add_f32_e32 v192, v192, v148
	v_bfe_i32 v179, v163, 0, 1
	v_add_f32_e32 v192, v192, v149
	v_and_b32_e32 v150, v162, v150
	v_and_b32_e32 v193, v183, v141
	v_exp_f32_e32 v141, v142
	v_and_b32_e32 v151, v188, v151
	v_add_f32_e32 v192, v192, v150
	v_and_b32_e32 v194, v179, v140
	v_exp_f32_e32 v140, v143
	v_add_f32_e32 v192, v192, v151
	v_bfe_i32 v190, v163, 2, 1
	v_add_f32_e32 v142, v192, v194
	v_bfe_i32 v189, v163, 3, 1
	v_add_f32_e32 v142, v142, v193
	v_and_b32_e32 v195, v190, v141
	v_and_b32_e32 v192, v189, v140
	v_add_f32_e32 v140, v142, v195
	v_exp_f32_e32 v141, v144
	v_add_f32_e32 v196, v140, v192
	v_exp_f32_e32 v140, v145
	v_exp_f32_e32 v142, v147
	v_exp_f32_e32 v143, v146
	v_bfe_i32 v185, v163, 16, 1
	v_bfe_i32 v184, v163, 17, 1
	v_bfe_i32 v191, v163, 19, 1
	v_and_b32_e32 v198, v185, v141
	v_exp_f32_e32 v136, v136
	v_bfe_i32 v163, v163, 18, 1
	v_and_b32_e32 v197, v184, v140
	v_and_b32_e32 v199, v191, v142
	v_cvt_pk_bf16_f32 v142, v148, v149
	v_add_f32_e32 v148, v196, v198
	v_exp_f32_e32 v137, v137
	v_and_b32_e32 v200, v163, v143
	v_add_f32_e32 v148, v148, v197
	v_exp_f32_e32 v138, v138
	v_add_f32_e32 v148, v148, v200
	v_exp_f32_e32 v139, v139
	v_add_f32_e32 v148, v148, v199
	v_and_b32_e32 v136, v178, v136
	v_exp_f32_e32 v132, v132
	v_add_f32_e32 v160, v160, v148
	v_and_b32_e32 v137, v180, v137
	v_add_f32_e32 v148, 0, v136
	v_exp_f32_e32 v133, v133
	v_add_f32_e32 v148, v148, v137
	v_and_b32_e32 v138, v187, v138
	v_exp_f32_e32 v134, v134
	v_exp_f32_e32 v125, v125
	v_and_b32_e32 v139, v186, v139
	v_add_f32_e32 v148, v148, v138
	v_exp_f32_e32 v135, v135
	v_exp_f32_e32 v124, v124
	v_add_f32_e32 v148, v148, v139
	v_and_b32_e32 v132, v182, v132
	v_and_b32_e32 v133, v181, v133
	v_add_f32_e32 v148, v148, v132
	v_add_f32_e32 v148, v148, v133
	v_and_b32_e32 v134, v162, v134
	v_and_b32_e32 v149, v183, v125
	v_exp_f32_e32 v125, v126
	v_cvt_pk_bf16_f32 v143, v150, v151
	v_and_b32_e32 v135, v188, v135
	v_add_f32_e32 v148, v148, v134
	v_and_b32_e32 v150, v179, v124
	v_exp_f32_e32 v124, v127
	v_add_f32_e32 v148, v148, v135
	v_add_f32_e32 v126, v148, v150
	v_add_f32_e32 v126, v126, v149
	v_and_b32_e32 v151, v190, v125
	v_and_b32_e32 v148, v189, v124
	v_add_f32_e32 v124, v126, v151
	v_cvt_pk_bf16_f32 v140, v152, v153
	v_add_f32_e32 v152, v124, v148
	v_exp_f32_e32 v124, v129
	v_exp_f32_e32 v125, v128
	v_exp_f32_e32 v126, v131
	v_exp_f32_e32 v127, v130
	v_cvt_pk_bf16_f32 v141, v154, v155
	v_and_b32_e32 v153, v184, v124
	v_and_b32_e32 v154, v185, v125
	v_cvt_pk_bf16_f32 v124, v136, v137
	v_and_b32_e32 v155, v191, v126
	v_and_b32_e32 v162, v163, v127
	v_cvt_pk_bf16_f32 v125, v138, v139
	v_cvt_pk_bf16_f32 v126, v132, v133
	v_cvt_pk_bf16_f32 v127, v134, v135
	v_cvt_pk_bf16_f32 v129, v151, v148
	v_add_f32_e32 v148, v152, v154
	ds_read_b128 v[132:135], v177 offset:19712
	ds_read_b128 v[136:139], v177 offset:19776
	v_add_f32_e32 v148, v148, v153
	v_add_f32_e32 v148, v148, v162
	v_add_f32_e32 v148, v148, v155
	v_add_f32_e32 v161, v161, v148
	v_cvt_pk_bf16_f32 v144, v194, v193
	v_cvt_pk_bf16_f32 v145, v195, v192
	v_cvt_pk_bf16_f32 v146, v198, v197
	v_cvt_pk_bf16_f32 v147, v200, v199
	v_cvt_pk_bf16_f32 v128, v150, v149
	v_cvt_pk_bf16_f32 v130, v154, v153
	v_cvt_pk_bf16_f32 v131, v162, v155
	s_waitcnt lgkmcnt(3)
; #define MMV(SRC, DT) do { __builtin_amdgcn_s_setprio(1); _Pragma("unroll") for (int c2 = 0; c2 < 2; ++c2) { o[0][DT] = mfma16(SRC[c2], pf[0][c2], o[0][DT]); o[1][DT] = mfma16(SRC[c2], pf[1][c2], o[1][DT]); } __builtin_amdgcn_s_setprio(0); } while (0)
; DEVINL void attn_item(const Params& p, int item, char* smem, int wv) {
;     ...
;     LDV(vfb, 1); MMV(vfa, 0);
;     LDV(vfa, 2); MMV(vfb, 1);
;     LDV(vfb, 3); MMV(vfa, 2);
;     LDV(vfa, 4); MMV(vfb, 3);
;     LDV(vfb, 5); MMV(vfa, 4);
;     LDV(vfa, 6); MMV(vfb, 5);
;     LDV(vfb, 7); MMV(vfa, 6);
;     MMV(vfb, 7);
	v_mfma_f32_16x16x32_bf16 v[88:91], v[116:119], v[140:143], v[88:91]
	v_mfma_f32_16x16x32_bf16 v[52:55], v[116:119], v[124:127], v[52:55]
	s_waitcnt lgkmcnt(2)
	v_mfma_f32_16x16x32_bf16 v[88:91], v[120:123], v[144:147], v[88:91]
	v_mfma_f32_16x16x32_bf16 v[52:55], v[120:123], v[128:131], v[52:55]
	ds_read_b128 v[116:119], v177 offset:22016
	ds_read_b128 v[120:123], v177 offset:22080
	s_waitcnt lgkmcnt(3)
	v_mfma_f32_16x16x32_bf16 v[84:87], v[132:135], v[140:143], v[84:87]
	v_mfma_f32_16x16x32_bf16 v[56:59], v[132:135], v[124:127], v[56:59]
	s_waitcnt lgkmcnt(2)
	v_mfma_f32_16x16x32_bf16 v[84:87], v[136:139], v[144:147], v[84:87]
	v_mfma_f32_16x16x32_bf16 v[56:59], v[136:139], v[128:131], v[56:59]
	ds_read_b128 v[132:135], v177 offset:24320
	ds_read_b128 v[136:139], v177 offset:24384
	s_waitcnt lgkmcnt(3)
	v_mfma_f32_16x16x32_bf16 v[92:95], v[116:119], v[140:143], v[92:95]
	v_mfma_f32_16x16x32_bf16 v[60:63], v[116:119], v[124:127], v[60:63]
	s_waitcnt lgkmcnt(2)
	v_mfma_f32_16x16x32_bf16 v[92:95], v[120:123], v[144:147], v[92:95]
	v_mfma_f32_16x16x32_bf16 v[60:63], v[120:123], v[128:131], v[60:63]
	ds_read_b128 v[116:119], v177 offset:26624
	ds_read_b128 v[120:123], v177 offset:26688
	s_waitcnt lgkmcnt(3)
	v_mfma_f32_16x16x32_bf16 v[96:99], v[132:135], v[140:143], v[96:99]
	v_mfma_f32_16x16x32_bf16 v[64:67], v[132:135], v[124:127], v[64:67]
	s_waitcnt lgkmcnt(2)
	v_mfma_f32_16x16x32_bf16 v[96:99], v[136:139], v[144:147], v[96:99]
	v_mfma_f32_16x16x32_bf16 v[64:67], v[136:139], v[128:131], v[64:67]
	ds_read_b128 v[132:135], v177 offset:28928
	ds_read_b128 v[136:139], v177 offset:28992
	s_waitcnt lgkmcnt(3)
	v_mfma_f32_16x16x32_bf16 v[104:107], v[116:119], v[140:143], v[104:107]
	v_mfma_f32_16x16x32_bf16 v[72:75], v[116:119], v[124:127], v[72:75]
	s_waitcnt lgkmcnt(2)
	v_mfma_f32_16x16x32_bf16 v[104:107], v[120:123], v[144:147], v[104:107]
	v_mfma_f32_16x16x32_bf16 v[72:75], v[120:123], v[128:131], v[72:75]
	ds_read_b128 v[116:119], v177 offset:31232
	ds_read_b128 v[120:123], v177 offset:31296
	s_waitcnt lgkmcnt(3)
	v_mfma_f32_16x16x32_bf16 v[108:111], v[132:135], v[140:143], v[108:111]
	v_mfma_f32_16x16x32_bf16 v[76:79], v[132:135], v[124:127], v[76:79]
	s_waitcnt lgkmcnt(2)
	v_mfma_f32_16x16x32_bf16 v[108:111], v[136:139], v[144:147], v[108:111]
	v_mfma_f32_16x16x32_bf16 v[76:79], v[136:139], v[128:131], v[76:79]
	ds_read_b128 v[132:135], v177 offset:33536
	ds_read_b128 v[136:139], v177 offset:33600
	s_waitcnt lgkmcnt(3)
	v_mfma_f32_16x16x32_bf16 v[112:115], v[116:119], v[140:143], v[112:115]
	v_mfma_f32_16x16x32_bf16 v[80:83], v[116:119], v[124:127], v[80:83]
	s_waitcnt lgkmcnt(2)
	v_mfma_f32_16x16x32_bf16 v[112:115], v[120:123], v[144:147], v[112:115]
	v_mfma_f32_16x16x32_bf16 v[80:83], v[120:123], v[128:131], v[80:83]
	s_waitcnt lgkmcnt(1)
	v_mfma_f32_16x16x32_bf16 v[100:103], v[132:135], v[140:143], v[100:103]
	v_mfma_f32_16x16x32_bf16 v[68:71], v[132:135], v[124:127], v[68:71]
	s_waitcnt lgkmcnt(0)
	v_mfma_f32_16x16x32_bf16 v[100:103], v[136:139], v[144:147], v[100:103]
	v_mfma_f32_16x16x32_bf16 v[68:71], v[136:139], v[128:131], v[68:71]

; #define STAGE(P,BASE,LD,br,kt) do{long _g=(long)(br)*(LD)+(long)(kt)*BK; \
;     _Pragma("unroll") for(int _i=0;_i<2;++_i){int _b=tid*16+_i*8192;int _r,_c;stage_rc(_b,_r,_c); \
;       __builtin_amdgcn_global_load_lds((const unsigned*)((BASE)+_g+(long)_r*(LD)+_c), \
;         (unsigned*)((char*)(P)+_b),16,0,0);}}while(0)
; #define STAGE(P,BASE,LD,br,kt) do{long _g=(long)(br)*(LD)+(long)(kt)*BK; \
;     _Pragma("unroll") for(int _i=0;_i<2;++_i){int _b=tid*16+_i*8192;int _r,_c;stage_rc(_b,_r,_c); \
;       __builtin_amdgcn_global_load_lds((const unsigned*)((BASE)+_g+(long)_r*(LD)+_c), \
;         (unsigned*)((char*)(P)+_b),16,0,0);}}while(0)
; #define LDA(dst,b,h) _Pragma("unroll") for(int m=0;m<4;++m) _Pragma("unroll") for(int k=0;k<2;++k) \
;     dst[m][k]=*reinterpret_cast<const bf16x8*>((char*)SA(b,h)+lds_byte(wr*64+m*16+fr,k*32+fq*8))
; #define LDB(dst,b,h) _Pragma("unroll") for(int n=0;n<2;++n) _Pragma("unroll") for(int k=0;k<2;++k) \
;     dst[n][k]=*reinterpret_cast<const bf16x8*>((char*)SB(b,h)+lds_byte(wc*32+n*16+fr,k*32+fq*8))
; #define MMA(ai,bj,At_,Bt_) do{__builtin_amdgcn_s_setprio(1); \
;     _Pragma("unroll") for(int m=0;m<4;++m) _Pragma("unroll") for(int n=0;n<2;++n) _Pragma("unroll") for(int k=0;k<2;++k) \
;       acc[ai][bj][m][n]=__builtin_amdgcn_mfma_f32_16x16x32_bf16(Bt_[n][k],At_[m][k],acc[ai][bj][m][n],0,0,0); \
;     __builtin_amdgcn_s_setprio(0);}while(0)
; #define WAIT_L(n) asm volatile("s_waitcnt lgkmcnt(" #n ")":::"memory")
; #define BAR __builtin_amdgcn_s_barrier()
; #define SCHED __builtin_amdgcn_sched_barrier(0)
; DEVINL void gemm8_mainloop(const u16* A, long lda, const u16* Bt, long ldb, int K, int brow, int bcol, f32x4 (&acc)[2][2][4][2], char* smem, int tid) {
;     ...
;   for(int t=0;t<nt-2;t+=2){
;     LDB(B0,0,0); SCHED; LDA(At,0,0); STAGE(SA(1,1),A,lda,brow+HALF,t+1);
;     WAIT_L(8); BAR; WAIT_L(0); MMA(0,0,At,B0); BAR; SCHED;
;     LDB(B1,0,1); STAGE(SB(0,0),Bt,ldb,bcol,t+2);
;     BAR; WAIT_L(0); MMA(0,1,At,B1); BAR;
;     LDA(At,0,1); STAGE(SA(0,0),A,lda,brow,t+2);
;     BAR; WAIT_L(0); MMA(1,0,At,B0); BAR; SCHED;
.LBB0_849:
	ds_read_b128 v[178:181], v163
	ds_read_b128 v[182:185], v163 offset:1024
	ds_read_b128 v[186:189], v163 offset:2048
	ds_read_b128 v[190:193], v163 offset:3072
	v_add_u32_e32 v174, 0xc000, v152
	v_lshl_add_u64 v[242:243], s[94:95], 0, v[146:147]
	v_readfirstlane_b32 s27, v174
	v_add_u32_e32 v175, 0xe000, v152
	v_add_u32_e32 v171, s0, v162
	v_add_u32_e32 v172, s1, v162
	v_add_u32_e32 v173, s29, v162
	v_lshl_add_u64 v[164:165], v[242:243], 0, s[4:5]
	s_mov_b32 m0, s27
	v_lshl_add_u64 v[244:245], s[94:95], 0, v[148:149]
	v_readfirstlane_b32 s27, v175
	ds_read_b128 v[166:169], v153
	ds_read_b128 v[194:197], v153 offset:1024
	ds_read_b128 v[198:201], v171
	ds_read_b128 v[202:205], v171 offset:1024
	ds_read_b128 v[206:209], v172
	ds_read_b128 v[210:213], v172 offset:1024
	ds_read_b128 v[214:217], v173
	ds_read_b128 v[218:221], v173 offset:1024
	global_load_lds_dwordx4 v[164:165], off
	v_lshl_add_u64 v[164:165], v[244:245], 0, s[4:5]
	s_mov_b32 m0, s27
	s_nop 0
	global_load_lds_dwordx4 v[164:165], off
	s_waitcnt lgkmcnt(8)
	s_barrier
	s_waitcnt lgkmcnt(0)
	s_setprio 1
	v_mfma_f32_16x16x32_bf16 v[124:127], v[178:181], v[166:169], v[124:127]
	v_mfma_f32_16x16x32_bf16 v[120:123], v[186:189], v[166:169], v[120:123]
	v_mfma_f32_16x16x32_bf16 v[116:119], v[178:181], v[198:201], v[116:119]
	v_mfma_f32_16x16x32_bf16 v[112:115], v[186:189], v[198:201], v[112:115]
	v_mfma_f32_16x16x32_bf16 v[108:111], v[178:181], v[206:209], v[108:111]
	v_mfma_f32_16x16x32_bf16 v[104:107], v[186:189], v[206:209], v[104:107]
	v_mfma_f32_16x16x32_bf16 v[100:103], v[178:181], v[214:217], v[100:103]
	v_mfma_f32_16x16x32_bf16 v[96:99], v[186:189], v[214:217], v[96:99]
	v_mfma_f32_16x16x32_bf16 v[124:127], v[182:185], v[194:197], v[124:127]
	v_mfma_f32_16x16x32_bf16 v[120:123], v[190:193], v[194:197], v[120:123]
	v_mfma_f32_16x16x32_bf16 v[116:119], v[182:185], v[202:205], v[116:119]
	v_mfma_f32_16x16x32_bf16 v[112:115], v[190:193], v[202:205], v[112:115]
	v_mfma_f32_16x16x32_bf16 v[108:111], v[182:185], v[210:213], v[108:111]
	v_mfma_f32_16x16x32_bf16 v[104:107], v[190:193], v[210:213], v[104:107]
	v_mfma_f32_16x16x32_bf16 v[100:103], v[182:185], v[218:221], v[100:103]
	v_mfma_f32_16x16x32_bf16 v[96:99], v[190:193], v[218:221], v[96:99]
	s_setprio 0
	s_barrier
	v_add_u32_e32 v164, s33, v154
	v_lshl_add_u64 v[246:247], s[94:95], 0, v[142:143]
	v_readfirstlane_b32 s27, v164
	v_add_u32_e32 v165, 0x2000, v164
	v_lshl_add_u64 v[238:239], v[246:247], 0, s[6:7]
	s_mov_b32 m0, s27
	v_lshl_add_u64 v[248:249], s[94:95], 0, v[144:145]
	v_readfirstlane_b32 s27, v165
	ds_read_b128 v[222:225], v160
	ds_read_b128 v[226:229], v160 offset:1024
	ds_read_b128 v[230:233], v160 offset:2048
	ds_read_b128 v[234:237], v160 offset:3072
	global_load_lds_dwordx4 v[238:239], off
	v_lshl_add_u64 v[238:239], v[248:249], 0, s[6:7]
	s_mov_b32 m0, s27
	s_nop 0
	global_load_lds_dwordx4 v[238:239], off
	s_barrier
	s_waitcnt lgkmcnt(0)
	s_setprio 1
	v_mfma_f32_16x16x32_bf16 v[92:95], v[222:225], v[166:169], v[92:95]
	v_mfma_f32_16x16x32_bf16 v[88:91], v[230:233], v[166:169], v[88:91]
	v_mfma_f32_16x16x32_bf16 v[84:87], v[222:225], v[198:201], v[84:87]
	v_mfma_f32_16x16x32_bf16 v[80:83], v[230:233], v[198:201], v[80:83]
	v_mfma_f32_16x16x32_bf16 v[76:79], v[222:225], v[206:209], v[76:79]
	v_mfma_f32_16x16x32_bf16 v[72:75], v[230:233], v[206:209], v[72:75]
	v_mfma_f32_16x16x32_bf16 v[68:71], v[222:225], v[214:217], v[68:71]
	v_mfma_f32_16x16x32_bf16 v[64:67], v[230:233], v[214:217], v[64:67]
	v_mfma_f32_16x16x32_bf16 v[92:95], v[226:229], v[194:197], v[92:95]
	v_mfma_f32_16x16x32_bf16 v[88:91], v[234:237], v[194:197], v[88:91]
	v_mfma_f32_16x16x32_bf16 v[84:87], v[226:229], v[202:205], v[84:87]
	v_mfma_f32_16x16x32_bf16 v[80:83], v[234:237], v[202:205], v[80:83]
	v_mfma_f32_16x16x32_bf16 v[76:79], v[226:229], v[210:213], v[76:79]
	v_mfma_f32_16x16x32_bf16 v[72:75], v[234:237], v[210:213], v[72:75]
	v_mfma_f32_16x16x32_bf16 v[68:71], v[226:229], v[218:221], v[68:71]
	v_mfma_f32_16x16x32_bf16 v[64:67], v[234:237], v[218:221], v[64:67]
	s_setprio 0
	v_readfirstlane_b32 s27, v152
	v_lshl_add_u64 v[166:167], v[242:243], 0, s[8:9]
	s_mov_b32 m0, s27
	s_barrier
	ds_read_b128 v[194:197], v153 offset:16384
	ds_read_b128 v[198:201], v153 offset:17408
	ds_read_b128 v[202:205], v171 offset:16384
	ds_read_b128 v[206:209], v171 offset:17408
	ds_read_b128 v[210:213], v172 offset:16384
	ds_read_b128 v[214:217], v172 offset:17408
	ds_read_b128 v[218:221], v173 offset:16384
	ds_read_b128 v[238:241], v173 offset:17408
	global_load_lds_dwordx4 v[166:167], off
	v_add_u32_e32 v166, 0x2000, v152
	v_lshl_add_u64 v[168:169], v[244:245], 0, s[8:9]
	v_readfirstlane_b32 s27, v166
	s_mov_b32 m0, s27
	s_nop 0
	global_load_lds_dwordx4 v[168:169], off
	s_barrier
	s_waitcnt lgkmcnt(0)
	s_setprio 1
	v_mfma_f32_16x16x32_bf16 v[60:63], v[178:181], v[194:197], v[60:63]
	v_mfma_f32_16x16x32_bf16 v[56:59], v[186:189], v[194:197], v[56:59]
	v_mfma_f32_16x16x32_bf16 v[52:55], v[178:181], v[202:205], v[52:55]
	v_mfma_f32_16x16x32_bf16 v[48:51], v[186:189], v[202:205], v[48:51]
	v_mfma_f32_16x16x32_bf16 v[44:47], v[178:181], v[210:213], v[44:47]
	v_mfma_f32_16x16x32_bf16 v[40:43], v[186:189], v[210:213], v[40:43]
	v_mfma_f32_16x16x32_bf16 v[36:39], v[178:181], v[218:221], v[36:39]
	v_mfma_f32_16x16x32_bf16 v[32:35], v[186:189], v[218:221], v[32:35]
	v_mfma_f32_16x16x32_bf16 v[60:63], v[182:185], v[198:201], v[60:63]
	v_mfma_f32_16x16x32_bf16 v[56:59], v[190:193], v[198:201], v[56:59]
	v_mfma_f32_16x16x32_bf16 v[52:55], v[182:185], v[206:209], v[52:55]
	v_mfma_f32_16x16x32_bf16 v[48:51], v[190:193], v[206:209], v[48:51]
	v_mfma_f32_16x16x32_bf16 v[44:47], v[182:185], v[214:217], v[44:47]
	v_mfma_f32_16x16x32_bf16 v[40:43], v[190:193], v[214:217], v[40:43]
	v_mfma_f32_16x16x32_bf16 v[36:39], v[182:185], v[238:241], v[36:39]
	v_mfma_f32_16x16x32_bf16 v[32:35], v[190:193], v[238:241], v[32:35]
	s_setprio 0
	s_barrier
; #define STAGE(P,BASE,LD,br,kt) do{long _g=(long)(br)*(LD)+(long)(kt)*BK; \
;     _Pragma("unroll") for(int _i=0;_i<2;++_i){int _b=tid*16+_i*8192;int _r,_c;stage_rc(_b,_r,_c); \
;       __builtin_amdgcn_global_load_lds((const unsigned*)((BASE)+_g+(long)_r*(LD)+_c), \
;         (unsigned*)((char*)(P)+_b),16,0,0);}}while(0)
; #define STAGE(P,BASE,LD,br,kt) do{long _g=(long)(br)*(LD)+(long)(kt)*BK; \
;     _Pragma("unroll") for(int _i=0;_i<2;++_i){int _b=tid*16+_i*8192;int _r,_c;stage_rc(_b,_r,_c); \
;       __builtin_amdgcn_global_load_lds((const unsigned*)((BASE)+_g+(long)_r*(LD)+_c), \
;         (unsigned*)((char*)(P)+_b),16,0,0);}}while(0)
; #define LDA(dst,b,h) _Pragma("unroll") for(int m=0;m<4;++m) _Pragma("unroll") for(int k=0;k<2;++k) \
;     dst[m][k]=*reinterpret_cast<const bf16x8*>((char*)SA(b,h)+lds_byte(wr*64+m*16+fr,k*32+fq*8))
; #define LDB(dst,b,h) _Pragma("unroll") for(int n=0;n<2;++n) _Pragma("unroll") for(int k=0;k<2;++k) \
;     dst[n][k]=*reinterpret_cast<const bf16x8*>((char*)SB(b,h)+lds_byte(wc*32+n*16+fr,k*32+fq*8))
; #define MMA(ai,bj,At_,Bt_) do{__builtin_amdgcn_s_setprio(1); \
;     _Pragma("unroll") for(int m=0;m<4;++m) _Pragma("unroll") for(int n=0;n<2;++n) _Pragma("unroll") for(int k=0;k<2;++k) \
;       acc[ai][bj][m][n]=__builtin_amdgcn_mfma_f32_16x16x32_bf16(Bt_[n][k],At_[m][k],acc[ai][bj][m][n],0,0,0); \
;     __builtin_amdgcn_s_setprio(0);}while(0)
; #define WAIT_V(n) asm volatile("s_waitcnt vmcnt(" #n ")":::"memory")
; #define WAIT_L(n) asm volatile("s_waitcnt lgkmcnt(" #n ")":::"memory")
; #define BAR __builtin_amdgcn_s_barrier()
; #define SCHED __builtin_amdgcn_sched_barrier(0)
; DEVINL void gemm8_mainloop(const u16* A, long lda, const u16* Bt, long ldb, int K, int brow, int bcol, f32x4 (&acc)[2][2][4][2], char* smem, int tid) {
;     ...
;     STAGE(SB(0,1),Bt,ldb,bcol+HALF,t+2);
;     WAIT_V(6); BAR; MMA(1,1,At,B1); BAR;
;     LDB(B0,1,0); SCHED; LDA(At,1,0); STAGE(SA(0,1),A,lda,brow+HALF,t+2);
;     WAIT_L(8); BAR; WAIT_L(0); MMA(0,0,At,B0); BAR; SCHED;
;     LDB(B1,1,1); STAGE(SB(1,0),Bt,ldb,bcol,t+3);
;     BAR; WAIT_L(0); MMA(0,1,At,B1); BAR;
	v_add_u32_e32 v167, s34, v154
	v_lshl_add_u64 v[168:169], v[246:247], 0, s[10:11]
	v_readfirstlane_b32 s27, v167
	s_mov_b32 m0, s27
	v_lshl_add_u64 v[178:179], v[248:249], 0, s[10:11]
	global_load_lds_dwordx4 v[168:169], off
	v_add_u32_e32 v168, 0x2000, v167
	s_nop 0
	v_readfirstlane_b32 s27, v168
	s_mov_b32 m0, s27
	s_nop 0
	global_load_lds_dwordx4 v[178:179], off
	s_waitcnt vmcnt(6)
	s_barrier
	s_setprio 1
	v_mfma_f32_16x16x32_bf16 v[28:31], v[222:225], v[194:197], v[28:31]
	v_mfma_f32_16x16x32_bf16 v[24:27], v[230:233], v[194:197], v[24:27]
	v_mfma_f32_16x16x32_bf16 v[20:23], v[222:225], v[202:205], v[20:23]
	v_mfma_f32_16x16x32_bf16 v[16:19], v[230:233], v[202:205], v[16:19]
	v_mfma_f32_16x16x32_bf16 v[12:15], v[222:225], v[210:213], v[12:15]
	v_mfma_f32_16x16x32_bf16 v[8:11], v[230:233], v[210:213], v[8:11]
	v_mfma_f32_16x16x32_bf16 v[4:7], v[222:225], v[218:221], v[4:7]
	v_mfma_f32_16x16x32_bf16 v[0:3], v[230:233], v[218:221], v[0:3]
	v_mfma_f32_16x16x32_bf16 v[28:31], v[226:229], v[198:201], v[28:31]
	v_mfma_f32_16x16x32_bf16 v[24:27], v[234:237], v[198:201], v[24:27]
	v_mfma_f32_16x16x32_bf16 v[20:23], v[226:229], v[206:209], v[20:23]
	v_mfma_f32_16x16x32_bf16 v[16:19], v[234:237], v[206:209], v[16:19]
	v_mfma_f32_16x16x32_bf16 v[12:15], v[226:229], v[214:217], v[12:15]
	v_mfma_f32_16x16x32_bf16 v[8:11], v[234:237], v[214:217], v[8:11]
	v_mfma_f32_16x16x32_bf16 v[4:7], v[226:229], v[238:241], v[4:7]
	v_mfma_f32_16x16x32_bf16 v[0:3], v[234:237], v[238:241], v[0:3]
	s_setprio 0
	s_barrier
	ds_read_b128 v[178:181], v157
	ds_read_b128 v[182:185], v157 offset:1024
	ds_read_b128 v[186:189], v157 offset:2048
	ds_read_b128 v[190:193], v157 offset:3072
	v_add_u32_e32 v169, 0x4000, v152
	v_add_u32_e32 v170, 0x6000, v152
	v_readfirstlane_b32 s27, v169
	v_lshl_add_u64 v[226:227], v[242:243], 0, s[12:13]
	s_mov_b32 m0, s27
	v_readfirstlane_b32 s27, v170
	ds_read_b128 v[194:197], v153 offset:32768
	ds_read_b128 v[198:201], v153 offset:33792
	ds_read_b128 v[202:205], v171 offset:32768
	ds_read_b128 v[206:209], v171 offset:33792
	ds_read_b128 v[210:213], v172 offset:32768
	ds_read_b128 v[214:217], v172 offset:33792
	ds_read_b128 v[218:221], v173 offset:32768
	ds_read_b128 v[222:225], v173 offset:33792
	global_load_lds_dwordx4 v[226:227], off
	v_lshl_add_u64 v[226:227], v[244:245], 0, s[12:13]
	s_mov_b32 m0, s27
	s_nop 0
	global_load_lds_dwordx4 v[226:227], off
	s_waitcnt lgkmcnt(8)
	s_barrier
	s_waitcnt lgkmcnt(0)
	s_setprio 1
	v_mfma_f32_16x16x32_bf16 v[124:127], v[178:181], v[194:197], v[124:127]
	v_mfma_f32_16x16x32_bf16 v[120:123], v[186:189], v[194:197], v[120:123]
	v_mfma_f32_16x16x32_bf16 v[116:119], v[178:181], v[202:205], v[116:119]
	v_mfma_f32_16x16x32_bf16 v[112:115], v[186:189], v[202:205], v[112:115]
	v_mfma_f32_16x16x32_bf16 v[108:111], v[178:181], v[210:213], v[108:111]
	v_mfma_f32_16x16x32_bf16 v[104:107], v[186:189], v[210:213], v[104:107]
	v_mfma_f32_16x16x32_bf16 v[100:103], v[178:181], v[218:221], v[100:103]
	v_mfma_f32_16x16x32_bf16 v[96:99], v[186:189], v[218:221], v[96:99]
	v_mfma_f32_16x16x32_bf16 v[124:127], v[182:185], v[198:201], v[124:127]
	v_mfma_f32_16x16x32_bf16 v[120:123], v[190:193], v[198:201], v[120:123]
	v_mfma_f32_16x16x32_bf16 v[116:119], v[182:185], v[206:209], v[116:119]
	v_mfma_f32_16x16x32_bf16 v[112:115], v[190:193], v[206:209], v[112:115]
	v_mfma_f32_16x16x32_bf16 v[108:111], v[182:185], v[214:217], v[108:111]
	v_mfma_f32_16x16x32_bf16 v[104:107], v[190:193], v[214:217], v[104:107]
	v_mfma_f32_16x16x32_bf16 v[100:103], v[182:185], v[222:225], v[100:103]
	v_mfma_f32_16x16x32_bf16 v[96:99], v[190:193], v[222:225], v[96:99]
	s_setprio 0
	s_barrier
	v_readfirstlane_b32 s27, v156
	v_add_u32_e32 v177, 0x2000, v156
	v_lshl_add_u64 v[250:251], v[246:247], 0, s[14:15]
	s_mov_b32 m0, s27
	v_readfirstlane_b32 s27, v177
	ds_read_b128 v[226:229], v155
	ds_read_b128 v[230:233], v155 offset:1024
	ds_read_b128 v[234:237], v155 offset:2048
	ds_read_b128 v[238:241], v155 offset:3072
	global_load_lds_dwordx4 v[250:251], off
	v_lshl_add_u64 v[250:251], v[248:249], 0, s[14:15]
	s_mov_b32 m0, s27
	s_nop 0
	global_load_lds_dwordx4 v[250:251], off
	s_barrier
	s_waitcnt lgkmcnt(0)
	s_setprio 1
	v_mfma_f32_16x16x32_bf16 v[92:95], v[226:229], v[194:197], v[92:95]
	v_mfma_f32_16x16x32_bf16 v[88:91], v[234:237], v[194:197], v[88:91]
	v_mfma_f32_16x16x32_bf16 v[84:87], v[226:229], v[202:205], v[84:87]
	v_mfma_f32_16x16x32_bf16 v[80:83], v[234:237], v[202:205], v[80:83]
	v_mfma_f32_16x16x32_bf16 v[76:79], v[226:229], v[210:213], v[76:79]
	v_mfma_f32_16x16x32_bf16 v[72:75], v[234:237], v[210:213], v[72:75]
	v_mfma_f32_16x16x32_bf16 v[68:71], v[226:229], v[218:221], v[68:71]
	v_mfma_f32_16x16x32_bf16 v[64:67], v[234:237], v[218:221], v[64:67]
	v_mfma_f32_16x16x32_bf16 v[92:95], v[230:233], v[198:201], v[92:95]
	v_mfma_f32_16x16x32_bf16 v[88:91], v[238:241], v[198:201], v[88:91]
	v_mfma_f32_16x16x32_bf16 v[84:87], v[230:233], v[206:209], v[84:87]
	v_mfma_f32_16x16x32_bf16 v[80:83], v[238:241], v[206:209], v[80:83]
	v_mfma_f32_16x16x32_bf16 v[76:79], v[230:233], v[214:217], v[76:79]
	v_mfma_f32_16x16x32_bf16 v[72:75], v[238:241], v[214:217], v[72:75]
	v_mfma_f32_16x16x32_bf16 v[68:71], v[230:233], v[222:225], v[68:71]
	v_mfma_f32_16x16x32_bf16 v[64:67], v[238:241], v[222:225], v[64:67]
	s_setprio 0
	v_readfirstlane_b32 s27, v158
	v_lshl_add_u64 v[242:243], v[242:243], 0, s[16:17]
	s_mov_b32 m0, s27
	v_readfirstlane_b32 s27, v159
	s_barrier
; #define STAGE(P,BASE,LD,br,kt) do{long _g=(long)(br)*(LD)+(long)(kt)*BK; \
;     _Pragma("unroll") for(int _i=0;_i<2;++_i){int _b=tid*16+_i*8192;int _r,_c;stage_rc(_b,_r,_c); \
;       __builtin_amdgcn_global_load_lds((const unsigned*)((BASE)+_g+(long)_r*(LD)+_c), \
;         (unsigned*)((char*)(P)+_b),16,0,0);}}while(0)
; #define STAGE(P,BASE,LD,br,kt) do{long _g=(long)(br)*(LD)+(long)(kt)*BK; \
;     _Pragma("unroll") for(int _i=0;_i<2;++_i){int _b=tid*16+_i*8192;int _r,_c;stage_rc(_b,_r,_c); \
;       __builtin_amdgcn_global_load_lds((const unsigned*)((BASE)+_g+(long)_r*(LD)+_c), \
;         (unsigned*)((char*)(P)+_b),16,0,0);}}while(0)
; #define LDA(dst,b,h) _Pragma("unroll") for(int m=0;m<4;++m) _Pragma("unroll") for(int k=0;k<2;++k) \
;     dst[m][k]=*reinterpret_cast<const bf16x8*>((char*)SA(b,h)+lds_byte(wr*64+m*16+fr,k*32+fq*8))
; #define LDB(dst,b,h) _Pragma("unroll") for(int n=0;n<2;++n) _Pragma("unroll") for(int k=0;k<2;++k) \
;     dst[n][k]=*reinterpret_cast<const bf16x8*>((char*)SB(b,h)+lds_byte(wc*32+n*16+fr,k*32+fq*8))
; #define MMA(ai,bj,At_,Bt_) do{__builtin_amdgcn_s_setprio(1); \
;     _Pragma("unroll") for(int m=0;m<4;++m) _Pragma("unroll") for(int n=0;n<2;++n) _Pragma("unroll") for(int k=0;k<2;++k) \
;       acc[ai][bj][m][n]=__builtin_amdgcn_mfma_f32_16x16x32_bf16(Bt_[n][k],At_[m][k],acc[ai][bj][m][n],0,0,0); \
;     __builtin_amdgcn_s_setprio(0);}while(0)
; #define WAIT_V(n) asm volatile("s_waitcnt vmcnt(" #n ")":::"memory")
; #define WAIT_L(n) asm volatile("s_waitcnt lgkmcnt(" #n ")":::"memory")
; #define BAR __builtin_amdgcn_s_barrier()
; #define SCHED __builtin_amdgcn_sched_barrier(0)
; DEVINL void gemm8_mainloop(const u16* A, long lda, const u16* Bt, long ldb, int K, int brow, int bcol, f32x4 (&acc)[2][2][4][2], char* smem, int tid) {
;     ...
;     LDA(At,1,1); STAGE(SA(1,0),A,lda,brow,t+3);
;     BAR; WAIT_L(0); MMA(1,0,At,B0); BAR; SCHED;
;     STAGE(SB(1,1),Bt,ldb,bcol+HALF,t+3);
;     WAIT_V(6); BAR; MMA(1,1,At,B1); BAR;
;   }
;   { LDB(B0,0,0); LDA(At,0,0); STAGE(SA(1,1),A,lda,brow+HALF,nt-1);
;     BAR; WAIT_L(0); MMA(0,0,At,B0); BAR;
	ds_read_b128 v[194:197], v153 offset:49152
	ds_read_b128 v[198:201], v153 offset:50176
	ds_read_b128 v[202:205], v171 offset:49152
	ds_read_b128 v[206:209], v171 offset:50176
	ds_read_b128 v[210:213], v172 offset:49152
	ds_read_b128 v[214:217], v172 offset:50176
	ds_read_b128 v[218:221], v173 offset:49152
	ds_read_b128 v[222:225], v173 offset:50176
	global_load_lds_dwordx4 v[242:243], off
	v_lshl_add_u64 v[242:243], v[244:245], 0, s[16:17]
	s_mov_b32 m0, s27
	s_nop 0
	global_load_lds_dwordx4 v[242:243], off
	s_barrier
	s_waitcnt lgkmcnt(0)
	s_setprio 1
	v_mfma_f32_16x16x32_bf16 v[60:63], v[178:181], v[194:197], v[60:63]
	v_mfma_f32_16x16x32_bf16 v[56:59], v[186:189], v[194:197], v[56:59]
	v_mfma_f32_16x16x32_bf16 v[52:55], v[178:181], v[202:205], v[52:55]
	v_mfma_f32_16x16x32_bf16 v[48:51], v[186:189], v[202:205], v[48:51]
	v_mfma_f32_16x16x32_bf16 v[44:47], v[178:181], v[210:213], v[44:47]
	v_mfma_f32_16x16x32_bf16 v[40:43], v[186:189], v[210:213], v[40:43]
	v_mfma_f32_16x16x32_bf16 v[36:39], v[178:181], v[218:221], v[36:39]
	v_mfma_f32_16x16x32_bf16 v[32:35], v[186:189], v[218:221], v[32:35]
	v_mfma_f32_16x16x32_bf16 v[60:63], v[182:185], v[198:201], v[60:63]
	v_mfma_f32_16x16x32_bf16 v[56:59], v[190:193], v[198:201], v[56:59]
	v_mfma_f32_16x16x32_bf16 v[52:55], v[182:185], v[206:209], v[52:55]
	v_mfma_f32_16x16x32_bf16 v[48:51], v[190:193], v[206:209], v[48:51]
	v_mfma_f32_16x16x32_bf16 v[44:47], v[182:185], v[214:217], v[44:47]
	v_mfma_f32_16x16x32_bf16 v[40:43], v[190:193], v[214:217], v[40:43]
	v_mfma_f32_16x16x32_bf16 v[36:39], v[182:185], v[222:225], v[36:39]
	v_mfma_f32_16x16x32_bf16 v[32:35], v[190:193], v[222:225], v[32:35]
	s_setprio 0
	s_barrier
	v_readfirstlane_b32 s27, v161
	v_add_u32_e32 v177, 0x2000, v161
	v_lshl_add_u64 v[178:179], v[246:247], 0, s[18:19]
	s_mov_b32 m0, s27
	v_readfirstlane_b32 s27, v177
	global_load_lds_dwordx4 v[178:179], off
	v_lshl_add_u64 v[178:179], v[248:249], 0, s[18:19]
	s_mov_b32 m0, s27
	s_nop 0
	global_load_lds_dwordx4 v[178:179], off
	s_waitcnt vmcnt(6)
	s_barrier
	s_setprio 1
	v_mfma_f32_16x16x32_bf16 v[28:31], v[226:229], v[194:197], v[28:31]
	v_mfma_f32_16x16x32_bf16 v[24:27], v[234:237], v[194:197], v[24:27]
	v_mfma_f32_16x16x32_bf16 v[20:23], v[226:229], v[202:205], v[20:23]
	v_mfma_f32_16x16x32_bf16 v[16:19], v[234:237], v[202:205], v[16:19]
	v_mfma_f32_16x16x32_bf16 v[12:15], v[226:229], v[210:213], v[12:15]
	v_mfma_f32_16x16x32_bf16 v[8:11], v[234:237], v[210:213], v[8:11]
	v_mfma_f32_16x16x32_bf16 v[4:7], v[226:229], v[218:221], v[4:7]
	v_mfma_f32_16x16x32_bf16 v[0:3], v[234:237], v[218:221], v[0:3]
	v_mfma_f32_16x16x32_bf16 v[28:31], v[230:233], v[198:201], v[28:31]
	v_mfma_f32_16x16x32_bf16 v[24:27], v[238:241], v[198:201], v[24:27]
	v_mfma_f32_16x16x32_bf16 v[20:23], v[230:233], v[206:209], v[20:23]
	v_mfma_f32_16x16x32_bf16 v[16:19], v[238:241], v[206:209], v[16:19]
	v_mfma_f32_16x16x32_bf16 v[12:15], v[230:233], v[214:217], v[12:15]
	v_mfma_f32_16x16x32_bf16 v[8:11], v[238:241], v[214:217], v[8:11]
	v_mfma_f32_16x16x32_bf16 v[4:7], v[230:233], v[222:225], v[4:7]
	v_mfma_f32_16x16x32_bf16 v[0:3], v[238:241], v[222:225], v[0:3]
	s_setprio 0
	s_add_i32 s26, s26, 2
	v_lshl_add_u64 v[142:143], v[142:143], 0, s[20:21]
	v_lshl_add_u64 v[144:145], v[144:145], 0, s[20:21]
	v_lshl_add_u64 v[146:147], v[146:147], 0, s[20:21]
	s_cmp_lt_u32 s26, 28
	v_lshl_add_u64 v[148:149], v[148:149], 0, s[20:21]
	s_barrier
	s_cbranch_scc1 .LBB0_849
	s_or_b32 s0, s28, 0x80
	s_ashr_i32 s1, s0, 31
	s_lshl_b64 s[0:1], s[0:1], 12
	s_add_u32 s0, s58, s0
	s_addc_u32 s1, s59, s1
	v_lshl_add_u64 v[158:159], v[134:135], 1, s[0:1]
	v_lshl_add_u64 v[138:139], v[138:139], 1, v[158:159]
	v_readfirstlane_b32 s26, v174
	v_lshl_add_u64 v[138:139], v[138:139], 0, s[22:23]
	s_mov_b32 m0, s26
	ds_read_b128 v[142:145], v163
	ds_read_b128 v[146:149], v163 offset:1024
	ds_read_b128 v[178:181], v163 offset:2048
	ds_read_b128 v[182:185], v163 offset:3072
	ds_read_b128 v[186:189], v153
	ds_read_b128 v[190:193], v153 offset:1024
	ds_read_b128 v[194:197], v171
	ds_read_b128 v[198:201], v171 offset:1024
	ds_read_b128 v[202:205], v172
	ds_read_b128 v[206:209], v172 offset:1024
	ds_read_b128 v[210:213], v173
	ds_read_b128 v[214:217], v173 offset:1024
	global_load_lds_dwordx4 v[138:139], off
	v_lshl_add_u64 v[138:139], v[136:137], 1, s[0:1]
	v_lshl_add_u64 v[138:139], v[140:141], 1, v[138:139]
	v_readfirstlane_b32 s0, v175
	v_lshl_add_u64 v[138:139], v[138:139], 0, s[22:23]
	s_mov_b32 m0, s0
	s_nop 0
	global_load_lds_dwordx4 v[138:139], off
	s_barrier
	s_waitcnt lgkmcnt(0)
	s_setprio 1
	v_mfma_f32_16x16x32_bf16 v[124:127], v[142:145], v[186:189], v[124:127]
	v_mfma_f32_16x16x32_bf16 v[120:123], v[178:181], v[186:189], v[120:123]
	v_mfma_f32_16x16x32_bf16 v[112:115], v[178:181], v[194:197], v[112:115]
	v_mfma_f32_16x16x32_bf16 v[104:107], v[178:181], v[202:205], v[104:107]
	v_mfma_f32_16x16x32_bf16 v[96:99], v[178:181], v[210:213], v[96:99]
	v_mfma_f32_16x16x32_bf16 v[124:127], v[146:149], v[190:193], v[124:127]
	v_mfma_f32_16x16x32_bf16 v[120:123], v[182:185], v[190:193], v[120:123]
	v_mfma_f32_16x16x32_bf16 v[116:119], v[142:145], v[194:197], v[116:119]
	v_mfma_f32_16x16x32_bf16 v[112:115], v[182:185], v[198:201], v[112:115]
	v_mfma_f32_16x16x32_bf16 v[108:111], v[142:145], v[202:205], v[108:111]
	v_mfma_f32_16x16x32_bf16 v[104:107], v[182:185], v[206:209], v[104:107]
	v_mfma_f32_16x16x32_bf16 v[100:103], v[142:145], v[210:213], v[100:103]
	v_mfma_f32_16x16x32_bf16 v[96:99], v[182:185], v[214:217], v[96:99]
	v_mfma_f32_16x16x32_bf16 v[138:141], v[146:149], v[198:201], v[116:119]
	v_mfma_f32_16x16x32_bf16 v[218:221], v[146:149], v[206:209], v[108:111]
	v_mfma_f32_16x16x32_bf16 v[222:225], v[146:149], v[214:217], v[100:103]
	s_setprio 0
	s_barrier
; #define LDA(dst,b,h) _Pragma("unroll") for(int m=0;m<4;++m) _Pragma("unroll") for(int k=0;k<2;++k) \
;     dst[m][k]=*reinterpret_cast<const bf16x8*>((char*)SA(b,h)+lds_byte(wr*64+m*16+fr,k*32+fq*8))
; #define LDB(dst,b,h) _Pragma("unroll") for(int n=0;n<2;++n) _Pragma("unroll") for(int k=0;k<2;++k) \
;     dst[n][k]=*reinterpret_cast<const bf16x8*>((char*)SB(b,h)+lds_byte(wc*32+n*16+fr,k*32+fq*8))
; #define MMA(ai,bj,At_,Bt_) do{__builtin_amdgcn_s_setprio(1); \
;     _Pragma("unroll") for(int m=0;m<4;++m) _Pragma("unroll") for(int n=0;n<2;++n) _Pragma("unroll") for(int k=0;k<2;++k) \
;       acc[ai][bj][m][n]=__builtin_amdgcn_mfma_f32_16x16x32_bf16(Bt_[n][k],At_[m][k],acc[ai][bj][m][n],0,0,0); \
;     __builtin_amdgcn_s_setprio(0);}while(0)
; #define WAIT_V(n) asm volatile("s_waitcnt vmcnt(" #n ")":::"memory")
; #define WAIT_L(n) asm volatile("s_waitcnt lgkmcnt(" #n ")":::"memory")
; #define BAR __builtin_amdgcn_s_barrier()
; DEVINL void gemm8_mainloop(const u16* A, long lda, const u16* Bt, long ldb, int K, int brow, int bcol, f32x4 (&acc)[2][2][4][2], char* smem, int tid) {
;     ...
;     LDB(B1,0,1); BAR; WAIT_L(0); MMA(0,1,At,B1); BAR;
;     LDA(At,0,1); WAIT_V(4); BAR; WAIT_L(0); MMA(1,0,At,B0); MMA(1,1,At,B1); BAR; }
;   { LDB(B0,1,0); LDA(At,1,0); WAIT_V(2); BAR; WAIT_L(0); MMA(0,0,At,B0); BAR;
	s_nop 1
	ds_read_b128 v[100:103], v160
	ds_read_b128 v[108:111], v160 offset:1024
	ds_read_b128 v[116:119], v160 offset:2048
	ds_read_b128 v[158:161], v160 offset:3072
	s_barrier
	s_waitcnt lgkmcnt(0)
	s_setprio 1
	v_mfma_f32_16x16x32_bf16 v[88:91], v[116:119], v[186:189], v[88:91]
	v_mfma_f32_16x16x32_bf16 v[80:83], v[116:119], v[194:197], v[80:83]
	v_mfma_f32_16x16x32_bf16 v[72:75], v[116:119], v[202:205], v[72:75]
	v_mfma_f32_16x16x32_bf16 v[64:67], v[116:119], v[210:213], v[64:67]
	v_mfma_f32_16x16x32_bf16 v[92:95], v[100:103], v[186:189], v[92:95]
	v_mfma_f32_16x16x32_bf16 v[88:91], v[158:161], v[190:193], v[88:91]
	v_mfma_f32_16x16x32_bf16 v[84:87], v[100:103], v[194:197], v[84:87]
	v_mfma_f32_16x16x32_bf16 v[80:83], v[158:161], v[198:201], v[80:83]
	v_mfma_f32_16x16x32_bf16 v[76:79], v[100:103], v[202:205], v[76:79]
	v_mfma_f32_16x16x32_bf16 v[72:75], v[158:161], v[206:209], v[72:75]
	v_mfma_f32_16x16x32_bf16 v[68:71], v[100:103], v[210:213], v[68:71]
	v_mfma_f32_16x16x32_bf16 v[64:67], v[158:161], v[214:217], v[64:67]
	v_mfma_f32_16x16x32_bf16 v[226:229], v[108:111], v[190:193], v[92:95]
	v_mfma_f32_16x16x32_bf16 v[186:189], v[108:111], v[198:201], v[84:87]
	v_mfma_f32_16x16x32_bf16 v[190:193], v[108:111], v[206:209], v[76:79]
	v_mfma_f32_16x16x32_bf16 v[194:197], v[108:111], v[214:217], v[68:71]
	s_setprio 0
	s_barrier
	s_nop 0
	ds_read_b128 v[68:71], v153 offset:16384
	ds_read_b128 v[76:79], v153 offset:17408
	ds_read_b128 v[84:87], v171 offset:16384
	ds_read_b128 v[92:95], v171 offset:17408
	ds_read_b128 v[198:201], v172 offset:16384
	ds_read_b128 v[202:205], v172 offset:17408
	ds_read_b128 v[206:209], v173 offset:16384
	ds_read_b128 v[210:213], v173 offset:17408
	s_waitcnt vmcnt(4)
	s_barrier
	s_waitcnt lgkmcnt(0)
	s_setprio 1
	v_mfma_f32_16x16x32_bf16 v[60:63], v[142:145], v[68:71], v[60:63]
	v_mfma_f32_16x16x32_bf16 v[56:59], v[178:181], v[68:71], v[56:59]
	v_mfma_f32_16x16x32_bf16 v[52:55], v[142:145], v[84:87], v[52:55]
	v_mfma_f32_16x16x32_bf16 v[48:51], v[178:181], v[84:87], v[48:51]
	v_mfma_f32_16x16x32_bf16 v[36:39], v[142:145], v[206:209], v[36:39]
	v_mfma_f32_16x16x32_bf16 v[32:35], v[178:181], v[206:209], v[32:35]
	v_mfma_f32_16x16x32_bf16 v[60:63], v[146:149], v[76:79], v[60:63]
	v_mfma_f32_16x16x32_bf16 v[56:59], v[182:185], v[76:79], v[56:59]
	v_mfma_f32_16x16x32_bf16 v[52:55], v[146:149], v[92:95], v[52:55]
	v_mfma_f32_16x16x32_bf16 v[48:51], v[182:185], v[92:95], v[48:51]
	v_mfma_f32_16x16x32_bf16 v[44:47], v[142:145], v[198:201], v[44:47]
	v_mfma_f32_16x16x32_bf16 v[40:43], v[178:181], v[198:201], v[40:43]
	v_mfma_f32_16x16x32_bf16 v[36:39], v[146:149], v[210:213], v[36:39]
	v_mfma_f32_16x16x32_bf16 v[32:35], v[182:185], v[210:213], v[32:35]
	v_mfma_f32_16x16x32_bf16 v[214:217], v[146:149], v[202:205], v[44:47]
	v_mfma_f32_16x16x32_bf16 v[230:233], v[182:185], v[202:205], v[40:43]
	s_setprio 0
	s_setprio 1
	v_mfma_f32_16x16x32_bf16 v[20:23], v[100:103], v[84:87], v[20:23]
	v_mfma_f32_16x16x32_bf16 v[16:19], v[116:119], v[84:87], v[16:19]
	v_mfma_f32_16x16x32_bf16 v[4:7], v[100:103], v[206:209], v[4:7]
	v_mfma_f32_16x16x32_bf16 v[0:3], v[116:119], v[206:209], v[0:3]
	v_mfma_f32_16x16x32_bf16 v[28:31], v[100:103], v[68:71], v[28:31]
	v_mfma_f32_16x16x32_bf16 v[24:27], v[116:119], v[68:71], v[24:27]
	v_mfma_f32_16x16x32_bf16 v[20:23], v[108:111], v[92:95], v[20:23]
	v_mfma_f32_16x16x32_bf16 v[16:19], v[158:161], v[92:95], v[16:19]
	v_mfma_f32_16x16x32_bf16 v[12:15], v[100:103], v[198:201], v[12:15]
	v_mfma_f32_16x16x32_bf16 v[8:11], v[116:119], v[198:201], v[8:11]
	v_mfma_f32_16x16x32_bf16 v[4:7], v[108:111], v[210:213], v[4:7]
	v_mfma_f32_16x16x32_bf16 v[0:3], v[158:161], v[210:213], v[0:3]
	v_mfma_f32_16x16x32_bf16 v[142:145], v[108:111], v[76:79], v[28:31]
	v_mfma_f32_16x16x32_bf16 v[146:149], v[158:161], v[76:79], v[24:27]
	v_mfma_f32_16x16x32_bf16 v[178:181], v[108:111], v[202:205], v[12:15]
	v_mfma_f32_16x16x32_bf16 v[182:185], v[158:161], v[202:205], v[8:11]
	s_setprio 0
	s_barrier
	s_nop 0
	ds_read_b128 v[8:11], v157
	ds_read_b128 v[12:15], v157 offset:1024
	ds_read_b128 v[158:161], v157 offset:2048
	ds_read_b128 v[198:201], v157 offset:3072
	ds_read_b128 v[24:27], v153 offset:32768
	ds_read_b128 v[28:31], v153 offset:33792
	ds_read_b128 v[40:43], v171 offset:32768
	ds_read_b128 v[44:47], v171 offset:33792
	ds_read_b128 v[202:205], v172 offset:32768
	ds_read_b128 v[206:209], v172 offset:33792
	ds_read_b128 v[210:213], v173 offset:32768
	ds_read_b128 v[234:237], v173 offset:33792
	s_waitcnt vmcnt(2)
	s_barrier
; #define LDA(dst,b,h) _Pragma("unroll") for(int m=0;m<4;++m) _Pragma("unroll") for(int k=0;k<2;++k) \
;     dst[m][k]=*reinterpret_cast<const bf16x8*>((char*)SA(b,h)+lds_byte(wr*64+m*16+fr,k*32+fq*8))
; #define LDB(dst,b,h) _Pragma("unroll") for(int n=0;n<2;++n) _Pragma("unroll") for(int k=0;k<2;++k) \
;     dst[n][k]=*reinterpret_cast<const bf16x8*>((char*)SB(b,h)+lds_byte(wc*32+n*16+fr,k*32+fq*8))
; #define MMA(ai,bj,At_,Bt_) do{__builtin_amdgcn_s_setprio(1); \
;     _Pragma("unroll") for(int m=0;m<4;++m) _Pragma("unroll") for(int n=0;n<2;++n) _Pragma("unroll") for(int k=0;k<2;++k) \
;       acc[ai][bj][m][n]=__builtin_amdgcn_mfma_f32_16x16x32_bf16(Bt_[n][k],At_[m][k],acc[ai][bj][m][n],0,0,0); \
;     __builtin_amdgcn_s_setprio(0);}while(0)
; #define WAIT_V(n) asm volatile("s_waitcnt vmcnt(" #n ")":::"memory")
; #define WAIT_L(n) asm volatile("s_waitcnt lgkmcnt(" #n ")":::"memory")
; #define BAR __builtin_amdgcn_s_barrier()
; DEVINL void gemm8_mainloop(const u16* A, long lda, const u16* Bt, long ldb, int K, int brow, int bcol, f32x4 (&acc)[2][2][4][2], char* smem, int tid) {
;     ...
;   { LDB(B0,1,0); LDA(At,1,0); WAIT_V(2); BAR; WAIT_L(0); MMA(0,0,At,B0); BAR;
;     LDB(B1,1,1); WAIT_V(0); BAR; WAIT_L(0); MMA(0,1,At,B1); BAR;
;     LDA(At,1,1); BAR; WAIT_L(0); MMA(1,0,At,B0); MMA(1,1,At,B1); BAR; }
;   if(wr==0)BAR;
	s_waitcnt lgkmcnt(0)
	s_setprio 1
	v_mfma_f32_16x16x32_bf16 v[68:71], v[8:11], v[24:27], v[124:127]
	v_mfma_f32_16x16x32_bf16 v[124:127], v[12:15], v[28:31], v[68:71]
	v_mfma_f32_16x16x32_bf16 v[68:71], v[158:161], v[24:27], v[120:123]
	v_mfma_f32_16x16x32_bf16 v[116:119], v[198:201], v[28:31], v[68:71]
	v_mfma_f32_16x16x32_bf16 v[68:71], v[8:11], v[40:43], v[138:141]
	v_mfma_f32_16x16x32_bf16 v[108:111], v[12:15], v[44:47], v[68:71]
	v_mfma_f32_16x16x32_bf16 v[68:71], v[158:161], v[40:43], v[112:115]
	v_mfma_f32_16x16x32_bf16 v[100:103], v[198:201], v[44:47], v[68:71]
	v_mfma_f32_16x16x32_bf16 v[68:71], v[8:11], v[202:205], v[218:221]
	v_mfma_f32_16x16x32_bf16 v[92:95], v[12:15], v[206:209], v[68:71]
	v_mfma_f32_16x16x32_bf16 v[68:71], v[158:161], v[202:205], v[104:107]
	v_mfma_f32_16x16x32_bf16 v[84:87], v[198:201], v[206:209], v[68:71]
	v_mfma_f32_16x16x32_bf16 v[68:71], v[8:11], v[210:213], v[222:225]
	v_mfma_f32_16x16x32_bf16 v[76:79], v[12:15], v[234:237], v[68:71]
	v_mfma_f32_16x16x32_bf16 v[68:71], v[158:161], v[210:213], v[96:99]
	v_mfma_f32_16x16x32_bf16 v[68:71], v[198:201], v[234:237], v[68:71]
	s_setprio 0
	s_barrier
	ds_read_b128 v[138:141], v155
	ds_read_b128 v[218:221], v155 offset:1024
	ds_read_b128 v[222:225], v155 offset:2048
	ds_read_b128 v[154:157], v155 offset:3072
	s_waitcnt vmcnt(0)
	s_barrier
	s_waitcnt lgkmcnt(0)
	s_setprio 1
	v_mfma_f32_16x16x32_bf16 v[96:99], v[138:141], v[24:27], v[226:229]
	v_mfma_f32_16x16x32_bf16 v[24:27], v[222:225], v[24:27], v[88:91]
	v_mfma_f32_16x16x32_bf16 v[112:115], v[154:157], v[28:31], v[24:27]
	v_mfma_f32_16x16x32_bf16 v[24:27], v[138:141], v[40:43], v[186:189]
	v_mfma_f32_16x16x32_bf16 v[104:107], v[218:221], v[44:47], v[24:27]
	v_mfma_f32_16x16x32_bf16 v[24:27], v[222:225], v[40:43], v[80:83]
	v_mfma_f32_16x16x32_bf16 v[120:123], v[218:221], v[28:31], v[96:99]
	v_mfma_f32_16x16x32_bf16 v[96:99], v[154:157], v[44:47], v[24:27]
	v_mfma_f32_16x16x32_bf16 v[24:27], v[138:141], v[202:205], v[190:193]
	v_mfma_f32_16x16x32_bf16 v[88:91], v[218:221], v[206:209], v[24:27]
	v_mfma_f32_16x16x32_bf16 v[24:27], v[222:225], v[202:205], v[72:75]
	v_mfma_f32_16x16x32_bf16 v[80:83], v[154:157], v[206:209], v[24:27]
	v_mfma_f32_16x16x32_bf16 v[24:27], v[138:141], v[210:213], v[194:197]
	v_mfma_f32_16x16x32_bf16 v[72:75], v[218:221], v[234:237], v[24:27]
	v_mfma_f32_16x16x32_bf16 v[24:27], v[222:225], v[210:213], v[64:67]
	v_mfma_f32_16x16x32_bf16 v[64:67], v[154:157], v[234:237], v[24:27]
	s_setprio 0
	s_barrier
	ds_read_b128 v[186:189], v153 offset:49152
	ds_read_b128 v[190:193], v153 offset:50176
	ds_read_b128 v[194:197], v171 offset:49152
	ds_read_b128 v[202:205], v171 offset:50176
	ds_read_b128 v[206:209], v172 offset:49152
	ds_read_b128 v[210:213], v172 offset:50176
	ds_read_b128 v[226:229], v173 offset:49152
	ds_read_b128 v[172:175], v173 offset:50176
	s_barrier
	s_waitcnt lgkmcnt(0)
	s_setprio 1
	v_mfma_f32_16x16x32_bf16 v[24:27], v[8:11], v[186:189], v[60:63]
	v_mfma_f32_16x16x32_bf16 v[60:63], v[12:15], v[190:193], v[24:27]
	v_mfma_f32_16x16x32_bf16 v[24:27], v[158:161], v[186:189], v[56:59]
	v_mfma_f32_16x16x32_bf16 v[56:59], v[198:201], v[190:193], v[24:27]
	v_mfma_f32_16x16x32_bf16 v[24:27], v[8:11], v[194:197], v[52:55]
	v_mfma_f32_16x16x32_bf16 v[44:47], v[12:15], v[202:205], v[24:27]
	v_mfma_f32_16x16x32_bf16 v[24:27], v[158:161], v[194:197], v[48:51]
	v_mfma_f32_16x16x32_bf16 v[40:43], v[198:201], v[202:205], v[24:27]
	v_mfma_f32_16x16x32_bf16 v[24:27], v[8:11], v[206:209], v[214:217]
	v_mfma_f32_16x16x32_bf16 v[8:11], v[8:11], v[226:229], v[36:39]
	v_mfma_f32_16x16x32_bf16 v[28:31], v[12:15], v[210:213], v[24:27]
	v_mfma_f32_16x16x32_bf16 v[24:27], v[158:161], v[206:209], v[230:233]
	v_mfma_f32_16x16x32_bf16 v[12:15], v[12:15], v[172:175], v[8:11]
	v_mfma_f32_16x16x32_bf16 v[8:11], v[158:161], v[226:229], v[32:35]
	v_mfma_f32_16x16x32_bf16 v[24:27], v[198:201], v[210:213], v[24:27]
	v_mfma_f32_16x16x32_bf16 v[8:11], v[198:201], v[172:175], v[8:11]
	s_setprio 0
	s_setprio 1
	v_mfma_f32_16x16x32_bf16 v[32:35], v[138:141], v[186:189], v[142:145]
	v_mfma_f32_16x16x32_bf16 v[52:55], v[218:221], v[190:193], v[32:35]
	v_mfma_f32_16x16x32_bf16 v[32:35], v[222:225], v[186:189], v[146:149]
	v_mfma_f32_16x16x32_bf16 v[16:19], v[222:225], v[194:197], v[16:19]
	v_mfma_f32_16x16x32_bf16 v[48:51], v[154:157], v[190:193], v[32:35]
	v_mfma_f32_16x16x32_bf16 v[20:23], v[138:141], v[194:197], v[20:23]
	v_mfma_f32_16x16x32_bf16 v[32:35], v[154:157], v[202:205], v[16:19]
	v_mfma_f32_16x16x32_bf16 v[16:19], v[138:141], v[206:209], v[178:181]
	v_mfma_f32_16x16x32_bf16 v[36:39], v[218:221], v[202:205], v[20:23]
	v_mfma_f32_16x16x32_bf16 v[20:23], v[218:221], v[210:213], v[16:19]
	v_mfma_f32_16x16x32_bf16 v[16:19], v[222:225], v[206:209], v[182:185]
	v_mfma_f32_16x16x32_bf16 v[4:7], v[138:141], v[226:229], v[4:7]
	v_mfma_f32_16x16x32_bf16 v[0:3], v[222:225], v[226:229], v[0:3]
	v_mfma_f32_16x16x32_bf16 v[16:19], v[154:157], v[210:213], v[16:19]
	v_mfma_f32_16x16x32_bf16 v[4:7], v[218:221], v[172:175], v[4:7]
	v_mfma_f32_16x16x32_bf16 v[0:3], v[154:157], v[172:175], v[0:3]
	s_setprio 0
	s_cmpk_gt_u32 s31, 0xff
	s_barrier
	s_cbranch_scc1 .LBB0_852
	s_barrier

; #define STAGE(P,BASE,LD,br,kt) do{long _g=(long)(br)*(LD)+(long)(kt)*BK; \
;     _Pragma("unroll") for(int _i=0;_i<2;++_i){int _b=tid*16+_i*8192;int _r,_c;stage_rc(_b,_r,_c); \
;       __builtin_amdgcn_global_load_lds((const unsigned*)((BASE)+_g+(long)_r*(LD)+_c), \
;         (unsigned*)((char*)(P)+_b),16,0,0);}}while(0)
; #define STAGE(P,BASE,LD,br,kt) do{long _g=(long)(br)*(LD)+(long)(kt)*BK; \
;     _Pragma("unroll") for(int _i=0;_i<2;++_i){int _b=tid*16+_i*8192;int _r,_c;stage_rc(_b,_r,_c); \
;       __builtin_amdgcn_global_load_lds((const unsigned*)((BASE)+_g+(long)_r*(LD)+_c), \
;         (unsigned*)((char*)(P)+_b),16,0,0);}}while(0)
; #define LDA(dst,b,h) _Pragma("unroll") for(int m=0;m<4;++m) _Pragma("unroll") for(int k=0;k<2;++k) \
;     dst[m][k]=*reinterpret_cast<const bf16x8*>((char*)SA(b,h)+lds_byte(wr*64+m*16+fr,k*32+fq*8))
; #define LDB(dst,b,h) _Pragma("unroll") for(int n=0;n<2;++n) _Pragma("unroll") for(int k=0;k<2;++k) \
;     dst[n][k]=*reinterpret_cast<const bf16x8*>((char*)SB(b,h)+lds_byte(wc*32+n*16+fr,k*32+fq*8))
; #define MMA(ai,bj,At_,Bt_) do{__builtin_amdgcn_s_setprio(1); \
;     _Pragma("unroll") for(int m=0;m<4;++m) _Pragma("unroll") for(int n=0;n<2;++n) _Pragma("unroll") for(int k=0;k<2;++k) \
;       acc[ai][bj][m][n]=__builtin_amdgcn_mfma_f32_16x16x32_bf16(Bt_[n][k],At_[m][k],acc[ai][bj][m][n],0,0,0); \
;     __builtin_amdgcn_s_setprio(0);}while(0)
; #define WAIT_L(n) asm volatile("s_waitcnt lgkmcnt(" #n ")":::"memory")
; #define BAR __builtin_amdgcn_s_barrier()
; #define SCHED __builtin_amdgcn_sched_barrier(0)
; DEVINL void gemm8_mainloop(const u16* A, long lda, const u16* Bt, long ldb, int K, int brow, int bcol, f32x4 (&acc)[2][2][4][2], char* smem, int tid) {
;     ...
;   for(int t=0;t<nt-2;t+=2){
;     LDB(B0,0,0); SCHED; LDA(At,0,0); STAGE(SA(1,1),A,lda,brow+HALF,t+1);
;     WAIT_L(8); BAR; WAIT_L(0); MMA(0,0,At,B0); BAR; SCHED;
;     LDB(B1,0,1); STAGE(SB(0,0),Bt,ldb,bcol,t+2);
;     BAR; WAIT_L(0); MMA(0,1,At,B1); BAR;
;     LDA(At,0,1); STAGE(SA(0,0),A,lda,brow,t+2);
;     BAR; WAIT_L(0); MMA(1,0,At,B0); BAR; SCHED;
.LBB0_916:
	ds_read_b128 v[180:183], v165
	ds_read_b128 v[184:187], v165 offset:1024
	ds_read_b128 v[188:191], v165 offset:2048
	ds_read_b128 v[192:195], v165 offset:3072
	v_add_u32_e32 v177, 0xc000, v154
	v_lshl_add_u64 v[244:245], s[94:95], 0, v[146:147]
	v_readfirstlane_b32 s29, v177
	v_add_u32_e32 v178, 0xe000, v154
	v_add_u32_e32 v173, s1, v164
	v_add_u32_e32 v174, s25, v164
	v_add_u32_e32 v175, s37, v164
	v_lshl_add_u64 v[166:167], v[244:245], 0, s[4:5]
	s_mov_b32 m0, s29
	v_lshl_add_u64 v[246:247], s[94:95], 0, v[148:149]
	v_readfirstlane_b32 s29, v178
	ds_read_b128 v[168:171], v155
	ds_read_b128 v[196:199], v155 offset:1024
	ds_read_b128 v[200:203], v173
	ds_read_b128 v[204:207], v173 offset:1024
	ds_read_b128 v[208:211], v174
	ds_read_b128 v[212:215], v174 offset:1024
	ds_read_b128 v[216:219], v175
	ds_read_b128 v[220:223], v175 offset:1024
	global_load_lds_dwordx4 v[166:167], off
	v_lshl_add_u64 v[166:167], v[246:247], 0, s[4:5]
	s_mov_b32 m0, s29
	s_nop 0
	global_load_lds_dwordx4 v[166:167], off
	s_waitcnt lgkmcnt(8)
	s_barrier
	s_waitcnt lgkmcnt(0)
	s_setprio 1
	v_mfma_f32_16x16x32_bf16 v[124:127], v[180:183], v[168:171], v[124:127]
	v_mfma_f32_16x16x32_bf16 v[120:123], v[188:191], v[168:171], v[120:123]
	v_mfma_f32_16x16x32_bf16 v[116:119], v[180:183], v[200:203], v[116:119]
	v_mfma_f32_16x16x32_bf16 v[112:115], v[188:191], v[200:203], v[112:115]
	v_mfma_f32_16x16x32_bf16 v[108:111], v[180:183], v[208:211], v[108:111]
	v_mfma_f32_16x16x32_bf16 v[104:107], v[188:191], v[208:211], v[104:107]
	v_mfma_f32_16x16x32_bf16 v[100:103], v[180:183], v[216:219], v[100:103]
	v_mfma_f32_16x16x32_bf16 v[96:99], v[188:191], v[216:219], v[96:99]
	v_mfma_f32_16x16x32_bf16 v[124:127], v[184:187], v[196:199], v[124:127]
	v_mfma_f32_16x16x32_bf16 v[120:123], v[192:195], v[196:199], v[120:123]
	v_mfma_f32_16x16x32_bf16 v[116:119], v[184:187], v[204:207], v[116:119]
	v_mfma_f32_16x16x32_bf16 v[112:115], v[192:195], v[204:207], v[112:115]
	v_mfma_f32_16x16x32_bf16 v[108:111], v[184:187], v[212:215], v[108:111]
	v_mfma_f32_16x16x32_bf16 v[104:107], v[192:195], v[212:215], v[104:107]
	v_mfma_f32_16x16x32_bf16 v[100:103], v[184:187], v[220:223], v[100:103]
	v_mfma_f32_16x16x32_bf16 v[96:99], v[192:195], v[220:223], v[96:99]
	s_setprio 0
	s_barrier
	v_add_u32_e32 v166, s30, v157
	v_lshl_add_u64 v[248:249], s[94:95], 0, v[142:143]
	v_readfirstlane_b32 s29, v166
	v_add_u32_e32 v167, 0x2000, v166
	v_lshl_add_u64 v[240:241], v[248:249], 0, s[6:7]
	s_mov_b32 m0, s29
	v_lshl_add_u64 v[250:251], s[94:95], 0, v[144:145]
	v_readfirstlane_b32 s29, v167
	ds_read_b128 v[224:227], v162
	ds_read_b128 v[228:231], v162 offset:1024
	ds_read_b128 v[232:235], v162 offset:2048
	ds_read_b128 v[236:239], v162 offset:3072
	global_load_lds_dwordx4 v[240:241], off
	v_lshl_add_u64 v[240:241], v[250:251], 0, s[6:7]
	s_mov_b32 m0, s29
	s_nop 0
	global_load_lds_dwordx4 v[240:241], off
	s_barrier
	s_waitcnt lgkmcnt(0)
	s_setprio 1
	v_mfma_f32_16x16x32_bf16 v[92:95], v[224:227], v[168:171], v[92:95]
	v_mfma_f32_16x16x32_bf16 v[88:91], v[232:235], v[168:171], v[88:91]
	v_mfma_f32_16x16x32_bf16 v[84:87], v[224:227], v[200:203], v[84:87]
	v_mfma_f32_16x16x32_bf16 v[80:83], v[232:235], v[200:203], v[80:83]
	v_mfma_f32_16x16x32_bf16 v[76:79], v[224:227], v[208:211], v[76:79]
	v_mfma_f32_16x16x32_bf16 v[72:75], v[232:235], v[208:211], v[72:75]
	v_mfma_f32_16x16x32_bf16 v[68:71], v[224:227], v[216:219], v[68:71]
	v_mfma_f32_16x16x32_bf16 v[64:67], v[232:235], v[216:219], v[64:67]
	v_mfma_f32_16x16x32_bf16 v[92:95], v[228:231], v[196:199], v[92:95]
	v_mfma_f32_16x16x32_bf16 v[88:91], v[236:239], v[196:199], v[88:91]
	v_mfma_f32_16x16x32_bf16 v[84:87], v[228:231], v[204:207], v[84:87]
	v_mfma_f32_16x16x32_bf16 v[80:83], v[236:239], v[204:207], v[80:83]
	v_mfma_f32_16x16x32_bf16 v[76:79], v[228:231], v[212:215], v[76:79]
	v_mfma_f32_16x16x32_bf16 v[72:75], v[236:239], v[212:215], v[72:75]
	v_mfma_f32_16x16x32_bf16 v[68:71], v[228:231], v[220:223], v[68:71]
	v_mfma_f32_16x16x32_bf16 v[64:67], v[236:239], v[220:223], v[64:67]
	s_setprio 0
	v_readfirstlane_b32 s29, v154
	v_lshl_add_u64 v[168:169], v[244:245], 0, s[8:9]
	s_mov_b32 m0, s29
	s_barrier
	ds_read_b128 v[196:199], v155 offset:16384
	ds_read_b128 v[200:203], v155 offset:17408
	ds_read_b128 v[204:207], v173 offset:16384
	ds_read_b128 v[208:211], v173 offset:17408
	ds_read_b128 v[212:215], v174 offset:16384
	ds_read_b128 v[216:219], v174 offset:17408
	ds_read_b128 v[220:223], v175 offset:16384
	ds_read_b128 v[240:243], v175 offset:17408
	global_load_lds_dwordx4 v[168:169], off
	v_add_u32_e32 v168, 0x2000, v154
	v_lshl_add_u64 v[170:171], v[246:247], 0, s[8:9]
	v_readfirstlane_b32 s29, v168
	s_mov_b32 m0, s29
	s_nop 0
	global_load_lds_dwordx4 v[170:171], off
	s_barrier
	s_waitcnt lgkmcnt(0)
	s_setprio 1
	v_mfma_f32_16x16x32_bf16 v[60:63], v[180:183], v[196:199], v[60:63]
	v_mfma_f32_16x16x32_bf16 v[56:59], v[188:191], v[196:199], v[56:59]
	v_mfma_f32_16x16x32_bf16 v[52:55], v[180:183], v[204:207], v[52:55]
	v_mfma_f32_16x16x32_bf16 v[48:51], v[188:191], v[204:207], v[48:51]
	v_mfma_f32_16x16x32_bf16 v[44:47], v[180:183], v[212:215], v[44:47]
	v_mfma_f32_16x16x32_bf16 v[40:43], v[188:191], v[212:215], v[40:43]
	v_mfma_f32_16x16x32_bf16 v[36:39], v[180:183], v[220:223], v[36:39]
	v_mfma_f32_16x16x32_bf16 v[32:35], v[188:191], v[220:223], v[32:35]
	v_mfma_f32_16x16x32_bf16 v[60:63], v[184:187], v[200:203], v[60:63]
	v_mfma_f32_16x16x32_bf16 v[56:59], v[192:195], v[200:203], v[56:59]
	v_mfma_f32_16x16x32_bf16 v[52:55], v[184:187], v[208:211], v[52:55]
	v_mfma_f32_16x16x32_bf16 v[48:51], v[192:195], v[208:211], v[48:51]
	v_mfma_f32_16x16x32_bf16 v[44:47], v[184:187], v[216:219], v[44:47]
	v_mfma_f32_16x16x32_bf16 v[40:43], v[192:195], v[216:219], v[40:43]
	v_mfma_f32_16x16x32_bf16 v[36:39], v[184:187], v[240:243], v[36:39]
	v_mfma_f32_16x16x32_bf16 v[32:35], v[192:195], v[240:243], v[32:35]
	s_setprio 0
	s_barrier
; #define STAGE(P,BASE,LD,br,kt) do{long _g=(long)(br)*(LD)+(long)(kt)*BK; \
;     _Pragma("unroll") for(int _i=0;_i<2;++_i){int _b=tid*16+_i*8192;int _r,_c;stage_rc(_b,_r,_c); \
;       __builtin_amdgcn_global_load_lds((const unsigned*)((BASE)+_g+(long)_r*(LD)+_c), \
;         (unsigned*)((char*)(P)+_b),16,0,0);}}while(0)
; #define STAGE(P,BASE,LD,br,kt) do{long _g=(long)(br)*(LD)+(long)(kt)*BK; \
;     _Pragma("unroll") for(int _i=0;_i<2;++_i){int _b=tid*16+_i*8192;int _r,_c;stage_rc(_b,_r,_c); \
;       __builtin_amdgcn_global_load_lds((const unsigned*)((BASE)+_g+(long)_r*(LD)+_c), \
;         (unsigned*)((char*)(P)+_b),16,0,0);}}while(0)
; #define LDA(dst,b,h) _Pragma("unroll") for(int m=0;m<4;++m) _Pragma("unroll") for(int k=0;k<2;++k) \
;     dst[m][k]=*reinterpret_cast<const bf16x8*>((char*)SA(b,h)+lds_byte(wr*64+m*16+fr,k*32+fq*8))
; #define LDB(dst,b,h) _Pragma("unroll") for(int n=0;n<2;++n) _Pragma("unroll") for(int k=0;k<2;++k) \
;     dst[n][k]=*reinterpret_cast<const bf16x8*>((char*)SB(b,h)+lds_byte(wc*32+n*16+fr,k*32+fq*8))
; #define MMA(ai,bj,At_,Bt_) do{__builtin_amdgcn_s_setprio(1); \
;     _Pragma("unroll") for(int m=0;m<4;++m) _Pragma("unroll") for(int n=0;n<2;++n) _Pragma("unroll") for(int k=0;k<2;++k) \
;       acc[ai][bj][m][n]=__builtin_amdgcn_mfma_f32_16x16x32_bf16(Bt_[n][k],At_[m][k],acc[ai][bj][m][n],0,0,0); \
;     __builtin_amdgcn_s_setprio(0);}while(0)
; #define WAIT_V(n) asm volatile("s_waitcnt vmcnt(" #n ")":::"memory")
; #define WAIT_L(n) asm volatile("s_waitcnt lgkmcnt(" #n ")":::"memory")
; #define BAR __builtin_amdgcn_s_barrier()
; #define SCHED __builtin_amdgcn_sched_barrier(0)
; DEVINL void gemm8_mainloop(const u16* A, long lda, const u16* Bt, long ldb, int K, int brow, int bcol, f32x4 (&acc)[2][2][4][2], char* smem, int tid) {
;     ...
;     STAGE(SB(0,1),Bt,ldb,bcol+HALF,t+2);
;     WAIT_V(6); BAR; MMA(1,1,At,B1); BAR;
;     LDB(B0,1,0); SCHED; LDA(At,1,0); STAGE(SA(0,1),A,lda,brow+HALF,t+2);
;     WAIT_L(8); BAR; WAIT_L(0); MMA(0,0,At,B0); BAR; SCHED;
;     LDB(B1,1,1); STAGE(SB(1,0),Bt,ldb,bcol,t+3);
;     BAR; WAIT_L(0); MMA(0,1,At,B1); BAR;
	v_add_u32_e32 v169, s31, v157
	v_lshl_add_u64 v[170:171], v[248:249], 0, s[10:11]
	v_readfirstlane_b32 s29, v169
	s_mov_b32 m0, s29
	v_lshl_add_u64 v[180:181], v[250:251], 0, s[10:11]
	global_load_lds_dwordx4 v[170:171], off
	v_add_u32_e32 v170, 0x2000, v169
	s_nop 0
	v_readfirstlane_b32 s29, v170
	s_mov_b32 m0, s29
	s_nop 0
	global_load_lds_dwordx4 v[180:181], off
	s_waitcnt vmcnt(6)
	s_barrier
	s_setprio 1
	v_mfma_f32_16x16x32_bf16 v[28:31], v[224:227], v[196:199], v[28:31]
	v_mfma_f32_16x16x32_bf16 v[24:27], v[232:235], v[196:199], v[24:27]
	v_mfma_f32_16x16x32_bf16 v[20:23], v[224:227], v[204:207], v[20:23]
	v_mfma_f32_16x16x32_bf16 v[16:19], v[232:235], v[204:207], v[16:19]
	v_mfma_f32_16x16x32_bf16 v[12:15], v[224:227], v[212:215], v[12:15]
	v_mfma_f32_16x16x32_bf16 v[8:11], v[232:235], v[212:215], v[8:11]
	v_mfma_f32_16x16x32_bf16 v[4:7], v[224:227], v[220:223], v[4:7]
	v_mfma_f32_16x16x32_bf16 v[0:3], v[232:235], v[220:223], v[0:3]
	v_mfma_f32_16x16x32_bf16 v[28:31], v[228:231], v[200:203], v[28:31]
	v_mfma_f32_16x16x32_bf16 v[24:27], v[236:239], v[200:203], v[24:27]
	v_mfma_f32_16x16x32_bf16 v[20:23], v[228:231], v[208:211], v[20:23]
	v_mfma_f32_16x16x32_bf16 v[16:19], v[236:239], v[208:211], v[16:19]
	v_mfma_f32_16x16x32_bf16 v[12:15], v[228:231], v[216:219], v[12:15]
	v_mfma_f32_16x16x32_bf16 v[8:11], v[236:239], v[216:219], v[8:11]
	v_mfma_f32_16x16x32_bf16 v[4:7], v[228:231], v[240:243], v[4:7]
	v_mfma_f32_16x16x32_bf16 v[0:3], v[236:239], v[240:243], v[0:3]
	s_setprio 0
	s_barrier
	ds_read_b128 v[180:183], v158
	ds_read_b128 v[184:187], v158 offset:1024
	ds_read_b128 v[188:191], v158 offset:2048
	ds_read_b128 v[192:195], v158 offset:3072
	v_add_u32_e32 v171, 0x4000, v154
	v_add_u32_e32 v172, 0x6000, v154
	v_readfirstlane_b32 s29, v171
	v_lshl_add_u64 v[228:229], v[244:245], 0, s[12:13]
	s_mov_b32 m0, s29
	v_readfirstlane_b32 s29, v172
	ds_read_b128 v[196:199], v155 offset:32768
	ds_read_b128 v[200:203], v155 offset:33792
	ds_read_b128 v[204:207], v173 offset:32768
	ds_read_b128 v[208:211], v173 offset:33792
	ds_read_b128 v[212:215], v174 offset:32768
	ds_read_b128 v[216:219], v174 offset:33792
	ds_read_b128 v[220:223], v175 offset:32768
	ds_read_b128 v[224:227], v175 offset:33792
	global_load_lds_dwordx4 v[228:229], off
	v_lshl_add_u64 v[228:229], v[246:247], 0, s[12:13]
	s_mov_b32 m0, s29
	s_nop 0
	global_load_lds_dwordx4 v[228:229], off
	s_waitcnt lgkmcnt(8)
	s_barrier
	s_waitcnt lgkmcnt(0)
	s_setprio 1
	v_mfma_f32_16x16x32_bf16 v[124:127], v[180:183], v[196:199], v[124:127]
	v_mfma_f32_16x16x32_bf16 v[120:123], v[188:191], v[196:199], v[120:123]
	v_mfma_f32_16x16x32_bf16 v[116:119], v[180:183], v[204:207], v[116:119]
	v_mfma_f32_16x16x32_bf16 v[112:115], v[188:191], v[204:207], v[112:115]
	v_mfma_f32_16x16x32_bf16 v[108:111], v[180:183], v[212:215], v[108:111]
	v_mfma_f32_16x16x32_bf16 v[104:107], v[188:191], v[212:215], v[104:107]
	v_mfma_f32_16x16x32_bf16 v[100:103], v[180:183], v[220:223], v[100:103]
	v_mfma_f32_16x16x32_bf16 v[96:99], v[188:191], v[220:223], v[96:99]
	v_mfma_f32_16x16x32_bf16 v[124:127], v[184:187], v[200:203], v[124:127]
	v_mfma_f32_16x16x32_bf16 v[120:123], v[192:195], v[200:203], v[120:123]
	v_mfma_f32_16x16x32_bf16 v[116:119], v[184:187], v[208:211], v[116:119]
	v_mfma_f32_16x16x32_bf16 v[112:115], v[192:195], v[208:211], v[112:115]
	v_mfma_f32_16x16x32_bf16 v[108:111], v[184:187], v[216:219], v[108:111]
	v_mfma_f32_16x16x32_bf16 v[104:107], v[192:195], v[216:219], v[104:107]
	v_mfma_f32_16x16x32_bf16 v[100:103], v[184:187], v[224:227], v[100:103]
	v_mfma_f32_16x16x32_bf16 v[96:99], v[192:195], v[224:227], v[96:99]
	s_setprio 0
	s_barrier
	v_readfirstlane_b32 s29, v159
	v_add_u32_e32 v179, 0x2000, v159
	v_lshl_add_u64 v[252:253], v[248:249], 0, s[14:15]
	s_mov_b32 m0, s29
	v_readfirstlane_b32 s29, v179
	ds_read_b128 v[228:231], v156
	ds_read_b128 v[232:235], v156 offset:1024
	ds_read_b128 v[236:239], v156 offset:2048
	ds_read_b128 v[240:243], v156 offset:3072
	global_load_lds_dwordx4 v[252:253], off
	v_lshl_add_u64 v[252:253], v[250:251], 0, s[14:15]
	s_mov_b32 m0, s29
	s_nop 0
	global_load_lds_dwordx4 v[252:253], off
	s_barrier
	s_waitcnt lgkmcnt(0)
	s_setprio 1
	v_mfma_f32_16x16x32_bf16 v[92:95], v[228:231], v[196:199], v[92:95]
	v_mfma_f32_16x16x32_bf16 v[88:91], v[236:239], v[196:199], v[88:91]
	v_mfma_f32_16x16x32_bf16 v[84:87], v[228:231], v[204:207], v[84:87]
	v_mfma_f32_16x16x32_bf16 v[80:83], v[236:239], v[204:207], v[80:83]
	v_mfma_f32_16x16x32_bf16 v[76:79], v[228:231], v[212:215], v[76:79]
	v_mfma_f32_16x16x32_bf16 v[72:75], v[236:239], v[212:215], v[72:75]
	v_mfma_f32_16x16x32_bf16 v[68:71], v[228:231], v[220:223], v[68:71]
	v_mfma_f32_16x16x32_bf16 v[64:67], v[236:239], v[220:223], v[64:67]
	v_mfma_f32_16x16x32_bf16 v[92:95], v[232:235], v[200:203], v[92:95]
	v_mfma_f32_16x16x32_bf16 v[88:91], v[240:243], v[200:203], v[88:91]
	v_mfma_f32_16x16x32_bf16 v[84:87], v[232:235], v[208:211], v[84:87]
	v_mfma_f32_16x16x32_bf16 v[80:83], v[240:243], v[208:211], v[80:83]
	v_mfma_f32_16x16x32_bf16 v[76:79], v[232:235], v[216:219], v[76:79]
	v_mfma_f32_16x16x32_bf16 v[72:75], v[240:243], v[216:219], v[72:75]
	v_mfma_f32_16x16x32_bf16 v[68:71], v[232:235], v[224:227], v[68:71]
	v_mfma_f32_16x16x32_bf16 v[64:67], v[240:243], v[224:227], v[64:67]
	s_setprio 0
	v_readfirstlane_b32 s29, v160
	v_lshl_add_u64 v[244:245], v[244:245], 0, s[16:17]
	s_mov_b32 m0, s29
	v_readfirstlane_b32 s29, v161
	s_barrier
; #define STAGE(P,BASE,LD,br,kt) do{long _g=(long)(br)*(LD)+(long)(kt)*BK; \
;     _Pragma("unroll") for(int _i=0;_i<2;++_i){int _b=tid*16+_i*8192;int _r,_c;stage_rc(_b,_r,_c); \
;       __builtin_amdgcn_global_load_lds((const unsigned*)((BASE)+_g+(long)_r*(LD)+_c), \
;         (unsigned*)((char*)(P)+_b),16,0,0);}}while(0)
; #define STAGE(P,BASE,LD,br,kt) do{long _g=(long)(br)*(LD)+(long)(kt)*BK; \
;     _Pragma("unroll") for(int _i=0;_i<2;++_i){int _b=tid*16+_i*8192;int _r,_c;stage_rc(_b,_r,_c); \
;       __builtin_amdgcn_global_load_lds((const unsigned*)((BASE)+_g+(long)_r*(LD)+_c), \
;         (unsigned*)((char*)(P)+_b),16,0,0);}}while(0)
; #define LDA(dst,b,h) _Pragma("unroll") for(int m=0;m<4;++m) _Pragma("unroll") for(int k=0;k<2;++k) \
;     dst[m][k]=*reinterpret_cast<const bf16x8*>((char*)SA(b,h)+lds_byte(wr*64+m*16+fr,k*32+fq*8))
; #define LDB(dst,b,h) _Pragma("unroll") for(int n=0;n<2;++n) _Pragma("unroll") for(int k=0;k<2;++k) \
;     dst[n][k]=*reinterpret_cast<const bf16x8*>((char*)SB(b,h)+lds_byte(wc*32+n*16+fr,k*32+fq*8))
; #define MMA(ai,bj,At_,Bt_) do{__builtin_amdgcn_s_setprio(1); \
;     _Pragma("unroll") for(int m=0;m<4;++m) _Pragma("unroll") for(int n=0;n<2;++n) _Pragma("unroll") for(int k=0;k<2;++k) \
;       acc[ai][bj][m][n]=__builtin_amdgcn_mfma_f32_16x16x32_bf16(Bt_[n][k],At_[m][k],acc[ai][bj][m][n],0,0,0); \
;     __builtin_amdgcn_s_setprio(0);}while(0)
; #define WAIT_V(n) asm volatile("s_waitcnt vmcnt(" #n ")":::"memory")
; #define WAIT_L(n) asm volatile("s_waitcnt lgkmcnt(" #n ")":::"memory")
; #define BAR __builtin_amdgcn_s_barrier()
; #define SCHED __builtin_amdgcn_sched_barrier(0)
; DEVINL void gemm8_mainloop(const u16* A, long lda, const u16* Bt, long ldb, int K, int brow, int bcol, f32x4 (&acc)[2][2][4][2], char* smem, int tid) {
;     ...
;     LDA(At,1,1); STAGE(SA(1,0),A,lda,brow,t+3);
;     BAR; WAIT_L(0); MMA(1,0,At,B0); BAR; SCHED;
;     STAGE(SB(1,1),Bt,ldb,bcol+HALF,t+3);
;     WAIT_V(6); BAR; MMA(1,1,At,B1); BAR;
;   }
;   { LDB(B0,0,0); LDA(At,0,0); STAGE(SA(1,1),A,lda,brow+HALF,nt-1);
;     BAR; WAIT_L(0); MMA(0,0,At,B0); BAR;
	ds_read_b128 v[196:199], v155 offset:49152
	ds_read_b128 v[200:203], v155 offset:50176
	ds_read_b128 v[204:207], v173 offset:49152
	ds_read_b128 v[208:211], v173 offset:50176
	ds_read_b128 v[212:215], v174 offset:49152
	ds_read_b128 v[216:219], v174 offset:50176
	ds_read_b128 v[220:223], v175 offset:49152
	ds_read_b128 v[224:227], v175 offset:50176
	global_load_lds_dwordx4 v[244:245], off
	v_lshl_add_u64 v[244:245], v[246:247], 0, s[16:17]
	s_mov_b32 m0, s29
	s_nop 0
	global_load_lds_dwordx4 v[244:245], off
	s_barrier
	s_waitcnt lgkmcnt(0)
	s_setprio 1
	v_mfma_f32_16x16x32_bf16 v[60:63], v[180:183], v[196:199], v[60:63]
	v_mfma_f32_16x16x32_bf16 v[56:59], v[188:191], v[196:199], v[56:59]
	v_mfma_f32_16x16x32_bf16 v[52:55], v[180:183], v[204:207], v[52:55]
	v_mfma_f32_16x16x32_bf16 v[48:51], v[188:191], v[204:207], v[48:51]
	v_mfma_f32_16x16x32_bf16 v[44:47], v[180:183], v[212:215], v[44:47]
	v_mfma_f32_16x16x32_bf16 v[40:43], v[188:191], v[212:215], v[40:43]
	v_mfma_f32_16x16x32_bf16 v[36:39], v[180:183], v[220:223], v[36:39]
	v_mfma_f32_16x16x32_bf16 v[32:35], v[188:191], v[220:223], v[32:35]
	v_mfma_f32_16x16x32_bf16 v[60:63], v[184:187], v[200:203], v[60:63]
	v_mfma_f32_16x16x32_bf16 v[56:59], v[192:195], v[200:203], v[56:59]
	v_mfma_f32_16x16x32_bf16 v[52:55], v[184:187], v[208:211], v[52:55]
	v_mfma_f32_16x16x32_bf16 v[48:51], v[192:195], v[208:211], v[48:51]
	v_mfma_f32_16x16x32_bf16 v[44:47], v[184:187], v[216:219], v[44:47]
	v_mfma_f32_16x16x32_bf16 v[40:43], v[192:195], v[216:219], v[40:43]
	v_mfma_f32_16x16x32_bf16 v[36:39], v[184:187], v[224:227], v[36:39]
	v_mfma_f32_16x16x32_bf16 v[32:35], v[192:195], v[224:227], v[32:35]
	s_setprio 0
	s_barrier
	v_readfirstlane_b32 s29, v163
	v_add_u32_e32 v179, 0x2000, v163
	v_lshl_add_u64 v[180:181], v[248:249], 0, s[18:19]
	s_mov_b32 m0, s29
	v_readfirstlane_b32 s29, v179
	global_load_lds_dwordx4 v[180:181], off
	v_lshl_add_u64 v[180:181], v[250:251], 0, s[18:19]
	s_mov_b32 m0, s29
	s_nop 0
	global_load_lds_dwordx4 v[180:181], off
	s_waitcnt vmcnt(6)
	s_barrier
	s_setprio 1
	v_mfma_f32_16x16x32_bf16 v[28:31], v[228:231], v[196:199], v[28:31]
	v_mfma_f32_16x16x32_bf16 v[24:27], v[236:239], v[196:199], v[24:27]
	v_mfma_f32_16x16x32_bf16 v[20:23], v[228:231], v[204:207], v[20:23]
	v_mfma_f32_16x16x32_bf16 v[16:19], v[236:239], v[204:207], v[16:19]
	v_mfma_f32_16x16x32_bf16 v[12:15], v[228:231], v[212:215], v[12:15]
	v_mfma_f32_16x16x32_bf16 v[8:11], v[236:239], v[212:215], v[8:11]
	v_mfma_f32_16x16x32_bf16 v[4:7], v[228:231], v[220:223], v[4:7]
	v_mfma_f32_16x16x32_bf16 v[0:3], v[236:239], v[220:223], v[0:3]
	v_mfma_f32_16x16x32_bf16 v[28:31], v[232:235], v[200:203], v[28:31]
	v_mfma_f32_16x16x32_bf16 v[24:27], v[240:243], v[200:203], v[24:27]
	v_mfma_f32_16x16x32_bf16 v[20:23], v[232:235], v[208:211], v[20:23]
	v_mfma_f32_16x16x32_bf16 v[16:19], v[240:243], v[208:211], v[16:19]
	v_mfma_f32_16x16x32_bf16 v[12:15], v[232:235], v[216:219], v[12:15]
	v_mfma_f32_16x16x32_bf16 v[8:11], v[240:243], v[216:219], v[8:11]
	v_mfma_f32_16x16x32_bf16 v[4:7], v[232:235], v[224:227], v[4:7]
	v_mfma_f32_16x16x32_bf16 v[0:3], v[240:243], v[224:227], v[0:3]
	s_setprio 0
	s_add_i32 s28, s28, 2
	v_lshl_add_u64 v[142:143], v[142:143], 0, s[20:21]
	v_lshl_add_u64 v[144:145], v[144:145], 0, s[20:21]
	v_lshl_add_u64 v[146:147], v[146:147], 0, s[20:21]
	s_cmp_lt_u32 s28, 28
	v_lshl_add_u64 v[148:149], v[148:149], 0, s[20:21]
	s_barrier
	s_cbranch_scc1 .LBB0_916
	s_or_b32 s28, s24, 0x80
	s_ashr_i32 s29, s28, 31
	s_lshl_b64 s[28:29], s[28:29], 12
	s_add_u32 s28, s90, s28
	s_addc_u32 s29, s91, s29
	v_lshl_add_u64 v[160:161], v[134:135], 1, s[28:29]
	v_lshl_add_u64 v[138:139], v[138:139], 1, v[160:161]
	v_readfirstlane_b32 s1, v177
	v_lshl_add_u64 v[138:139], v[138:139], 0, s[22:23]
	s_mov_b32 m0, s1
	ds_read_b128 v[142:145], v165
	ds_read_b128 v[146:149], v165 offset:1024
	ds_read_b128 v[180:183], v165 offset:2048
	ds_read_b128 v[184:187], v165 offset:3072
	ds_read_b128 v[188:191], v155
	ds_read_b128 v[192:195], v155 offset:1024
	ds_read_b128 v[196:199], v173
	ds_read_b128 v[200:203], v173 offset:1024
	ds_read_b128 v[204:207], v174
	ds_read_b128 v[208:211], v174 offset:1024
	ds_read_b128 v[212:215], v175
	ds_read_b128 v[216:219], v175 offset:1024
	global_load_lds_dwordx4 v[138:139], off
	v_lshl_add_u64 v[138:139], v[136:137], 1, s[28:29]
	v_lshl_add_u64 v[138:139], v[140:141], 1, v[138:139]
	v_readfirstlane_b32 s1, v178
	v_lshl_add_u64 v[138:139], v[138:139], 0, s[22:23]
	s_mov_b32 m0, s1
	s_nop 0
	global_load_lds_dwordx4 v[138:139], off
	s_barrier
	s_waitcnt lgkmcnt(0)
	s_setprio 1
	v_mfma_f32_16x16x32_bf16 v[124:127], v[142:145], v[188:191], v[124:127]
	v_mfma_f32_16x16x32_bf16 v[120:123], v[180:183], v[188:191], v[120:123]
	v_mfma_f32_16x16x32_bf16 v[116:119], v[142:145], v[196:199], v[116:119]
	v_mfma_f32_16x16x32_bf16 v[112:115], v[180:183], v[196:199], v[112:115]
	v_mfma_f32_16x16x32_bf16 v[104:107], v[180:183], v[204:207], v[104:107]
	v_mfma_f32_16x16x32_bf16 v[96:99], v[180:183], v[212:215], v[96:99]
	v_mfma_f32_16x16x32_bf16 v[124:127], v[146:149], v[192:195], v[124:127]
	v_mfma_f32_16x16x32_bf16 v[120:123], v[184:187], v[192:195], v[120:123]
	v_mfma_f32_16x16x32_bf16 v[116:119], v[146:149], v[200:203], v[116:119]
	v_mfma_f32_16x16x32_bf16 v[112:115], v[184:187], v[200:203], v[112:115]
	v_mfma_f32_16x16x32_bf16 v[108:111], v[142:145], v[204:207], v[108:111]
	v_mfma_f32_16x16x32_bf16 v[104:107], v[184:187], v[208:211], v[104:107]
	v_mfma_f32_16x16x32_bf16 v[100:103], v[142:145], v[212:215], v[100:103]
	v_mfma_f32_16x16x32_bf16 v[96:99], v[184:187], v[216:219], v[96:99]
	v_mfma_f32_16x16x32_bf16 v[138:141], v[146:149], v[208:211], v[108:111]
	v_mfma_f32_16x16x32_bf16 v[220:223], v[146:149], v[216:219], v[100:103]
	s_setprio 0
	s_barrier
; #define LDA(dst,b,h) _Pragma("unroll") for(int m=0;m<4;++m) _Pragma("unroll") for(int k=0;k<2;++k) \
;     dst[m][k]=*reinterpret_cast<const bf16x8*>((char*)SA(b,h)+lds_byte(wr*64+m*16+fr,k*32+fq*8))
; #define LDB(dst,b,h) _Pragma("unroll") for(int n=0;n<2;++n) _Pragma("unroll") for(int k=0;k<2;++k) \
;     dst[n][k]=*reinterpret_cast<const bf16x8*>((char*)SB(b,h)+lds_byte(wc*32+n*16+fr,k*32+fq*8))
; #define MMA(ai,bj,At_,Bt_) do{__builtin_amdgcn_s_setprio(1); \
;     _Pragma("unroll") for(int m=0;m<4;++m) _Pragma("unroll") for(int n=0;n<2;++n) _Pragma("unroll") for(int k=0;k<2;++k) \
;       acc[ai][bj][m][n]=__builtin_amdgcn_mfma_f32_16x16x32_bf16(Bt_[n][k],At_[m][k],acc[ai][bj][m][n],0,0,0); \
;     __builtin_amdgcn_s_setprio(0);}while(0)
; #define WAIT_V(n) asm volatile("s_waitcnt vmcnt(" #n ")":::"memory")
; #define WAIT_L(n) asm volatile("s_waitcnt lgkmcnt(" #n ")":::"memory")
; #define BAR __builtin_amdgcn_s_barrier()
; DEVINL void gemm8_mainloop(const u16* A, long lda, const u16* Bt, long ldb, int K, int brow, int bcol, f32x4 (&acc)[2][2][4][2], char* smem, int tid) {
;     ...
;     LDB(B1,0,1); BAR; WAIT_L(0); MMA(0,1,At,B1); BAR;
;     LDA(At,0,1); WAIT_V(4); BAR; WAIT_L(0); MMA(1,0,At,B0); MMA(1,1,At,B1); BAR; }
;   { LDB(B0,1,0); LDA(At,1,0); WAIT_V(2); BAR; WAIT_L(0); MMA(0,0,At,B0); BAR;
	s_nop 2
	ds_read_b128 v[100:103], v162
	ds_read_b128 v[108:111], v162 offset:1024
	ds_read_b128 v[224:227], v162 offset:2048
	ds_read_b128 v[160:163], v162 offset:3072
	s_barrier
	s_waitcnt lgkmcnt(0)
	s_setprio 1
	v_mfma_f32_16x16x32_bf16 v[88:91], v[224:227], v[188:191], v[88:91]
	v_mfma_f32_16x16x32_bf16 v[80:83], v[224:227], v[196:199], v[80:83]
	v_mfma_f32_16x16x32_bf16 v[72:75], v[224:227], v[204:207], v[72:75]
	v_mfma_f32_16x16x32_bf16 v[64:67], v[224:227], v[212:215], v[64:67]
	v_mfma_f32_16x16x32_bf16 v[92:95], v[100:103], v[188:191], v[92:95]
	v_mfma_f32_16x16x32_bf16 v[88:91], v[160:163], v[192:195], v[88:91]
	v_mfma_f32_16x16x32_bf16 v[84:87], v[100:103], v[196:199], v[84:87]
	v_mfma_f32_16x16x32_bf16 v[80:83], v[160:163], v[200:203], v[80:83]
	v_mfma_f32_16x16x32_bf16 v[76:79], v[100:103], v[204:207], v[76:79]
	v_mfma_f32_16x16x32_bf16 v[72:75], v[160:163], v[208:211], v[72:75]
	v_mfma_f32_16x16x32_bf16 v[68:71], v[100:103], v[212:215], v[68:71]
	v_mfma_f32_16x16x32_bf16 v[64:67], v[160:163], v[216:219], v[64:67]
	v_mfma_f32_16x16x32_bf16 v[228:231], v[108:111], v[192:195], v[92:95]
	v_mfma_f32_16x16x32_bf16 v[188:191], v[108:111], v[200:203], v[84:87]
	v_mfma_f32_16x16x32_bf16 v[192:195], v[108:111], v[208:211], v[76:79]
	v_mfma_f32_16x16x32_bf16 v[196:199], v[108:111], v[216:219], v[68:71]
	s_setprio 0
	s_barrier
	s_nop 0
	ds_read_b128 v[68:71], v155 offset:16384
	ds_read_b128 v[76:79], v155 offset:17408
	ds_read_b128 v[84:87], v173 offset:16384
	ds_read_b128 v[92:95], v173 offset:17408
	ds_read_b128 v[200:203], v174 offset:16384
	ds_read_b128 v[204:207], v174 offset:17408
	ds_read_b128 v[208:211], v175 offset:16384
	ds_read_b128 v[212:215], v175 offset:17408
	s_waitcnt vmcnt(4)
	s_barrier
	s_waitcnt lgkmcnt(0)
	s_setprio 1
	v_mfma_f32_16x16x32_bf16 v[60:63], v[142:145], v[68:71], v[60:63]
	v_mfma_f32_16x16x32_bf16 v[56:59], v[180:183], v[68:71], v[56:59]
	v_mfma_f32_16x16x32_bf16 v[48:51], v[180:183], v[84:87], v[48:51]
	v_mfma_f32_16x16x32_bf16 v[40:43], v[180:183], v[200:203], v[40:43]
	v_mfma_f32_16x16x32_bf16 v[32:35], v[180:183], v[208:211], v[32:35]
	v_mfma_f32_16x16x32_bf16 v[60:63], v[146:149], v[76:79], v[60:63]
	v_mfma_f32_16x16x32_bf16 v[56:59], v[184:187], v[76:79], v[56:59]
	v_mfma_f32_16x16x32_bf16 v[52:55], v[142:145], v[84:87], v[52:55]
	v_mfma_f32_16x16x32_bf16 v[48:51], v[184:187], v[92:95], v[48:51]
	v_mfma_f32_16x16x32_bf16 v[44:47], v[142:145], v[200:203], v[44:47]
	v_mfma_f32_16x16x32_bf16 v[40:43], v[184:187], v[204:207], v[40:43]
	v_mfma_f32_16x16x32_bf16 v[36:39], v[142:145], v[208:211], v[36:39]
	v_mfma_f32_16x16x32_bf16 v[32:35], v[184:187], v[212:215], v[32:35]
	v_mfma_f32_16x16x32_bf16 v[216:219], v[146:149], v[92:95], v[52:55]
	v_mfma_f32_16x16x32_bf16 v[232:235], v[146:149], v[204:207], v[44:47]
	v_mfma_f32_16x16x32_bf16 v[142:145], v[146:149], v[212:215], v[36:39]
	s_setprio 0
	s_setprio 1
	v_mfma_f32_16x16x32_bf16 v[24:27], v[224:227], v[68:71], v[24:27]
	v_mfma_f32_16x16x32_bf16 v[16:19], v[224:227], v[84:87], v[16:19]
	v_mfma_f32_16x16x32_bf16 v[4:7], v[100:103], v[208:211], v[4:7]
	v_mfma_f32_16x16x32_bf16 v[0:3], v[224:227], v[208:211], v[0:3]
	v_mfma_f32_16x16x32_bf16 v[28:31], v[100:103], v[68:71], v[28:31]
	v_mfma_f32_16x16x32_bf16 v[24:27], v[160:163], v[76:79], v[24:27]
	v_mfma_f32_16x16x32_bf16 v[20:23], v[100:103], v[84:87], v[20:23]
	v_mfma_f32_16x16x32_bf16 v[16:19], v[160:163], v[92:95], v[16:19]
	v_mfma_f32_16x16x32_bf16 v[12:15], v[100:103], v[200:203], v[12:15]
	v_mfma_f32_16x16x32_bf16 v[8:11], v[224:227], v[200:203], v[8:11]
	v_mfma_f32_16x16x32_bf16 v[4:7], v[108:111], v[212:215], v[4:7]
	v_mfma_f32_16x16x32_bf16 v[0:3], v[160:163], v[212:215], v[0:3]
	v_mfma_f32_16x16x32_bf16 v[146:149], v[108:111], v[76:79], v[28:31]
	v_mfma_f32_16x16x32_bf16 v[178:181], v[108:111], v[92:95], v[20:23]
	v_mfma_f32_16x16x32_bf16 v[182:185], v[108:111], v[204:207], v[12:15]
	v_mfma_f32_16x16x32_bf16 v[200:203], v[160:163], v[204:207], v[8:11]
	s_setprio 0
	s_barrier
	s_nop 0
	ds_read_b128 v[8:11], v158
	ds_read_b128 v[12:15], v158 offset:1024
	ds_read_b128 v[160:163], v158 offset:2048
	ds_read_b128 v[204:207], v158 offset:3072
	ds_read_b128 v[20:23], v155 offset:32768
	ds_read_b128 v[28:31], v155 offset:33792
	ds_read_b128 v[36:39], v173 offset:32768
	ds_read_b128 v[44:47], v173 offset:33792
	ds_read_b128 v[52:55], v174 offset:32768
	ds_read_b128 v[208:211], v174 offset:33792
	ds_read_b128 v[212:215], v175 offset:32768
	ds_read_b128 v[224:227], v175 offset:33792
	s_waitcnt vmcnt(2)
	s_barrier
; #define LDA(dst,b,h) _Pragma("unroll") for(int m=0;m<4;++m) _Pragma("unroll") for(int k=0;k<2;++k) \
;     dst[m][k]=*reinterpret_cast<const bf16x8*>((char*)SA(b,h)+lds_byte(wr*64+m*16+fr,k*32+fq*8))
; #define LDB(dst,b,h) _Pragma("unroll") for(int n=0;n<2;++n) _Pragma("unroll") for(int k=0;k<2;++k) \
;     dst[n][k]=*reinterpret_cast<const bf16x8*>((char*)SB(b,h)+lds_byte(wc*32+n*16+fr,k*32+fq*8))
; #define MMA(ai,bj,At_,Bt_) do{__builtin_amdgcn_s_setprio(1); \
;     _Pragma("unroll") for(int m=0;m<4;++m) _Pragma("unroll") for(int n=0;n<2;++n) _Pragma("unroll") for(int k=0;k<2;++k) \
;       acc[ai][bj][m][n]=__builtin_amdgcn_mfma_f32_16x16x32_bf16(Bt_[n][k],At_[m][k],acc[ai][bj][m][n],0,0,0); \
;     __builtin_amdgcn_s_setprio(0);}while(0)
; #define WAIT_V(n) asm volatile("s_waitcnt vmcnt(" #n ")":::"memory")
; #define WAIT_L(n) asm volatile("s_waitcnt lgkmcnt(" #n ")":::"memory")
; #define BAR __builtin_amdgcn_s_barrier()
; DEVINL void gemm8_mainloop(const u16* A, long lda, const u16* Bt, long ldb, int K, int brow, int bcol, f32x4 (&acc)[2][2][4][2], char* smem, int tid) {
;     ...
;   { LDB(B0,1,0); LDA(At,1,0); WAIT_V(2); BAR; WAIT_L(0); MMA(0,0,At,B0); BAR;
;     LDB(B1,1,1); WAIT_V(0); BAR; WAIT_L(0); MMA(0,1,At,B1); BAR;
;     LDA(At,1,1); BAR; WAIT_L(0); MMA(1,0,At,B0); MMA(1,1,At,B1); BAR; }
;   if(wr==0)BAR;
	s_waitcnt lgkmcnt(0)
	s_setprio 1
	v_mfma_f32_16x16x32_bf16 v[68:71], v[8:11], v[20:23], v[124:127]
	v_mfma_f32_16x16x32_bf16 v[124:127], v[12:15], v[28:31], v[68:71]
	v_mfma_f32_16x16x32_bf16 v[68:71], v[160:163], v[20:23], v[120:123]
	v_mfma_f32_16x16x32_bf16 v[120:123], v[204:207], v[28:31], v[68:71]
	v_mfma_f32_16x16x32_bf16 v[68:71], v[8:11], v[36:39], v[116:119]
	v_mfma_f32_16x16x32_bf16 v[108:111], v[12:15], v[44:47], v[68:71]
	v_mfma_f32_16x16x32_bf16 v[68:71], v[160:163], v[36:39], v[112:115]
	v_mfma_f32_16x16x32_bf16 v[100:103], v[204:207], v[44:47], v[68:71]
	v_mfma_f32_16x16x32_bf16 v[68:71], v[8:11], v[52:55], v[138:141]
	v_mfma_f32_16x16x32_bf16 v[92:95], v[12:15], v[208:211], v[68:71]
	v_mfma_f32_16x16x32_bf16 v[68:71], v[160:163], v[52:55], v[104:107]
	v_mfma_f32_16x16x32_bf16 v[84:87], v[204:207], v[208:211], v[68:71]
	v_mfma_f32_16x16x32_bf16 v[68:71], v[8:11], v[212:215], v[220:223]
	v_mfma_f32_16x16x32_bf16 v[76:79], v[12:15], v[224:227], v[68:71]
	v_mfma_f32_16x16x32_bf16 v[68:71], v[160:163], v[212:215], v[96:99]
	v_mfma_f32_16x16x32_bf16 v[68:71], v[204:207], v[224:227], v[68:71]
	s_setprio 0
	s_barrier
	ds_read_b128 v[138:141], v156
	ds_read_b128 v[220:223], v156 offset:1024
	ds_read_b128 v[236:239], v156 offset:2048
	ds_read_b128 v[156:159], v156 offset:3072
	s_waitcnt vmcnt(0)
	s_barrier
	s_waitcnt lgkmcnt(0)
	s_setprio 1
	v_mfma_f32_16x16x32_bf16 v[96:99], v[138:141], v[20:23], v[228:231]
	v_mfma_f32_16x16x32_bf16 v[20:23], v[236:239], v[20:23], v[88:91]
	v_mfma_f32_16x16x32_bf16 v[112:115], v[156:159], v[28:31], v[20:23]
	v_mfma_f32_16x16x32_bf16 v[20:23], v[138:141], v[36:39], v[188:191]
	v_mfma_f32_16x16x32_bf16 v[104:107], v[220:223], v[44:47], v[20:23]
	v_mfma_f32_16x16x32_bf16 v[20:23], v[236:239], v[36:39], v[80:83]
	v_mfma_f32_16x16x32_bf16 v[116:119], v[220:223], v[28:31], v[96:99]
	v_mfma_f32_16x16x32_bf16 v[96:99], v[156:159], v[44:47], v[20:23]
	v_mfma_f32_16x16x32_bf16 v[20:23], v[138:141], v[52:55], v[192:195]
	v_mfma_f32_16x16x32_bf16 v[88:91], v[220:223], v[208:211], v[20:23]
	v_mfma_f32_16x16x32_bf16 v[20:23], v[236:239], v[52:55], v[72:75]
	v_mfma_f32_16x16x32_bf16 v[80:83], v[156:159], v[208:211], v[20:23]
	v_mfma_f32_16x16x32_bf16 v[20:23], v[138:141], v[212:215], v[196:199]
	v_mfma_f32_16x16x32_bf16 v[72:75], v[220:223], v[224:227], v[20:23]
	v_mfma_f32_16x16x32_bf16 v[20:23], v[236:239], v[212:215], v[64:67]
	v_mfma_f32_16x16x32_bf16 v[64:67], v[156:159], v[224:227], v[20:23]
	s_setprio 0
	s_barrier
	ds_read_b128 v[186:189], v155 offset:49152
	ds_read_b128 v[190:193], v155 offset:50176
	ds_read_b128 v[194:197], v173 offset:49152
	ds_read_b128 v[208:211], v173 offset:50176
	ds_read_b128 v[212:215], v174 offset:49152
	ds_read_b128 v[224:227], v174 offset:50176
	ds_read_b128 v[228:231], v175 offset:49152
	ds_read_b128 v[240:243], v175 offset:50176
	s_barrier
	s_waitcnt lgkmcnt(0)
	s_setprio 1
	v_mfma_f32_16x16x32_bf16 v[20:23], v[8:11], v[186:189], v[60:63]
	v_mfma_f32_16x16x32_bf16 v[60:63], v[12:15], v[190:193], v[20:23]
	v_mfma_f32_16x16x32_bf16 v[20:23], v[160:163], v[186:189], v[56:59]
	v_mfma_f32_16x16x32_bf16 v[52:55], v[204:207], v[190:193], v[20:23]
	v_mfma_f32_16x16x32_bf16 v[20:23], v[8:11], v[194:197], v[216:219]
	v_mfma_f32_16x16x32_bf16 v[44:47], v[12:15], v[208:211], v[20:23]
	v_mfma_f32_16x16x32_bf16 v[20:23], v[160:163], v[194:197], v[48:51]
	v_mfma_f32_16x16x32_bf16 v[36:39], v[204:207], v[208:211], v[20:23]
	v_mfma_f32_16x16x32_bf16 v[20:23], v[8:11], v[212:215], v[232:235]
	v_mfma_f32_16x16x32_bf16 v[8:11], v[8:11], v[228:231], v[142:145]
	v_mfma_f32_16x16x32_bf16 v[28:31], v[12:15], v[224:227], v[20:23]
	v_mfma_f32_16x16x32_bf16 v[20:23], v[160:163], v[212:215], v[40:43]
	v_mfma_f32_16x16x32_bf16 v[12:15], v[12:15], v[240:243], v[8:11]
	v_mfma_f32_16x16x32_bf16 v[8:11], v[160:163], v[228:231], v[32:35]
	v_mfma_f32_16x16x32_bf16 v[20:23], v[204:207], v[224:227], v[20:23]
	v_mfma_f32_16x16x32_bf16 v[8:11], v[204:207], v[240:243], v[8:11]
	s_setprio 0
	s_setprio 1
	v_mfma_f32_16x16x32_bf16 v[32:35], v[138:141], v[186:189], v[146:149]
	v_mfma_f32_16x16x32_bf16 v[24:27], v[236:239], v[186:189], v[24:27]
	v_mfma_f32_16x16x32_bf16 v[16:19], v[236:239], v[194:197], v[16:19]
	v_mfma_f32_16x16x32_bf16 v[56:59], v[220:223], v[190:193], v[32:35]
	v_mfma_f32_16x16x32_bf16 v[48:51], v[156:159], v[190:193], v[24:27]
	v_mfma_f32_16x16x32_bf16 v[24:27], v[138:141], v[194:197], v[178:181]
	v_mfma_f32_16x16x32_bf16 v[32:35], v[156:159], v[208:211], v[16:19]
	v_mfma_f32_16x16x32_bf16 v[16:19], v[138:141], v[212:215], v[182:185]
	v_mfma_f32_16x16x32_bf16 v[40:43], v[220:223], v[208:211], v[24:27]
	v_mfma_f32_16x16x32_bf16 v[24:27], v[220:223], v[224:227], v[16:19]
	v_mfma_f32_16x16x32_bf16 v[16:19], v[236:239], v[212:215], v[200:203]
	v_mfma_f32_16x16x32_bf16 v[4:7], v[138:141], v[228:231], v[4:7]
	v_mfma_f32_16x16x32_bf16 v[0:3], v[236:239], v[228:231], v[0:3]
	v_mfma_f32_16x16x32_bf16 v[16:19], v[156:159], v[224:227], v[16:19]
	v_mfma_f32_16x16x32_bf16 v[4:7], v[220:223], v[240:243], v[4:7]
	v_mfma_f32_16x16x32_bf16 v[0:3], v[156:159], v[240:243], v[0:3]
	s_setprio 0
	s_cmpk_gt_u32 s0, 0xff
	s_barrier
	s_cbranch_scc1 .LBB0_919
	s_barrier

; #define STAGE(P,BASE,LD,br,kt) do{long _g=(long)(br)*(LD)+(long)(kt)*BK; \
;     _Pragma("unroll") for(int _i=0;_i<2;++_i){int _b=tid*16+_i*8192;int _r,_c;stage_rc(_b,_r,_c); \
;       __builtin_amdgcn_global_load_lds((const unsigned*)((BASE)+_g+(long)_r*(LD)+_c), \
;         (unsigned*)((char*)(P)+_b),16,0,0);}}while(0)
; #define STAGE(P,BASE,LD,br,kt) do{long _g=(long)(br)*(LD)+(long)(kt)*BK; \
;     _Pragma("unroll") for(int _i=0;_i<2;++_i){int _b=tid*16+_i*8192;int _r,_c;stage_rc(_b,_r,_c); \
;       __builtin_amdgcn_global_load_lds((const unsigned*)((BASE)+_g+(long)_r*(LD)+_c), \
;         (unsigned*)((char*)(P)+_b),16,0,0);}}while(0)
; #define LDA(dst,b,h) _Pragma("unroll") for(int m=0;m<4;++m) _Pragma("unroll") for(int k=0;k<2;++k) \
;     dst[m][k]=*reinterpret_cast<const bf16x8*>((char*)SA(b,h)+lds_byte(wr*64+m*16+fr,k*32+fq*8))
; #define LDB(dst,b,h) _Pragma("unroll") for(int n=0;n<2;++n) _Pragma("unroll") for(int k=0;k<2;++k) \
;     dst[n][k]=*reinterpret_cast<const bf16x8*>((char*)SB(b,h)+lds_byte(wc*32+n*16+fr,k*32+fq*8))
; #define MMA(ai,bj,At_,Bt_) do{__builtin_amdgcn_s_setprio(1); \
;     _Pragma("unroll") for(int m=0;m<4;++m) _Pragma("unroll") for(int n=0;n<2;++n) _Pragma("unroll") for(int k=0;k<2;++k) \
;       acc[ai][bj][m][n]=__builtin_amdgcn_mfma_f32_16x16x32_bf16(Bt_[n][k],At_[m][k],acc[ai][bj][m][n],0,0,0); \
;     __builtin_amdgcn_s_setprio(0);}while(0)
; #define WAIT_L(n) asm volatile("s_waitcnt lgkmcnt(" #n ")":::"memory")
; #define BAR __builtin_amdgcn_s_barrier()
; #define SCHED __builtin_amdgcn_sched_barrier(0)
; DEVINL void gemm8_mainloop(const u16* A, long lda, const u16* Bt, long ldb, int K, int brow, int bcol, f32x4 (&acc)[2][2][4][2], char* smem, int tid) {
;     ...
;   for(int t=0;t<nt-2;t+=2){
;     LDB(B0,0,0); SCHED; LDA(At,0,0); STAGE(SA(1,1),A,lda,brow+HALF,t+1);
;     WAIT_L(8); BAR; WAIT_L(0); MMA(0,0,At,B0); BAR; SCHED;
;     LDB(B1,0,1); STAGE(SB(0,0),Bt,ldb,bcol,t+2);
;     BAR; WAIT_L(0); MMA(0,1,At,B1); BAR;
;     LDA(At,0,1); STAGE(SA(0,0),A,lda,brow,t+2);
;     BAR; WAIT_L(0); MMA(1,0,At,B0); BAR; SCHED;
.LBB0_965:
	ds_read_b128 v[178:181], v163
	ds_read_b128 v[182:185], v163 offset:1024
	ds_read_b128 v[186:189], v163 offset:2048
	ds_read_b128 v[190:193], v163 offset:3072
	v_add_u32_e32 v174, 0xc000, v152
	v_lshl_add_u64 v[242:243], s[94:95], 0, v[146:147]
	v_readfirstlane_b32 s25, v174
	v_add_u32_e32 v175, 0xe000, v152
	v_add_u32_e32 v171, s0, v162
	v_add_u32_e32 v172, s1, v162
	v_add_u32_e32 v173, s27, v162
	v_lshl_add_u64 v[164:165], v[242:243], 0, s[4:5]
	s_mov_b32 m0, s25
	v_lshl_add_u64 v[244:245], s[94:95], 0, v[148:149]
	v_readfirstlane_b32 s25, v175
	ds_read_b128 v[166:169], v153
	ds_read_b128 v[194:197], v153 offset:1024
	ds_read_b128 v[198:201], v171
	ds_read_b128 v[202:205], v171 offset:1024
	ds_read_b128 v[206:209], v172
	ds_read_b128 v[210:213], v172 offset:1024
	ds_read_b128 v[214:217], v173
	ds_read_b128 v[218:221], v173 offset:1024
	global_load_lds_dwordx4 v[164:165], off
	v_lshl_add_u64 v[164:165], v[244:245], 0, s[4:5]
	s_mov_b32 m0, s25
	s_nop 0
	global_load_lds_dwordx4 v[164:165], off
	s_waitcnt lgkmcnt(8)
	s_barrier
	s_waitcnt lgkmcnt(0)
	s_setprio 1
	v_mfma_f32_16x16x32_bf16 v[124:127], v[178:181], v[166:169], v[124:127]
	v_mfma_f32_16x16x32_bf16 v[120:123], v[186:189], v[166:169], v[120:123]
	v_mfma_f32_16x16x32_bf16 v[116:119], v[178:181], v[198:201], v[116:119]
	v_mfma_f32_16x16x32_bf16 v[112:115], v[186:189], v[198:201], v[112:115]
	v_mfma_f32_16x16x32_bf16 v[108:111], v[178:181], v[206:209], v[108:111]
	v_mfma_f32_16x16x32_bf16 v[104:107], v[186:189], v[206:209], v[104:107]
	v_mfma_f32_16x16x32_bf16 v[100:103], v[178:181], v[214:217], v[100:103]
	v_mfma_f32_16x16x32_bf16 v[96:99], v[186:189], v[214:217], v[96:99]
	v_mfma_f32_16x16x32_bf16 v[124:127], v[182:185], v[194:197], v[124:127]
	v_mfma_f32_16x16x32_bf16 v[120:123], v[190:193], v[194:197], v[120:123]
	v_mfma_f32_16x16x32_bf16 v[116:119], v[182:185], v[202:205], v[116:119]
	v_mfma_f32_16x16x32_bf16 v[112:115], v[190:193], v[202:205], v[112:115]
	v_mfma_f32_16x16x32_bf16 v[108:111], v[182:185], v[210:213], v[108:111]
	v_mfma_f32_16x16x32_bf16 v[104:107], v[190:193], v[210:213], v[104:107]
	v_mfma_f32_16x16x32_bf16 v[100:103], v[182:185], v[218:221], v[100:103]
	v_mfma_f32_16x16x32_bf16 v[96:99], v[190:193], v[218:221], v[96:99]
	s_setprio 0
	s_barrier
	v_add_u32_e32 v164, s30, v154
	v_lshl_add_u64 v[246:247], s[94:95], 0, v[142:143]
	v_readfirstlane_b32 s25, v164
	v_add_u32_e32 v165, 0x2000, v164
	v_lshl_add_u64 v[238:239], v[246:247], 0, s[6:7]
	s_mov_b32 m0, s25
	v_lshl_add_u64 v[248:249], s[94:95], 0, v[144:145]
	v_readfirstlane_b32 s25, v165
	ds_read_b128 v[222:225], v160
	ds_read_b128 v[226:229], v160 offset:1024
	ds_read_b128 v[230:233], v160 offset:2048
	ds_read_b128 v[234:237], v160 offset:3072
	global_load_lds_dwordx4 v[238:239], off
	v_lshl_add_u64 v[238:239], v[248:249], 0, s[6:7]
	s_mov_b32 m0, s25
	s_nop 0
	global_load_lds_dwordx4 v[238:239], off
	s_barrier
	s_waitcnt lgkmcnt(0)
	s_setprio 1
	v_mfma_f32_16x16x32_bf16 v[92:95], v[222:225], v[166:169], v[92:95]
	v_mfma_f32_16x16x32_bf16 v[88:91], v[230:233], v[166:169], v[88:91]
	v_mfma_f32_16x16x32_bf16 v[84:87], v[222:225], v[198:201], v[84:87]
	v_mfma_f32_16x16x32_bf16 v[80:83], v[230:233], v[198:201], v[80:83]
	v_mfma_f32_16x16x32_bf16 v[76:79], v[222:225], v[206:209], v[76:79]
	v_mfma_f32_16x16x32_bf16 v[72:75], v[230:233], v[206:209], v[72:75]
	v_mfma_f32_16x16x32_bf16 v[68:71], v[222:225], v[214:217], v[68:71]
	v_mfma_f32_16x16x32_bf16 v[64:67], v[230:233], v[214:217], v[64:67]
	v_mfma_f32_16x16x32_bf16 v[92:95], v[226:229], v[194:197], v[92:95]
	v_mfma_f32_16x16x32_bf16 v[88:91], v[234:237], v[194:197], v[88:91]
	v_mfma_f32_16x16x32_bf16 v[84:87], v[226:229], v[202:205], v[84:87]
	v_mfma_f32_16x16x32_bf16 v[80:83], v[234:237], v[202:205], v[80:83]
	v_mfma_f32_16x16x32_bf16 v[76:79], v[226:229], v[210:213], v[76:79]
	v_mfma_f32_16x16x32_bf16 v[72:75], v[234:237], v[210:213], v[72:75]
	v_mfma_f32_16x16x32_bf16 v[68:71], v[226:229], v[218:221], v[68:71]
	v_mfma_f32_16x16x32_bf16 v[64:67], v[234:237], v[218:221], v[64:67]
	s_setprio 0
	v_readfirstlane_b32 s25, v152
	v_lshl_add_u64 v[166:167], v[242:243], 0, s[8:9]
	s_mov_b32 m0, s25
	s_barrier
	ds_read_b128 v[194:197], v153 offset:16384
	ds_read_b128 v[198:201], v153 offset:17408
	ds_read_b128 v[202:205], v171 offset:16384
	ds_read_b128 v[206:209], v171 offset:17408
	ds_read_b128 v[210:213], v172 offset:16384
	ds_read_b128 v[214:217], v172 offset:17408
	ds_read_b128 v[218:221], v173 offset:16384
	ds_read_b128 v[238:241], v173 offset:17408
	global_load_lds_dwordx4 v[166:167], off
	v_add_u32_e32 v166, 0x2000, v152
	v_lshl_add_u64 v[168:169], v[244:245], 0, s[8:9]
	v_readfirstlane_b32 s25, v166
	s_mov_b32 m0, s25
	s_nop 0
	global_load_lds_dwordx4 v[168:169], off
	s_barrier
	s_waitcnt lgkmcnt(0)
	s_setprio 1
	v_mfma_f32_16x16x32_bf16 v[60:63], v[178:181], v[194:197], v[60:63]
	v_mfma_f32_16x16x32_bf16 v[56:59], v[186:189], v[194:197], v[56:59]
	v_mfma_f32_16x16x32_bf16 v[52:55], v[178:181], v[202:205], v[52:55]
	v_mfma_f32_16x16x32_bf16 v[48:51], v[186:189], v[202:205], v[48:51]
	v_mfma_f32_16x16x32_bf16 v[44:47], v[178:181], v[210:213], v[44:47]
	v_mfma_f32_16x16x32_bf16 v[40:43], v[186:189], v[210:213], v[40:43]
	v_mfma_f32_16x16x32_bf16 v[36:39], v[178:181], v[218:221], v[36:39]
	v_mfma_f32_16x16x32_bf16 v[32:35], v[186:189], v[218:221], v[32:35]
	v_mfma_f32_16x16x32_bf16 v[60:63], v[182:185], v[198:201], v[60:63]
	v_mfma_f32_16x16x32_bf16 v[56:59], v[190:193], v[198:201], v[56:59]
	v_mfma_f32_16x16x32_bf16 v[52:55], v[182:185], v[206:209], v[52:55]
	v_mfma_f32_16x16x32_bf16 v[48:51], v[190:193], v[206:209], v[48:51]
	v_mfma_f32_16x16x32_bf16 v[44:47], v[182:185], v[214:217], v[44:47]
	v_mfma_f32_16x16x32_bf16 v[40:43], v[190:193], v[214:217], v[40:43]
	v_mfma_f32_16x16x32_bf16 v[36:39], v[182:185], v[238:241], v[36:39]
	v_mfma_f32_16x16x32_bf16 v[32:35], v[190:193], v[238:241], v[32:35]
	s_setprio 0
	s_barrier
; #define STAGE(P,BASE,LD,br,kt) do{long _g=(long)(br)*(LD)+(long)(kt)*BK; \
;     _Pragma("unroll") for(int _i=0;_i<2;++_i){int _b=tid*16+_i*8192;int _r,_c;stage_rc(_b,_r,_c); \
;       __builtin_amdgcn_global_load_lds((const unsigned*)((BASE)+_g+(long)_r*(LD)+_c), \
;         (unsigned*)((char*)(P)+_b),16,0,0);}}while(0)
; #define STAGE(P,BASE,LD,br,kt) do{long _g=(long)(br)*(LD)+(long)(kt)*BK; \
;     _Pragma("unroll") for(int _i=0;_i<2;++_i){int _b=tid*16+_i*8192;int _r,_c;stage_rc(_b,_r,_c); \
;       __builtin_amdgcn_global_load_lds((const unsigned*)((BASE)+_g+(long)_r*(LD)+_c), \
;         (unsigned*)((char*)(P)+_b),16,0,0);}}while(0)
; #define LDA(dst,b,h) _Pragma("unroll") for(int m=0;m<4;++m) _Pragma("unroll") for(int k=0;k<2;++k) \
;     dst[m][k]=*reinterpret_cast<const bf16x8*>((char*)SA(b,h)+lds_byte(wr*64+m*16+fr,k*32+fq*8))
; #define LDB(dst,b,h) _Pragma("unroll") for(int n=0;n<2;++n) _Pragma("unroll") for(int k=0;k<2;++k) \
;     dst[n][k]=*reinterpret_cast<const bf16x8*>((char*)SB(b,h)+lds_byte(wc*32+n*16+fr,k*32+fq*8))
; #define MMA(ai,bj,At_,Bt_) do{__builtin_amdgcn_s_setprio(1); \
;     _Pragma("unroll") for(int m=0;m<4;++m) _Pragma("unroll") for(int n=0;n<2;++n) _Pragma("unroll") for(int k=0;k<2;++k) \
;       acc[ai][bj][m][n]=__builtin_amdgcn_mfma_f32_16x16x32_bf16(Bt_[n][k],At_[m][k],acc[ai][bj][m][n],0,0,0); \
;     __builtin_amdgcn_s_setprio(0);}while(0)
; #define WAIT_V(n) asm volatile("s_waitcnt vmcnt(" #n ")":::"memory")
; #define WAIT_L(n) asm volatile("s_waitcnt lgkmcnt(" #n ")":::"memory")
; #define BAR __builtin_amdgcn_s_barrier()
; #define SCHED __builtin_amdgcn_sched_barrier(0)
; DEVINL void gemm8_mainloop(const u16* A, long lda, const u16* Bt, long ldb, int K, int brow, int bcol, f32x4 (&acc)[2][2][4][2], char* smem, int tid) {
;     ...
;     STAGE(SB(0,1),Bt,ldb,bcol+HALF,t+2);
;     WAIT_V(6); BAR; MMA(1,1,At,B1); BAR;
;     LDB(B0,1,0); SCHED; LDA(At,1,0); STAGE(SA(0,1),A,lda,brow+HALF,t+2);
;     WAIT_L(8); BAR; WAIT_L(0); MMA(0,0,At,B0); BAR; SCHED;
;     LDB(B1,1,1); STAGE(SB(1,0),Bt,ldb,bcol,t+3);
;     BAR; WAIT_L(0); MMA(0,1,At,B1); BAR;
	v_add_u32_e32 v167, s31, v154
	v_lshl_add_u64 v[168:169], v[246:247], 0, s[10:11]
	v_readfirstlane_b32 s25, v167
	s_mov_b32 m0, s25
	v_lshl_add_u64 v[178:179], v[248:249], 0, s[10:11]
	global_load_lds_dwordx4 v[168:169], off
	v_add_u32_e32 v168, 0x2000, v167
	s_nop 0
	v_readfirstlane_b32 s25, v168
	s_mov_b32 m0, s25
	s_nop 0
	global_load_lds_dwordx4 v[178:179], off
	s_waitcnt vmcnt(6)
	s_barrier
	s_setprio 1
	v_mfma_f32_16x16x32_bf16 v[28:31], v[222:225], v[194:197], v[28:31]
	v_mfma_f32_16x16x32_bf16 v[24:27], v[230:233], v[194:197], v[24:27]
	v_mfma_f32_16x16x32_bf16 v[20:23], v[222:225], v[202:205], v[20:23]
	v_mfma_f32_16x16x32_bf16 v[16:19], v[230:233], v[202:205], v[16:19]
	v_mfma_f32_16x16x32_bf16 v[12:15], v[222:225], v[210:213], v[12:15]
	v_mfma_f32_16x16x32_bf16 v[8:11], v[230:233], v[210:213], v[8:11]
	v_mfma_f32_16x16x32_bf16 v[4:7], v[222:225], v[218:221], v[4:7]
	v_mfma_f32_16x16x32_bf16 v[0:3], v[230:233], v[218:221], v[0:3]
	v_mfma_f32_16x16x32_bf16 v[28:31], v[226:229], v[198:201], v[28:31]
	v_mfma_f32_16x16x32_bf16 v[24:27], v[234:237], v[198:201], v[24:27]
	v_mfma_f32_16x16x32_bf16 v[20:23], v[226:229], v[206:209], v[20:23]
	v_mfma_f32_16x16x32_bf16 v[16:19], v[234:237], v[206:209], v[16:19]
	v_mfma_f32_16x16x32_bf16 v[12:15], v[226:229], v[214:217], v[12:15]
	v_mfma_f32_16x16x32_bf16 v[8:11], v[234:237], v[214:217], v[8:11]
	v_mfma_f32_16x16x32_bf16 v[4:7], v[226:229], v[238:241], v[4:7]
	v_mfma_f32_16x16x32_bf16 v[0:3], v[234:237], v[238:241], v[0:3]
	s_setprio 0
	s_barrier
	ds_read_b128 v[178:181], v157
	ds_read_b128 v[182:185], v157 offset:1024
	ds_read_b128 v[186:189], v157 offset:2048
	ds_read_b128 v[190:193], v157 offset:3072
	v_add_u32_e32 v169, 0x4000, v152
	v_add_u32_e32 v170, 0x6000, v152
	v_readfirstlane_b32 s25, v169
	v_lshl_add_u64 v[226:227], v[242:243], 0, s[12:13]
	s_mov_b32 m0, s25
	v_readfirstlane_b32 s25, v170
	ds_read_b128 v[194:197], v153 offset:32768
	ds_read_b128 v[198:201], v153 offset:33792
	ds_read_b128 v[202:205], v171 offset:32768
	ds_read_b128 v[206:209], v171 offset:33792
	ds_read_b128 v[210:213], v172 offset:32768
	ds_read_b128 v[214:217], v172 offset:33792
	ds_read_b128 v[218:221], v173 offset:32768
	ds_read_b128 v[222:225], v173 offset:33792
	global_load_lds_dwordx4 v[226:227], off
	v_lshl_add_u64 v[226:227], v[244:245], 0, s[12:13]
	s_mov_b32 m0, s25
	s_nop 0
	global_load_lds_dwordx4 v[226:227], off
	s_waitcnt lgkmcnt(8)
	s_barrier
	s_waitcnt lgkmcnt(0)
	s_setprio 1
	v_mfma_f32_16x16x32_bf16 v[124:127], v[178:181], v[194:197], v[124:127]
	v_mfma_f32_16x16x32_bf16 v[120:123], v[186:189], v[194:197], v[120:123]
	v_mfma_f32_16x16x32_bf16 v[116:119], v[178:181], v[202:205], v[116:119]
	v_mfma_f32_16x16x32_bf16 v[112:115], v[186:189], v[202:205], v[112:115]
	v_mfma_f32_16x16x32_bf16 v[108:111], v[178:181], v[210:213], v[108:111]
	v_mfma_f32_16x16x32_bf16 v[104:107], v[186:189], v[210:213], v[104:107]
	v_mfma_f32_16x16x32_bf16 v[100:103], v[178:181], v[218:221], v[100:103]
	v_mfma_f32_16x16x32_bf16 v[96:99], v[186:189], v[218:221], v[96:99]
	v_mfma_f32_16x16x32_bf16 v[124:127], v[182:185], v[198:201], v[124:127]
	v_mfma_f32_16x16x32_bf16 v[120:123], v[190:193], v[198:201], v[120:123]
	v_mfma_f32_16x16x32_bf16 v[116:119], v[182:185], v[206:209], v[116:119]
	v_mfma_f32_16x16x32_bf16 v[112:115], v[190:193], v[206:209], v[112:115]
	v_mfma_f32_16x16x32_bf16 v[108:111], v[182:185], v[214:217], v[108:111]
	v_mfma_f32_16x16x32_bf16 v[104:107], v[190:193], v[214:217], v[104:107]
	v_mfma_f32_16x16x32_bf16 v[100:103], v[182:185], v[222:225], v[100:103]
	v_mfma_f32_16x16x32_bf16 v[96:99], v[190:193], v[222:225], v[96:99]
	s_setprio 0
	s_barrier
	v_readfirstlane_b32 s25, v156
	v_add_u32_e32 v177, 0x2000, v156
	v_lshl_add_u64 v[250:251], v[246:247], 0, s[14:15]
	s_mov_b32 m0, s25
	v_readfirstlane_b32 s25, v177
	ds_read_b128 v[226:229], v155
	ds_read_b128 v[230:233], v155 offset:1024
	ds_read_b128 v[234:237], v155 offset:2048
	ds_read_b128 v[238:241], v155 offset:3072
	global_load_lds_dwordx4 v[250:251], off
	v_lshl_add_u64 v[250:251], v[248:249], 0, s[14:15]
	s_mov_b32 m0, s25
	s_nop 0
	global_load_lds_dwordx4 v[250:251], off
	s_barrier
	s_waitcnt lgkmcnt(0)
	s_setprio 1
	v_mfma_f32_16x16x32_bf16 v[92:95], v[226:229], v[194:197], v[92:95]
	v_mfma_f32_16x16x32_bf16 v[88:91], v[234:237], v[194:197], v[88:91]
	v_mfma_f32_16x16x32_bf16 v[84:87], v[226:229], v[202:205], v[84:87]
	v_mfma_f32_16x16x32_bf16 v[80:83], v[234:237], v[202:205], v[80:83]
	v_mfma_f32_16x16x32_bf16 v[76:79], v[226:229], v[210:213], v[76:79]
	v_mfma_f32_16x16x32_bf16 v[72:75], v[234:237], v[210:213], v[72:75]
	v_mfma_f32_16x16x32_bf16 v[68:71], v[226:229], v[218:221], v[68:71]
	v_mfma_f32_16x16x32_bf16 v[64:67], v[234:237], v[218:221], v[64:67]
	v_mfma_f32_16x16x32_bf16 v[92:95], v[230:233], v[198:201], v[92:95]
	v_mfma_f32_16x16x32_bf16 v[88:91], v[238:241], v[198:201], v[88:91]
	v_mfma_f32_16x16x32_bf16 v[84:87], v[230:233], v[206:209], v[84:87]
	v_mfma_f32_16x16x32_bf16 v[80:83], v[238:241], v[206:209], v[80:83]
	v_mfma_f32_16x16x32_bf16 v[76:79], v[230:233], v[214:217], v[76:79]
	v_mfma_f32_16x16x32_bf16 v[72:75], v[238:241], v[214:217], v[72:75]
	v_mfma_f32_16x16x32_bf16 v[68:71], v[230:233], v[222:225], v[68:71]
	v_mfma_f32_16x16x32_bf16 v[64:67], v[238:241], v[222:225], v[64:67]
	s_setprio 0
	v_readfirstlane_b32 s25, v158
	v_lshl_add_u64 v[242:243], v[242:243], 0, s[16:17]
	s_mov_b32 m0, s25
	v_readfirstlane_b32 s25, v159
	s_barrier
; #define STAGE(P,BASE,LD,br,kt) do{long _g=(long)(br)*(LD)+(long)(kt)*BK; \
;     _Pragma("unroll") for(int _i=0;_i<2;++_i){int _b=tid*16+_i*8192;int _r,_c;stage_rc(_b,_r,_c); \
;       __builtin_amdgcn_global_load_lds((const unsigned*)((BASE)+_g+(long)_r*(LD)+_c), \
;         (unsigned*)((char*)(P)+_b),16,0,0);}}while(0)
; #define STAGE(P,BASE,LD,br,kt) do{long _g=(long)(br)*(LD)+(long)(kt)*BK; \
;     _Pragma("unroll") for(int _i=0;_i<2;++_i){int _b=tid*16+_i*8192;int _r,_c;stage_rc(_b,_r,_c); \
;       __builtin_amdgcn_global_load_lds((const unsigned*)((BASE)+_g+(long)_r*(LD)+_c), \
;         (unsigned*)((char*)(P)+_b),16,0,0);}}while(0)
; #define LDA(dst,b,h) _Pragma("unroll") for(int m=0;m<4;++m) _Pragma("unroll") for(int k=0;k<2;++k) \
;     dst[m][k]=*reinterpret_cast<const bf16x8*>((char*)SA(b,h)+lds_byte(wr*64+m*16+fr,k*32+fq*8))
; #define LDB(dst,b,h) _Pragma("unroll") for(int n=0;n<2;++n) _Pragma("unroll") for(int k=0;k<2;++k) \
;     dst[n][k]=*reinterpret_cast<const bf16x8*>((char*)SB(b,h)+lds_byte(wc*32+n*16+fr,k*32+fq*8))
; #define MMA(ai,bj,At_,Bt_) do{__builtin_amdgcn_s_setprio(1); \
;     _Pragma("unroll") for(int m=0;m<4;++m) _Pragma("unroll") for(int n=0;n<2;++n) _Pragma("unroll") for(int k=0;k<2;++k) \
;       acc[ai][bj][m][n]=__builtin_amdgcn_mfma_f32_16x16x32_bf16(Bt_[n][k],At_[m][k],acc[ai][bj][m][n],0,0,0); \
;     __builtin_amdgcn_s_setprio(0);}while(0)
; #define WAIT_V(n) asm volatile("s_waitcnt vmcnt(" #n ")":::"memory")
; #define WAIT_L(n) asm volatile("s_waitcnt lgkmcnt(" #n ")":::"memory")
; #define BAR __builtin_amdgcn_s_barrier()
; #define SCHED __builtin_amdgcn_sched_barrier(0)
; DEVINL void gemm8_mainloop(const u16* A, long lda, const u16* Bt, long ldb, int K, int brow, int bcol, f32x4 (&acc)[2][2][4][2], char* smem, int tid) {
;     ...
;     LDA(At,1,1); STAGE(SA(1,0),A,lda,brow,t+3);
;     BAR; WAIT_L(0); MMA(1,0,At,B0); BAR; SCHED;
;     STAGE(SB(1,1),Bt,ldb,bcol+HALF,t+3);
;     WAIT_V(6); BAR; MMA(1,1,At,B1); BAR;
;   }
;   { LDB(B0,0,0); LDA(At,0,0); STAGE(SA(1,1),A,lda,brow+HALF,nt-1);
;     BAR; WAIT_L(0); MMA(0,0,At,B0); BAR;
	ds_read_b128 v[194:197], v153 offset:49152
	ds_read_b128 v[198:201], v153 offset:50176
	ds_read_b128 v[202:205], v171 offset:49152
	ds_read_b128 v[206:209], v171 offset:50176
	ds_read_b128 v[210:213], v172 offset:49152
	ds_read_b128 v[214:217], v172 offset:50176
	ds_read_b128 v[218:221], v173 offset:49152
	ds_read_b128 v[222:225], v173 offset:50176
	global_load_lds_dwordx4 v[242:243], off
	v_lshl_add_u64 v[242:243], v[244:245], 0, s[16:17]
	s_mov_b32 m0, s25
	s_nop 0
	global_load_lds_dwordx4 v[242:243], off
	s_barrier
	s_waitcnt lgkmcnt(0)
	s_setprio 1
	v_mfma_f32_16x16x32_bf16 v[60:63], v[178:181], v[194:197], v[60:63]
	v_mfma_f32_16x16x32_bf16 v[56:59], v[186:189], v[194:197], v[56:59]
	v_mfma_f32_16x16x32_bf16 v[52:55], v[178:181], v[202:205], v[52:55]
	v_mfma_f32_16x16x32_bf16 v[48:51], v[186:189], v[202:205], v[48:51]
	v_mfma_f32_16x16x32_bf16 v[44:47], v[178:181], v[210:213], v[44:47]
	v_mfma_f32_16x16x32_bf16 v[40:43], v[186:189], v[210:213], v[40:43]
	v_mfma_f32_16x16x32_bf16 v[36:39], v[178:181], v[218:221], v[36:39]
	v_mfma_f32_16x16x32_bf16 v[32:35], v[186:189], v[218:221], v[32:35]
	v_mfma_f32_16x16x32_bf16 v[60:63], v[182:185], v[198:201], v[60:63]
	v_mfma_f32_16x16x32_bf16 v[56:59], v[190:193], v[198:201], v[56:59]
	v_mfma_f32_16x16x32_bf16 v[52:55], v[182:185], v[206:209], v[52:55]
	v_mfma_f32_16x16x32_bf16 v[48:51], v[190:193], v[206:209], v[48:51]
	v_mfma_f32_16x16x32_bf16 v[44:47], v[182:185], v[214:217], v[44:47]
	v_mfma_f32_16x16x32_bf16 v[40:43], v[190:193], v[214:217], v[40:43]
	v_mfma_f32_16x16x32_bf16 v[36:39], v[182:185], v[222:225], v[36:39]
	v_mfma_f32_16x16x32_bf16 v[32:35], v[190:193], v[222:225], v[32:35]
	s_setprio 0
	s_barrier
	v_readfirstlane_b32 s25, v161
	v_add_u32_e32 v177, 0x2000, v161
	v_lshl_add_u64 v[178:179], v[246:247], 0, s[18:19]
	s_mov_b32 m0, s25
	v_readfirstlane_b32 s25, v177
	global_load_lds_dwordx4 v[178:179], off
	v_lshl_add_u64 v[178:179], v[248:249], 0, s[18:19]
	s_mov_b32 m0, s25
	s_nop 0
	global_load_lds_dwordx4 v[178:179], off
	s_waitcnt vmcnt(6)
	s_barrier
	s_setprio 1
	v_mfma_f32_16x16x32_bf16 v[28:31], v[226:229], v[194:197], v[28:31]
	v_mfma_f32_16x16x32_bf16 v[24:27], v[234:237], v[194:197], v[24:27]
	v_mfma_f32_16x16x32_bf16 v[20:23], v[226:229], v[202:205], v[20:23]
	v_mfma_f32_16x16x32_bf16 v[16:19], v[234:237], v[202:205], v[16:19]
	v_mfma_f32_16x16x32_bf16 v[12:15], v[226:229], v[210:213], v[12:15]
	v_mfma_f32_16x16x32_bf16 v[8:11], v[234:237], v[210:213], v[8:11]
	v_mfma_f32_16x16x32_bf16 v[4:7], v[226:229], v[218:221], v[4:7]
	v_mfma_f32_16x16x32_bf16 v[0:3], v[234:237], v[218:221], v[0:3]
	v_mfma_f32_16x16x32_bf16 v[28:31], v[230:233], v[198:201], v[28:31]
	v_mfma_f32_16x16x32_bf16 v[24:27], v[238:241], v[198:201], v[24:27]
	v_mfma_f32_16x16x32_bf16 v[20:23], v[230:233], v[206:209], v[20:23]
	v_mfma_f32_16x16x32_bf16 v[16:19], v[238:241], v[206:209], v[16:19]
	v_mfma_f32_16x16x32_bf16 v[12:15], v[230:233], v[214:217], v[12:15]
	v_mfma_f32_16x16x32_bf16 v[8:11], v[238:241], v[214:217], v[8:11]
	v_mfma_f32_16x16x32_bf16 v[4:7], v[230:233], v[222:225], v[4:7]
	v_mfma_f32_16x16x32_bf16 v[0:3], v[238:241], v[222:225], v[0:3]
	s_setprio 0
	s_add_i32 s24, s24, 2
	v_lshl_add_u64 v[142:143], v[142:143], 0, s[20:21]
	v_lshl_add_u64 v[144:145], v[144:145], 0, s[20:21]
	v_lshl_add_u64 v[146:147], v[146:147], 0, s[20:21]
	s_cmpk_lt_u32 s24, 0x7c
	v_lshl_add_u64 v[148:149], v[148:149], 0, s[20:21]
	s_barrier
	s_cbranch_scc1 .LBB0_965
	s_or_b32 s0, s26, 0x80
	s_ashr_i32 s1, s0, 31
	s_lshl_b64 s[0:1], s[0:1], 14
	s_add_u32 s0, s62, s0
	s_addc_u32 s1, s63, s1
	s_add_u32 s0, s0, 0x3f80
	s_addc_u32 s1, s1, 0
	v_lshl_add_u64 v[158:159], v[134:135], 1, s[0:1]
	v_readfirstlane_b32 s24, v174
	v_lshl_add_u64 v[138:139], v[138:139], 1, v[158:159]
	s_mov_b32 m0, s24
	ds_read_b128 v[142:145], v163
	ds_read_b128 v[146:149], v163 offset:1024
	ds_read_b128 v[178:181], v163 offset:2048
	ds_read_b128 v[182:185], v163 offset:3072
	ds_read_b128 v[186:189], v153
	ds_read_b128 v[190:193], v153 offset:1024
	ds_read_b128 v[194:197], v171
	ds_read_b128 v[198:201], v171 offset:1024
	ds_read_b128 v[202:205], v172
	ds_read_b128 v[206:209], v172 offset:1024
	ds_read_b128 v[210:213], v173
	ds_read_b128 v[214:217], v173 offset:1024
	global_load_lds_dwordx4 v[138:139], off
	v_lshl_add_u64 v[138:139], v[136:137], 1, s[0:1]
	v_readfirstlane_b32 s0, v175
	v_lshl_add_u64 v[138:139], v[140:141], 1, v[138:139]
	s_mov_b32 m0, s0
	s_nop 0
	global_load_lds_dwordx4 v[138:139], off
	s_barrier
	s_waitcnt lgkmcnt(0)
	s_setprio 1
	v_mfma_f32_16x16x32_bf16 v[124:127], v[142:145], v[186:189], v[124:127]
	v_mfma_f32_16x16x32_bf16 v[120:123], v[178:181], v[186:189], v[120:123]
	v_mfma_f32_16x16x32_bf16 v[116:119], v[142:145], v[194:197], v[116:119]
	v_mfma_f32_16x16x32_bf16 v[112:115], v[178:181], v[194:197], v[112:115]
	v_mfma_f32_16x16x32_bf16 v[100:103], v[142:145], v[210:213], v[100:103]
	v_mfma_f32_16x16x32_bf16 v[96:99], v[178:181], v[210:213], v[96:99]
	v_mfma_f32_16x16x32_bf16 v[124:127], v[146:149], v[190:193], v[124:127]
	v_mfma_f32_16x16x32_bf16 v[120:123], v[182:185], v[190:193], v[120:123]
	v_mfma_f32_16x16x32_bf16 v[116:119], v[146:149], v[198:201], v[116:119]
	v_mfma_f32_16x16x32_bf16 v[112:115], v[182:185], v[198:201], v[112:115]
	v_mfma_f32_16x16x32_bf16 v[108:111], v[142:145], v[202:205], v[108:111]
	v_mfma_f32_16x16x32_bf16 v[104:107], v[178:181], v[202:205], v[104:107]
	v_mfma_f32_16x16x32_bf16 v[100:103], v[146:149], v[214:217], v[100:103]
	v_mfma_f32_16x16x32_bf16 v[96:99], v[182:185], v[214:217], v[96:99]
	v_mfma_f32_16x16x32_bf16 v[138:141], v[146:149], v[206:209], v[108:111]
	v_mfma_f32_16x16x32_bf16 v[218:221], v[182:185], v[206:209], v[104:107]
	s_setprio 0
	s_barrier
; #define LDA(dst,b,h) _Pragma("unroll") for(int m=0;m<4;++m) _Pragma("unroll") for(int k=0;k<2;++k) \
;     dst[m][k]=*reinterpret_cast<const bf16x8*>((char*)SA(b,h)+lds_byte(wr*64+m*16+fr,k*32+fq*8))
; #define LDB(dst,b,h) _Pragma("unroll") for(int n=0;n<2;++n) _Pragma("unroll") for(int k=0;k<2;++k) \
;     dst[n][k]=*reinterpret_cast<const bf16x8*>((char*)SB(b,h)+lds_byte(wc*32+n*16+fr,k*32+fq*8))
; #define MMA(ai,bj,At_,Bt_) do{__builtin_amdgcn_s_setprio(1); \
;     _Pragma("unroll") for(int m=0;m<4;++m) _Pragma("unroll") for(int n=0;n<2;++n) _Pragma("unroll") for(int k=0;k<2;++k) \
;       acc[ai][bj][m][n]=__builtin_amdgcn_mfma_f32_16x16x32_bf16(Bt_[n][k],At_[m][k],acc[ai][bj][m][n],0,0,0); \
;     __builtin_amdgcn_s_setprio(0);}while(0)
; #define WAIT_V(n) asm volatile("s_waitcnt vmcnt(" #n ")":::"memory")
; #define WAIT_L(n) asm volatile("s_waitcnt lgkmcnt(" #n ")":::"memory")
; #define BAR __builtin_amdgcn_s_barrier()
; DEVINL void gemm8_mainloop(const u16* A, long lda, const u16* Bt, long ldb, int K, int brow, int bcol, f32x4 (&acc)[2][2][4][2], char* smem, int tid) {
;     ...
;     LDB(B1,0,1); BAR; WAIT_L(0); MMA(0,1,At,B1); BAR;
;     LDA(At,0,1); WAIT_V(4); BAR; WAIT_L(0); MMA(1,0,At,B0); MMA(1,1,At,B1); BAR; }
;   { LDB(B0,1,0); LDA(At,1,0); WAIT_V(2); BAR; WAIT_L(0); MMA(0,0,At,B0); BAR;
	s_nop 1
	ds_read_b128 v[104:107], v160
	ds_read_b128 v[108:111], v160 offset:1024
	ds_read_b128 v[222:225], v160 offset:2048
	ds_read_b128 v[158:161], v160 offset:3072
	s_barrier
	s_waitcnt lgkmcnt(0)
	s_setprio 1
	v_mfma_f32_16x16x32_bf16 v[84:87], v[104:107], v[194:197], v[84:87]
	v_mfma_f32_16x16x32_bf16 v[80:83], v[222:225], v[194:197], v[80:83]
	v_mfma_f32_16x16x32_bf16 v[68:71], v[104:107], v[210:213], v[68:71]
	v_mfma_f32_16x16x32_bf16 v[92:95], v[104:107], v[186:189], v[92:95]
	v_mfma_f32_16x16x32_bf16 v[88:91], v[222:225], v[186:189], v[88:91]
	v_mfma_f32_16x16x32_bf16 v[84:87], v[108:111], v[198:201], v[84:87]
	v_mfma_f32_16x16x32_bf16 v[80:83], v[158:161], v[198:201], v[80:83]
	v_mfma_f32_16x16x32_bf16 v[76:79], v[104:107], v[202:205], v[76:79]
	v_mfma_f32_16x16x32_bf16 v[72:75], v[222:225], v[202:205], v[72:75]
	v_mfma_f32_16x16x32_bf16 v[68:71], v[108:111], v[214:217], v[68:71]
	v_mfma_f32_16x16x32_bf16 v[64:67], v[222:225], v[210:213], v[64:67]
	v_mfma_f32_16x16x32_bf16 v[226:229], v[108:111], v[190:193], v[92:95]
	v_mfma_f32_16x16x32_bf16 v[186:189], v[158:161], v[190:193], v[88:91]
	v_mfma_f32_16x16x32_bf16 v[190:193], v[108:111], v[206:209], v[76:79]
	v_mfma_f32_16x16x32_bf16 v[194:197], v[158:161], v[206:209], v[72:75]
	v_mfma_f32_16x16x32_bf16 v[198:201], v[158:161], v[214:217], v[64:67]
	s_setprio 0
	s_barrier
	s_nop 0
	ds_read_b128 v[64:67], v153 offset:16384
	ds_read_b128 v[72:75], v153 offset:17408
	ds_read_b128 v[76:79], v171 offset:16384
	ds_read_b128 v[88:91], v171 offset:17408
	ds_read_b128 v[92:95], v172 offset:16384
	ds_read_b128 v[202:205], v172 offset:17408
	ds_read_b128 v[206:209], v173 offset:16384
	ds_read_b128 v[210:213], v173 offset:17408
	s_waitcnt vmcnt(4)
	s_barrier
	s_waitcnt lgkmcnt(0)
	s_setprio 1
	v_mfma_f32_16x16x32_bf16 v[60:63], v[142:145], v[64:67], v[60:63]
	v_mfma_f32_16x16x32_bf16 v[56:59], v[178:181], v[64:67], v[56:59]
	v_mfma_f32_16x16x32_bf16 v[52:55], v[142:145], v[76:79], v[52:55]
	v_mfma_f32_16x16x32_bf16 v[48:51], v[178:181], v[76:79], v[48:51]
	v_mfma_f32_16x16x32_bf16 v[36:39], v[142:145], v[206:209], v[36:39]
	v_mfma_f32_16x16x32_bf16 v[32:35], v[178:181], v[206:209], v[32:35]
	v_mfma_f32_16x16x32_bf16 v[60:63], v[146:149], v[72:75], v[60:63]
	v_mfma_f32_16x16x32_bf16 v[56:59], v[182:185], v[72:75], v[56:59]
	v_mfma_f32_16x16x32_bf16 v[52:55], v[146:149], v[88:91], v[52:55]
	v_mfma_f32_16x16x32_bf16 v[48:51], v[182:185], v[88:91], v[48:51]
	v_mfma_f32_16x16x32_bf16 v[44:47], v[142:145], v[92:95], v[44:47]
	v_mfma_f32_16x16x32_bf16 v[40:43], v[178:181], v[92:95], v[40:43]
	v_mfma_f32_16x16x32_bf16 v[36:39], v[146:149], v[210:213], v[36:39]
	v_mfma_f32_16x16x32_bf16 v[32:35], v[182:185], v[210:213], v[32:35]
	v_mfma_f32_16x16x32_bf16 v[214:217], v[146:149], v[202:205], v[44:47]
	v_mfma_f32_16x16x32_bf16 v[230:233], v[182:185], v[202:205], v[40:43]
	s_setprio 0
	s_setprio 1
	v_mfma_f32_16x16x32_bf16 v[20:23], v[104:107], v[76:79], v[20:23]
	v_mfma_f32_16x16x32_bf16 v[16:19], v[222:225], v[76:79], v[16:19]
	v_mfma_f32_16x16x32_bf16 v[4:7], v[104:107], v[206:209], v[4:7]
	v_mfma_f32_16x16x32_bf16 v[0:3], v[222:225], v[206:209], v[0:3]
	v_mfma_f32_16x16x32_bf16 v[28:31], v[104:107], v[64:67], v[28:31]
	v_mfma_f32_16x16x32_bf16 v[24:27], v[222:225], v[64:67], v[24:27]
	v_mfma_f32_16x16x32_bf16 v[20:23], v[108:111], v[88:91], v[20:23]
	v_mfma_f32_16x16x32_bf16 v[16:19], v[158:161], v[88:91], v[16:19]
	v_mfma_f32_16x16x32_bf16 v[12:15], v[104:107], v[92:95], v[12:15]
	v_mfma_f32_16x16x32_bf16 v[8:11], v[222:225], v[92:95], v[8:11]
	v_mfma_f32_16x16x32_bf16 v[4:7], v[108:111], v[210:213], v[4:7]
	v_mfma_f32_16x16x32_bf16 v[0:3], v[158:161], v[210:213], v[0:3]
	v_mfma_f32_16x16x32_bf16 v[142:145], v[108:111], v[72:75], v[28:31]
	v_mfma_f32_16x16x32_bf16 v[146:149], v[158:161], v[72:75], v[24:27]
	v_mfma_f32_16x16x32_bf16 v[178:181], v[108:111], v[202:205], v[12:15]
	v_mfma_f32_16x16x32_bf16 v[182:185], v[158:161], v[202:205], v[8:11]
	s_setprio 0
	s_barrier
	s_nop 0
	ds_read_b128 v[8:11], v157
	ds_read_b128 v[12:15], v157 offset:1024
	ds_read_b128 v[158:161], v157 offset:2048
	ds_read_b128 v[202:205], v157 offset:3072
	ds_read_b128 v[24:27], v153 offset:32768
	ds_read_b128 v[28:31], v153 offset:33792
	ds_read_b128 v[40:43], v171 offset:32768
	ds_read_b128 v[44:47], v171 offset:33792
	ds_read_b128 v[64:67], v172 offset:32768
	ds_read_b128 v[206:209], v172 offset:33792
	ds_read_b128 v[210:213], v173 offset:32768
	ds_read_b128 v[222:225], v173 offset:33792
	s_waitcnt vmcnt(2)
	s_barrier
; #define LDA(dst,b,h) _Pragma("unroll") for(int m=0;m<4;++m) _Pragma("unroll") for(int k=0;k<2;++k) \
;     dst[m][k]=*reinterpret_cast<const bf16x8*>((char*)SA(b,h)+lds_byte(wr*64+m*16+fr,k*32+fq*8))
; #define LDB(dst,b,h) _Pragma("unroll") for(int n=0;n<2;++n) _Pragma("unroll") for(int k=0;k<2;++k) \
;     dst[n][k]=*reinterpret_cast<const bf16x8*>((char*)SB(b,h)+lds_byte(wc*32+n*16+fr,k*32+fq*8))
; #define MMA(ai,bj,At_,Bt_) do{__builtin_amdgcn_s_setprio(1); \
;     _Pragma("unroll") for(int m=0;m<4;++m) _Pragma("unroll") for(int n=0;n<2;++n) _Pragma("unroll") for(int k=0;k<2;++k) \
;       acc[ai][bj][m][n]=__builtin_amdgcn_mfma_f32_16x16x32_bf16(Bt_[n][k],At_[m][k],acc[ai][bj][m][n],0,0,0); \
;     __builtin_amdgcn_s_setprio(0);}while(0)
; #define WAIT_V(n) asm volatile("s_waitcnt vmcnt(" #n ")":::"memory")
; #define WAIT_L(n) asm volatile("s_waitcnt lgkmcnt(" #n ")":::"memory")
; #define BAR __builtin_amdgcn_s_barrier()
; DEVINL void gemm8_mainloop(const u16* A, long lda, const u16* Bt, long ldb, int K, int brow, int bcol, f32x4 (&acc)[2][2][4][2], char* smem, int tid) {
;     ...
;   { LDB(B0,1,0); LDA(At,1,0); WAIT_V(2); BAR; WAIT_L(0); MMA(0,0,At,B0); BAR;
;     LDB(B1,1,1); WAIT_V(0); BAR; WAIT_L(0); MMA(0,1,At,B1); BAR;
;     LDA(At,1,1); BAR; WAIT_L(0); MMA(1,0,At,B0); MMA(1,1,At,B1); BAR; }
;   if(wr==0)BAR;
	s_waitcnt lgkmcnt(0)
	s_setprio 1
	v_mfma_f32_16x16x32_bf16 v[72:75], v[8:11], v[24:27], v[124:127]
	v_mfma_f32_16x16x32_bf16 v[124:127], v[12:15], v[28:31], v[72:75]
	v_mfma_f32_16x16x32_bf16 v[72:75], v[158:161], v[24:27], v[120:123]
	v_mfma_f32_16x16x32_bf16 v[120:123], v[202:205], v[28:31], v[72:75]
	v_mfma_f32_16x16x32_bf16 v[72:75], v[8:11], v[40:43], v[116:119]
	v_mfma_f32_16x16x32_bf16 v[108:111], v[12:15], v[44:47], v[72:75]
	v_mfma_f32_16x16x32_bf16 v[72:75], v[158:161], v[40:43], v[112:115]
	v_mfma_f32_16x16x32_bf16 v[104:107], v[202:205], v[44:47], v[72:75]
	v_mfma_f32_16x16x32_bf16 v[72:75], v[8:11], v[64:67], v[138:141]
	v_mfma_f32_16x16x32_bf16 v[92:95], v[12:15], v[206:209], v[72:75]
	v_mfma_f32_16x16x32_bf16 v[72:75], v[158:161], v[64:67], v[218:221]
	v_mfma_f32_16x16x32_bf16 v[88:91], v[202:205], v[206:209], v[72:75]
	v_mfma_f32_16x16x32_bf16 v[72:75], v[8:11], v[210:213], v[100:103]
	v_mfma_f32_16x16x32_bf16 v[76:79], v[12:15], v[222:225], v[72:75]
	v_mfma_f32_16x16x32_bf16 v[72:75], v[158:161], v[210:213], v[96:99]
	v_mfma_f32_16x16x32_bf16 v[72:75], v[202:205], v[222:225], v[72:75]
	s_setprio 0
	s_barrier
	ds_read_b128 v[138:141], v155
	ds_read_b128 v[218:221], v155 offset:1024
	ds_read_b128 v[234:237], v155 offset:2048
	ds_read_b128 v[154:157], v155 offset:3072
	s_waitcnt vmcnt(0)
	s_barrier
	s_waitcnt lgkmcnt(0)
	s_setprio 1
	v_mfma_f32_16x16x32_bf16 v[96:99], v[138:141], v[24:27], v[226:229]
	v_mfma_f32_16x16x32_bf16 v[24:27], v[234:237], v[24:27], v[186:189]
	v_mfma_f32_16x16x32_bf16 v[116:119], v[154:157], v[28:31], v[24:27]
	v_mfma_f32_16x16x32_bf16 v[24:27], v[138:141], v[40:43], v[84:87]
	v_mfma_f32_16x16x32_bf16 v[112:115], v[218:221], v[28:31], v[96:99]
	v_mfma_f32_16x16x32_bf16 v[96:99], v[218:221], v[44:47], v[24:27]
	v_mfma_f32_16x16x32_bf16 v[24:27], v[234:237], v[40:43], v[80:83]
	v_mfma_f32_16x16x32_bf16 v[100:103], v[154:157], v[44:47], v[24:27]
	v_mfma_f32_16x16x32_bf16 v[24:27], v[138:141], v[64:67], v[190:193]
	v_mfma_f32_16x16x32_bf16 v[80:83], v[218:221], v[206:209], v[24:27]
	v_mfma_f32_16x16x32_bf16 v[24:27], v[234:237], v[64:67], v[194:197]
	v_mfma_f32_16x16x32_bf16 v[84:87], v[154:157], v[206:209], v[24:27]
	v_mfma_f32_16x16x32_bf16 v[24:27], v[138:141], v[210:213], v[68:71]
	v_mfma_f32_16x16x32_bf16 v[64:67], v[218:221], v[222:225], v[24:27]
	v_mfma_f32_16x16x32_bf16 v[24:27], v[234:237], v[210:213], v[198:201]
	v_mfma_f32_16x16x32_bf16 v[68:71], v[154:157], v[222:225], v[24:27]
	s_setprio 0
	s_barrier
	ds_read_b128 v[186:189], v153 offset:49152
	ds_read_b128 v[190:193], v153 offset:50176
	ds_read_b128 v[194:197], v171 offset:49152
	ds_read_b128 v[198:201], v171 offset:50176
	ds_read_b128 v[206:209], v172 offset:49152
	ds_read_b128 v[210:213], v172 offset:50176
	ds_read_b128 v[222:225], v173 offset:49152
	ds_read_b128 v[172:175], v173 offset:50176
	s_barrier
	s_waitcnt lgkmcnt(0)
	s_setprio 1
	v_mfma_f32_16x16x32_bf16 v[24:27], v[8:11], v[186:189], v[60:63]
	v_mfma_f32_16x16x32_bf16 v[60:63], v[12:15], v[190:193], v[24:27]
	v_mfma_f32_16x16x32_bf16 v[24:27], v[158:161], v[186:189], v[56:59]
	v_mfma_f32_16x16x32_bf16 v[56:59], v[202:205], v[190:193], v[24:27]
	v_mfma_f32_16x16x32_bf16 v[24:27], v[8:11], v[194:197], v[52:55]
	v_mfma_f32_16x16x32_bf16 v[44:47], v[12:15], v[198:201], v[24:27]
	v_mfma_f32_16x16x32_bf16 v[24:27], v[158:161], v[194:197], v[48:51]
	v_mfma_f32_16x16x32_bf16 v[40:43], v[202:205], v[198:201], v[24:27]
	v_mfma_f32_16x16x32_bf16 v[24:27], v[8:11], v[206:209], v[214:217]
	v_mfma_f32_16x16x32_bf16 v[8:11], v[8:11], v[222:225], v[36:39]
	v_mfma_f32_16x16x32_bf16 v[28:31], v[12:15], v[210:213], v[24:27]
	v_mfma_f32_16x16x32_bf16 v[24:27], v[158:161], v[206:209], v[230:233]
	v_mfma_f32_16x16x32_bf16 v[12:15], v[12:15], v[172:175], v[8:11]
	v_mfma_f32_16x16x32_bf16 v[8:11], v[158:161], v[222:225], v[32:35]
	v_mfma_f32_16x16x32_bf16 v[24:27], v[202:205], v[210:213], v[24:27]
	v_mfma_f32_16x16x32_bf16 v[8:11], v[202:205], v[172:175], v[8:11]
	s_setprio 0
	s_setprio 1
	v_mfma_f32_16x16x32_bf16 v[32:35], v[138:141], v[186:189], v[142:145]
	v_mfma_f32_16x16x32_bf16 v[48:51], v[218:221], v[190:193], v[32:35]
	v_mfma_f32_16x16x32_bf16 v[32:35], v[234:237], v[186:189], v[146:149]
	v_mfma_f32_16x16x32_bf16 v[20:23], v[138:141], v[194:197], v[20:23]
	v_mfma_f32_16x16x32_bf16 v[16:19], v[234:237], v[194:197], v[16:19]
	v_mfma_f32_16x16x32_bf16 v[52:55], v[154:157], v[190:193], v[32:35]
	v_mfma_f32_16x16x32_bf16 v[32:35], v[218:221], v[198:201], v[20:23]
	v_mfma_f32_16x16x32_bf16 v[36:39], v[154:157], v[198:201], v[16:19]
	v_mfma_f32_16x16x32_bf16 v[16:19], v[138:141], v[206:209], v[178:181]
	v_mfma_f32_16x16x32_bf16 v[20:23], v[234:237], v[206:209], v[182:185]
	v_mfma_f32_16x16x32_bf16 v[4:7], v[138:141], v[222:225], v[4:7]
	v_mfma_f32_16x16x32_bf16 v[0:3], v[234:237], v[222:225], v[0:3]
	v_mfma_f32_16x16x32_bf16 v[16:19], v[218:221], v[210:213], v[16:19]
	v_mfma_f32_16x16x32_bf16 v[20:23], v[154:157], v[210:213], v[20:23]
	v_mfma_f32_16x16x32_bf16 v[4:7], v[218:221], v[172:175], v[4:7]
	v_mfma_f32_16x16x32_bf16 v[0:3], v[154:157], v[172:175], v[0:3]
	s_setprio 0
	s_cmpk_gt_u32 s29, 0xff
	s_barrier
	s_cbranch_scc1 .LBB0_968
	s_barrier

; #define STAGE(P,BASE,LD,br,kt) do{long _g=(long)(br)*(LD)+(long)(kt)*BK; \
;     _Pragma("unroll") for(int _i=0;_i<2;++_i){int _b=tid*16+_i*8192;int _r,_c;stage_rc(_b,_r,_c); \
;       __builtin_amdgcn_global_load_lds((const unsigned*)((BASE)+_g+(long)_r*(LD)+_c), \
;         (unsigned*)((char*)(P)+_b),16,0,0);}}while(0)
; #define STAGE(P,BASE,LD,br,kt) do{long _g=(long)(br)*(LD)+(long)(kt)*BK; \
;     _Pragma("unroll") for(int _i=0;_i<2;++_i){int _b=tid*16+_i*8192;int _r,_c;stage_rc(_b,_r,_c); \
;       __builtin_amdgcn_global_load_lds((const unsigned*)((BASE)+_g+(long)_r*(LD)+_c), \
;         (unsigned*)((char*)(P)+_b),16,0,0);}}while(0)
; #define LDA(dst,b,h) _Pragma("unroll") for(int m=0;m<4;++m) _Pragma("unroll") for(int k=0;k<2;++k) \
;     dst[m][k]=*reinterpret_cast<const bf16x8*>((char*)SA(b,h)+lds_byte(wr*64+m*16+fr,k*32+fq*8))
; #define LDB(dst,b,h) _Pragma("unroll") for(int n=0;n<2;++n) _Pragma("unroll") for(int k=0;k<2;++k) \
;     dst[n][k]=*reinterpret_cast<const bf16x8*>((char*)SB(b,h)+lds_byte(wc*32+n*16+fr,k*32+fq*8))
; #define MMA(ai,bj,At_,Bt_) do{__builtin_amdgcn_s_setprio(1); \
;     _Pragma("unroll") for(int m=0;m<4;++m) _Pragma("unroll") for(int n=0;n<2;++n) _Pragma("unroll") for(int k=0;k<2;++k) \
;       acc[ai][bj][m][n]=__builtin_amdgcn_mfma_f32_16x16x32_bf16(Bt_[n][k],At_[m][k],acc[ai][bj][m][n],0,0,0); \
;     __builtin_amdgcn_s_setprio(0);}while(0)
; #define WAIT_L(n) asm volatile("s_waitcnt lgkmcnt(" #n ")":::"memory")
; #define BAR __builtin_amdgcn_s_barrier()
; #define SCHED __builtin_amdgcn_sched_barrier(0)
; DEVINL void gemm8_mainloop(const u16* A, long lda, const u16* Bt, long ldb, int K, int brow, int bcol, f32x4 (&acc)[2][2][4][2], char* smem, int tid) {
;     ...
;   for(int t=0;t<nt-2;t+=2){
;     LDB(B0,0,0); SCHED; LDA(At,0,0); STAGE(SA(1,1),A,lda,brow+HALF,t+1);
;     WAIT_L(8); BAR; WAIT_L(0); MMA(0,0,At,B0); BAR; SCHED;
;     LDB(B1,0,1); STAGE(SB(0,0),Bt,ldb,bcol,t+2);
;     BAR; WAIT_L(0); MMA(0,1,At,B1); BAR;
;     LDA(At,0,1); STAGE(SA(0,0),A,lda,brow,t+2);
;     BAR; WAIT_L(0); MMA(1,0,At,B0); BAR; SCHED;
.LBB0_1292:
	ds_read_b128 v[170:173], v161
	ds_read_b128 v[180:183], v161 offset:1024
	ds_read_b128 v[184:187], v161 offset:2048
	ds_read_b128 v[188:191], v161 offset:3072
	v_add_u32_e32 v178, 0xc000, v128
	v_lshl_add_u64 v[244:245], s[94:95], 0, v[148:149]
	v_readfirstlane_b32 s5, v178
	v_add_u32_e32 v179, 0xe000, v128
	v_add_u32_e32 v174, s1, v160
	v_add_u32_e32 v175, s37, v160
	v_add_u32_e32 v177, s40, v160
	v_lshl_add_u64 v[162:163], v[244:245], 0, s[8:9]
	s_mov_b32 m0, s5
	v_lshl_add_u64 v[246:247], s[94:95], 0, v[150:151]
	v_readfirstlane_b32 s5, v179
	ds_read_b128 v[192:195], v131
	ds_read_b128 v[196:199], v131 offset:1024
	ds_read_b128 v[200:203], v174
	ds_read_b128 v[204:207], v174 offset:1024
	ds_read_b128 v[208:211], v175
	ds_read_b128 v[212:215], v175 offset:1024
	ds_read_b128 v[216:219], v177
	ds_read_b128 v[220:223], v177 offset:1024
	global_load_lds_dwordx4 v[162:163], off
	v_lshl_add_u64 v[162:163], v[246:247], 0, s[8:9]
	s_mov_b32 m0, s5
	s_nop 0
	global_load_lds_dwordx4 v[162:163], off
	s_waitcnt lgkmcnt(8)
	s_barrier
	s_waitcnt lgkmcnt(0)
	s_setprio 1
	v_mfma_f32_16x16x32_bf16 v[124:127], v[170:173], v[192:195], v[124:127]
	v_mfma_f32_16x16x32_bf16 v[120:123], v[184:187], v[192:195], v[120:123]
	v_mfma_f32_16x16x32_bf16 v[116:119], v[170:173], v[200:203], v[116:119]
	v_mfma_f32_16x16x32_bf16 v[112:115], v[184:187], v[200:203], v[112:115]
	v_mfma_f32_16x16x32_bf16 v[108:111], v[170:173], v[208:211], v[108:111]
	v_mfma_f32_16x16x32_bf16 v[104:107], v[184:187], v[208:211], v[104:107]
	v_mfma_f32_16x16x32_bf16 v[100:103], v[170:173], v[216:219], v[100:103]
	v_mfma_f32_16x16x32_bf16 v[96:99], v[184:187], v[216:219], v[96:99]
	v_mfma_f32_16x16x32_bf16 v[124:127], v[180:183], v[196:199], v[124:127]
	v_mfma_f32_16x16x32_bf16 v[120:123], v[188:191], v[196:199], v[120:123]
	v_mfma_f32_16x16x32_bf16 v[116:119], v[180:183], v[204:207], v[116:119]
	v_mfma_f32_16x16x32_bf16 v[112:115], v[188:191], v[204:207], v[112:115]
	v_mfma_f32_16x16x32_bf16 v[108:111], v[180:183], v[212:215], v[108:111]
	v_mfma_f32_16x16x32_bf16 v[104:107], v[188:191], v[212:215], v[104:107]
	v_mfma_f32_16x16x32_bf16 v[100:103], v[180:183], v[220:223], v[100:103]
	v_mfma_f32_16x16x32_bf16 v[96:99], v[188:191], v[220:223], v[96:99]
	s_setprio 0
	s_barrier
	v_add_u32_e32 v162, s27, v153
	v_lshl_add_u64 v[248:249], s[94:95], 0, v[144:145]
	v_readfirstlane_b32 s5, v162
	v_add_u32_e32 v163, 0x2000, v162
	v_lshl_add_u64 v[240:241], v[248:249], 0, s[10:11]
	s_mov_b32 m0, s5
	v_lshl_add_u64 v[250:251], s[94:95], 0, v[146:147]
	v_readfirstlane_b32 s5, v163
	ds_read_b128 v[224:227], v158
	ds_read_b128 v[228:231], v158 offset:1024
	ds_read_b128 v[232:235], v158 offset:2048
	ds_read_b128 v[236:239], v158 offset:3072
	global_load_lds_dwordx4 v[240:241], off
	v_lshl_add_u64 v[240:241], v[250:251], 0, s[10:11]
	s_mov_b32 m0, s5
	s_nop 0
	global_load_lds_dwordx4 v[240:241], off
	s_barrier
	s_waitcnt lgkmcnt(0)
	s_setprio 1
	v_mfma_f32_16x16x32_bf16 v[92:95], v[224:227], v[192:195], v[92:95]
	v_mfma_f32_16x16x32_bf16 v[88:91], v[232:235], v[192:195], v[88:91]
	v_mfma_f32_16x16x32_bf16 v[84:87], v[224:227], v[200:203], v[84:87]
	v_mfma_f32_16x16x32_bf16 v[80:83], v[232:235], v[200:203], v[80:83]
	v_mfma_f32_16x16x32_bf16 v[76:79], v[224:227], v[208:211], v[76:79]
	v_mfma_f32_16x16x32_bf16 v[72:75], v[232:235], v[208:211], v[72:75]
	v_mfma_f32_16x16x32_bf16 v[68:71], v[224:227], v[216:219], v[68:71]
	v_mfma_f32_16x16x32_bf16 v[64:67], v[232:235], v[216:219], v[64:67]
	v_mfma_f32_16x16x32_bf16 v[92:95], v[228:231], v[196:199], v[92:95]
	v_mfma_f32_16x16x32_bf16 v[88:91], v[236:239], v[196:199], v[88:91]
	v_mfma_f32_16x16x32_bf16 v[84:87], v[228:231], v[204:207], v[84:87]
	v_mfma_f32_16x16x32_bf16 v[80:83], v[236:239], v[204:207], v[80:83]
	v_mfma_f32_16x16x32_bf16 v[76:79], v[228:231], v[212:215], v[76:79]
	v_mfma_f32_16x16x32_bf16 v[72:75], v[236:239], v[212:215], v[72:75]
	v_mfma_f32_16x16x32_bf16 v[68:71], v[228:231], v[220:223], v[68:71]
	v_mfma_f32_16x16x32_bf16 v[64:67], v[236:239], v[220:223], v[64:67]
	s_setprio 0
	v_readfirstlane_b32 s5, v128
	v_add_u32_e32 v169, 0x2000, v128
	v_lshl_add_u64 v[240:241], v[244:245], 0, s[12:13]
	s_mov_b32 m0, s5
	v_readfirstlane_b32 s5, v169
	s_barrier
	ds_read_b128 v[192:195], v131 offset:16384
	ds_read_b128 v[196:199], v131 offset:17408
	ds_read_b128 v[200:203], v174 offset:16384
	ds_read_b128 v[204:207], v174 offset:17408
	ds_read_b128 v[208:211], v175 offset:16384
	ds_read_b128 v[212:215], v175 offset:17408
	ds_read_b128 v[216:219], v177 offset:16384
	ds_read_b128 v[220:223], v177 offset:17408
	global_load_lds_dwordx4 v[240:241], off
	v_lshl_add_u64 v[240:241], v[246:247], 0, s[12:13]
	s_mov_b32 m0, s5
	s_nop 0
	global_load_lds_dwordx4 v[240:241], off
	s_barrier
	s_waitcnt lgkmcnt(0)
	s_setprio 1
	v_mfma_f32_16x16x32_bf16 v[60:63], v[170:173], v[192:195], v[60:63]
	v_mfma_f32_16x16x32_bf16 v[56:59], v[184:187], v[192:195], v[56:59]
	v_mfma_f32_16x16x32_bf16 v[52:55], v[170:173], v[200:203], v[52:55]
	v_mfma_f32_16x16x32_bf16 v[48:51], v[184:187], v[200:203], v[48:51]
	v_mfma_f32_16x16x32_bf16 v[44:47], v[170:173], v[208:211], v[44:47]
	v_mfma_f32_16x16x32_bf16 v[40:43], v[184:187], v[208:211], v[40:43]
	v_mfma_f32_16x16x32_bf16 v[36:39], v[170:173], v[216:219], v[36:39]
	v_mfma_f32_16x16x32_bf16 v[32:35], v[184:187], v[216:219], v[32:35]
	v_mfma_f32_16x16x32_bf16 v[60:63], v[180:183], v[196:199], v[60:63]
	v_mfma_f32_16x16x32_bf16 v[56:59], v[188:191], v[196:199], v[56:59]
	v_mfma_f32_16x16x32_bf16 v[52:55], v[180:183], v[204:207], v[52:55]
	v_mfma_f32_16x16x32_bf16 v[48:51], v[188:191], v[204:207], v[48:51]
	v_mfma_f32_16x16x32_bf16 v[44:47], v[180:183], v[212:215], v[44:47]
	v_mfma_f32_16x16x32_bf16 v[40:43], v[188:191], v[212:215], v[40:43]
	v_mfma_f32_16x16x32_bf16 v[36:39], v[180:183], v[220:223], v[36:39]
	v_mfma_f32_16x16x32_bf16 v[32:35], v[188:191], v[220:223], v[32:35]
	s_setprio 0
	s_barrier
; #define STAGE(P,BASE,LD,br,kt) do{long _g=(long)(br)*(LD)+(long)(kt)*BK; \
;     _Pragma("unroll") for(int _i=0;_i<2;++_i){int _b=tid*16+_i*8192;int _r,_c;stage_rc(_b,_r,_c); \
;       __builtin_amdgcn_global_load_lds((const unsigned*)((BASE)+_g+(long)_r*(LD)+_c), \
;         (unsigned*)((char*)(P)+_b),16,0,0);}}while(0)
; #define STAGE(P,BASE,LD,br,kt) do{long _g=(long)(br)*(LD)+(long)(kt)*BK; \
;     _Pragma("unroll") for(int _i=0;_i<2;++_i){int _b=tid*16+_i*8192;int _r,_c;stage_rc(_b,_r,_c); \
;       __builtin_amdgcn_global_load_lds((const unsigned*)((BASE)+_g+(long)_r*(LD)+_c), \
;         (unsigned*)((char*)(P)+_b),16,0,0);}}while(0)
; #define LDA(dst,b,h) _Pragma("unroll") for(int m=0;m<4;++m) _Pragma("unroll") for(int k=0;k<2;++k) \
;     dst[m][k]=*reinterpret_cast<const bf16x8*>((char*)SA(b,h)+lds_byte(wr*64+m*16+fr,k*32+fq*8))
; #define LDB(dst,b,h) _Pragma("unroll") for(int n=0;n<2;++n) _Pragma("unroll") for(int k=0;k<2;++k) \
;     dst[n][k]=*reinterpret_cast<const bf16x8*>((char*)SB(b,h)+lds_byte(wc*32+n*16+fr,k*32+fq*8))
; #define MMA(ai,bj,At_,Bt_) do{__builtin_amdgcn_s_setprio(1); \
;     _Pragma("unroll") for(int m=0;m<4;++m) _Pragma("unroll") for(int n=0;n<2;++n) _Pragma("unroll") for(int k=0;k<2;++k) \
;       acc[ai][bj][m][n]=__builtin_amdgcn_mfma_f32_16x16x32_bf16(Bt_[n][k],At_[m][k],acc[ai][bj][m][n],0,0,0); \
;     __builtin_amdgcn_s_setprio(0);}while(0)
; #define WAIT_V(n) asm volatile("s_waitcnt vmcnt(" #n ")":::"memory")
; #define WAIT_L(n) asm volatile("s_waitcnt lgkmcnt(" #n ")":::"memory")
; #define BAR __builtin_amdgcn_s_barrier()
; #define SCHED __builtin_amdgcn_sched_barrier(0)
; DEVINL void gemm8_mainloop(const u16* A, long lda, const u16* Bt, long ldb, int K, int brow, int bcol, f32x4 (&acc)[2][2][4][2], char* smem, int tid) {
;     ...
;     STAGE(SB(0,1),Bt,ldb,bcol+HALF,t+2);
;     WAIT_V(6); BAR; MMA(1,1,At,B1); BAR;
;     LDB(B0,1,0); SCHED; LDA(At,1,0); STAGE(SA(0,1),A,lda,brow+HALF,t+2);
;     WAIT_L(8); BAR; WAIT_L(0); MMA(0,0,At,B0); BAR; SCHED;
;     LDB(B1,1,1); STAGE(SB(1,0),Bt,ldb,bcol,t+3);
;     BAR; WAIT_L(0); MMA(0,1,At,B1); BAR;
	v_add_u32_e32 v170, s29, v153
	v_add_u32_e32 v171, 0x2000, v170
	v_readfirstlane_b32 s5, v170
	v_lshl_add_u64 v[172:173], v[248:249], 0, s[14:15]
	s_mov_b32 m0, s5
	v_readfirstlane_b32 s5, v171
	global_load_lds_dwordx4 v[172:173], off
	v_lshl_add_u64 v[172:173], v[250:251], 0, s[14:15]
	s_mov_b32 m0, s5
	s_nop 0
	global_load_lds_dwordx4 v[172:173], off
	s_waitcnt vmcnt(6)
	s_barrier
	s_setprio 1
	v_mfma_f32_16x16x32_bf16 v[28:31], v[224:227], v[192:195], v[28:31]
	v_mfma_f32_16x16x32_bf16 v[24:27], v[232:235], v[192:195], v[24:27]
	v_mfma_f32_16x16x32_bf16 v[20:23], v[224:227], v[200:203], v[20:23]
	v_mfma_f32_16x16x32_bf16 v[16:19], v[232:235], v[200:203], v[16:19]
	v_mfma_f32_16x16x32_bf16 v[12:15], v[224:227], v[208:211], v[12:15]
	v_mfma_f32_16x16x32_bf16 v[8:11], v[232:235], v[208:211], v[8:11]
	v_mfma_f32_16x16x32_bf16 v[4:7], v[224:227], v[216:219], v[4:7]
	v_mfma_f32_16x16x32_bf16 v[0:3], v[232:235], v[216:219], v[0:3]
	v_mfma_f32_16x16x32_bf16 v[28:31], v[228:231], v[196:199], v[28:31]
	v_mfma_f32_16x16x32_bf16 v[24:27], v[236:239], v[196:199], v[24:27]
	v_mfma_f32_16x16x32_bf16 v[20:23], v[228:231], v[204:207], v[20:23]
	v_mfma_f32_16x16x32_bf16 v[16:19], v[236:239], v[204:207], v[16:19]
	v_mfma_f32_16x16x32_bf16 v[12:15], v[228:231], v[212:215], v[12:15]
	v_mfma_f32_16x16x32_bf16 v[8:11], v[236:239], v[212:215], v[8:11]
	v_mfma_f32_16x16x32_bf16 v[4:7], v[228:231], v[220:223], v[4:7]
	v_mfma_f32_16x16x32_bf16 v[0:3], v[236:239], v[220:223], v[0:3]
	s_setprio 0
	s_barrier
	ds_read_b128 v[180:183], v154
	ds_read_b128 v[184:187], v154 offset:1024
	ds_read_b128 v[188:191], v154 offset:2048
	ds_read_b128 v[192:195], v154 offset:3072
	v_add_u32_e32 v172, 0x4000, v128
	v_add_u32_e32 v173, 0x6000, v128
	v_readfirstlane_b32 s5, v172
	v_lshl_add_u64 v[228:229], v[244:245], 0, s[16:17]
	s_mov_b32 m0, s5
	v_readfirstlane_b32 s5, v173
	ds_read_b128 v[196:199], v131 offset:32768
	ds_read_b128 v[200:203], v131 offset:33792
	ds_read_b128 v[204:207], v174 offset:32768
	ds_read_b128 v[208:211], v174 offset:33792
	ds_read_b128 v[212:215], v175 offset:32768
	ds_read_b128 v[216:219], v175 offset:33792
	ds_read_b128 v[220:223], v177 offset:32768
	ds_read_b128 v[224:227], v177 offset:33792
	global_load_lds_dwordx4 v[228:229], off
	v_lshl_add_u64 v[228:229], v[246:247], 0, s[16:17]
	s_mov_b32 m0, s5
	s_nop 0
	global_load_lds_dwordx4 v[228:229], off
	s_waitcnt lgkmcnt(8)
	s_barrier
	s_waitcnt lgkmcnt(0)
	s_setprio 1
	v_mfma_f32_16x16x32_bf16 v[124:127], v[180:183], v[196:199], v[124:127]
	v_mfma_f32_16x16x32_bf16 v[120:123], v[188:191], v[196:199], v[120:123]
	v_mfma_f32_16x16x32_bf16 v[116:119], v[180:183], v[204:207], v[116:119]
	v_mfma_f32_16x16x32_bf16 v[112:115], v[188:191], v[204:207], v[112:115]
	v_mfma_f32_16x16x32_bf16 v[108:111], v[180:183], v[212:215], v[108:111]
	v_mfma_f32_16x16x32_bf16 v[104:107], v[188:191], v[212:215], v[104:107]
	v_mfma_f32_16x16x32_bf16 v[100:103], v[180:183], v[220:223], v[100:103]
	v_mfma_f32_16x16x32_bf16 v[96:99], v[188:191], v[220:223], v[96:99]
	v_mfma_f32_16x16x32_bf16 v[124:127], v[184:187], v[200:203], v[124:127]
	v_mfma_f32_16x16x32_bf16 v[120:123], v[192:195], v[200:203], v[120:123]
	v_mfma_f32_16x16x32_bf16 v[116:119], v[184:187], v[208:211], v[116:119]
	v_mfma_f32_16x16x32_bf16 v[112:115], v[192:195], v[208:211], v[112:115]
	v_mfma_f32_16x16x32_bf16 v[108:111], v[184:187], v[216:219], v[108:111]
	v_mfma_f32_16x16x32_bf16 v[104:107], v[192:195], v[216:219], v[104:107]
	v_mfma_f32_16x16x32_bf16 v[100:103], v[184:187], v[224:227], v[100:103]
	v_mfma_f32_16x16x32_bf16 v[96:99], v[192:195], v[224:227], v[96:99]
	s_setprio 0
	s_barrier
	v_readfirstlane_b32 s5, v155
	v_add_u32_e32 v165, 0x2000, v155
	v_lshl_add_u64 v[252:253], v[248:249], 0, s[18:19]
	s_mov_b32 m0, s5
	v_readfirstlane_b32 s5, v165
	ds_read_b128 v[228:231], v152
	ds_read_b128 v[232:235], v152 offset:1024
	ds_read_b128 v[236:239], v152 offset:2048
	ds_read_b128 v[240:243], v152 offset:3072
	global_load_lds_dwordx4 v[252:253], off
	v_lshl_add_u64 v[252:253], v[250:251], 0, s[18:19]
	s_mov_b32 m0, s5
	s_nop 0
	global_load_lds_dwordx4 v[252:253], off
	s_barrier
	s_waitcnt lgkmcnt(0)
	s_setprio 1
	v_mfma_f32_16x16x32_bf16 v[92:95], v[228:231], v[196:199], v[92:95]
	v_mfma_f32_16x16x32_bf16 v[88:91], v[236:239], v[196:199], v[88:91]
	v_mfma_f32_16x16x32_bf16 v[84:87], v[228:231], v[204:207], v[84:87]
	v_mfma_f32_16x16x32_bf16 v[80:83], v[236:239], v[204:207], v[80:83]
	v_mfma_f32_16x16x32_bf16 v[76:79], v[228:231], v[212:215], v[76:79]
	v_mfma_f32_16x16x32_bf16 v[72:75], v[236:239], v[212:215], v[72:75]
	v_mfma_f32_16x16x32_bf16 v[68:71], v[228:231], v[220:223], v[68:71]
	v_mfma_f32_16x16x32_bf16 v[64:67], v[236:239], v[220:223], v[64:67]
	v_mfma_f32_16x16x32_bf16 v[92:95], v[232:235], v[200:203], v[92:95]
	v_mfma_f32_16x16x32_bf16 v[88:91], v[240:243], v[200:203], v[88:91]
	v_mfma_f32_16x16x32_bf16 v[84:87], v[232:235], v[208:211], v[84:87]
	v_mfma_f32_16x16x32_bf16 v[80:83], v[240:243], v[208:211], v[80:83]
	v_mfma_f32_16x16x32_bf16 v[76:79], v[232:235], v[216:219], v[76:79]
	v_mfma_f32_16x16x32_bf16 v[72:75], v[240:243], v[216:219], v[72:75]
	v_mfma_f32_16x16x32_bf16 v[68:71], v[232:235], v[224:227], v[68:71]
	v_mfma_f32_16x16x32_bf16 v[64:67], v[240:243], v[224:227], v[64:67]
	s_setprio 0
	v_readfirstlane_b32 s5, v156
	v_lshl_add_u64 v[244:245], v[244:245], 0, s[20:21]
	s_mov_b32 m0, s5
	v_readfirstlane_b32 s5, v157
	s_barrier
; #define STAGE(P,BASE,LD,br,kt) do{long _g=(long)(br)*(LD)+(long)(kt)*BK; \
;     _Pragma("unroll") for(int _i=0;_i<2;++_i){int _b=tid*16+_i*8192;int _r,_c;stage_rc(_b,_r,_c); \
;       __builtin_amdgcn_global_load_lds((const unsigned*)((BASE)+_g+(long)_r*(LD)+_c), \
;         (unsigned*)((char*)(P)+_b),16,0,0);}}while(0)
; #define STAGE(P,BASE,LD,br,kt) do{long _g=(long)(br)*(LD)+(long)(kt)*BK; \
;     _Pragma("unroll") for(int _i=0;_i<2;++_i){int _b=tid*16+_i*8192;int _r,_c;stage_rc(_b,_r,_c); \
;       __builtin_amdgcn_global_load_lds((const unsigned*)((BASE)+_g+(long)_r*(LD)+_c), \
;         (unsigned*)((char*)(P)+_b),16,0,0);}}while(0)
; #define LDA(dst,b,h) _Pragma("unroll") for(int m=0;m<4;++m) _Pragma("unroll") for(int k=0;k<2;++k) \
;     dst[m][k]=*reinterpret_cast<const bf16x8*>((char*)SA(b,h)+lds_byte(wr*64+m*16+fr,k*32+fq*8))
; #define LDB(dst,b,h) _Pragma("unroll") for(int n=0;n<2;++n) _Pragma("unroll") for(int k=0;k<2;++k) \
;     dst[n][k]=*reinterpret_cast<const bf16x8*>((char*)SB(b,h)+lds_byte(wc*32+n*16+fr,k*32+fq*8))
; #define MMA(ai,bj,At_,Bt_) do{__builtin_amdgcn_s_setprio(1); \
;     _Pragma("unroll") for(int m=0;m<4;++m) _Pragma("unroll") for(int n=0;n<2;++n) _Pragma("unroll") for(int k=0;k<2;++k) \
;       acc[ai][bj][m][n]=__builtin_amdgcn_mfma_f32_16x16x32_bf16(Bt_[n][k],At_[m][k],acc[ai][bj][m][n],0,0,0); \
;     __builtin_amdgcn_s_setprio(0);}while(0)
; #define WAIT_V(n) asm volatile("s_waitcnt vmcnt(" #n ")":::"memory")
; #define WAIT_L(n) asm volatile("s_waitcnt lgkmcnt(" #n ")":::"memory")
; #define BAR __builtin_amdgcn_s_barrier()
; #define SCHED __builtin_amdgcn_sched_barrier(0)
; DEVINL void gemm8_mainloop(const u16* A, long lda, const u16* Bt, long ldb, int K, int brow, int bcol, f32x4 (&acc)[2][2][4][2], char* smem, int tid) {
;     ...
;     LDA(At,1,1); STAGE(SA(1,0),A,lda,brow,t+3);
;     BAR; WAIT_L(0); MMA(1,0,At,B0); BAR; SCHED;
;     STAGE(SB(1,1),Bt,ldb,bcol+HALF,t+3);
;     WAIT_V(6); BAR; MMA(1,1,At,B1); BAR;
;   }
;   { LDB(B0,0,0); LDA(At,0,0); STAGE(SA(1,1),A,lda,brow+HALF,nt-1);
;     BAR; WAIT_L(0); MMA(0,0,At,B0); BAR;
	ds_read_b128 v[196:199], v131 offset:49152
	ds_read_b128 v[200:203], v131 offset:50176
	ds_read_b128 v[204:207], v174 offset:49152
	ds_read_b128 v[208:211], v174 offset:50176
	ds_read_b128 v[212:215], v175 offset:49152
	ds_read_b128 v[216:219], v175 offset:50176
	ds_read_b128 v[220:223], v177 offset:49152
	ds_read_b128 v[224:227], v177 offset:50176
	global_load_lds_dwordx4 v[244:245], off
	v_lshl_add_u64 v[244:245], v[246:247], 0, s[20:21]
	s_mov_b32 m0, s5
	s_nop 0
	global_load_lds_dwordx4 v[244:245], off
	s_barrier
	s_waitcnt lgkmcnt(0)
	s_setprio 1
	v_mfma_f32_16x16x32_bf16 v[60:63], v[180:183], v[196:199], v[60:63]
	v_mfma_f32_16x16x32_bf16 v[56:59], v[188:191], v[196:199], v[56:59]
	v_mfma_f32_16x16x32_bf16 v[52:55], v[180:183], v[204:207], v[52:55]
	v_mfma_f32_16x16x32_bf16 v[48:51], v[188:191], v[204:207], v[48:51]
	v_mfma_f32_16x16x32_bf16 v[44:47], v[180:183], v[212:215], v[44:47]
	v_mfma_f32_16x16x32_bf16 v[40:43], v[188:191], v[212:215], v[40:43]
	v_mfma_f32_16x16x32_bf16 v[36:39], v[180:183], v[220:223], v[36:39]
	v_mfma_f32_16x16x32_bf16 v[32:35], v[188:191], v[220:223], v[32:35]
	v_mfma_f32_16x16x32_bf16 v[60:63], v[184:187], v[200:203], v[60:63]
	v_mfma_f32_16x16x32_bf16 v[56:59], v[192:195], v[200:203], v[56:59]
	v_mfma_f32_16x16x32_bf16 v[52:55], v[184:187], v[208:211], v[52:55]
	v_mfma_f32_16x16x32_bf16 v[48:51], v[192:195], v[208:211], v[48:51]
	v_mfma_f32_16x16x32_bf16 v[44:47], v[184:187], v[216:219], v[44:47]
	v_mfma_f32_16x16x32_bf16 v[40:43], v[192:195], v[216:219], v[40:43]
	v_mfma_f32_16x16x32_bf16 v[36:39], v[184:187], v[224:227], v[36:39]
	v_mfma_f32_16x16x32_bf16 v[32:35], v[192:195], v[224:227], v[32:35]
	s_setprio 0
	s_barrier
	v_readfirstlane_b32 s5, v159
	v_add_u32_e32 v165, 0x2000, v159
	v_lshl_add_u64 v[180:181], v[248:249], 0, s[22:23]
	s_mov_b32 m0, s5
	v_readfirstlane_b32 s5, v165
	global_load_lds_dwordx4 v[180:181], off
	v_lshl_add_u64 v[180:181], v[250:251], 0, s[22:23]
	s_mov_b32 m0, s5
	s_nop 0
	global_load_lds_dwordx4 v[180:181], off
	s_waitcnt vmcnt(6)
	s_barrier
	s_setprio 1
	v_mfma_f32_16x16x32_bf16 v[28:31], v[228:231], v[196:199], v[28:31]
	v_mfma_f32_16x16x32_bf16 v[24:27], v[236:239], v[196:199], v[24:27]
	v_mfma_f32_16x16x32_bf16 v[20:23], v[228:231], v[204:207], v[20:23]
	v_mfma_f32_16x16x32_bf16 v[16:19], v[236:239], v[204:207], v[16:19]
	v_mfma_f32_16x16x32_bf16 v[12:15], v[228:231], v[212:215], v[12:15]
	v_mfma_f32_16x16x32_bf16 v[8:11], v[236:239], v[212:215], v[8:11]
	v_mfma_f32_16x16x32_bf16 v[4:7], v[228:231], v[220:223], v[4:7]
	v_mfma_f32_16x16x32_bf16 v[0:3], v[236:239], v[220:223], v[0:3]
	v_mfma_f32_16x16x32_bf16 v[28:31], v[232:235], v[200:203], v[28:31]
	v_mfma_f32_16x16x32_bf16 v[24:27], v[240:243], v[200:203], v[24:27]
	v_mfma_f32_16x16x32_bf16 v[20:23], v[232:235], v[208:211], v[20:23]
	v_mfma_f32_16x16x32_bf16 v[16:19], v[240:243], v[208:211], v[16:19]
	v_mfma_f32_16x16x32_bf16 v[12:15], v[232:235], v[216:219], v[12:15]
	v_mfma_f32_16x16x32_bf16 v[8:11], v[240:243], v[216:219], v[8:11]
	v_mfma_f32_16x16x32_bf16 v[4:7], v[232:235], v[224:227], v[4:7]
	v_mfma_f32_16x16x32_bf16 v[0:3], v[240:243], v[224:227], v[0:3]
	s_setprio 0
	s_add_i32 s4, s4, 2
	v_lshl_add_u64 v[144:145], v[144:145], 0, s[10:11]
	v_lshl_add_u64 v[146:147], v[146:147], 0, s[10:11]
	v_lshl_add_u64 v[148:149], v[148:149], 0, s[10:11]
	s_cmp_lt_u32 s4, 28
	v_lshl_add_u64 v[150:151], v[150:151], 0, s[10:11]
	s_barrier
	s_cbranch_scc1 .LBB0_1292
	s_or_b32 s4, s36, 0x80
	s_ashr_i32 s5, s4, 31
	s_lshl_b64 s[4:5], s[4:5], 12
	s_add_u32 s4, s90, s4
	s_addc_u32 s5, s91, s5
	v_lshl_add_u64 v[156:157], v[136:137], 1, s[4:5]
	v_lshl_add_u64 v[140:141], v[140:141], 1, v[156:157]
	v_readfirstlane_b32 s1, v178
	v_lshl_add_u64 v[140:141], v[140:141], 0, s[24:25]
	s_mov_b32 m0, s1
	ds_read_b128 v[144:147], v161
	ds_read_b128 v[148:151], v161 offset:1024
	ds_read_b128 v[180:183], v161 offset:2048
	ds_read_b128 v[184:187], v161 offset:3072
	ds_read_b128 v[188:191], v131
	ds_read_b128 v[192:195], v131 offset:1024
	ds_read_b128 v[196:199], v174
	ds_read_b128 v[200:203], v174 offset:1024
	ds_read_b128 v[204:207], v175
	ds_read_b128 v[208:211], v175 offset:1024
	ds_read_b128 v[212:215], v177
	ds_read_b128 v[216:219], v177 offset:1024
	global_load_lds_dwordx4 v[140:141], off
	v_lshl_add_u64 v[140:141], v[138:139], 1, s[4:5]
	v_lshl_add_u64 v[140:141], v[142:143], 1, v[140:141]
	v_readfirstlane_b32 s1, v179
	v_lshl_add_u64 v[140:141], v[140:141], 0, s[24:25]
	s_mov_b32 m0, s1
	s_nop 0
	global_load_lds_dwordx4 v[140:141], off
	s_barrier
	s_waitcnt lgkmcnt(0)
	s_setprio 1
	v_mfma_f32_16x16x32_bf16 v[124:127], v[144:147], v[188:191], v[124:127]
	v_mfma_f32_16x16x32_bf16 v[120:123], v[180:183], v[188:191], v[120:123]
	v_mfma_f32_16x16x32_bf16 v[108:111], v[144:147], v[204:207], v[108:111]
	v_mfma_f32_16x16x32_bf16 v[104:107], v[180:183], v[204:207], v[104:107]
	v_mfma_f32_16x16x32_bf16 v[124:127], v[148:151], v[192:195], v[124:127]
	v_mfma_f32_16x16x32_bf16 v[120:123], v[184:187], v[192:195], v[120:123]
	v_mfma_f32_16x16x32_bf16 v[116:119], v[144:147], v[196:199], v[116:119]
	v_mfma_f32_16x16x32_bf16 v[112:115], v[180:183], v[196:199], v[112:115]
	v_mfma_f32_16x16x32_bf16 v[108:111], v[148:151], v[208:211], v[108:111]
	v_mfma_f32_16x16x32_bf16 v[104:107], v[184:187], v[208:211], v[104:107]
	v_mfma_f32_16x16x32_bf16 v[100:103], v[144:147], v[212:215], v[100:103]
	v_mfma_f32_16x16x32_bf16 v[96:99], v[180:183], v[212:215], v[96:99]
	v_mfma_f32_16x16x32_bf16 v[140:143], v[148:151], v[200:203], v[116:119]
	v_mfma_f32_16x16x32_bf16 v[220:223], v[184:187], v[200:203], v[112:115]
	v_mfma_f32_16x16x32_bf16 v[224:227], v[148:151], v[216:219], v[100:103]
	v_mfma_f32_16x16x32_bf16 v[228:231], v[184:187], v[216:219], v[96:99]
	s_setprio 0
	s_barrier
; #define LDA(dst,b,h) _Pragma("unroll") for(int m=0;m<4;++m) _Pragma("unroll") for(int k=0;k<2;++k) \
;     dst[m][k]=*reinterpret_cast<const bf16x8*>((char*)SA(b,h)+lds_byte(wr*64+m*16+fr,k*32+fq*8))
; #define LDB(dst,b,h) _Pragma("unroll") for(int n=0;n<2;++n) _Pragma("unroll") for(int k=0;k<2;++k) \
;     dst[n][k]=*reinterpret_cast<const bf16x8*>((char*)SB(b,h)+lds_byte(wc*32+n*16+fr,k*32+fq*8))
; #define MMA(ai,bj,At_,Bt_) do{__builtin_amdgcn_s_setprio(1); \
;     _Pragma("unroll") for(int m=0;m<4;++m) _Pragma("unroll") for(int n=0;n<2;++n) _Pragma("unroll") for(int k=0;k<2;++k) \
;       acc[ai][bj][m][n]=__builtin_amdgcn_mfma_f32_16x16x32_bf16(Bt_[n][k],At_[m][k],acc[ai][bj][m][n],0,0,0); \
;     __builtin_amdgcn_s_setprio(0);}while(0)
; #define WAIT_V(n) asm volatile("s_waitcnt vmcnt(" #n ")":::"memory")
; #define WAIT_L(n) asm volatile("s_waitcnt lgkmcnt(" #n ")":::"memory")
; #define BAR __builtin_amdgcn_s_barrier()
; DEVINL void gemm8_mainloop(const u16* A, long lda, const u16* Bt, long ldb, int K, int brow, int bcol, f32x4 (&acc)[2][2][4][2], char* smem, int tid) {
;     ...
;     LDB(B1,0,1); BAR; WAIT_L(0); MMA(0,1,At,B1); BAR;
;     LDA(At,0,1); WAIT_V(4); BAR; WAIT_L(0); MMA(1,0,At,B0); MMA(1,1,At,B1); BAR; }
;   { LDB(B0,1,0); LDA(At,1,0); WAIT_V(2); BAR; WAIT_L(0); MMA(0,0,At,B0); BAR;
	s_nop 1
	ds_read_b128 v[96:99], v158
	ds_read_b128 v[100:103], v158 offset:1024
	ds_read_b128 v[112:115], v158 offset:2048
	ds_read_b128 v[116:119], v158 offset:3072
	s_barrier
	s_waitcnt lgkmcnt(0)
	s_setprio 1
	v_mfma_f32_16x16x32_bf16 v[92:95], v[96:99], v[188:191], v[92:95]
	v_mfma_f32_16x16x32_bf16 v[88:91], v[112:115], v[188:191], v[88:91]
	v_mfma_f32_16x16x32_bf16 v[76:79], v[96:99], v[204:207], v[76:79]
	v_mfma_f32_16x16x32_bf16 v[72:75], v[112:115], v[204:207], v[72:75]
	v_mfma_f32_16x16x32_bf16 v[92:95], v[100:103], v[192:195], v[92:95]
	v_mfma_f32_16x16x32_bf16 v[88:91], v[116:119], v[192:195], v[88:91]
	v_mfma_f32_16x16x32_bf16 v[84:87], v[96:99], v[196:199], v[84:87]
	v_mfma_f32_16x16x32_bf16 v[80:83], v[112:115], v[196:199], v[80:83]
	v_mfma_f32_16x16x32_bf16 v[76:79], v[100:103], v[208:211], v[76:79]
	v_mfma_f32_16x16x32_bf16 v[72:75], v[116:119], v[208:211], v[72:75]
	v_mfma_f32_16x16x32_bf16 v[68:71], v[96:99], v[212:215], v[68:71]
	v_mfma_f32_16x16x32_bf16 v[64:67], v[112:115], v[212:215], v[64:67]
	v_mfma_f32_16x16x32_bf16 v[156:159], v[100:103], v[200:203], v[84:87]
	v_mfma_f32_16x16x32_bf16 v[188:191], v[116:119], v[200:203], v[80:83]
	v_mfma_f32_16x16x32_bf16 v[192:195], v[100:103], v[216:219], v[68:71]
	v_mfma_f32_16x16x32_bf16 v[196:199], v[116:119], v[216:219], v[64:67]
	s_setprio 0
	s_barrier
	s_nop 1
	ds_read_b128 v[64:67], v131 offset:16384
	ds_read_b128 v[68:71], v131 offset:17408
	ds_read_b128 v[80:83], v174 offset:16384
	ds_read_b128 v[84:87], v174 offset:17408
	ds_read_b128 v[200:203], v175 offset:16384
	ds_read_b128 v[204:207], v175 offset:17408
	ds_read_b128 v[208:211], v177 offset:16384
	ds_read_b128 v[212:215], v177 offset:17408
	s_waitcnt vmcnt(4)
	s_barrier
	s_waitcnt lgkmcnt(0)
	s_setprio 1
	v_mfma_f32_16x16x32_bf16 v[60:63], v[144:147], v[64:67], v[60:63]
	v_mfma_f32_16x16x32_bf16 v[52:55], v[144:147], v[80:83], v[52:55]
	v_mfma_f32_16x16x32_bf16 v[44:47], v[144:147], v[200:203], v[44:47]
	v_mfma_f32_16x16x32_bf16 v[40:43], v[180:183], v[200:203], v[40:43]
	v_mfma_f32_16x16x32_bf16 v[60:63], v[148:151], v[68:71], v[60:63]
	v_mfma_f32_16x16x32_bf16 v[56:59], v[180:183], v[64:67], v[56:59]
	v_mfma_f32_16x16x32_bf16 v[52:55], v[148:151], v[84:87], v[52:55]
	v_mfma_f32_16x16x32_bf16 v[48:51], v[180:183], v[80:83], v[48:51]
	v_mfma_f32_16x16x32_bf16 v[44:47], v[148:151], v[204:207], v[44:47]
	v_mfma_f32_16x16x32_bf16 v[40:43], v[184:187], v[204:207], v[40:43]
	v_mfma_f32_16x16x32_bf16 v[36:39], v[144:147], v[208:211], v[36:39]
	v_mfma_f32_16x16x32_bf16 v[32:35], v[180:183], v[208:211], v[32:35]
	v_mfma_f32_16x16x32_bf16 v[216:219], v[184:187], v[68:71], v[56:59]
	v_mfma_f32_16x16x32_bf16 v[232:235], v[184:187], v[84:87], v[48:51]
	v_mfma_f32_16x16x32_bf16 v[144:147], v[148:151], v[212:215], v[36:39]
	v_mfma_f32_16x16x32_bf16 v[148:151], v[184:187], v[212:215], v[32:35]
	s_setprio 0
	s_setprio 1
	v_mfma_f32_16x16x32_bf16 v[28:31], v[96:99], v[64:67], v[28:31]
	v_mfma_f32_16x16x32_bf16 v[20:23], v[96:99], v[80:83], v[20:23]
	v_mfma_f32_16x16x32_bf16 v[12:15], v[96:99], v[200:203], v[12:15]
	v_mfma_f32_16x16x32_bf16 v[4:7], v[96:99], v[208:211], v[4:7]
	v_mfma_f32_16x16x32_bf16 v[28:31], v[100:103], v[68:71], v[28:31]
	v_mfma_f32_16x16x32_bf16 v[24:27], v[112:115], v[64:67], v[24:27]
	v_mfma_f32_16x16x32_bf16 v[20:23], v[100:103], v[84:87], v[20:23]
	v_mfma_f32_16x16x32_bf16 v[16:19], v[112:115], v[80:83], v[16:19]
	v_mfma_f32_16x16x32_bf16 v[12:15], v[100:103], v[204:207], v[12:15]
	v_mfma_f32_16x16x32_bf16 v[8:11], v[112:115], v[200:203], v[8:11]
	v_mfma_f32_16x16x32_bf16 v[4:7], v[100:103], v[212:215], v[4:7]
	v_mfma_f32_16x16x32_bf16 v[0:3], v[112:115], v[208:211], v[0:3]
	v_mfma_f32_16x16x32_bf16 v[178:181], v[116:119], v[68:71], v[24:27]
	v_mfma_f32_16x16x32_bf16 v[182:185], v[116:119], v[84:87], v[16:19]
	v_mfma_f32_16x16x32_bf16 v[200:203], v[116:119], v[204:207], v[8:11]
	v_mfma_f32_16x16x32_bf16 v[204:207], v[116:119], v[212:215], v[0:3]
	s_setprio 0
	s_barrier
	s_nop 1
	ds_read_b128 v[0:3], v154
	ds_read_b128 v[8:11], v154 offset:1024
	ds_read_b128 v[208:211], v154 offset:2048
	ds_read_b128 v[212:215], v154 offset:3072
	ds_read_b128 v[16:19], v131 offset:32768
	ds_read_b128 v[24:27], v131 offset:33792
	ds_read_b128 v[32:35], v174 offset:32768
	ds_read_b128 v[36:39], v174 offset:33792
	ds_read_b128 v[48:51], v175 offset:32768
	ds_read_b128 v[56:59], v175 offset:33792
	ds_read_b128 v[236:239], v177 offset:32768
	ds_read_b128 v[240:243], v177 offset:33792
	s_waitcnt vmcnt(2)
	s_barrier
; #define LDA(dst,b,h) _Pragma("unroll") for(int m=0;m<4;++m) _Pragma("unroll") for(int k=0;k<2;++k) \
;     dst[m][k]=*reinterpret_cast<const bf16x8*>((char*)SA(b,h)+lds_byte(wr*64+m*16+fr,k*32+fq*8))
; #define LDB(dst,b,h) _Pragma("unroll") for(int n=0;n<2;++n) _Pragma("unroll") for(int k=0;k<2;++k) \
;     dst[n][k]=*reinterpret_cast<const bf16x8*>((char*)SB(b,h)+lds_byte(wc*32+n*16+fr,k*32+fq*8))
; #define MMA(ai,bj,At_,Bt_) do{__builtin_amdgcn_s_setprio(1); \
;     _Pragma("unroll") for(int m=0;m<4;++m) _Pragma("unroll") for(int n=0;n<2;++n) _Pragma("unroll") for(int k=0;k<2;++k) \
;       acc[ai][bj][m][n]=__builtin_amdgcn_mfma_f32_16x16x32_bf16(Bt_[n][k],At_[m][k],acc[ai][bj][m][n],0,0,0); \
;     __builtin_amdgcn_s_setprio(0);}while(0)
; #define WAIT_V(n) asm volatile("s_waitcnt vmcnt(" #n ")":::"memory")
; #define WAIT_L(n) asm volatile("s_waitcnt lgkmcnt(" #n ")":::"memory")
; #define BAR __builtin_amdgcn_s_barrier()
; DEVINL void gemm8_mainloop(const u16* A, long lda, const u16* Bt, long ldb, int K, int brow, int bcol, f32x4 (&acc)[2][2][4][2], char* smem, int tid) {
;     ...
;   { LDB(B0,1,0); LDA(At,1,0); WAIT_V(2); BAR; WAIT_L(0); MMA(0,0,At,B0); BAR;
;     LDB(B1,1,1); WAIT_V(0); BAR; WAIT_L(0); MMA(0,1,At,B1); BAR;
;     LDA(At,1,1); BAR; WAIT_L(0); MMA(1,0,At,B0); MMA(1,1,At,B1); BAR; }
;   if(wr==0)BAR;
	s_waitcnt lgkmcnt(0)
	s_setprio 1
	v_mfma_f32_16x16x32_bf16 v[64:67], v[0:3], v[16:19], v[124:127]
	v_mfma_f32_16x16x32_bf16 v[116:119], v[8:11], v[24:27], v[64:67]
	v_mfma_f32_16x16x32_bf16 v[64:67], v[208:211], v[16:19], v[120:123]
	v_mfma_f32_16x16x32_bf16 v[112:115], v[212:215], v[24:27], v[64:67]
	v_mfma_f32_16x16x32_bf16 v[64:67], v[0:3], v[32:35], v[140:143]
	v_mfma_f32_16x16x32_bf16 v[100:103], v[8:11], v[36:39], v[64:67]
	v_mfma_f32_16x16x32_bf16 v[64:67], v[208:211], v[32:35], v[220:223]
	v_mfma_f32_16x16x32_bf16 v[96:99], v[212:215], v[36:39], v[64:67]
	v_mfma_f32_16x16x32_bf16 v[64:67], v[0:3], v[48:51], v[108:111]
	v_mfma_f32_16x16x32_bf16 v[84:87], v[8:11], v[56:59], v[64:67]
	v_mfma_f32_16x16x32_bf16 v[64:67], v[208:211], v[48:51], v[104:107]
	v_mfma_f32_16x16x32_bf16 v[80:83], v[212:215], v[56:59], v[64:67]
	v_mfma_f32_16x16x32_bf16 v[64:67], v[0:3], v[236:239], v[224:227]
	v_mfma_f32_16x16x32_bf16 v[68:71], v[8:11], v[240:243], v[64:67]
	v_mfma_f32_16x16x32_bf16 v[64:67], v[208:211], v[236:239], v[228:231]
	v_mfma_f32_16x16x32_bf16 v[64:67], v[212:215], v[240:243], v[64:67]
	s_setprio 0
	s_barrier
	ds_read_b128 v[140:143], v152
	ds_read_b128 v[220:223], v152 offset:1024
	ds_read_b128 v[224:227], v152 offset:2048
	ds_read_b128 v[152:155], v152 offset:3072
	s_waitcnt vmcnt(0)
	s_barrier
	s_waitcnt lgkmcnt(0)
	s_setprio 1
	v_mfma_f32_16x16x32_bf16 v[92:95], v[140:143], v[16:19], v[92:95]
	v_mfma_f32_16x16x32_bf16 v[16:19], v[224:227], v[16:19], v[88:91]
	v_mfma_f32_16x16x32_bf16 v[120:123], v[152:155], v[24:27], v[16:19]
	v_mfma_f32_16x16x32_bf16 v[16:19], v[140:143], v[32:35], v[156:159]
	v_mfma_f32_16x16x32_bf16 v[104:107], v[220:223], v[36:39], v[16:19]
	v_mfma_f32_16x16x32_bf16 v[16:19], v[224:227], v[32:35], v[188:191]
	v_mfma_f32_16x16x32_bf16 v[108:111], v[152:155], v[36:39], v[16:19]
	v_mfma_f32_16x16x32_bf16 v[16:19], v[140:143], v[48:51], v[76:79]
	v_mfma_f32_16x16x32_bf16 v[124:127], v[220:223], v[24:27], v[92:95]
	v_mfma_f32_16x16x32_bf16 v[92:95], v[220:223], v[56:59], v[16:19]
	v_mfma_f32_16x16x32_bf16 v[16:19], v[224:227], v[48:51], v[72:75]
	v_mfma_f32_16x16x32_bf16 v[88:91], v[152:155], v[56:59], v[16:19]
	v_mfma_f32_16x16x32_bf16 v[16:19], v[140:143], v[236:239], v[192:195]
	v_mfma_f32_16x16x32_bf16 v[72:75], v[220:223], v[240:243], v[16:19]
	v_mfma_f32_16x16x32_bf16 v[16:19], v[224:227], v[236:239], v[196:199]
	v_mfma_f32_16x16x32_bf16 v[76:79], v[152:155], v[240:243], v[16:19]
	s_setprio 0
	s_barrier
	ds_read_b128 v[156:159], v131 offset:49152
	ds_read_b128 v[186:189], v131 offset:50176
	ds_read_b128 v[190:193], v174 offset:49152
	ds_read_b128 v[194:197], v174 offset:50176
	ds_read_b128 v[228:231], v175 offset:49152
	ds_read_b128 v[236:239], v175 offset:50176
	ds_read_b128 v[240:243], v177 offset:49152
	ds_read_b128 v[244:247], v177 offset:50176
	s_barrier
	s_waitcnt lgkmcnt(0)
	s_setprio 1
	v_mfma_f32_16x16x32_bf16 v[16:19], v[0:3], v[156:159], v[60:63]
	v_mfma_f32_16x16x32_bf16 v[56:59], v[8:11], v[186:189], v[16:19]
	v_mfma_f32_16x16x32_bf16 v[16:19], v[208:211], v[156:159], v[216:219]
	v_mfma_f32_16x16x32_bf16 v[48:51], v[212:215], v[186:189], v[16:19]
	v_mfma_f32_16x16x32_bf16 v[16:19], v[0:3], v[190:193], v[52:55]
	v_mfma_f32_16x16x32_bf16 v[36:39], v[8:11], v[194:197], v[16:19]
	v_mfma_f32_16x16x32_bf16 v[16:19], v[208:211], v[190:193], v[232:235]
	v_mfma_f32_16x16x32_bf16 v[32:35], v[212:215], v[194:197], v[16:19]
	v_mfma_f32_16x16x32_bf16 v[16:19], v[0:3], v[228:231], v[44:47]
	v_mfma_f32_16x16x32_bf16 v[0:3], v[0:3], v[240:243], v[144:147]
	v_mfma_f32_16x16x32_bf16 v[24:27], v[8:11], v[236:239], v[16:19]
	v_mfma_f32_16x16x32_bf16 v[16:19], v[208:211], v[228:231], v[40:43]
	v_mfma_f32_16x16x32_bf16 v[8:11], v[8:11], v[244:247], v[0:3]
	v_mfma_f32_16x16x32_bf16 v[0:3], v[208:211], v[240:243], v[148:151]
	v_mfma_f32_16x16x32_bf16 v[16:19], v[212:215], v[236:239], v[16:19]
	v_mfma_f32_16x16x32_bf16 v[0:3], v[212:215], v[244:247], v[0:3]
	s_setprio 0
	s_setprio 1
	v_mfma_f32_16x16x32_bf16 v[28:31], v[140:143], v[156:159], v[28:31]
	v_mfma_f32_16x16x32_bf16 v[60:63], v[220:223], v[186:189], v[28:31]
	v_mfma_f32_16x16x32_bf16 v[28:31], v[224:227], v[156:159], v[178:181]
	v_mfma_f32_16x16x32_bf16 v[20:23], v[140:143], v[190:193], v[20:23]
	v_mfma_f32_16x16x32_bf16 v[12:15], v[140:143], v[228:231], v[12:15]
	v_mfma_f32_16x16x32_bf16 v[52:55], v[152:155], v[186:189], v[28:31]
	v_mfma_f32_16x16x32_bf16 v[40:43], v[220:223], v[194:197], v[20:23]
	v_mfma_f32_16x16x32_bf16 v[20:23], v[224:227], v[190:193], v[182:185]
	v_mfma_f32_16x16x32_bf16 v[28:31], v[220:223], v[236:239], v[12:15]
	v_mfma_f32_16x16x32_bf16 v[12:15], v[224:227], v[228:231], v[200:203]
	v_mfma_f32_16x16x32_bf16 v[4:7], v[140:143], v[240:243], v[4:7]
	v_mfma_f32_16x16x32_bf16 v[44:47], v[152:155], v[194:197], v[20:23]
	v_mfma_f32_16x16x32_bf16 v[20:23], v[152:155], v[236:239], v[12:15]
	v_mfma_f32_16x16x32_bf16 v[12:15], v[220:223], v[244:247], v[4:7]
	v_mfma_f32_16x16x32_bf16 v[4:7], v[224:227], v[240:243], v[204:207]
	v_mfma_f32_16x16x32_bf16 v[4:7], v[152:155], v[244:247], v[4:7]
	s_setprio 0
	s_cmpk_gt_u32 s0, 0xff
	s_barrier
	s_cbranch_scc1 .LBB0_1295
	s_barrier

; #define LDK(DST, KQ) _Pragma("unroll") for (int kc = 0; kc < 4; ++kc) DST[kc] = *(const bf16x8*)(Ks + ((KQ) * 16 + fr) * 136 + kc * 32 + fq * 8)
; #define MMS(SRC, KQ) do { s[0][KQ] = f32x4{-mrun[0], -mrun[0], -mrun[0], -mrun[0]}; s[1][KQ] = f32x4{-mrun[1], -mrun[1], -mrun[1], -mrun[1]}; __builtin_amdgcn_s_setprio(1); \
;       _Pragma("unroll") for (int kc = 0; kc < 4; ++kc) { s[0][KQ] = mfma16(SRC[kc], qf[0][kc], s[0][KQ]); s[1][KQ] = mfma16(SRC[kc], qf[1][kc], s[1][KQ]); } __builtin_amdgcn_s_setprio(0); } while (0)
; DEVINL void attn_item(const Params& p, int item, char* smem, int wv) {
;     ...
;   unsigned long long mw_next = bits[qtok * 64];
;   u32x4 rk[2], rv[2];
;   const u16* kg = hb + ((size_t)b * SEQ + (tid >> 4)) * HS + 3584 + kvh * 128 + (tid & 15) * 8;
;   const u16* vg = vT + ((size_t)(b * 4 + kvh) * 128 + (tid >> 3)) * SEQ + (tid & 7) * 8;
; #pragma unroll
;   for (int i = 0; i < 2; ++i) {
;     rk[i] = *(const u32x4*)(kg + (size_t)(32 * i) * HS);
;     rv[i] = *(const u32x4*)(vg + (size_t)(64 * i) * SEQ);
;   }
;   for (int kt = 0; kt < ntile; ++kt) {
; #pragma unroll
;     for (int i = 0; i < 2; ++i) {
;       *(u32x4*)(Ks + ((tid >> 4) + 32 * i) * 136 + (tid & 15) * 8) = rk[i];
;       *(u32x4*)(Vs + ((tid >> 3) + 64 * i) * 72 + (tid & 7) * 8) = rv[i];
;     }
;     __syncthreads();
;     if (kt + 1 < ntile) {
; #pragma unroll
;       for (int i = 0; i < 2; ++i) {
;         rk[i] = *(const u32x4*)(kg + (size_t)((kt + 1) * 64 + 32 * i) * HS);
;         rv[i] = *(const u32x4*)(vg + (size_t)(64 * i) * SEQ + (kt + 1) * 64);
;       }
;     }
;     const unsigned long long mw = mw_next;
;     if (kt + 1 < ntile) mw_next = bits[qtok * 64 + kt + 1];
;     if (kt * 64 <= qlast) {
;     f32x4 s[2][4];
;     bf16x8 kfa[4], kfb[4];
;     bf16x8 vfa[2], vfb[2];
;     ...
;     LDK(kfa, 0);
;     LDK(kfb, 1); MMS(kfa, 0);
;     LDK(kfa, 2); MMS(kfb, 1);
;     LDK(kfb, 3); MMS(kfa, 2);
;     LDV(vfa, 0); MMS(kfb, 3);
.Lprio_skip_a1:
	s_and_b32 s34, s3, 0x3000
	v_and_b32_e32 v60, 15, v120
	s_and_b32 s2, s7, -16
	s_add_i32 s10, s6, s34
	s_ashr_i32 s3, s2, 31
	v_or_b32_e32 v0, s10, v60
	v_lshl_add_u64 v[156:157], v[0:1], 0, s[2:3]
	v_mov_b64_e32 v[2:3], s[62:63]
	v_mad_u64_u32 v[4:5], s[2:3], v156, s22, v[2:3]
	s_and_b32 s5, s1, 3
	v_mad_i32_i24 v5, v157, s22, v5
	v_and_b32_e32 v0, 48, v120
	v_lshl_add_u64 v[4:5], v[4:5], 0, v[0:1]
	s_lshl_b32 s10, s5, 9
	v_ashrrev_i32_e32 v14, 4, v120
	v_lshl_add_u64 v[8:9], v[4:5], 0, s[10:11]
	v_add_u32_e32 v4, s34, v14
	s_lshl_b32 s18, s5, 8
	s_mov_b32 s19, s11
	v_mad_i64_i32 v[2:3], s[2:3], v4, s22, v[2:3]
	v_lshlrev_b32_e32 v6, 4, v120
	v_lshl_add_u64 v[2:3], v[2:3], 0, s[18:19]
	v_and_b32_e32 v10, 0xf0, v6
	v_mov_b32_e32 v11, v1
	v_lshl_add_u64 v[116:117], v[2:3], 0, v[10:11]
	s_lshl_b32 s1, s1, 7
	v_ashrrev_i32_e32 v2, 3, v120
	s_and_b32 s10, s1, 0x780
	v_ashrrev_i32_e32 v3, 31, v2
	v_lshl_add_u64 v[4:5], v[2:3], 0, s[10:11]
	v_lshlrev_b64 v[4:5], 13, v[4:5]
	v_lshl_add_u64 v[4:5], s[40:41], 0, v[4:5]
	v_and_b32_e32 v12, 0x70, v6
	v_mov_b32_e32 v13, v1
	v_lshl_add_u64 v[158:159], v[4:5], 0, v[12:13]
	v_add_co_u32_e32 v4, vcc, s23, v116
	global_load_dwordx4 v[36:39], v[158:159], off
	s_nop 0
	v_addc_co_u32_e32 v5, vcc, 0, v117, vcc
	v_add_co_u32_e32 v6, vcc, s24, v116
	v_mul_lo_u32 v2, v2, s27
	s_nop 0
	v_addc_co_u32_e32 v7, vcc, 0, v117, vcc
	global_load_dwordx4 v[40:43], v[4:5], off offset:3072
	global_load_dwordx4 v[44:47], v[6:7], off offset:3072
	v_add_co_u32_e32 v52, vcc, s25, v158
	v_add_u32_e32 v11, 0, v12
	s_nop 0
	v_addc_co_u32_e32 v53, vcc, 0, v159, vcc
	global_load_dwordx4 v[48:51], v[52:53], off
	v_mul_lo_u32 v3, v14, s26
	v_add_u32_e32 v10, 0, v10
	v_and_b32_e32 v173, 64, v12
	v_bfe_u32 v11, v12, 4, 1
	v_lshl_or_b32 v173, v11, 5, v173
	v_bfe_u32 v11, v12, 5, 1
	v_lshl_or_b32 v173, v11, 3, v173
	v_add_u32_e32 v173, v173, v2
	v_add_co_u32_e64 v2, s[2:3], s23, v8
	v_lshl_add_u64 v[28:29], v[8:9], 0, s[12:13]
	v_add_u32_e32 v172, v10, v3
	v_lshlrev_b64 v[118:119], 9, v[156:157]
	v_add_co_u32_e32 v54, vcc, 0xa1000, v116
	v_addc_co_u32_e64 v3, s[2:3], 0, v9, s[2:3]
	global_load_dwordx4 v[4:7], v[28:29], off offset:64
	v_lshl_add_u64 v[56:57], s[38:39], 0, v[118:119]
	v_addc_co_u32_e32 v55, vcc, 0, v117, vcc
	global_load_dwordx4 v[8:11], v[28:29], off offset:128
	global_load_dwordx4 v[12:15], v[28:29], off offset:192
	global_load_dwordx4 v[16:19], v[28:29], off offset:256
	global_load_dwordx4 v[20:23], v[28:29], off offset:320
	global_load_dwordx4 v[24:27], v[28:29], off offset:384
	s_nop 0
	global_load_dwordx4 v[28:31], v[28:29], off offset:448
	s_nop 0
	global_load_dwordx4 v[32:35], v[2:3], off offset:1024
	s_nop 0
	global_load_dwordx2 v[2:3], v[56:57], off
	v_add_co_u32_e32 v58, vcc, 0xf1000, v116
	s_add_i32 s1, s7, s6
	s_nop 0
	v_addc_co_u32_e32 v59, vcc, 0, v117, vcc
	s_cmp_gt_i32 s1, -1
	s_mov_b64 s[2:3], -1
	s_waitcnt vmcnt(11)
	ds_write_b128 v172, v[40:43]
	ds_write_b64 v173, v[36:37] offset:17408
	ds_write_b64 v173, v[38:39] offset:17424
	s_waitcnt vmcnt(10)
	ds_write_b128 v172, v[44:47] offset:8704
	s_waitcnt vmcnt(9)
	ds_write_b64 v173, v[48:49] offset:26624
	ds_write_b64 v173, v[50:51] offset:26640
	s_waitcnt lgkmcnt(0)
	s_barrier
	global_load_dwordx4 v[44:47], v[58:59], off offset:3072
	global_load_dwordx4 v[36:39], v[54:55], off offset:3072
	global_load_dwordx4 v[48:51], v[52:53], off offset:128
	global_load_dwordx4 v[40:43], v[158:159], off offset:128
	global_load_dwordx2 v[162:163], v[56:57], off offset:8
	v_mad_u32_u24 v52, v60, s26, 0
	v_lshlrev_b32_e32 v53, 7, v60
	v_lshrrev_b32_e32 v54, 2, v120
	v_sub_u32_e32 v53, v52, v53
	v_and_b32_e32 v174, 12, v54
	v_add_u32_e32 v175, v52, v0
	v_lshl_add_u32 v177, v174, 2, v53
	s_cbranch_scc0 .LBB0_1726
	ds_read_b128 v[52:55], v175
	ds_read_b128 v[56:59], v175 offset:64
	ds_read_b128 v[60:63], v175 offset:128
	ds_read_b128 v[64:67], v175 offset:192
	ds_read_b128 v[68:71], v175 offset:4352
	ds_read_b128 v[72:75], v175 offset:4416
	ds_read_b128 v[76:79], v175 offset:4480
	ds_read_b128 v[80:83], v175 offset:4544
	s_mov_b32 s6, s4
	s_mov_b32 s7, s4
	s_mov_b32 s5, s4
	v_mov_b64_e32 v[86:87], s[6:7]
	v_mov_b64_e32 v[84:85], s[4:5]
	s_waitcnt vmcnt(6) lgkmcnt(7)
	s_nop 0
	v_mfma_f32_16x16x32_bf16 v[88:91], v[52:55], v[32:35], v[84:87]
	v_mfma_f32_16x16x32_bf16 v[52:55], v[52:55], v[16:19], v[84:87]
	s_waitcnt lgkmcnt(6)
	v_mfma_f32_16x16x32_bf16 v[88:91], v[56:59], v[4:7], v[88:91]
	v_mfma_f32_16x16x32_bf16 v[52:55], v[56:59], v[20:23], v[52:55]
	s_waitcnt lgkmcnt(5)
	v_mfma_f32_16x16x32_bf16 v[56:59], v[60:63], v[8:11], v[88:91]
	v_mfma_f32_16x16x32_bf16 v[52:55], v[60:63], v[24:27], v[52:55]
	s_waitcnt lgkmcnt(4)
	v_mfma_f32_16x16x32_bf16 v[60:63], v[64:67], v[12:15], v[56:59]
	v_mfma_f32_16x16x32_bf16 v[64:67], v[64:67], v[28:31], v[52:55]
	s_nop 3
	s_nop 0
	ds_read_b128 v[52:55], v175 offset:8704
	ds_read_b128 v[56:59], v175 offset:8768
	ds_read_b128 v[88:91], v175 offset:8832
	ds_read_b128 v[92:95], v175 offset:8896
	s_waitcnt lgkmcnt(7)
	v_mfma_f32_16x16x32_bf16 v[96:99], v[68:71], v[32:35], v[84:87]
	v_mfma_f32_16x16x32_bf16 v[68:71], v[68:71], v[16:19], v[84:87]
	s_waitcnt lgkmcnt(6)
	v_mfma_f32_16x16x32_bf16 v[96:99], v[72:75], v[4:7], v[96:99]
	v_mfma_f32_16x16x32_bf16 v[68:71], v[72:75], v[20:23], v[68:71]
	s_waitcnt lgkmcnt(5)
	v_mfma_f32_16x16x32_bf16 v[72:75], v[76:79], v[8:11], v[96:99]
	v_mfma_f32_16x16x32_bf16 v[68:71], v[76:79], v[24:27], v[68:71]
	s_waitcnt lgkmcnt(4)
	v_mfma_f32_16x16x32_bf16 v[72:75], v[80:83], v[12:15], v[72:75]
	v_mfma_f32_16x16x32_bf16 v[68:71], v[80:83], v[28:31], v[68:71]
	ds_read_b128 v[76:79], v175 offset:13056
	ds_read_b128 v[80:83], v175 offset:13120
	ds_read_b128 v[96:99], v175 offset:13184
	ds_read_b128 v[100:103], v175 offset:13248
	s_waitcnt lgkmcnt(7)
; DEVINL void attn_item(const Params& p, int item, char* smem, int wv) {
;     ...
;     LDV(vfa, 0); MMS(kfb, 3);
;     bf16x8 pf[2][2];
;     {
;       const unsigned long long msh = mw >> (fq * 4);
;       const int mlo = (int)(unsigned)msh, mhi = (int)(unsigned)(msh >> 32);
;       int mk[4][4];
; #pragma unroll
;       for (int j = 0; j < 4; ++j) {
;         mk[0][j] = __builtin_amdgcn_sbfe(mlo, j, 1); mk[1][j] = __builtin_amdgcn_sbfe(mlo, 16 + j, 1);
;         mk[2][j] = __builtin_amdgcn_sbfe(mhi, j, 1); mk[3][j] = __builtin_amdgcn_sbfe(mhi, 16 + j, 1);
;       }
; #pragma unroll
;       for (int hh = 0; hh < 2; ++hh) {
;         float mx = s[hh][0][0];
; #pragma unroll
;         for (int kq = 0; kq < 4; ++kq)
; #pragma unroll
;           for (int j = 0; j < 4; ++j) mx = fmaxf(mx, s[hh][kq][j]);
;         {
;           auto r1 = __builtin_amdgcn_permlane16_swap(__float_as_uint(mx), __float_as_uint(mx), false, false);
;           mx = fmaxf(__uint_as_float(r1[0]), __uint_as_float(r1[1]));
;           auto r2 = __builtin_amdgcn_permlane32_swap(__float_as_uint(mx), __float_as_uint(mx), false, false);
;           mx = fmaxf(__uint_as_float(r2[0]), __uint_as_float(r2[1]));
;         }
;         if (kt == 0 || __ballot(mx > 8.f)) {
;           const float delta = (kt == 0) ? mx : fmaxf(mx, 0.f);
;           const float alpha = fexp2(-delta);
;           mrun[hh] += delta;
;           lsum[hh] *= alpha;
; #pragma unroll
;           for (int dt = 0; dt < 8; ++dt) o[hh][dt] *= alpha;
; #pragma unroll
;           for (int kq = 0; kq < 4; ++kq)
; #pragma unroll
;             for (int j = 0; j < 4; ++j) s[hh][kq][j] -= delta;
;         }
;         float ps = 0.f;
;         float pv[4][4];
; #pragma unroll
;         for (int kq = 0; kq < 4; ++kq)
; #pragma unroll
;           for (int j = 0; j < 4; ++j) {
;             pv[kq][j] = __uint_as_float(__float_as_uint(fexp2(s[hh][kq][j])) & (unsigned)mk[kq][j]);
;             ps += pv[kq][j];
;           }
; #pragma unroll
;         for (int c2 = 0; c2 < 2; ++c2) {
;           u32x4 pw;
;           pw[0] = pk2(pv[2 * c2][0], pv[2 * c2][1]); pw[1] = pk2(pv[2 * c2][2], pv[2 * c2][3]);
;           pw[2] = pk2(pv[2 * c2 + 1][0], pv[2 * c2 + 1][1]); pw[3] = pk2(pv[2 * c2 + 1][2], pv[2 * c2 + 1][3]);
;           pf[hh][c2] = *(bf16x8*)&pw;
;         }
;         lsum[hh] += ps;
;       }
;     }
;     LDV(vfb, 1); MMV(vfa, 0);
	v_mfma_f32_16x16x32_bf16 v[104:107], v[52:55], v[32:35], v[84:87]
	v_mfma_f32_16x16x32_bf16 v[52:55], v[52:55], v[16:19], v[84:87]
	s_waitcnt lgkmcnt(6)
	v_mfma_f32_16x16x32_bf16 v[104:107], v[56:59], v[4:7], v[104:107]
	v_mfma_f32_16x16x32_bf16 v[52:55], v[56:59], v[20:23], v[52:55]
	s_waitcnt lgkmcnt(5)
	v_mfma_f32_16x16x32_bf16 v[56:59], v[88:91], v[8:11], v[104:107]
	v_mfma_f32_16x16x32_bf16 v[52:55], v[88:91], v[24:27], v[52:55]
	s_waitcnt lgkmcnt(4)
	v_mfma_f32_16x16x32_bf16 v[88:91], v[92:95], v[12:15], v[56:59]
	v_mfma_f32_16x16x32_bf16 v[92:95], v[92:95], v[28:31], v[52:55]
	s_nop 2
	s_nop 1
	ds_read_b128 v[52:55], v177 offset:17408
	ds_read_b128 v[56:59], v177 offset:17472
	s_waitcnt lgkmcnt(5)
	v_mfma_f32_16x16x32_bf16 v[104:107], v[76:79], v[32:35], v[84:87]
	v_mfma_f32_16x16x32_bf16 v[76:79], v[76:79], v[16:19], v[84:87]
	s_waitcnt lgkmcnt(4)
	v_mfma_f32_16x16x32_bf16 v[84:87], v[80:83], v[4:7], v[104:107]
	v_mfma_f32_16x16x32_bf16 v[76:79], v[80:83], v[20:23], v[76:79]
	s_waitcnt lgkmcnt(3)
	v_mfma_f32_16x16x32_bf16 v[80:83], v[96:99], v[8:11], v[84:87]
	v_mfma_f32_16x16x32_bf16 v[76:79], v[96:99], v[24:27], v[76:79]
	s_waitcnt lgkmcnt(2)
	v_mfma_f32_16x16x32_bf16 v[80:83], v[100:103], v[12:15], v[80:83]
	v_mfma_f32_16x16x32_bf16 v[76:79], v[100:103], v[28:31], v[76:79]
	s_waitcnt vmcnt(5)
	v_lshrrev_b64 v[2:3], v174, v[2:3]
	v_bfe_i32 v0, v2, 0, 1
	v_bfe_i32 v86, v2, 16, 1
	v_bfe_i32 v87, v3, 0, 1
	v_bfe_i32 v96, v3, 16, 1
	v_bfe_i32 v97, v2, 1, 1
	v_bfe_i32 v98, v2, 17, 1
	v_bfe_i32 v99, v3, 1, 1
	v_bfe_i32 v104, v3, 17, 1
	v_bfe_i32 v100, v2, 2, 1
	v_bfe_i32 v101, v2, 18, 1
	v_bfe_i32 v105, v3, 2, 1
	v_bfe_i32 v106, v3, 18, 1
	v_bfe_i32 v102, v2, 3, 1
	v_bfe_i32 v103, v2, 19, 1
	v_bfe_i32 v107, v3, 3, 1
	v_bfe_i32 v108, v3, 19, 1
	v_max_f32_e32 v3, v60, v60
	v_max_f32_e32 v2, v3, v61
	v_max3_f32 v2, v2, v62, v63
	v_max3_f32 v2, v2, v72, v73
	v_max3_f32 v2, v2, v74, v75
	v_max3_f32 v2, v2, v88, v89
	v_max3_f32 v2, v2, v90, v91
	v_max3_f32 v2, v2, v80, v81
	v_max3_f32 v2, v2, v82, v83
	v_mov_b32_e32 v3, v2
	s_nop 1
	v_permlane16_swap_b32_e32 v2, v3
	v_max_f32_e32 v2, v2, v3
	v_mov_b32_e32 v3, v2
	s_nop 1
	v_permlane32_swap_b32_e32 v2, v3
	v_max_f32_e32 v3, v2, v3
	v_sub_f32_e32 v2, v80, v3
	v_sub_f32_e32 v61, v61, v3
	v_sub_f32_e32 v80, v81, v3
	v_sub_f32_e32 v81, v82, v3
	v_sub_f32_e32 v82, v83, v3
	v_sub_f32_e32 v83, v88, v3
	v_sub_f32_e32 v88, v90, v3
	v_exp_f32_e32 v90, v61
	v_exp_f32_e32 v115, v2
	v_max_f32_e32 v61, v64, v64
	v_max_f32_e32 v2, v61, v65
	v_max3_f32 v2, v2, v66, v67
	v_max3_f32 v2, v2, v68, v69
	v_max3_f32 v2, v2, v70, v71
	v_max3_f32 v2, v2, v92, v93
	v_max3_f32 v2, v2, v94, v95
	v_max3_f32 v2, v2, v76, v77
	v_max3_f32 v2, v2, v78, v79
	v_mov_b32_e32 v61, v2
	s_nop 1
	v_permlane16_swap_b32_e32 v2, v61
	v_max_f32_e32 v2, v2, v61
	v_mov_b32_e32 v61, v2
	s_nop 1
	v_permlane32_swap_b32_e32 v2, v61
	v_max_f32_e32 v2, v2, v61
	v_sub_f32_e32 v60, v60, v3
	v_sub_f32_e32 v64, v64, v2
	v_exp_f32_e32 v60, v60
	v_sub_f32_e32 v65, v65, v2
	v_exp_f32_e32 v64, v64
	v_sub_f32_e32 v62, v62, v3
	v_sub_f32_e32 v66, v66, v2
	v_exp_f32_e32 v65, v65
	v_sub_f32_e32 v85, v89, v3
	v_sub_f32_e32 v89, v91, v3
	v_sub_f32_e32 v63, v63, v3
	v_exp_f32_e32 v91, v62
	v_sub_f32_e32 v67, v67, v2
	v_exp_f32_e32 v66, v66
	v_sub_f32_e32 v72, v72, v3
	v_exp_f32_e32 v109, v63
	v_sub_f32_e32 v61, v68, v2
	v_sub_f32_e32 v62, v69, v2
	v_exp_f32_e32 v67, v67
	v_sub_f32_e32 v73, v73, v3
	v_exp_f32_e32 v72, v72
	v_exp_f32_e32 v113, v83
	v_exp_f32_e32 v125, v82
	v_sub_f32_e32 v82, v92, v2
	v_sub_f32_e32 v83, v93, v2
	v_sub_f32_e32 v63, v70, v2
	v_sub_f32_e32 v68, v71, v2
	v_exp_f32_e32 v70, v61
	v_exp_f32_e32 v71, v62
	v_and_b32_e32 v61, v0, v64
	v_and_b32_e32 v60, v0, v60
	v_and_b32_e32 v62, v97, v90
	v_sub_f32_e32 v74, v74, v3
	v_exp_f32_e32 v110, v73
	v_exp_f32_e32 v121, v80
	v_exp_f32_e32 v124, v81
	v_sub_f32_e32 v122, v76, v2
	v_sub_f32_e32 v126, v78, v2
	v_exp_f32_e32 v76, v63
	v_exp_f32_e32 v78, v68
	v_and_b32_e32 v63, v97, v65
	v_cvt_pk_bf16_f32 v68, v60, v62
	v_pk_add_f32 v[80:81], v[60:61], 0 op_sel_hi:[1,0]
	v_exp_f32_e32 v0, v82
	v_exp_f32_e32 v60, v83
	v_sub_f32_e32 v75, v75, v3
	v_exp_f32_e32 v111, v74
	v_and_b32_e32 v65, v100, v66
	v_and_b32_e32 v64, v100, v91
	v_pk_add_f32 v[80:81], v[80:81], v[62:63]
	v_exp_f32_e32 v112, v75
	v_and_b32_e32 v67, v102, v67
	v_and_b32_e32 v66, v102, v109
	v_pk_add_f32 v[80:81], v[80:81], v[64:65]
	v_sub_f32_e32 v93, v95, v2
	v_and_b32_e32 v73, v86, v70
	v_and_b32_e32 v72, v86, v72
	v_pk_add_f32 v[80:81], v[80:81], v[66:67]
	v_exp_f32_e32 v114, v85
	v_sub_f32_e32 v92, v94, v2
	v_and_b32_e32 v75, v98, v71
	v_and_b32_e32 v74, v98, v110
	v_pk_add_f32 v[80:81], v[80:81], v[72:73]
	v_and_b32_e32 v83, v87, v0
	v_and_b32_e32 v82, v87, v113
	v_and_b32_e32 v87, v99, v60
	v_exp_f32_e32 v60, v93
	v_exp_f32_e32 v88, v88
	v_sub_f32_e32 v123, v77, v2
	v_and_b32_e32 v77, v101, v76
	v_and_b32_e32 v76, v101, v111
	v_pk_add_f32 v[80:81], v[80:81], v[74:75]
	v_exp_f32_e32 v0, v92
	v_exp_f32_e32 v89, v89
	v_sub_f32_e32 v127, v79, v2
	v_and_b32_e32 v79, v103, v78
	v_and_b32_e32 v78, v103, v112
	v_pk_add_f32 v[80:81], v[80:81], v[76:77]
	v_exp_f32_e32 v62, v122
	v_pk_add_f32 v[80:81], v[80:81], v[78:79]
	v_cvt_pk_bf16_f32 v69, v64, v66
	v_and_b32_e32 v86, v99, v114
	v_exp_f32_e32 v64, v123
	v_cvt_pk_bf16_f32 v100, v61, v63
	v_cvt_pk_bf16_f32 v102, v73, v75
	v_and_b32_e32 v75, v107, v60
	v_pk_add_f32 v[60:61], v[80:81], v[82:83]
	v_cvt_pk_bf16_f32 v70, v72, v74
	v_exp_f32_e32 v66, v126
	v_and_b32_e32 v73, v105, v0
	v_and_b32_e32 v72, v105, v88
	v_pk_add_f32 v[60:61], v[60:61], v[86:87]
	v_exp_f32_e32 v90, v127
	v_and_b32_e32 v74, v107, v89
	v_pk_add_f32 v[60:61], v[60:61], v[72:73]
	v_cvt_pk_bf16_f32 v71, v76, v78
	v_cvt_pk_bf16_f32 v103, v77, v79
	v_and_b32_e32 v77, v96, v62
	v_and_b32_e32 v76, v96, v115
	v_pk_add_f32 v[60:61], v[60:61], v[74:75]
	v_and_b32_e32 v79, v104, v64
	v_and_b32_e32 v78, v104, v121
	v_pk_add_f32 v[60:61], v[60:61], v[76:77]
	v_and_b32_e32 v89, v106, v66
	v_and_b32_e32 v88, v106, v124
	v_pk_add_f32 v[60:61], v[60:61], v[78:79]
	v_and_b32_e32 v91, v108, v90
	v_and_b32_e32 v90, v108, v125
	v_pk_add_f32 v[60:61], v[60:61], v[88:89]
	v_exp_f32_e64 v84, -v3
	v_exp_f32_e64 v85, -v2
	v_cvt_pk_bf16_f32 v101, v65, v67
	v_pk_add_f32 v[80:81], v[60:61], v[90:91]
	ds_read_b128 v[60:63], v177 offset:19712
	ds_read_b128 v[64:67], v177 offset:19776
	v_pk_add_f32 v[2:3], v[2:3], 0 op_sel_hi:[1,0]
	v_pk_mul_f32 v[122:123], v[84:85], 0 op_sel_hi:[1,0]
	v_pk_fma_f32 v[160:161], v[84:85], 0, v[80:81] op_sel_hi:[1,0,1]
	v_mov_b32_e32 v126, v122
	v_mov_b32_e32 v127, v122
	v_mov_b32_e32 v128, v122
	v_mov_b32_e32 v129, v122
	v_cvt_pk_bf16_f32 v130, v82, v86
	v_cvt_pk_bf16_f32 v131, v72, v74
	v_cvt_pk_bf16_f32 v132, v76, v78
	v_cvt_pk_bf16_f32 v133, v88, v90
	v_mov_b32_e32 v122, v123
	v_mov_b32_e32 v124, v123
	v_mov_b32_e32 v125, v123
	v_cvt_pk_bf16_f32 v134, v83, v87
	v_cvt_pk_bf16_f32 v135, v73, v75
	v_cvt_pk_bf16_f32 v136, v77, v79
	v_cvt_pk_bf16_f32 v137, v89, v91
	s_waitcnt lgkmcnt(3)
; #define MMV(SRC, DT) do { __builtin_amdgcn_s_setprio(1); _Pragma("unroll") for (int c2 = 0; c2 < 2; ++c2) { o[0][DT] = mfma16(SRC[c2], pf[0][c2], o[0][DT]); o[1][DT] = mfma16(SRC[c2], pf[1][c2], o[1][DT]); } __builtin_amdgcn_s_setprio(0); } while (0)
; DEVINL void attn_item(const Params& p, int item, char* smem, int wv) {
;     ...
;     LDV(vfb, 1); MMV(vfa, 0);
;     LDV(vfa, 2); MMV(vfb, 1);
;     LDV(vfb, 3); MMV(vfa, 2);
;     LDV(vfa, 4); MMV(vfb, 3);
;     LDV(vfb, 5); MMV(vfa, 4);
;     LDV(vfa, 6); MMV(vfb, 5);
;     LDV(vfb, 7); MMV(vfa, 6);
;     MMV(vfb, 7);
	v_mfma_f32_16x16x32_bf16 v[72:75], v[52:55], v[68:71], v[126:129]
	v_mfma_f32_16x16x32_bf16 v[52:55], v[52:55], v[100:103], v[122:125]
	s_waitcnt lgkmcnt(2)
	v_mfma_f32_16x16x32_bf16 v[88:91], v[56:59], v[130:133], v[72:75]
	v_mfma_f32_16x16x32_bf16 v[52:55], v[56:59], v[134:137], v[52:55]
	s_nop 1
	s_nop 1
	ds_read_b128 v[72:75], v177 offset:22016
	ds_read_b128 v[76:79], v177 offset:22080
	s_waitcnt lgkmcnt(3)
	v_mfma_f32_16x16x32_bf16 v[56:59], v[60:63], v[68:71], v[126:129]
	v_mfma_f32_16x16x32_bf16 v[60:63], v[60:63], v[100:103], v[122:125]
	s_waitcnt lgkmcnt(2)
	v_mfma_f32_16x16x32_bf16 v[84:87], v[64:67], v[130:133], v[56:59]
	v_mfma_f32_16x16x32_bf16 v[56:59], v[64:67], v[134:137], v[60:63]
	ds_read_b128 v[64:67], v177 offset:24320
	ds_read_b128 v[80:83], v177 offset:24384
	s_waitcnt lgkmcnt(3)
	v_mfma_f32_16x16x32_bf16 v[60:63], v[72:75], v[68:71], v[126:129]
	v_mfma_f32_16x16x32_bf16 v[72:75], v[72:75], v[100:103], v[122:125]
	s_waitcnt lgkmcnt(2)
	v_mfma_f32_16x16x32_bf16 v[92:95], v[76:79], v[130:133], v[60:63]
	v_mfma_f32_16x16x32_bf16 v[60:63], v[76:79], v[134:137], v[72:75]
	s_nop 2
	s_nop 1
	ds_read_b128 v[72:75], v177 offset:26624
	ds_read_b128 v[76:79], v177 offset:26688
	s_waitcnt lgkmcnt(3)
	v_mfma_f32_16x16x32_bf16 v[96:99], v[64:67], v[68:71], v[126:129]
	v_mfma_f32_16x16x32_bf16 v[64:67], v[64:67], v[100:103], v[122:125]
	s_waitcnt lgkmcnt(2)
	v_mfma_f32_16x16x32_bf16 v[96:99], v[80:83], v[130:133], v[96:99]
	v_mfma_f32_16x16x32_bf16 v[64:67], v[80:83], v[134:137], v[64:67]
	ds_read_b128 v[80:83], v177 offset:28928
	ds_read_b128 v[112:115], v177 offset:28992
	s_waitcnt lgkmcnt(3)
	v_mfma_f32_16x16x32_bf16 v[104:107], v[72:75], v[68:71], v[126:129]
	v_mfma_f32_16x16x32_bf16 v[72:75], v[72:75], v[100:103], v[122:125]
	s_waitcnt lgkmcnt(2)
	v_mfma_f32_16x16x32_bf16 v[104:107], v[76:79], v[130:133], v[104:107]
	v_mfma_f32_16x16x32_bf16 v[72:75], v[76:79], v[134:137], v[72:75]
	ds_read_b128 v[138:141], v177 offset:31232
	ds_read_b128 v[142:145], v177 offset:31296
	s_waitcnt lgkmcnt(3)
	v_mfma_f32_16x16x32_bf16 v[76:79], v[80:83], v[68:71], v[126:129]
	v_mfma_f32_16x16x32_bf16 v[80:83], v[80:83], v[100:103], v[122:125]
	s_waitcnt lgkmcnt(2)
	v_mfma_f32_16x16x32_bf16 v[108:111], v[112:115], v[130:133], v[76:79]
	v_mfma_f32_16x16x32_bf16 v[76:79], v[112:115], v[134:137], v[80:83]
	ds_read_b128 v[146:149], v177 offset:33536
	ds_read_b128 v[150:153], v177 offset:33600
	s_waitcnt lgkmcnt(3)
	v_mfma_f32_16x16x32_bf16 v[80:83], v[138:141], v[68:71], v[126:129]
	v_mfma_f32_16x16x32_bf16 v[138:141], v[138:141], v[100:103], v[122:125]
	s_waitcnt lgkmcnt(2)
	v_mfma_f32_16x16x32_bf16 v[112:115], v[142:145], v[130:133], v[80:83]
	v_mfma_f32_16x16x32_bf16 v[80:83], v[142:145], v[134:137], v[138:141]
	s_waitcnt lgkmcnt(1)
	v_mfma_f32_16x16x32_bf16 v[68:71], v[146:149], v[68:71], v[126:129]
	v_mfma_f32_16x16x32_bf16 v[122:125], v[146:149], v[100:103], v[122:125]
	s_waitcnt lgkmcnt(0)
	v_mfma_f32_16x16x32_bf16 v[100:103], v[150:153], v[130:133], v[68:71]
	v_mfma_f32_16x16x32_bf16 v[68:71], v[150:153], v[134:137], v[122:125]
	s_cbranch_execz .LBB0_1727
	s_branch .LBB0_1728

; DEVINL float fexp2(float x) { return __builtin_amdgcn_exp2f(x); }
; #define LDK(DST, KQ) _Pragma("unroll") for (int kc = 0; kc < 4; ++kc) DST[kc] = *(const bf16x8*)(Ks + ((KQ) * 16 + fr) * 136 + kc * 32 + fq * 8)
; DEVINL void attn_item(const Params& p, int item, char* smem, int wv) {
;     ...
;     if (kt * 64 <= qlast) {
;     f32x4 s[2][4];
;     bf16x8 kfa[4], kfb[4];
;     bf16x8 vfa[2], vfb[2];
;     ...
;     LDK(kfa, 0);
;     LDK(kfb, 1); MMS(kfa, 0);
;     LDK(kfa, 2); MMS(kfb, 1);
;     LDK(kfb, 3); MMS(kfa, 2);
;     LDV(vfa, 0); MMS(kfb, 3);
;     bf16x8 pf[2][2];
;     {
;       const unsigned long long msh = mw >> (fq * 4);
;       const int mlo = (int)(unsigned)msh, mhi = (int)(unsigned)(msh >> 32);
;       int mk[4][4];
; #pragma unroll
;       for (int j = 0; j < 4; ++j) {
;         mk[0][j] = __builtin_amdgcn_sbfe(mlo, j, 1); mk[1][j] = __builtin_amdgcn_sbfe(mlo, 16 + j, 1);
;         mk[2][j] = __builtin_amdgcn_sbfe(mhi, j, 1); mk[3][j] = __builtin_amdgcn_sbfe(mhi, 16 + j, 1);
;       }
; #pragma unroll
;       for (int hh = 0; hh < 2; ++hh) {
;         float mx = s[hh][0][0];
; #pragma unroll
;         for (int kq = 0; kq < 4; ++kq)
; #pragma unroll
;           for (int j = 0; j < 4; ++j) mx = fmaxf(mx, s[hh][kq][j]);
;         {
;           auto r1 = __builtin_amdgcn_permlane16_swap(__float_as_uint(mx), __float_as_uint(mx), false, false);
;           mx = fmaxf(__uint_as_float(r1[0]), __uint_as_float(r1[1]));
;           auto r2 = __builtin_amdgcn_permlane32_swap(__float_as_uint(mx), __float_as_uint(mx), false, false);
;           mx = fmaxf(__uint_as_float(r2[0]), __uint_as_float(r2[1]));
;         }
;         if (kt == 0 || __ballot(mx > 8.f)) {
;           const float delta = (kt == 0) ? mx : fmaxf(mx, 0.f);
;           const float alpha = fexp2(-delta);
;           mrun[hh] += delta;
;           lsum[hh] *= alpha;
; #pragma unroll
;           for (int dt = 0; dt < 8; ++dt) o[hh][dt] *= alpha;
; #pragma unroll
;           for (int kq = 0; kq < 4; ++kq)
; #pragma unroll
;             for (int j = 0; j < 4; ++j) s[hh][kq][j] -= delta;
;         }
.LBB0_1731:
	s_add_i32 s6, s3, 0xffffffa0
	s_cmp_gt_i32 s6, s1
	s_cbranch_scc1 .LBB0_1737
	ds_read_b128 v[116:119], v175
	ds_read_b128 v[120:123], v175 offset:64
	ds_read_b128 v[124:127], v175 offset:128
	ds_read_b128 v[128:131], v175 offset:192
	ds_read_b128 v[132:135], v175 offset:4352
	ds_read_b128 v[140:143], v175 offset:4416
	ds_read_b128 v[144:147], v175 offset:4480
	ds_read_b128 v[178:181], v175 offset:4544
	v_xor_b32_e32 v182, 0x80000000, v3
	v_xor_b32_e32 v186, 0x80000000, v2
	v_mov_b32_e32 v183, v182
	v_mov_b32_e32 v184, v182
	v_mov_b32_e32 v185, v182
	v_mov_b32_e32 v187, v186
	v_mov_b32_e32 v188, v186
	v_mov_b32_e32 v189, v186
	s_waitcnt lgkmcnt(7)
	v_mfma_f32_16x16x32_bf16 v[136:139], v[116:119], v[32:35], v[182:185]
	v_mfma_f32_16x16x32_bf16 v[116:119], v[116:119], v[16:19], v[186:189]
	s_waitcnt lgkmcnt(6)
	v_mfma_f32_16x16x32_bf16 v[136:139], v[120:123], v[4:7], v[136:139]
	v_mfma_f32_16x16x32_bf16 v[116:119], v[120:123], v[20:23], v[116:119]
	s_waitcnt lgkmcnt(5)
	v_mfma_f32_16x16x32_bf16 v[120:123], v[124:127], v[8:11], v[136:139]
	v_mfma_f32_16x16x32_bf16 v[116:119], v[124:127], v[24:27], v[116:119]
	s_waitcnt lgkmcnt(4)
	v_mfma_f32_16x16x32_bf16 v[152:155], v[128:131], v[12:15], v[120:123]
	v_mfma_f32_16x16x32_bf16 v[136:139], v[128:131], v[28:31], v[116:119]
	s_nop 3
	s_nop 0
	ds_read_b128 v[116:119], v175 offset:8704
	ds_read_b128 v[120:123], v175 offset:8768
	ds_read_b128 v[124:127], v175 offset:8832
	ds_read_b128 v[128:131], v175 offset:8896
	s_waitcnt lgkmcnt(7)
	v_mfma_f32_16x16x32_bf16 v[148:151], v[132:135], v[32:35], v[182:185]
	v_mfma_f32_16x16x32_bf16 v[132:135], v[132:135], v[16:19], v[186:189]
	s_waitcnt lgkmcnt(6)
	v_mfma_f32_16x16x32_bf16 v[148:151], v[140:143], v[4:7], v[148:151]
	v_mfma_f32_16x16x32_bf16 v[132:135], v[140:143], v[20:23], v[132:135]
	s_waitcnt lgkmcnt(5)
	v_mfma_f32_16x16x32_bf16 v[140:143], v[144:147], v[8:11], v[148:151]
	v_mfma_f32_16x16x32_bf16 v[132:135], v[144:147], v[24:27], v[132:135]
	s_waitcnt lgkmcnt(4)
	v_mfma_f32_16x16x32_bf16 v[148:151], v[178:181], v[12:15], v[140:143]
	v_mfma_f32_16x16x32_bf16 v[132:135], v[178:181], v[28:31], v[132:135]
	ds_read_b128 v[144:147], v175 offset:13056
	ds_read_b128 v[178:181], v175 offset:13120
	ds_read_b128 v[190:193], v175 offset:13184
	ds_read_b128 v[194:197], v175 offset:13248
	s_waitcnt lgkmcnt(7)
	v_mfma_f32_16x16x32_bf16 v[140:143], v[116:119], v[32:35], v[182:185]
	v_mfma_f32_16x16x32_bf16 v[116:119], v[116:119], v[16:19], v[186:189]
	s_waitcnt lgkmcnt(6)
	v_mfma_f32_16x16x32_bf16 v[140:143], v[120:123], v[4:7], v[140:143]
	v_mfma_f32_16x16x32_bf16 v[116:119], v[120:123], v[20:23], v[116:119]
	s_waitcnt lgkmcnt(5)
	v_mfma_f32_16x16x32_bf16 v[120:123], v[124:127], v[8:11], v[140:143]
	v_mfma_f32_16x16x32_bf16 v[116:119], v[124:127], v[24:27], v[116:119]
	s_waitcnt lgkmcnt(4)
	v_mfma_f32_16x16x32_bf16 v[140:143], v[128:131], v[12:15], v[120:123]
	v_mfma_f32_16x16x32_bf16 v[124:127], v[128:131], v[28:31], v[116:119]
	s_nop 2
	s_nop 1
	ds_read_b128 v[116:119], v177 offset:17408
	ds_read_b128 v[120:123], v177 offset:17472
	s_waitcnt lgkmcnt(5)
	v_mfma_f32_16x16x32_bf16 v[128:131], v[144:147], v[32:35], v[182:185]
	v_mfma_f32_16x16x32_bf16 v[144:147], v[144:147], v[16:19], v[186:189]
	s_waitcnt lgkmcnt(4)
	v_mfma_f32_16x16x32_bf16 v[128:131], v[178:181], v[4:7], v[128:131]
	v_mfma_f32_16x16x32_bf16 v[144:147], v[178:181], v[20:23], v[144:147]
	s_waitcnt lgkmcnt(3)
	v_mfma_f32_16x16x32_bf16 v[128:131], v[190:193], v[8:11], v[128:131]
	v_mfma_f32_16x16x32_bf16 v[178:181], v[190:193], v[24:27], v[144:147]
	s_waitcnt lgkmcnt(2)
	v_mfma_f32_16x16x32_bf16 v[144:147], v[194:197], v[12:15], v[128:131]
	v_mfma_f32_16x16x32_bf16 v[128:131], v[194:197], v[28:31], v[178:181]
	s_nop 3
	s_nop 0
	v_max_f32_e32 v179, v152, v152
	v_max_f32_e32 v178, v179, v153
	v_max3_f32 v178, v178, v154, v155
	v_max3_f32 v178, v178, v148, v149
	v_max3_f32 v178, v178, v150, v151
	v_max3_f32 v178, v178, v140, v141
	v_max3_f32 v178, v178, v142, v143
	v_max3_f32 v178, v178, v144, v145
	v_max3_f32 v178, v178, v146, v147
	v_mov_b32_e32 v179, v178
	s_nop 1
	v_permlane16_swap_b32_e32 v178, v179
	v_max_f32_e32 v178, v178, v179
	v_mov_b32_e32 v179, v178
	s_nop 1
	v_permlane32_swap_b32_e32 v178, v179
	v_max_f32_e32 v178, v178, v179
	v_cmp_lt_f32_e32 vcc, s28, v178
	s_cbranch_vccz .LBB0_1734
	v_max_f32_e32 v178, 0, v178
	v_exp_f32_e64 v180, -v178
	v_add_f32_e32 v3, v3, v178
	v_pk_add_f32 v[152:153], v[152:153], v[178:179] op_sel_hi:[1,0] neg_lo:[0,1] neg_hi:[0,1]
	v_pk_add_f32 v[154:155], v[154:155], v[178:179] op_sel_hi:[1,0] neg_lo:[0,1] neg_hi:[0,1]
	v_mul_f32_e32 v160, v160, v180
	v_pk_mul_f32 v[90:91], v[90:91], v[180:181] op_sel_hi:[1,0]
	v_pk_mul_f32 v[88:89], v[88:89], v[180:181] op_sel_hi:[1,0]
	v_pk_mul_f32 v[86:87], v[86:87], v[180:181] op_sel_hi:[1,0]
	v_pk_mul_f32 v[84:85], v[84:85], v[180:181] op_sel_hi:[1,0]
	v_pk_mul_f32 v[94:95], v[94:95], v[180:181] op_sel_hi:[1,0]
	v_pk_mul_f32 v[92:93], v[92:93], v[180:181] op_sel_hi:[1,0]
	v_pk_mul_f32 v[98:99], v[98:99], v[180:181] op_sel_hi:[1,0]
	v_pk_mul_f32 v[96:97], v[96:97], v[180:181] op_sel_hi:[1,0]
	v_pk_mul_f32 v[106:107], v[106:107], v[180:181] op_sel_hi:[1,0]
	v_pk_mul_f32 v[104:105], v[104:105], v[180:181] op_sel_hi:[1,0]
	v_pk_mul_f32 v[110:111], v[110:111], v[180:181] op_sel_hi:[1,0]
	v_pk_mul_f32 v[108:109], v[108:109], v[180:181] op_sel_hi:[1,0]
	v_pk_mul_f32 v[114:115], v[114:115], v[180:181] op_sel_hi:[1,0]
	v_pk_mul_f32 v[112:113], v[112:113], v[180:181] op_sel_hi:[1,0]
	v_pk_mul_f32 v[102:103], v[102:103], v[180:181] op_sel_hi:[1,0]
	v_pk_mul_f32 v[100:101], v[100:101], v[180:181] op_sel_hi:[1,0]
	v_pk_add_f32 v[148:149], v[148:149], v[178:179] op_sel_hi:[1,0] neg_lo:[0,1] neg_hi:[0,1]
	v_pk_add_f32 v[150:151], v[150:151], v[178:179] op_sel_hi:[1,0] neg_lo:[0,1] neg_hi:[0,1]
	v_pk_add_f32 v[140:141], v[140:141], v[178:179] op_sel_hi:[1,0] neg_lo:[0,1] neg_hi:[0,1]
	v_pk_add_f32 v[142:143], v[142:143], v[178:179] op_sel_hi:[1,0] neg_lo:[0,1] neg_hi:[0,1]
	v_pk_add_f32 v[144:145], v[144:145], v[178:179] op_sel_hi:[1,0] neg_lo:[0,1] neg_hi:[0,1]
	v_pk_add_f32 v[146:147], v[146:147], v[178:179] op_sel_hi:[1,0] neg_lo:[0,1] neg_hi:[0,1]

; #define STAGE(P,BASE,LD,br,kt) do{long _g=(long)(br)*(LD)+(long)(kt)*BK; \
;     _Pragma("unroll") for(int _i=0;_i<2;++_i){int _b=tid*16+_i*8192;int _r,_c;stage_rc(_b,_r,_c); \
;       __builtin_amdgcn_global_load_lds((const unsigned*)((BASE)+_g+(long)_r*(LD)+_c), \
;         (unsigned*)((char*)(P)+_b),16,0,0);}}while(0)
; #define STAGE(P,BASE,LD,br,kt) do{long _g=(long)(br)*(LD)+(long)(kt)*BK; \
;     _Pragma("unroll") for(int _i=0;_i<2;++_i){int _b=tid*16+_i*8192;int _r,_c;stage_rc(_b,_r,_c); \
;       __builtin_amdgcn_global_load_lds((const unsigned*)((BASE)+_g+(long)_r*(LD)+_c), \
;         (unsigned*)((char*)(P)+_b),16,0,0);}}while(0)
; #define LDA(dst,b,h) _Pragma("unroll") for(int m=0;m<4;++m) _Pragma("unroll") for(int k=0;k<2;++k) \
;     dst[m][k]=*reinterpret_cast<const bf16x8*>((char*)SA(b,h)+lds_byte(wr*64+m*16+fr,k*32+fq*8))
; #define LDB(dst,b,h) _Pragma("unroll") for(int n=0;n<2;++n) _Pragma("unroll") for(int k=0;k<2;++k) \
;     dst[n][k]=*reinterpret_cast<const bf16x8*>((char*)SB(b,h)+lds_byte(wc*32+n*16+fr,k*32+fq*8))
; #define MMA(ai,bj,At_,Bt_) do{__builtin_amdgcn_s_setprio(1); \
;     _Pragma("unroll") for(int m=0;m<4;++m) _Pragma("unroll") for(int n=0;n<2;++n) _Pragma("unroll") for(int k=0;k<2;++k) \
;       acc[ai][bj][m][n]=__builtin_amdgcn_mfma_f32_16x16x32_bf16(Bt_[n][k],At_[m][k],acc[ai][bj][m][n],0,0,0); \
;     __builtin_amdgcn_s_setprio(0);}while(0)
; #define WAIT_L(n) asm volatile("s_waitcnt lgkmcnt(" #n ")":::"memory")
; #define BAR __builtin_amdgcn_s_barrier()
; #define SCHED __builtin_amdgcn_sched_barrier(0)
; DEVINL void gemm8_mainloop(const u16* A, long lda, const u16* Bt, long ldb, int K, int brow, int bcol, f32x4 (&acc)[2][2][4][2], char* smem, int tid) {
;     ...
;   for(int t=0;t<nt-2;t+=2){
;     LDB(B0,0,0); SCHED; LDA(At,0,0); STAGE(SA(1,1),A,lda,brow+HALF,t+1);
;     WAIT_L(8); BAR; WAIT_L(0); MMA(0,0,At,B0); BAR; SCHED;
;     LDB(B1,0,1); STAGE(SB(0,0),Bt,ldb,bcol,t+2);
;     BAR; WAIT_L(0); MMA(0,1,At,B1); BAR;
;     LDA(At,0,1); STAGE(SA(0,0),A,lda,brow,t+2);
;     BAR; WAIT_L(0); MMA(1,0,At,B0); BAR; SCHED;
;     STAGE(SB(0,1),Bt,ldb,bcol+HALF,t+2);
.LBB0_1871:
	ds_read_b128 v[178:181], v163
	ds_read_b128 v[182:185], v163 offset:1024
	ds_read_b128 v[186:189], v163 offset:2048
	ds_read_b128 v[190:193], v163 offset:3072
	v_add_u32_e32 v174, 0xc000, v152
	v_lshl_add_u64 v[242:243], s[94:95], 0, v[146:147]
	v_readfirstlane_b32 s27, v174
	v_add_u32_e32 v175, 0xe000, v152
	v_add_u32_e32 v171, s25, v162
	v_add_u32_e32 v172, s37, v162
	v_add_u32_e32 v173, s38, v162
	v_lshl_add_u64 v[164:165], v[242:243], 0, s[2:3]
	s_mov_b32 m0, s27
	v_lshl_add_u64 v[244:245], s[94:95], 0, v[148:149]
	v_readfirstlane_b32 s27, v175
	ds_read_b128 v[166:169], v153
	ds_read_b128 v[194:197], v153 offset:1024
	ds_read_b128 v[198:201], v171
	ds_read_b128 v[202:205], v171 offset:1024
	ds_read_b128 v[206:209], v172
	ds_read_b128 v[210:213], v172 offset:1024
	ds_read_b128 v[214:217], v173
	ds_read_b128 v[218:221], v173 offset:1024
	global_load_lds_dwordx4 v[164:165], off
	v_lshl_add_u64 v[164:165], v[244:245], 0, s[2:3]
	s_mov_b32 m0, s27
	s_nop 0
	global_load_lds_dwordx4 v[164:165], off
	s_waitcnt lgkmcnt(8)
	s_barrier
	s_waitcnt lgkmcnt(0)
	s_setprio 1
	v_mfma_f32_16x16x32_bf16 v[124:127], v[178:181], v[166:169], v[124:127]
	v_mfma_f32_16x16x32_bf16 v[120:123], v[186:189], v[166:169], v[120:123]
	v_mfma_f32_16x16x32_bf16 v[116:119], v[178:181], v[198:201], v[116:119]
	v_mfma_f32_16x16x32_bf16 v[112:115], v[186:189], v[198:201], v[112:115]
	v_mfma_f32_16x16x32_bf16 v[108:111], v[178:181], v[206:209], v[108:111]
	v_mfma_f32_16x16x32_bf16 v[104:107], v[186:189], v[206:209], v[104:107]
	v_mfma_f32_16x16x32_bf16 v[100:103], v[178:181], v[214:217], v[100:103]
	v_mfma_f32_16x16x32_bf16 v[96:99], v[186:189], v[214:217], v[96:99]
	v_mfma_f32_16x16x32_bf16 v[124:127], v[182:185], v[194:197], v[124:127]
	v_mfma_f32_16x16x32_bf16 v[120:123], v[190:193], v[194:197], v[120:123]
	v_mfma_f32_16x16x32_bf16 v[116:119], v[182:185], v[202:205], v[116:119]
	v_mfma_f32_16x16x32_bf16 v[112:115], v[190:193], v[202:205], v[112:115]
	v_mfma_f32_16x16x32_bf16 v[108:111], v[182:185], v[210:213], v[108:111]
	v_mfma_f32_16x16x32_bf16 v[104:107], v[190:193], v[210:213], v[104:107]
	v_mfma_f32_16x16x32_bf16 v[100:103], v[182:185], v[218:221], v[100:103]
	v_mfma_f32_16x16x32_bf16 v[96:99], v[190:193], v[218:221], v[96:99]
	s_setprio 0
	s_barrier
	v_add_u32_e32 v164, s30, v154
	v_lshl_add_u64 v[246:247], s[94:95], 0, v[142:143]
	v_readfirstlane_b32 s27, v164
	v_add_u32_e32 v165, 0x2000, v164
	v_lshl_add_u64 v[238:239], v[246:247], 0, s[4:5]
	s_mov_b32 m0, s27
	v_lshl_add_u64 v[248:249], s[94:95], 0, v[144:145]
	v_readfirstlane_b32 s27, v165
	ds_read_b128 v[222:225], v160
	ds_read_b128 v[226:229], v160 offset:1024
	ds_read_b128 v[230:233], v160 offset:2048
	ds_read_b128 v[234:237], v160 offset:3072
	global_load_lds_dwordx4 v[238:239], off
	v_lshl_add_u64 v[238:239], v[248:249], 0, s[4:5]
	s_mov_b32 m0, s27
	s_nop 0
	global_load_lds_dwordx4 v[238:239], off
	s_barrier
	s_waitcnt lgkmcnt(0)
	s_setprio 1
	v_mfma_f32_16x16x32_bf16 v[92:95], v[222:225], v[166:169], v[92:95]
	v_mfma_f32_16x16x32_bf16 v[88:91], v[230:233], v[166:169], v[88:91]
	v_mfma_f32_16x16x32_bf16 v[84:87], v[222:225], v[198:201], v[84:87]
	v_mfma_f32_16x16x32_bf16 v[80:83], v[230:233], v[198:201], v[80:83]
	v_mfma_f32_16x16x32_bf16 v[76:79], v[222:225], v[206:209], v[76:79]
	v_mfma_f32_16x16x32_bf16 v[72:75], v[230:233], v[206:209], v[72:75]
	v_mfma_f32_16x16x32_bf16 v[68:71], v[222:225], v[214:217], v[68:71]
	v_mfma_f32_16x16x32_bf16 v[64:67], v[230:233], v[214:217], v[64:67]
	v_mfma_f32_16x16x32_bf16 v[92:95], v[226:229], v[194:197], v[92:95]
	v_mfma_f32_16x16x32_bf16 v[88:91], v[234:237], v[194:197], v[88:91]
	v_mfma_f32_16x16x32_bf16 v[84:87], v[226:229], v[202:205], v[84:87]
	v_mfma_f32_16x16x32_bf16 v[80:83], v[234:237], v[202:205], v[80:83]
	v_mfma_f32_16x16x32_bf16 v[76:79], v[226:229], v[210:213], v[76:79]
	v_mfma_f32_16x16x32_bf16 v[72:75], v[234:237], v[210:213], v[72:75]
	v_mfma_f32_16x16x32_bf16 v[68:71], v[226:229], v[218:221], v[68:71]
	v_mfma_f32_16x16x32_bf16 v[64:67], v[234:237], v[218:221], v[64:67]
	s_setprio 0
	v_readfirstlane_b32 s27, v152
	v_lshl_add_u64 v[166:167], v[242:243], 0, s[6:7]
	s_mov_b32 m0, s27
	s_barrier
	ds_read_b128 v[194:197], v153 offset:16384
	ds_read_b128 v[198:201], v153 offset:17408
	ds_read_b128 v[202:205], v171 offset:16384
	ds_read_b128 v[206:209], v171 offset:17408
	ds_read_b128 v[210:213], v172 offset:16384
	ds_read_b128 v[214:217], v172 offset:17408
	ds_read_b128 v[218:221], v173 offset:16384
	ds_read_b128 v[238:241], v173 offset:17408
	global_load_lds_dwordx4 v[166:167], off
	v_add_u32_e32 v166, 0x2000, v152
	v_lshl_add_u64 v[168:169], v[244:245], 0, s[6:7]
	v_readfirstlane_b32 s27, v166
	s_mov_b32 m0, s27
	s_nop 0
	global_load_lds_dwordx4 v[168:169], off
	s_barrier
	s_waitcnt lgkmcnt(0)
	s_setprio 1
	v_mfma_f32_16x16x32_bf16 v[60:63], v[178:181], v[194:197], v[60:63]
	v_mfma_f32_16x16x32_bf16 v[56:59], v[186:189], v[194:197], v[56:59]
	v_mfma_f32_16x16x32_bf16 v[52:55], v[178:181], v[202:205], v[52:55]
	v_mfma_f32_16x16x32_bf16 v[48:51], v[186:189], v[202:205], v[48:51]
	v_mfma_f32_16x16x32_bf16 v[44:47], v[178:181], v[210:213], v[44:47]
	v_mfma_f32_16x16x32_bf16 v[40:43], v[186:189], v[210:213], v[40:43]
	v_mfma_f32_16x16x32_bf16 v[36:39], v[178:181], v[218:221], v[36:39]
	v_mfma_f32_16x16x32_bf16 v[32:35], v[186:189], v[218:221], v[32:35]
	v_mfma_f32_16x16x32_bf16 v[60:63], v[182:185], v[198:201], v[60:63]
	v_mfma_f32_16x16x32_bf16 v[56:59], v[190:193], v[198:201], v[56:59]
	v_mfma_f32_16x16x32_bf16 v[52:55], v[182:185], v[206:209], v[52:55]
	v_mfma_f32_16x16x32_bf16 v[48:51], v[190:193], v[206:209], v[48:51]
	v_mfma_f32_16x16x32_bf16 v[44:47], v[182:185], v[214:217], v[44:47]
	v_mfma_f32_16x16x32_bf16 v[40:43], v[190:193], v[214:217], v[40:43]
	v_mfma_f32_16x16x32_bf16 v[36:39], v[182:185], v[238:241], v[36:39]
	v_mfma_f32_16x16x32_bf16 v[32:35], v[190:193], v[238:241], v[32:35]
	s_setprio 0
	s_barrier
; #define STAGE(P,BASE,LD,br,kt) do{long _g=(long)(br)*(LD)+(long)(kt)*BK; \
;     _Pragma("unroll") for(int _i=0;_i<2;++_i){int _b=tid*16+_i*8192;int _r,_c;stage_rc(_b,_r,_c); \
;       __builtin_amdgcn_global_load_lds((const unsigned*)((BASE)+_g+(long)_r*(LD)+_c), \
;         (unsigned*)((char*)(P)+_b),16,0,0);}}while(0)
; #define STAGE(P,BASE,LD,br,kt) do{long _g=(long)(br)*(LD)+(long)(kt)*BK; \
;     _Pragma("unroll") for(int _i=0;_i<2;++_i){int _b=tid*16+_i*8192;int _r,_c;stage_rc(_b,_r,_c); \
;       __builtin_amdgcn_global_load_lds((const unsigned*)((BASE)+_g+(long)_r*(LD)+_c), \
;         (unsigned*)((char*)(P)+_b),16,0,0);}}while(0)
; #define LDA(dst,b,h) _Pragma("unroll") for(int m=0;m<4;++m) _Pragma("unroll") for(int k=0;k<2;++k) \
;     dst[m][k]=*reinterpret_cast<const bf16x8*>((char*)SA(b,h)+lds_byte(wr*64+m*16+fr,k*32+fq*8))
; #define LDB(dst,b,h) _Pragma("unroll") for(int n=0;n<2;++n) _Pragma("unroll") for(int k=0;k<2;++k) \
;     dst[n][k]=*reinterpret_cast<const bf16x8*>((char*)SB(b,h)+lds_byte(wc*32+n*16+fr,k*32+fq*8))
; #define MMA(ai,bj,At_,Bt_) do{__builtin_amdgcn_s_setprio(1); \
;     _Pragma("unroll") for(int m=0;m<4;++m) _Pragma("unroll") for(int n=0;n<2;++n) _Pragma("unroll") for(int k=0;k<2;++k) \
;       acc[ai][bj][m][n]=__builtin_amdgcn_mfma_f32_16x16x32_bf16(Bt_[n][k],At_[m][k],acc[ai][bj][m][n],0,0,0); \
;     __builtin_amdgcn_s_setprio(0);}while(0)
; #define WAIT_V(n) asm volatile("s_waitcnt vmcnt(" #n ")":::"memory")
; #define WAIT_L(n) asm volatile("s_waitcnt lgkmcnt(" #n ")":::"memory")
; #define BAR __builtin_amdgcn_s_barrier()
; #define SCHED __builtin_amdgcn_sched_barrier(0)
; DEVINL void gemm8_mainloop(const u16* A, long lda, const u16* Bt, long ldb, int K, int brow, int bcol, f32x4 (&acc)[2][2][4][2], char* smem, int tid) {
;     ...
;     STAGE(SB(0,1),Bt,ldb,bcol+HALF,t+2);
;     WAIT_V(6); BAR; MMA(1,1,At,B1); BAR;
;     LDB(B0,1,0); SCHED; LDA(At,1,0); STAGE(SA(0,1),A,lda,brow+HALF,t+2);
;     WAIT_L(8); BAR; WAIT_L(0); MMA(0,0,At,B0); BAR; SCHED;
;     LDB(B1,1,1); STAGE(SB(1,0),Bt,ldb,bcol,t+3);
;     BAR; WAIT_L(0); MMA(0,1,At,B1); BAR;
;     LDA(At,1,1); STAGE(SA(1,0),A,lda,brow,t+3);
	v_add_u32_e32 v167, s31, v154
	v_lshl_add_u64 v[168:169], v[246:247], 0, s[8:9]
	v_readfirstlane_b32 s27, v167
	s_mov_b32 m0, s27
	v_lshl_add_u64 v[178:179], v[248:249], 0, s[8:9]
	global_load_lds_dwordx4 v[168:169], off
	v_add_u32_e32 v168, 0x2000, v167
	s_nop 0
	v_readfirstlane_b32 s27, v168
	s_mov_b32 m0, s27
	s_nop 0
	global_load_lds_dwordx4 v[178:179], off
	s_waitcnt vmcnt(6)
	s_barrier
	s_setprio 1
	v_mfma_f32_16x16x32_bf16 v[28:31], v[222:225], v[194:197], v[28:31]
	v_mfma_f32_16x16x32_bf16 v[24:27], v[230:233], v[194:197], v[24:27]
	v_mfma_f32_16x16x32_bf16 v[20:23], v[222:225], v[202:205], v[20:23]
	v_mfma_f32_16x16x32_bf16 v[16:19], v[230:233], v[202:205], v[16:19]
	v_mfma_f32_16x16x32_bf16 v[12:15], v[222:225], v[210:213], v[12:15]
	v_mfma_f32_16x16x32_bf16 v[8:11], v[230:233], v[210:213], v[8:11]
	v_mfma_f32_16x16x32_bf16 v[4:7], v[222:225], v[218:221], v[4:7]
	v_mfma_f32_16x16x32_bf16 v[0:3], v[230:233], v[218:221], v[0:3]
	v_mfma_f32_16x16x32_bf16 v[28:31], v[226:229], v[198:201], v[28:31]
	v_mfma_f32_16x16x32_bf16 v[24:27], v[234:237], v[198:201], v[24:27]
	v_mfma_f32_16x16x32_bf16 v[20:23], v[226:229], v[206:209], v[20:23]
	v_mfma_f32_16x16x32_bf16 v[16:19], v[234:237], v[206:209], v[16:19]
	v_mfma_f32_16x16x32_bf16 v[12:15], v[226:229], v[214:217], v[12:15]
	v_mfma_f32_16x16x32_bf16 v[8:11], v[234:237], v[214:217], v[8:11]
	v_mfma_f32_16x16x32_bf16 v[4:7], v[226:229], v[238:241], v[4:7]
	v_mfma_f32_16x16x32_bf16 v[0:3], v[234:237], v[238:241], v[0:3]
	s_setprio 0
	s_barrier
	ds_read_b128 v[178:181], v156
	ds_read_b128 v[182:185], v156 offset:1024
	ds_read_b128 v[186:189], v156 offset:2048
	ds_read_b128 v[190:193], v156 offset:3072
	v_add_u32_e32 v169, 0x4000, v152
	v_add_u32_e32 v170, 0x6000, v152
	v_readfirstlane_b32 s27, v169
	v_lshl_add_u64 v[226:227], v[242:243], 0, s[10:11]
	s_mov_b32 m0, s27
	v_readfirstlane_b32 s27, v170
	ds_read_b128 v[194:197], v153 offset:32768
	ds_read_b128 v[198:201], v153 offset:33792
	ds_read_b128 v[202:205], v171 offset:32768
	ds_read_b128 v[206:209], v171 offset:33792
	ds_read_b128 v[210:213], v172 offset:32768
	ds_read_b128 v[214:217], v172 offset:33792
	ds_read_b128 v[218:221], v173 offset:32768
	ds_read_b128 v[222:225], v173 offset:33792
	global_load_lds_dwordx4 v[226:227], off
	v_lshl_add_u64 v[226:227], v[244:245], 0, s[10:11]
	s_mov_b32 m0, s27
	s_nop 0
	global_load_lds_dwordx4 v[226:227], off
	s_waitcnt lgkmcnt(8)
	s_barrier
	s_waitcnt lgkmcnt(0)
	s_setprio 1
	v_mfma_f32_16x16x32_bf16 v[124:127], v[178:181], v[194:197], v[124:127]
	v_mfma_f32_16x16x32_bf16 v[120:123], v[186:189], v[194:197], v[120:123]
	v_mfma_f32_16x16x32_bf16 v[116:119], v[178:181], v[202:205], v[116:119]
	v_mfma_f32_16x16x32_bf16 v[112:115], v[186:189], v[202:205], v[112:115]
	v_mfma_f32_16x16x32_bf16 v[108:111], v[178:181], v[210:213], v[108:111]
	v_mfma_f32_16x16x32_bf16 v[104:107], v[186:189], v[210:213], v[104:107]
	v_mfma_f32_16x16x32_bf16 v[100:103], v[178:181], v[218:221], v[100:103]
	v_mfma_f32_16x16x32_bf16 v[96:99], v[186:189], v[218:221], v[96:99]
	v_mfma_f32_16x16x32_bf16 v[124:127], v[182:185], v[198:201], v[124:127]
	v_mfma_f32_16x16x32_bf16 v[120:123], v[190:193], v[198:201], v[120:123]
	v_mfma_f32_16x16x32_bf16 v[116:119], v[182:185], v[206:209], v[116:119]
	v_mfma_f32_16x16x32_bf16 v[112:115], v[190:193], v[206:209], v[112:115]
	v_mfma_f32_16x16x32_bf16 v[108:111], v[182:185], v[214:217], v[108:111]
	v_mfma_f32_16x16x32_bf16 v[104:107], v[190:193], v[214:217], v[104:107]
	v_mfma_f32_16x16x32_bf16 v[100:103], v[182:185], v[222:225], v[100:103]
	v_mfma_f32_16x16x32_bf16 v[96:99], v[190:193], v[222:225], v[96:99]
	s_setprio 0
	s_barrier
	v_readfirstlane_b32 s27, v157
	v_add_u32_e32 v177, 0x2000, v157
	v_lshl_add_u64 v[250:251], v[246:247], 0, s[12:13]
	s_mov_b32 m0, s27
	v_readfirstlane_b32 s27, v177
	ds_read_b128 v[226:229], v155
	ds_read_b128 v[230:233], v155 offset:1024
	ds_read_b128 v[234:237], v155 offset:2048
	ds_read_b128 v[238:241], v155 offset:3072
	global_load_lds_dwordx4 v[250:251], off
	v_lshl_add_u64 v[250:251], v[248:249], 0, s[12:13]
	s_mov_b32 m0, s27
	s_nop 0
	global_load_lds_dwordx4 v[250:251], off
	s_barrier
	s_waitcnt lgkmcnt(0)
	s_setprio 1
	v_mfma_f32_16x16x32_bf16 v[92:95], v[226:229], v[194:197], v[92:95]
	v_mfma_f32_16x16x32_bf16 v[88:91], v[234:237], v[194:197], v[88:91]
	v_mfma_f32_16x16x32_bf16 v[84:87], v[226:229], v[202:205], v[84:87]
	v_mfma_f32_16x16x32_bf16 v[80:83], v[234:237], v[202:205], v[80:83]
	v_mfma_f32_16x16x32_bf16 v[76:79], v[226:229], v[210:213], v[76:79]
	v_mfma_f32_16x16x32_bf16 v[72:75], v[234:237], v[210:213], v[72:75]
	v_mfma_f32_16x16x32_bf16 v[68:71], v[226:229], v[218:221], v[68:71]
	v_mfma_f32_16x16x32_bf16 v[64:67], v[234:237], v[218:221], v[64:67]
	v_mfma_f32_16x16x32_bf16 v[92:95], v[230:233], v[198:201], v[92:95]
	v_mfma_f32_16x16x32_bf16 v[88:91], v[238:241], v[198:201], v[88:91]
	v_mfma_f32_16x16x32_bf16 v[84:87], v[230:233], v[206:209], v[84:87]
	v_mfma_f32_16x16x32_bf16 v[80:83], v[238:241], v[206:209], v[80:83]
	v_mfma_f32_16x16x32_bf16 v[76:79], v[230:233], v[214:217], v[76:79]
	v_mfma_f32_16x16x32_bf16 v[72:75], v[238:241], v[214:217], v[72:75]
	v_mfma_f32_16x16x32_bf16 v[68:71], v[230:233], v[222:225], v[68:71]
	v_mfma_f32_16x16x32_bf16 v[64:67], v[238:241], v[222:225], v[64:67]
	s_setprio 0
	v_readfirstlane_b32 s27, v158
	v_lshl_add_u64 v[242:243], v[242:243], 0, s[14:15]
	s_mov_b32 m0, s27
	v_readfirstlane_b32 s27, v159
	s_barrier
; #define STAGE(P,BASE,LD,br,kt) do{long _g=(long)(br)*(LD)+(long)(kt)*BK; \
;     _Pragma("unroll") for(int _i=0;_i<2;++_i){int _b=tid*16+_i*8192;int _r,_c;stage_rc(_b,_r,_c); \
;       __builtin_amdgcn_global_load_lds((const unsigned*)((BASE)+_g+(long)_r*(LD)+_c), \
;         (unsigned*)((char*)(P)+_b),16,0,0);}}while(0)
; #define STAGE(P,BASE,LD,br,kt) do{long _g=(long)(br)*(LD)+(long)(kt)*BK; \
;     _Pragma("unroll") for(int _i=0;_i<2;++_i){int _b=tid*16+_i*8192;int _r,_c;stage_rc(_b,_r,_c); \
;       __builtin_amdgcn_global_load_lds((const unsigned*)((BASE)+_g+(long)_r*(LD)+_c), \
;         (unsigned*)((char*)(P)+_b),16,0,0);}}while(0)
; #define LDA(dst,b,h) _Pragma("unroll") for(int m=0;m<4;++m) _Pragma("unroll") for(int k=0;k<2;++k) \
;     dst[m][k]=*reinterpret_cast<const bf16x8*>((char*)SA(b,h)+lds_byte(wr*64+m*16+fr,k*32+fq*8))
; #define LDB(dst,b,h) _Pragma("unroll") for(int n=0;n<2;++n) _Pragma("unroll") for(int k=0;k<2;++k) \
;     dst[n][k]=*reinterpret_cast<const bf16x8*>((char*)SB(b,h)+lds_byte(wc*32+n*16+fr,k*32+fq*8))
; #define MMA(ai,bj,At_,Bt_) do{__builtin_amdgcn_s_setprio(1); \
;     _Pragma("unroll") for(int m=0;m<4;++m) _Pragma("unroll") for(int n=0;n<2;++n) _Pragma("unroll") for(int k=0;k<2;++k) \
;       acc[ai][bj][m][n]=__builtin_amdgcn_mfma_f32_16x16x32_bf16(Bt_[n][k],At_[m][k],acc[ai][bj][m][n],0,0,0); \
;     __builtin_amdgcn_s_setprio(0);}while(0)
; #define WAIT_V(n) asm volatile("s_waitcnt vmcnt(" #n ")":::"memory")
; #define WAIT_L(n) asm volatile("s_waitcnt lgkmcnt(" #n ")":::"memory")
; #define BAR __builtin_amdgcn_s_barrier()
; #define SCHED __builtin_amdgcn_sched_barrier(0)
; DEVINL void gemm8_mainloop(const u16* A, long lda, const u16* Bt, long ldb, int K, int brow, int bcol, f32x4 (&acc)[2][2][4][2], char* smem, int tid) {
;     ...
;     LDA(At,1,1); STAGE(SA(1,0),A,lda,brow,t+3);
;     BAR; WAIT_L(0); MMA(1,0,At,B0); BAR; SCHED;
;     STAGE(SB(1,1),Bt,ldb,bcol+HALF,t+3);
;     WAIT_V(6); BAR; MMA(1,1,At,B1); BAR;
;   }
;   { LDB(B0,0,0); LDA(At,0,0); STAGE(SA(1,1),A,lda,brow+HALF,nt-1);
;     BAR; WAIT_L(0); MMA(0,0,At,B0); BAR;
	ds_read_b128 v[194:197], v153 offset:49152
	ds_read_b128 v[198:201], v153 offset:50176
	ds_read_b128 v[202:205], v171 offset:49152
	ds_read_b128 v[206:209], v171 offset:50176
	ds_read_b128 v[210:213], v172 offset:49152
	ds_read_b128 v[214:217], v172 offset:50176
	ds_read_b128 v[218:221], v173 offset:49152
	ds_read_b128 v[222:225], v173 offset:50176
	global_load_lds_dwordx4 v[242:243], off
	v_lshl_add_u64 v[242:243], v[244:245], 0, s[14:15]
	s_mov_b32 m0, s27
	s_nop 0
	global_load_lds_dwordx4 v[242:243], off
	s_barrier
	s_waitcnt lgkmcnt(0)
	s_setprio 1
	v_mfma_f32_16x16x32_bf16 v[60:63], v[178:181], v[194:197], v[60:63]
	v_mfma_f32_16x16x32_bf16 v[56:59], v[186:189], v[194:197], v[56:59]
	v_mfma_f32_16x16x32_bf16 v[52:55], v[178:181], v[202:205], v[52:55]
	v_mfma_f32_16x16x32_bf16 v[48:51], v[186:189], v[202:205], v[48:51]
	v_mfma_f32_16x16x32_bf16 v[44:47], v[178:181], v[210:213], v[44:47]
	v_mfma_f32_16x16x32_bf16 v[40:43], v[186:189], v[210:213], v[40:43]
	v_mfma_f32_16x16x32_bf16 v[36:39], v[178:181], v[218:221], v[36:39]
	v_mfma_f32_16x16x32_bf16 v[32:35], v[186:189], v[218:221], v[32:35]
	v_mfma_f32_16x16x32_bf16 v[60:63], v[182:185], v[198:201], v[60:63]
	v_mfma_f32_16x16x32_bf16 v[56:59], v[190:193], v[198:201], v[56:59]
	v_mfma_f32_16x16x32_bf16 v[52:55], v[182:185], v[206:209], v[52:55]
	v_mfma_f32_16x16x32_bf16 v[48:51], v[190:193], v[206:209], v[48:51]
	v_mfma_f32_16x16x32_bf16 v[44:47], v[182:185], v[214:217], v[44:47]
	v_mfma_f32_16x16x32_bf16 v[40:43], v[190:193], v[214:217], v[40:43]
	v_mfma_f32_16x16x32_bf16 v[36:39], v[182:185], v[222:225], v[36:39]
	v_mfma_f32_16x16x32_bf16 v[32:35], v[190:193], v[222:225], v[32:35]
	s_setprio 0
	s_barrier
	v_readfirstlane_b32 s27, v161
	v_add_u32_e32 v177, 0x2000, v161
	v_lshl_add_u64 v[178:179], v[246:247], 0, s[16:17]
	s_mov_b32 m0, s27
	v_readfirstlane_b32 s27, v177
	global_load_lds_dwordx4 v[178:179], off
	v_lshl_add_u64 v[178:179], v[248:249], 0, s[16:17]
	s_mov_b32 m0, s27
	s_nop 0
	global_load_lds_dwordx4 v[178:179], off
	s_waitcnt vmcnt(6)
	s_barrier
	s_setprio 1
	v_mfma_f32_16x16x32_bf16 v[28:31], v[226:229], v[194:197], v[28:31]
	v_mfma_f32_16x16x32_bf16 v[24:27], v[234:237], v[194:197], v[24:27]
	v_mfma_f32_16x16x32_bf16 v[20:23], v[226:229], v[202:205], v[20:23]
	v_mfma_f32_16x16x32_bf16 v[16:19], v[234:237], v[202:205], v[16:19]
	v_mfma_f32_16x16x32_bf16 v[12:15], v[226:229], v[210:213], v[12:15]
	v_mfma_f32_16x16x32_bf16 v[8:11], v[234:237], v[210:213], v[8:11]
	v_mfma_f32_16x16x32_bf16 v[4:7], v[226:229], v[218:221], v[4:7]
	v_mfma_f32_16x16x32_bf16 v[0:3], v[234:237], v[218:221], v[0:3]
	v_mfma_f32_16x16x32_bf16 v[28:31], v[230:233], v[198:201], v[28:31]
	v_mfma_f32_16x16x32_bf16 v[24:27], v[238:241], v[198:201], v[24:27]
	v_mfma_f32_16x16x32_bf16 v[20:23], v[230:233], v[206:209], v[20:23]
	v_mfma_f32_16x16x32_bf16 v[16:19], v[238:241], v[206:209], v[16:19]
	v_mfma_f32_16x16x32_bf16 v[12:15], v[230:233], v[214:217], v[12:15]
	v_mfma_f32_16x16x32_bf16 v[8:11], v[238:241], v[214:217], v[8:11]
	v_mfma_f32_16x16x32_bf16 v[4:7], v[230:233], v[222:225], v[4:7]
	v_mfma_f32_16x16x32_bf16 v[0:3], v[238:241], v[222:225], v[0:3]
	s_setprio 0
	s_add_i32 s26, s26, 2
	v_lshl_add_u64 v[142:143], v[142:143], 0, s[18:19]
	v_lshl_add_u64 v[144:145], v[144:145], 0, s[18:19]
	v_lshl_add_u64 v[146:147], v[146:147], 0, s[18:19]
	s_cmp_lt_u32 s26, 28
	v_lshl_add_u64 v[148:149], v[148:149], 0, s[18:19]
	s_barrier
	s_cbranch_scc1 .LBB0_1871
	s_or_b32 s26, s24, 0x80
	s_ashr_i32 s27, s26, 31
	s_lshl_b64 s[26:27], s[26:27], 12
	s_add_u32 s26, s47, s26
	s_addc_u32 s27, s48, s27
	v_lshl_add_u64 v[158:159], v[134:135], 1, s[26:27]
	v_lshl_add_u64 v[138:139], v[138:139], 1, v[158:159]
	v_readfirstlane_b32 s25, v174
	v_lshl_add_u64 v[138:139], v[138:139], 0, s[20:21]
	s_mov_b32 m0, s25
	ds_read_b128 v[142:145], v163
	ds_read_b128 v[146:149], v163 offset:1024
	ds_read_b128 v[178:181], v163 offset:2048
	ds_read_b128 v[182:185], v163 offset:3072
	ds_read_b128 v[186:189], v153
	ds_read_b128 v[190:193], v153 offset:1024
	ds_read_b128 v[194:197], v171
	ds_read_b128 v[198:201], v171 offset:1024
	ds_read_b128 v[202:205], v172
	ds_read_b128 v[206:209], v172 offset:1024
	ds_read_b128 v[210:213], v173
	ds_read_b128 v[214:217], v173 offset:1024
	global_load_lds_dwordx4 v[138:139], off
	v_lshl_add_u64 v[138:139], v[136:137], 1, s[26:27]
	v_lshl_add_u64 v[138:139], v[140:141], 1, v[138:139]
	v_readfirstlane_b32 s25, v175
	v_lshl_add_u64 v[138:139], v[138:139], 0, s[20:21]
	s_mov_b32 m0, s25
	s_nop 0
	global_load_lds_dwordx4 v[138:139], off
	s_barrier
	s_waitcnt lgkmcnt(0)
	s_setprio 1
	v_mfma_f32_16x16x32_bf16 v[124:127], v[142:145], v[186:189], v[124:127]
	v_mfma_f32_16x16x32_bf16 v[120:123], v[178:181], v[186:189], v[120:123]
	v_mfma_f32_16x16x32_bf16 v[116:119], v[142:145], v[194:197], v[116:119]
	v_mfma_f32_16x16x32_bf16 v[112:115], v[178:181], v[194:197], v[112:115]
	v_mfma_f32_16x16x32_bf16 v[100:103], v[142:145], v[210:213], v[100:103]
	v_mfma_f32_16x16x32_bf16 v[96:99], v[178:181], v[210:213], v[96:99]
	v_mfma_f32_16x16x32_bf16 v[124:127], v[146:149], v[190:193], v[124:127]
	v_mfma_f32_16x16x32_bf16 v[120:123], v[182:185], v[190:193], v[120:123]
	v_mfma_f32_16x16x32_bf16 v[116:119], v[146:149], v[198:201], v[116:119]
	v_mfma_f32_16x16x32_bf16 v[112:115], v[182:185], v[198:201], v[112:115]
	v_mfma_f32_16x16x32_bf16 v[108:111], v[142:145], v[202:205], v[108:111]
	v_mfma_f32_16x16x32_bf16 v[104:107], v[178:181], v[202:205], v[104:107]
	v_mfma_f32_16x16x32_bf16 v[100:103], v[146:149], v[214:217], v[100:103]
	v_mfma_f32_16x16x32_bf16 v[96:99], v[182:185], v[214:217], v[96:99]
	v_mfma_f32_16x16x32_bf16 v[138:141], v[146:149], v[206:209], v[108:111]
	v_mfma_f32_16x16x32_bf16 v[218:221], v[182:185], v[206:209], v[104:107]
	s_setprio 0
	s_barrier
; #define LDA(dst,b,h) _Pragma("unroll") for(int m=0;m<4;++m) _Pragma("unroll") for(int k=0;k<2;++k) \
;     dst[m][k]=*reinterpret_cast<const bf16x8*>((char*)SA(b,h)+lds_byte(wr*64+m*16+fr,k*32+fq*8))
; #define LDB(dst,b,h) _Pragma("unroll") for(int n=0;n<2;++n) _Pragma("unroll") for(int k=0;k<2;++k) \
;     dst[n][k]=*reinterpret_cast<const bf16x8*>((char*)SB(b,h)+lds_byte(wc*32+n*16+fr,k*32+fq*8))
; #define MMA(ai,bj,At_,Bt_) do{__builtin_amdgcn_s_setprio(1); \
;     _Pragma("unroll") for(int m=0;m<4;++m) _Pragma("unroll") for(int n=0;n<2;++n) _Pragma("unroll") for(int k=0;k<2;++k) \
;       acc[ai][bj][m][n]=__builtin_amdgcn_mfma_f32_16x16x32_bf16(Bt_[n][k],At_[m][k],acc[ai][bj][m][n],0,0,0); \
;     __builtin_amdgcn_s_setprio(0);}while(0)
; #define WAIT_V(n) asm volatile("s_waitcnt vmcnt(" #n ")":::"memory")
; #define WAIT_L(n) asm volatile("s_waitcnt lgkmcnt(" #n ")":::"memory")
; #define BAR __builtin_amdgcn_s_barrier()
; DEVINL void gemm8_mainloop(const u16* A, long lda, const u16* Bt, long ldb, int K, int brow, int bcol, f32x4 (&acc)[2][2][4][2], char* smem, int tid) {
;     ...
;     BAR; WAIT_L(0); MMA(0,0,At,B0); BAR;
;     LDB(B1,0,1); BAR; WAIT_L(0); MMA(0,1,At,B1); BAR;
;     LDA(At,0,1); WAIT_V(4); BAR; WAIT_L(0); MMA(1,0,At,B0); MMA(1,1,At,B1); BAR; }
;   { LDB(B0,1,0); LDA(At,1,0); WAIT_V(2); BAR; WAIT_L(0); MMA(0,0,At,B0); BAR;
	s_nop 1
	ds_read_b128 v[104:107], v160
	ds_read_b128 v[108:111], v160 offset:1024
	ds_read_b128 v[222:225], v160 offset:2048
	ds_read_b128 v[158:161], v160 offset:3072
	s_barrier
	s_waitcnt lgkmcnt(0)
	s_setprio 1
	v_mfma_f32_16x16x32_bf16 v[84:87], v[104:107], v[194:197], v[84:87]
	v_mfma_f32_16x16x32_bf16 v[80:83], v[222:225], v[194:197], v[80:83]
	v_mfma_f32_16x16x32_bf16 v[68:71], v[104:107], v[210:213], v[68:71]
	v_mfma_f32_16x16x32_bf16 v[92:95], v[104:107], v[186:189], v[92:95]
	v_mfma_f32_16x16x32_bf16 v[88:91], v[222:225], v[186:189], v[88:91]
	v_mfma_f32_16x16x32_bf16 v[84:87], v[108:111], v[198:201], v[84:87]
	v_mfma_f32_16x16x32_bf16 v[80:83], v[158:161], v[198:201], v[80:83]
	v_mfma_f32_16x16x32_bf16 v[76:79], v[104:107], v[202:205], v[76:79]
	v_mfma_f32_16x16x32_bf16 v[72:75], v[222:225], v[202:205], v[72:75]
	v_mfma_f32_16x16x32_bf16 v[68:71], v[108:111], v[214:217], v[68:71]
	v_mfma_f32_16x16x32_bf16 v[64:67], v[222:225], v[210:213], v[64:67]
	v_mfma_f32_16x16x32_bf16 v[226:229], v[108:111], v[190:193], v[92:95]
	v_mfma_f32_16x16x32_bf16 v[186:189], v[158:161], v[190:193], v[88:91]
	v_mfma_f32_16x16x32_bf16 v[190:193], v[108:111], v[206:209], v[76:79]
	v_mfma_f32_16x16x32_bf16 v[194:197], v[158:161], v[206:209], v[72:75]
	v_mfma_f32_16x16x32_bf16 v[198:201], v[158:161], v[214:217], v[64:67]
	s_setprio 0
	s_barrier
	s_nop 0
	ds_read_b128 v[64:67], v153 offset:16384
	ds_read_b128 v[72:75], v153 offset:17408
	ds_read_b128 v[76:79], v171 offset:16384
	ds_read_b128 v[88:91], v171 offset:17408
	ds_read_b128 v[92:95], v172 offset:16384
	ds_read_b128 v[202:205], v172 offset:17408
	ds_read_b128 v[206:209], v173 offset:16384
	ds_read_b128 v[210:213], v173 offset:17408
	s_waitcnt vmcnt(4)
	s_barrier
	s_waitcnt lgkmcnt(0)
	s_setprio 1
	v_mfma_f32_16x16x32_bf16 v[60:63], v[142:145], v[64:67], v[60:63]
	v_mfma_f32_16x16x32_bf16 v[56:59], v[178:181], v[64:67], v[56:59]
	v_mfma_f32_16x16x32_bf16 v[52:55], v[142:145], v[76:79], v[52:55]
	v_mfma_f32_16x16x32_bf16 v[48:51], v[178:181], v[76:79], v[48:51]
	v_mfma_f32_16x16x32_bf16 v[36:39], v[142:145], v[206:209], v[36:39]
	v_mfma_f32_16x16x32_bf16 v[32:35], v[178:181], v[206:209], v[32:35]
	v_mfma_f32_16x16x32_bf16 v[60:63], v[146:149], v[72:75], v[60:63]
	v_mfma_f32_16x16x32_bf16 v[56:59], v[182:185], v[72:75], v[56:59]
	v_mfma_f32_16x16x32_bf16 v[52:55], v[146:149], v[88:91], v[52:55]
	v_mfma_f32_16x16x32_bf16 v[48:51], v[182:185], v[88:91], v[48:51]
	v_mfma_f32_16x16x32_bf16 v[44:47], v[142:145], v[92:95], v[44:47]
	v_mfma_f32_16x16x32_bf16 v[40:43], v[178:181], v[92:95], v[40:43]
	v_mfma_f32_16x16x32_bf16 v[36:39], v[146:149], v[210:213], v[36:39]
	v_mfma_f32_16x16x32_bf16 v[32:35], v[182:185], v[210:213], v[32:35]
	v_mfma_f32_16x16x32_bf16 v[214:217], v[146:149], v[202:205], v[44:47]
	v_mfma_f32_16x16x32_bf16 v[230:233], v[182:185], v[202:205], v[40:43]
	s_setprio 0
	s_setprio 1
	v_mfma_f32_16x16x32_bf16 v[20:23], v[104:107], v[76:79], v[20:23]
	v_mfma_f32_16x16x32_bf16 v[16:19], v[222:225], v[76:79], v[16:19]
	v_mfma_f32_16x16x32_bf16 v[4:7], v[104:107], v[206:209], v[4:7]
	v_mfma_f32_16x16x32_bf16 v[28:31], v[104:107], v[64:67], v[28:31]
	v_mfma_f32_16x16x32_bf16 v[24:27], v[222:225], v[64:67], v[24:27]
	v_mfma_f32_16x16x32_bf16 v[20:23], v[108:111], v[88:91], v[20:23]
	v_mfma_f32_16x16x32_bf16 v[16:19], v[158:161], v[88:91], v[16:19]
	v_mfma_f32_16x16x32_bf16 v[12:15], v[104:107], v[92:95], v[12:15]
	v_mfma_f32_16x16x32_bf16 v[8:11], v[222:225], v[92:95], v[8:11]
	v_mfma_f32_16x16x32_bf16 v[4:7], v[108:111], v[210:213], v[4:7]
	v_mfma_f32_16x16x32_bf16 v[0:3], v[222:225], v[206:209], v[0:3]
	v_mfma_f32_16x16x32_bf16 v[142:145], v[108:111], v[72:75], v[28:31]
	v_mfma_f32_16x16x32_bf16 v[146:149], v[158:161], v[72:75], v[24:27]
	v_mfma_f32_16x16x32_bf16 v[178:181], v[108:111], v[202:205], v[12:15]
	v_mfma_f32_16x16x32_bf16 v[182:185], v[158:161], v[202:205], v[8:11]
	v_mfma_f32_16x16x32_bf16 v[158:161], v[158:161], v[210:213], v[0:3]
	s_setprio 0
	s_barrier
	s_nop 0
	ds_read_b128 v[0:3], v156
	ds_read_b128 v[8:11], v156 offset:1024
	ds_read_b128 v[202:205], v156 offset:2048
	ds_read_b128 v[206:209], v156 offset:3072
	ds_read_b128 v[12:15], v153 offset:32768
	ds_read_b128 v[24:27], v153 offset:33792
	ds_read_b128 v[28:31], v171 offset:32768
	ds_read_b128 v[40:43], v171 offset:33792
	ds_read_b128 v[44:47], v172 offset:32768
	ds_read_b128 v[64:67], v172 offset:33792
	ds_read_b128 v[210:213], v173 offset:32768
	ds_read_b128 v[222:225], v173 offset:33792
	s_waitcnt vmcnt(2)
	s_barrier
; #define LDA(dst,b,h) _Pragma("unroll") for(int m=0;m<4;++m) _Pragma("unroll") for(int k=0;k<2;++k) \
;     dst[m][k]=*reinterpret_cast<const bf16x8*>((char*)SA(b,h)+lds_byte(wr*64+m*16+fr,k*32+fq*8))
; #define LDB(dst,b,h) _Pragma("unroll") for(int n=0;n<2;++n) _Pragma("unroll") for(int k=0;k<2;++k) \
;     dst[n][k]=*reinterpret_cast<const bf16x8*>((char*)SB(b,h)+lds_byte(wc*32+n*16+fr,k*32+fq*8))
; #define MMA(ai,bj,At_,Bt_) do{__builtin_amdgcn_s_setprio(1); \
;     _Pragma("unroll") for(int m=0;m<4;++m) _Pragma("unroll") for(int n=0;n<2;++n) _Pragma("unroll") for(int k=0;k<2;++k) \
;       acc[ai][bj][m][n]=__builtin_amdgcn_mfma_f32_16x16x32_bf16(Bt_[n][k],At_[m][k],acc[ai][bj][m][n],0,0,0); \
;     __builtin_amdgcn_s_setprio(0);}while(0)
; #define WAIT_V(n) asm volatile("s_waitcnt vmcnt(" #n ")":::"memory")
; #define WAIT_L(n) asm volatile("s_waitcnt lgkmcnt(" #n ")":::"memory")
; #define BAR __builtin_amdgcn_s_barrier()
; DEVINL void gemm8_mainloop(const u16* A, long lda, const u16* Bt, long ldb, int K, int brow, int bcol, f32x4 (&acc)[2][2][4][2], char* smem, int tid) {
;     ...
;     LDA(At,0,1); WAIT_V(4); BAR; WAIT_L(0); MMA(1,0,At,B0); MMA(1,1,At,B1); BAR; }
;   { LDB(B0,1,0); LDA(At,1,0); WAIT_V(2); BAR; WAIT_L(0); MMA(0,0,At,B0); BAR;
;     LDB(B1,1,1); WAIT_V(0); BAR; WAIT_L(0); MMA(0,1,At,B1); BAR;
;     LDA(At,1,1); BAR; WAIT_L(0); MMA(1,0,At,B0); MMA(1,1,At,B1); BAR; }
;   if(wr==0)BAR;
	s_waitcnt lgkmcnt(0)
	s_setprio 1
	v_mfma_f32_16x16x32_bf16 v[72:75], v[0:3], v[12:15], v[124:127]
	v_mfma_f32_16x16x32_bf16 v[124:127], v[8:11], v[24:27], v[72:75]
	v_mfma_f32_16x16x32_bf16 v[72:75], v[202:205], v[12:15], v[120:123]
	v_mfma_f32_16x16x32_bf16 v[120:123], v[206:209], v[24:27], v[72:75]
	v_mfma_f32_16x16x32_bf16 v[72:75], v[0:3], v[28:31], v[116:119]
	v_mfma_f32_16x16x32_bf16 v[108:111], v[8:11], v[40:43], v[72:75]
	v_mfma_f32_16x16x32_bf16 v[72:75], v[202:205], v[28:31], v[112:115]
	v_mfma_f32_16x16x32_bf16 v[104:107], v[206:209], v[40:43], v[72:75]
	v_mfma_f32_16x16x32_bf16 v[72:75], v[0:3], v[44:47], v[138:141]
	v_mfma_f32_16x16x32_bf16 v[92:95], v[8:11], v[64:67], v[72:75]
	v_mfma_f32_16x16x32_bf16 v[72:75], v[202:205], v[44:47], v[218:221]
	v_mfma_f32_16x16x32_bf16 v[88:91], v[206:209], v[64:67], v[72:75]
	v_mfma_f32_16x16x32_bf16 v[72:75], v[0:3], v[210:213], v[100:103]
	v_mfma_f32_16x16x32_bf16 v[76:79], v[8:11], v[222:225], v[72:75]
	v_mfma_f32_16x16x32_bf16 v[72:75], v[202:205], v[210:213], v[96:99]
	v_mfma_f32_16x16x32_bf16 v[72:75], v[206:209], v[222:225], v[72:75]
	s_setprio 0
	s_barrier
	ds_read_b128 v[138:141], v155
	ds_read_b128 v[218:221], v155 offset:1024
	ds_read_b128 v[234:237], v155 offset:2048
	ds_read_b128 v[154:157], v155 offset:3072
	s_waitcnt vmcnt(0)
	s_barrier
	s_waitcnt lgkmcnt(0)
	s_setprio 1
	v_mfma_f32_16x16x32_bf16 v[96:99], v[138:141], v[12:15], v[226:229]
	v_mfma_f32_16x16x32_bf16 v[12:15], v[234:237], v[12:15], v[186:189]
	v_mfma_f32_16x16x32_bf16 v[116:119], v[154:157], v[24:27], v[12:15]
	v_mfma_f32_16x16x32_bf16 v[12:15], v[138:141], v[28:31], v[84:87]
	v_mfma_f32_16x16x32_bf16 v[112:115], v[218:221], v[24:27], v[96:99]
	v_mfma_f32_16x16x32_bf16 v[96:99], v[218:221], v[40:43], v[12:15]
	v_mfma_f32_16x16x32_bf16 v[12:15], v[234:237], v[28:31], v[80:83]
	v_mfma_f32_16x16x32_bf16 v[100:103], v[154:157], v[40:43], v[12:15]
	v_mfma_f32_16x16x32_bf16 v[12:15], v[138:141], v[44:47], v[190:193]
	v_mfma_f32_16x16x32_bf16 v[80:83], v[218:221], v[64:67], v[12:15]
	v_mfma_f32_16x16x32_bf16 v[12:15], v[234:237], v[44:47], v[194:197]
	v_mfma_f32_16x16x32_bf16 v[84:87], v[154:157], v[64:67], v[12:15]
	v_mfma_f32_16x16x32_bf16 v[12:15], v[138:141], v[210:213], v[68:71]
	v_mfma_f32_16x16x32_bf16 v[64:67], v[218:221], v[222:225], v[12:15]
	v_mfma_f32_16x16x32_bf16 v[12:15], v[234:237], v[210:213], v[198:201]
	v_mfma_f32_16x16x32_bf16 v[68:71], v[154:157], v[222:225], v[12:15]
	s_setprio 0
	s_barrier
	ds_read_b128 v[186:189], v153 offset:49152
	ds_read_b128 v[190:193], v153 offset:50176
	ds_read_b128 v[194:197], v171 offset:49152
	ds_read_b128 v[198:201], v171 offset:50176
	ds_read_b128 v[210:213], v172 offset:49152
	ds_read_b128 v[222:225], v172 offset:50176
	ds_read_b128 v[226:229], v173 offset:49152
	ds_read_b128 v[172:175], v173 offset:50176
	s_barrier
	s_waitcnt lgkmcnt(0)
	s_setprio 1
	v_mfma_f32_16x16x32_bf16 v[12:15], v[0:3], v[186:189], v[60:63]
	v_mfma_f32_16x16x32_bf16 v[60:63], v[8:11], v[190:193], v[12:15]
	v_mfma_f32_16x16x32_bf16 v[12:15], v[202:205], v[186:189], v[56:59]
	v_mfma_f32_16x16x32_bf16 v[56:59], v[206:209], v[190:193], v[12:15]
	v_mfma_f32_16x16x32_bf16 v[12:15], v[0:3], v[194:197], v[52:55]
	v_mfma_f32_16x16x32_bf16 v[44:47], v[8:11], v[198:201], v[12:15]
	v_mfma_f32_16x16x32_bf16 v[12:15], v[202:205], v[194:197], v[48:51]
	v_mfma_f32_16x16x32_bf16 v[40:43], v[206:209], v[198:201], v[12:15]
	v_mfma_f32_16x16x32_bf16 v[12:15], v[0:3], v[210:213], v[214:217]
	v_mfma_f32_16x16x32_bf16 v[28:31], v[8:11], v[222:225], v[12:15]
	v_mfma_f32_16x16x32_bf16 v[12:15], v[202:205], v[210:213], v[230:233]
	v_mfma_f32_16x16x32_bf16 v[0:3], v[0:3], v[226:229], v[36:39]
	v_mfma_f32_16x16x32_bf16 v[24:27], v[206:209], v[222:225], v[12:15]
	v_mfma_f32_16x16x32_bf16 v[12:15], v[8:11], v[172:175], v[0:3]
	v_mfma_f32_16x16x32_bf16 v[0:3], v[202:205], v[226:229], v[32:35]
	v_mfma_f32_16x16x32_bf16 v[8:11], v[206:209], v[172:175], v[0:3]
	s_setprio 0
	s_setprio 1
	v_mfma_f32_16x16x32_bf16 v[0:3], v[138:141], v[186:189], v[142:145]
	v_mfma_f32_16x16x32_bf16 v[48:51], v[218:221], v[190:193], v[0:3]
	v_mfma_f32_16x16x32_bf16 v[0:3], v[234:237], v[186:189], v[146:149]
	v_mfma_f32_16x16x32_bf16 v[52:55], v[154:157], v[190:193], v[0:3]
	v_mfma_f32_16x16x32_bf16 v[0:3], v[138:141], v[194:197], v[20:23]
	v_mfma_f32_16x16x32_bf16 v[32:35], v[218:221], v[198:201], v[0:3]
	v_mfma_f32_16x16x32_bf16 v[0:3], v[234:237], v[194:197], v[16:19]
	v_mfma_f32_16x16x32_bf16 v[36:39], v[154:157], v[198:201], v[0:3]
	v_mfma_f32_16x16x32_bf16 v[0:3], v[138:141], v[210:213], v[178:181]
	v_mfma_f32_16x16x32_bf16 v[16:19], v[218:221], v[222:225], v[0:3]
	v_mfma_f32_16x16x32_bf16 v[0:3], v[234:237], v[210:213], v[182:185]
	v_mfma_f32_16x16x32_bf16 v[20:23], v[154:157], v[222:225], v[0:3]
	v_mfma_f32_16x16x32_bf16 v[0:3], v[138:141], v[226:229], v[4:7]
	v_mfma_f32_16x16x32_bf16 v[4:7], v[234:237], v[226:229], v[158:161]
	v_mfma_f32_16x16x32_bf16 v[0:3], v[218:221], v[172:175], v[0:3]
	v_mfma_f32_16x16x32_bf16 v[4:7], v[154:157], v[172:175], v[4:7]
	s_setprio 0
	s_cmpk_gt_u32 s29, 0xff
	s_barrier
	s_cbranch_scc1 .LBB0_1874
	s_barrier

; #define STAGE(P,BASE,LD,br,kt) do{long _g=(long)(br)*(LD)+(long)(kt)*BK; \
;     _Pragma("unroll") for(int _i=0;_i<2;++_i){int _b=tid*16+_i*8192;int _r,_c;stage_rc(_b,_r,_c); \
;       __builtin_amdgcn_global_load_lds((const unsigned*)((BASE)+_g+(long)_r*(LD)+_c), \
;         (unsigned*)((char*)(P)+_b),16,0,0);}}while(0)
; #define STAGE(P,BASE,LD,br,kt) do{long _g=(long)(br)*(LD)+(long)(kt)*BK; \
;     _Pragma("unroll") for(int _i=0;_i<2;++_i){int _b=tid*16+_i*8192;int _r,_c;stage_rc(_b,_r,_c); \
;       __builtin_amdgcn_global_load_lds((const unsigned*)((BASE)+_g+(long)_r*(LD)+_c), \
;         (unsigned*)((char*)(P)+_b),16,0,0);}}while(0)
; #define LDA(dst,b,h) _Pragma("unroll") for(int m=0;m<4;++m) _Pragma("unroll") for(int k=0;k<2;++k) \
;     dst[m][k]=*reinterpret_cast<const bf16x8*>((char*)SA(b,h)+lds_byte(wr*64+m*16+fr,k*32+fq*8))
; #define LDB(dst,b,h) _Pragma("unroll") for(int n=0;n<2;++n) _Pragma("unroll") for(int k=0;k<2;++k) \
;     dst[n][k]=*reinterpret_cast<const bf16x8*>((char*)SB(b,h)+lds_byte(wc*32+n*16+fr,k*32+fq*8))
; #define MMA(ai,bj,At_,Bt_) do{__builtin_amdgcn_s_setprio(1); \
;     _Pragma("unroll") for(int m=0;m<4;++m) _Pragma("unroll") for(int n=0;n<2;++n) _Pragma("unroll") for(int k=0;k<2;++k) \
;       acc[ai][bj][m][n]=__builtin_amdgcn_mfma_f32_16x16x32_bf16(Bt_[n][k],At_[m][k],acc[ai][bj][m][n],0,0,0); \
;     __builtin_amdgcn_s_setprio(0);}while(0)
; #define WAIT_L(n) asm volatile("s_waitcnt lgkmcnt(" #n ")":::"memory")
; #define BAR __builtin_amdgcn_s_barrier()
; #define SCHED __builtin_amdgcn_sched_barrier(0)
; DEVINL void gemm8_mainloop(const u16* A, long lda, const u16* Bt, long ldb, int K, int brow, int bcol, f32x4 (&acc)[2][2][4][2], char* smem, int tid) {
;     ...
;   for(int t=0;t<nt-2;t+=2){
;     LDB(B0,0,0); SCHED; LDA(At,0,0); STAGE(SA(1,1),A,lda,brow+HALF,t+1);
;     WAIT_L(8); BAR; WAIT_L(0); MMA(0,0,At,B0); BAR; SCHED;
;     LDB(B1,0,1); STAGE(SB(0,0),Bt,ldb,bcol,t+2);
;     BAR; WAIT_L(0); MMA(0,1,At,B1); BAR;
;     LDA(At,0,1); STAGE(SA(0,0),A,lda,brow,t+2);
;     BAR; WAIT_L(0); MMA(1,0,At,B0); BAR; SCHED;
;     STAGE(SB(0,1),Bt,ldb,bcol+HALF,t+2);
.LBB0_1938:
	ds_read_b128 v[180:183], v165
	ds_read_b128 v[184:187], v165 offset:1024
	ds_read_b128 v[188:191], v165 offset:2048
	ds_read_b128 v[192:195], v165 offset:3072
	v_add_u32_e32 v177, 0xc000, v154
	v_lshl_add_u64 v[244:245], s[94:95], 0, v[146:147]
	v_readfirstlane_b32 s27, v177
	v_add_u32_e32 v178, 0xe000, v154
	v_add_u32_e32 v173, s23, v164
	v_add_u32_e32 v174, s38, v164
	v_add_u32_e32 v175, s39, v164
	v_lshl_add_u64 v[166:167], v[244:245], 0, s[2:3]
	s_mov_b32 m0, s27
	v_lshl_add_u64 v[246:247], s[94:95], 0, v[148:149]
	v_readfirstlane_b32 s27, v178
	ds_read_b128 v[168:171], v155
	ds_read_b128 v[196:199], v155 offset:1024
	ds_read_b128 v[200:203], v173
	ds_read_b128 v[204:207], v173 offset:1024
	ds_read_b128 v[208:211], v174
	ds_read_b128 v[212:215], v174 offset:1024
	ds_read_b128 v[216:219], v175
	ds_read_b128 v[220:223], v175 offset:1024
	global_load_lds_dwordx4 v[166:167], off
	v_lshl_add_u64 v[166:167], v[246:247], 0, s[2:3]
	s_mov_b32 m0, s27
	s_nop 0
	global_load_lds_dwordx4 v[166:167], off
	s_waitcnt lgkmcnt(8)
	s_barrier
	s_waitcnt lgkmcnt(0)
	s_setprio 1
	v_mfma_f32_16x16x32_bf16 v[124:127], v[180:183], v[168:171], v[124:127]
	v_mfma_f32_16x16x32_bf16 v[120:123], v[188:191], v[168:171], v[120:123]
	v_mfma_f32_16x16x32_bf16 v[116:119], v[180:183], v[200:203], v[116:119]
	v_mfma_f32_16x16x32_bf16 v[112:115], v[188:191], v[200:203], v[112:115]
	v_mfma_f32_16x16x32_bf16 v[108:111], v[180:183], v[208:211], v[108:111]
	v_mfma_f32_16x16x32_bf16 v[104:107], v[188:191], v[208:211], v[104:107]
	v_mfma_f32_16x16x32_bf16 v[100:103], v[180:183], v[216:219], v[100:103]
	v_mfma_f32_16x16x32_bf16 v[96:99], v[188:191], v[216:219], v[96:99]
	v_mfma_f32_16x16x32_bf16 v[124:127], v[184:187], v[196:199], v[124:127]
	v_mfma_f32_16x16x32_bf16 v[120:123], v[192:195], v[196:199], v[120:123]
	v_mfma_f32_16x16x32_bf16 v[116:119], v[184:187], v[204:207], v[116:119]
	v_mfma_f32_16x16x32_bf16 v[112:115], v[192:195], v[204:207], v[112:115]
	v_mfma_f32_16x16x32_bf16 v[108:111], v[184:187], v[212:215], v[108:111]
	v_mfma_f32_16x16x32_bf16 v[104:107], v[192:195], v[212:215], v[104:107]
	v_mfma_f32_16x16x32_bf16 v[100:103], v[184:187], v[220:223], v[100:103]
	v_mfma_f32_16x16x32_bf16 v[96:99], v[192:195], v[220:223], v[96:99]
	s_setprio 0
	s_barrier
	v_add_u32_e32 v166, s28, v157
	v_lshl_add_u64 v[248:249], s[94:95], 0, v[142:143]
	v_readfirstlane_b32 s27, v166
	v_add_u32_e32 v167, 0x2000, v166
	v_lshl_add_u64 v[240:241], v[248:249], 0, s[4:5]
	s_mov_b32 m0, s27
	v_lshl_add_u64 v[250:251], s[94:95], 0, v[144:145]
	v_readfirstlane_b32 s27, v167
	ds_read_b128 v[224:227], v161
	ds_read_b128 v[228:231], v161 offset:1024
	ds_read_b128 v[232:235], v161 offset:2048
	ds_read_b128 v[236:239], v161 offset:3072
	global_load_lds_dwordx4 v[240:241], off
	v_lshl_add_u64 v[240:241], v[250:251], 0, s[4:5]
	s_mov_b32 m0, s27
	s_nop 0
	global_load_lds_dwordx4 v[240:241], off
	s_barrier
	s_waitcnt lgkmcnt(0)
	s_setprio 1
	v_mfma_f32_16x16x32_bf16 v[92:95], v[224:227], v[168:171], v[92:95]
	v_mfma_f32_16x16x32_bf16 v[88:91], v[232:235], v[168:171], v[88:91]
	v_mfma_f32_16x16x32_bf16 v[84:87], v[224:227], v[200:203], v[84:87]
	v_mfma_f32_16x16x32_bf16 v[80:83], v[232:235], v[200:203], v[80:83]
	v_mfma_f32_16x16x32_bf16 v[76:79], v[224:227], v[208:211], v[76:79]
	v_mfma_f32_16x16x32_bf16 v[72:75], v[232:235], v[208:211], v[72:75]
	v_mfma_f32_16x16x32_bf16 v[68:71], v[224:227], v[216:219], v[68:71]
	v_mfma_f32_16x16x32_bf16 v[64:67], v[232:235], v[216:219], v[64:67]
	v_mfma_f32_16x16x32_bf16 v[92:95], v[228:231], v[196:199], v[92:95]
	v_mfma_f32_16x16x32_bf16 v[88:91], v[236:239], v[196:199], v[88:91]
	v_mfma_f32_16x16x32_bf16 v[84:87], v[228:231], v[204:207], v[84:87]
	v_mfma_f32_16x16x32_bf16 v[80:83], v[236:239], v[204:207], v[80:83]
	v_mfma_f32_16x16x32_bf16 v[76:79], v[228:231], v[212:215], v[76:79]
	v_mfma_f32_16x16x32_bf16 v[72:75], v[236:239], v[212:215], v[72:75]
	v_mfma_f32_16x16x32_bf16 v[68:71], v[228:231], v[220:223], v[68:71]
	v_mfma_f32_16x16x32_bf16 v[64:67], v[236:239], v[220:223], v[64:67]
	s_setprio 0
	v_readfirstlane_b32 s27, v154
	v_lshl_add_u64 v[168:169], v[244:245], 0, s[6:7]
	s_mov_b32 m0, s27
	s_barrier
	ds_read_b128 v[196:199], v155 offset:16384
	ds_read_b128 v[200:203], v155 offset:17408
	ds_read_b128 v[204:207], v173 offset:16384
	ds_read_b128 v[208:211], v173 offset:17408
	ds_read_b128 v[212:215], v174 offset:16384
	ds_read_b128 v[216:219], v174 offset:17408
	ds_read_b128 v[220:223], v175 offset:16384
	ds_read_b128 v[240:243], v175 offset:17408
	global_load_lds_dwordx4 v[168:169], off
	v_add_u32_e32 v168, 0x2000, v154
	v_lshl_add_u64 v[170:171], v[246:247], 0, s[6:7]
	v_readfirstlane_b32 s27, v168
	s_mov_b32 m0, s27
	s_nop 0
	global_load_lds_dwordx4 v[170:171], off
	s_barrier
	s_waitcnt lgkmcnt(0)
	s_setprio 1
	v_mfma_f32_16x16x32_bf16 v[60:63], v[180:183], v[196:199], v[60:63]
	v_mfma_f32_16x16x32_bf16 v[56:59], v[188:191], v[196:199], v[56:59]
	v_mfma_f32_16x16x32_bf16 v[52:55], v[180:183], v[204:207], v[52:55]
	v_mfma_f32_16x16x32_bf16 v[48:51], v[188:191], v[204:207], v[48:51]
	v_mfma_f32_16x16x32_bf16 v[44:47], v[180:183], v[212:215], v[44:47]
	v_mfma_f32_16x16x32_bf16 v[40:43], v[188:191], v[212:215], v[40:43]
	v_mfma_f32_16x16x32_bf16 v[36:39], v[180:183], v[220:223], v[36:39]
	v_mfma_f32_16x16x32_bf16 v[32:35], v[188:191], v[220:223], v[32:35]
	v_mfma_f32_16x16x32_bf16 v[60:63], v[184:187], v[200:203], v[60:63]
	v_mfma_f32_16x16x32_bf16 v[56:59], v[192:195], v[200:203], v[56:59]
	v_mfma_f32_16x16x32_bf16 v[52:55], v[184:187], v[208:211], v[52:55]
	v_mfma_f32_16x16x32_bf16 v[48:51], v[192:195], v[208:211], v[48:51]
	v_mfma_f32_16x16x32_bf16 v[44:47], v[184:187], v[216:219], v[44:47]
	v_mfma_f32_16x16x32_bf16 v[40:43], v[192:195], v[216:219], v[40:43]
	v_mfma_f32_16x16x32_bf16 v[36:39], v[184:187], v[240:243], v[36:39]
	v_mfma_f32_16x16x32_bf16 v[32:35], v[192:195], v[240:243], v[32:35]
	s_setprio 0
	s_barrier
; #define STAGE(P,BASE,LD,br,kt) do{long _g=(long)(br)*(LD)+(long)(kt)*BK; \
;     _Pragma("unroll") for(int _i=0;_i<2;++_i){int _b=tid*16+_i*8192;int _r,_c;stage_rc(_b,_r,_c); \
;       __builtin_amdgcn_global_load_lds((const unsigned*)((BASE)+_g+(long)_r*(LD)+_c), \
;         (unsigned*)((char*)(P)+_b),16,0,0);}}while(0)
; #define STAGE(P,BASE,LD,br,kt) do{long _g=(long)(br)*(LD)+(long)(kt)*BK; \
;     _Pragma("unroll") for(int _i=0;_i<2;++_i){int _b=tid*16+_i*8192;int _r,_c;stage_rc(_b,_r,_c); \
;       __builtin_amdgcn_global_load_lds((const unsigned*)((BASE)+_g+(long)_r*(LD)+_c), \
;         (unsigned*)((char*)(P)+_b),16,0,0);}}while(0)
; #define LDA(dst,b,h) _Pragma("unroll") for(int m=0;m<4;++m) _Pragma("unroll") for(int k=0;k<2;++k) \
;     dst[m][k]=*reinterpret_cast<const bf16x8*>((char*)SA(b,h)+lds_byte(wr*64+m*16+fr,k*32+fq*8))
; #define LDB(dst,b,h) _Pragma("unroll") for(int n=0;n<2;++n) _Pragma("unroll") for(int k=0;k<2;++k) \
;     dst[n][k]=*reinterpret_cast<const bf16x8*>((char*)SB(b,h)+lds_byte(wc*32+n*16+fr,k*32+fq*8))
; #define MMA(ai,bj,At_,Bt_) do{__builtin_amdgcn_s_setprio(1); \
;     _Pragma("unroll") for(int m=0;m<4;++m) _Pragma("unroll") for(int n=0;n<2;++n) _Pragma("unroll") for(int k=0;k<2;++k) \
;       acc[ai][bj][m][n]=__builtin_amdgcn_mfma_f32_16x16x32_bf16(Bt_[n][k],At_[m][k],acc[ai][bj][m][n],0,0,0); \
;     __builtin_amdgcn_s_setprio(0);}while(0)
; #define WAIT_V(n) asm volatile("s_waitcnt vmcnt(" #n ")":::"memory")
; #define WAIT_L(n) asm volatile("s_waitcnt lgkmcnt(" #n ")":::"memory")
; #define BAR __builtin_amdgcn_s_barrier()
; #define SCHED __builtin_amdgcn_sched_barrier(0)
; DEVINL void gemm8_mainloop(const u16* A, long lda, const u16* Bt, long ldb, int K, int brow, int bcol, f32x4 (&acc)[2][2][4][2], char* smem, int tid) {
;     ...
;     STAGE(SB(0,1),Bt,ldb,bcol+HALF,t+2);
;     WAIT_V(6); BAR; MMA(1,1,At,B1); BAR;
;     LDB(B0,1,0); SCHED; LDA(At,1,0); STAGE(SA(0,1),A,lda,brow+HALF,t+2);
;     WAIT_L(8); BAR; WAIT_L(0); MMA(0,0,At,B0); BAR; SCHED;
;     LDB(B1,1,1); STAGE(SB(1,0),Bt,ldb,bcol,t+3);
;     BAR; WAIT_L(0); MMA(0,1,At,B1); BAR;
;     LDA(At,1,1); STAGE(SA(1,0),A,lda,brow,t+3);
	v_add_u32_e32 v169, s29, v157
	v_lshl_add_u64 v[170:171], v[248:249], 0, s[8:9]
	v_readfirstlane_b32 s27, v169
	s_mov_b32 m0, s27
	v_lshl_add_u64 v[180:181], v[250:251], 0, s[8:9]
	global_load_lds_dwordx4 v[170:171], off
	v_add_u32_e32 v170, 0x2000, v169
	s_nop 0
	v_readfirstlane_b32 s27, v170
	s_mov_b32 m0, s27
	s_nop 0
	global_load_lds_dwordx4 v[180:181], off
	s_waitcnt vmcnt(6)
	s_barrier
	s_setprio 1
	v_mfma_f32_16x16x32_bf16 v[28:31], v[224:227], v[196:199], v[28:31]
	v_mfma_f32_16x16x32_bf16 v[24:27], v[232:235], v[196:199], v[24:27]
	v_mfma_f32_16x16x32_bf16 v[20:23], v[224:227], v[204:207], v[20:23]
	v_mfma_f32_16x16x32_bf16 v[16:19], v[232:235], v[204:207], v[16:19]
	v_mfma_f32_16x16x32_bf16 v[12:15], v[224:227], v[212:215], v[12:15]
	v_mfma_f32_16x16x32_bf16 v[8:11], v[232:235], v[212:215], v[8:11]
	v_mfma_f32_16x16x32_bf16 v[4:7], v[224:227], v[220:223], v[4:7]
	v_mfma_f32_16x16x32_bf16 v[0:3], v[232:235], v[220:223], v[0:3]
	v_mfma_f32_16x16x32_bf16 v[28:31], v[228:231], v[200:203], v[28:31]
	v_mfma_f32_16x16x32_bf16 v[24:27], v[236:239], v[200:203], v[24:27]
	v_mfma_f32_16x16x32_bf16 v[20:23], v[228:231], v[208:211], v[20:23]
	v_mfma_f32_16x16x32_bf16 v[16:19], v[236:239], v[208:211], v[16:19]
	v_mfma_f32_16x16x32_bf16 v[12:15], v[228:231], v[216:219], v[12:15]
	v_mfma_f32_16x16x32_bf16 v[8:11], v[236:239], v[216:219], v[8:11]
	v_mfma_f32_16x16x32_bf16 v[4:7], v[228:231], v[240:243], v[4:7]
	v_mfma_f32_16x16x32_bf16 v[0:3], v[236:239], v[240:243], v[0:3]
	s_setprio 0
	s_barrier
	ds_read_b128 v[180:183], v158
	ds_read_b128 v[184:187], v158 offset:1024
	ds_read_b128 v[188:191], v158 offset:2048
	ds_read_b128 v[192:195], v158 offset:3072
	v_add_u32_e32 v171, 0x4000, v154
	v_add_u32_e32 v172, 0x6000, v154
	v_readfirstlane_b32 s27, v171
	v_lshl_add_u64 v[228:229], v[244:245], 0, s[10:11]
	s_mov_b32 m0, s27
	v_readfirstlane_b32 s27, v172
	ds_read_b128 v[196:199], v155 offset:32768
	ds_read_b128 v[200:203], v155 offset:33792
	ds_read_b128 v[204:207], v173 offset:32768
	ds_read_b128 v[208:211], v173 offset:33792
	ds_read_b128 v[212:215], v174 offset:32768
	ds_read_b128 v[216:219], v174 offset:33792
	ds_read_b128 v[220:223], v175 offset:32768
	ds_read_b128 v[224:227], v175 offset:33792
	global_load_lds_dwordx4 v[228:229], off
	v_lshl_add_u64 v[228:229], v[246:247], 0, s[10:11]
	s_mov_b32 m0, s27
	s_nop 0
	global_load_lds_dwordx4 v[228:229], off
	s_waitcnt lgkmcnt(8)
	s_barrier
	s_waitcnt lgkmcnt(0)
	s_setprio 1
	v_mfma_f32_16x16x32_bf16 v[124:127], v[180:183], v[196:199], v[124:127]
	v_mfma_f32_16x16x32_bf16 v[120:123], v[188:191], v[196:199], v[120:123]
	v_mfma_f32_16x16x32_bf16 v[116:119], v[180:183], v[204:207], v[116:119]
	v_mfma_f32_16x16x32_bf16 v[112:115], v[188:191], v[204:207], v[112:115]
	v_mfma_f32_16x16x32_bf16 v[108:111], v[180:183], v[212:215], v[108:111]
	v_mfma_f32_16x16x32_bf16 v[104:107], v[188:191], v[212:215], v[104:107]
	v_mfma_f32_16x16x32_bf16 v[100:103], v[180:183], v[220:223], v[100:103]
	v_mfma_f32_16x16x32_bf16 v[96:99], v[188:191], v[220:223], v[96:99]
	v_mfma_f32_16x16x32_bf16 v[124:127], v[184:187], v[200:203], v[124:127]
	v_mfma_f32_16x16x32_bf16 v[120:123], v[192:195], v[200:203], v[120:123]
	v_mfma_f32_16x16x32_bf16 v[116:119], v[184:187], v[208:211], v[116:119]
	v_mfma_f32_16x16x32_bf16 v[112:115], v[192:195], v[208:211], v[112:115]
	v_mfma_f32_16x16x32_bf16 v[108:111], v[184:187], v[216:219], v[108:111]
	v_mfma_f32_16x16x32_bf16 v[104:107], v[192:195], v[216:219], v[104:107]
	v_mfma_f32_16x16x32_bf16 v[100:103], v[184:187], v[224:227], v[100:103]
	v_mfma_f32_16x16x32_bf16 v[96:99], v[192:195], v[224:227], v[96:99]
	s_setprio 0
	s_barrier
	v_readfirstlane_b32 s27, v159
	v_add_u32_e32 v179, 0x2000, v159
	v_lshl_add_u64 v[252:253], v[248:249], 0, s[12:13]
	s_mov_b32 m0, s27
	v_readfirstlane_b32 s27, v179
	ds_read_b128 v[228:231], v156
	ds_read_b128 v[232:235], v156 offset:1024
	ds_read_b128 v[236:239], v156 offset:2048
	ds_read_b128 v[240:243], v156 offset:3072
	global_load_lds_dwordx4 v[252:253], off
	v_lshl_add_u64 v[252:253], v[250:251], 0, s[12:13]
	s_mov_b32 m0, s27
	s_nop 0
	global_load_lds_dwordx4 v[252:253], off
	s_barrier
	s_waitcnt lgkmcnt(0)
	s_setprio 1
	v_mfma_f32_16x16x32_bf16 v[92:95], v[228:231], v[196:199], v[92:95]
	v_mfma_f32_16x16x32_bf16 v[88:91], v[236:239], v[196:199], v[88:91]
	v_mfma_f32_16x16x32_bf16 v[84:87], v[228:231], v[204:207], v[84:87]
	v_mfma_f32_16x16x32_bf16 v[80:83], v[236:239], v[204:207], v[80:83]
	v_mfma_f32_16x16x32_bf16 v[76:79], v[228:231], v[212:215], v[76:79]
	v_mfma_f32_16x16x32_bf16 v[72:75], v[236:239], v[212:215], v[72:75]
	v_mfma_f32_16x16x32_bf16 v[68:71], v[228:231], v[220:223], v[68:71]
	v_mfma_f32_16x16x32_bf16 v[64:67], v[236:239], v[220:223], v[64:67]
	v_mfma_f32_16x16x32_bf16 v[92:95], v[232:235], v[200:203], v[92:95]
	v_mfma_f32_16x16x32_bf16 v[88:91], v[240:243], v[200:203], v[88:91]
	v_mfma_f32_16x16x32_bf16 v[84:87], v[232:235], v[208:211], v[84:87]
	v_mfma_f32_16x16x32_bf16 v[80:83], v[240:243], v[208:211], v[80:83]
	v_mfma_f32_16x16x32_bf16 v[76:79], v[232:235], v[216:219], v[76:79]
	v_mfma_f32_16x16x32_bf16 v[72:75], v[240:243], v[216:219], v[72:75]
	v_mfma_f32_16x16x32_bf16 v[68:71], v[232:235], v[224:227], v[68:71]
	v_mfma_f32_16x16x32_bf16 v[64:67], v[240:243], v[224:227], v[64:67]
	s_setprio 0
	v_readfirstlane_b32 s27, v160
	v_lshl_add_u64 v[244:245], v[244:245], 0, s[14:15]
	s_mov_b32 m0, s27
	v_readfirstlane_b32 s27, v162
	s_barrier
; #define STAGE(P,BASE,LD,br,kt) do{long _g=(long)(br)*(LD)+(long)(kt)*BK; \
;     _Pragma("unroll") for(int _i=0;_i<2;++_i){int _b=tid*16+_i*8192;int _r,_c;stage_rc(_b,_r,_c); \
;       __builtin_amdgcn_global_load_lds((const unsigned*)((BASE)+_g+(long)_r*(LD)+_c), \
;         (unsigned*)((char*)(P)+_b),16,0,0);}}while(0)
; #define STAGE(P,BASE,LD,br,kt) do{long _g=(long)(br)*(LD)+(long)(kt)*BK; \
;     _Pragma("unroll") for(int _i=0;_i<2;++_i){int _b=tid*16+_i*8192;int _r,_c;stage_rc(_b,_r,_c); \
;       __builtin_amdgcn_global_load_lds((const unsigned*)((BASE)+_g+(long)_r*(LD)+_c), \
;         (unsigned*)((char*)(P)+_b),16,0,0);}}while(0)
; #define LDA(dst,b,h) _Pragma("unroll") for(int m=0;m<4;++m) _Pragma("unroll") for(int k=0;k<2;++k) \
;     dst[m][k]=*reinterpret_cast<const bf16x8*>((char*)SA(b,h)+lds_byte(wr*64+m*16+fr,k*32+fq*8))
; #define LDB(dst,b,h) _Pragma("unroll") for(int n=0;n<2;++n) _Pragma("unroll") for(int k=0;k<2;++k) \
;     dst[n][k]=*reinterpret_cast<const bf16x8*>((char*)SB(b,h)+lds_byte(wc*32+n*16+fr,k*32+fq*8))
; #define MMA(ai,bj,At_,Bt_) do{__builtin_amdgcn_s_setprio(1); \
;     _Pragma("unroll") for(int m=0;m<4;++m) _Pragma("unroll") for(int n=0;n<2;++n) _Pragma("unroll") for(int k=0;k<2;++k) \
;       acc[ai][bj][m][n]=__builtin_amdgcn_mfma_f32_16x16x32_bf16(Bt_[n][k],At_[m][k],acc[ai][bj][m][n],0,0,0); \
;     __builtin_amdgcn_s_setprio(0);}while(0)
; #define WAIT_V(n) asm volatile("s_waitcnt vmcnt(" #n ")":::"memory")
; #define WAIT_L(n) asm volatile("s_waitcnt lgkmcnt(" #n ")":::"memory")
; #define BAR __builtin_amdgcn_s_barrier()
; #define SCHED __builtin_amdgcn_sched_barrier(0)
; DEVINL void gemm8_mainloop(const u16* A, long lda, const u16* Bt, long ldb, int K, int brow, int bcol, f32x4 (&acc)[2][2][4][2], char* smem, int tid) {
;     ...
;     LDA(At,1,1); STAGE(SA(1,0),A,lda,brow,t+3);
;     BAR; WAIT_L(0); MMA(1,0,At,B0); BAR; SCHED;
;     STAGE(SB(1,1),Bt,ldb,bcol+HALF,t+3);
;     WAIT_V(6); BAR; MMA(1,1,At,B1); BAR;
;   }
;   { LDB(B0,0,0); LDA(At,0,0); STAGE(SA(1,1),A,lda,brow+HALF,nt-1);
;     BAR; WAIT_L(0); MMA(0,0,At,B0); BAR;
	ds_read_b128 v[196:199], v155 offset:49152
	ds_read_b128 v[200:203], v155 offset:50176
	ds_read_b128 v[204:207], v173 offset:49152
	ds_read_b128 v[208:211], v173 offset:50176
	ds_read_b128 v[212:215], v174 offset:49152
	ds_read_b128 v[216:219], v174 offset:50176
	ds_read_b128 v[220:223], v175 offset:49152
	ds_read_b128 v[224:227], v175 offset:50176
	global_load_lds_dwordx4 v[244:245], off
	v_lshl_add_u64 v[244:245], v[246:247], 0, s[14:15]
	s_mov_b32 m0, s27
	s_nop 0
	global_load_lds_dwordx4 v[244:245], off
	s_barrier
	s_waitcnt lgkmcnt(0)
	s_setprio 1
	v_mfma_f32_16x16x32_bf16 v[60:63], v[180:183], v[196:199], v[60:63]
	v_mfma_f32_16x16x32_bf16 v[56:59], v[188:191], v[196:199], v[56:59]
	v_mfma_f32_16x16x32_bf16 v[52:55], v[180:183], v[204:207], v[52:55]
	v_mfma_f32_16x16x32_bf16 v[48:51], v[188:191], v[204:207], v[48:51]
	v_mfma_f32_16x16x32_bf16 v[44:47], v[180:183], v[212:215], v[44:47]
	v_mfma_f32_16x16x32_bf16 v[40:43], v[188:191], v[212:215], v[40:43]
	v_mfma_f32_16x16x32_bf16 v[36:39], v[180:183], v[220:223], v[36:39]
	v_mfma_f32_16x16x32_bf16 v[32:35], v[188:191], v[220:223], v[32:35]
	v_mfma_f32_16x16x32_bf16 v[60:63], v[184:187], v[200:203], v[60:63]
	v_mfma_f32_16x16x32_bf16 v[56:59], v[192:195], v[200:203], v[56:59]
	v_mfma_f32_16x16x32_bf16 v[52:55], v[184:187], v[208:211], v[52:55]
	v_mfma_f32_16x16x32_bf16 v[48:51], v[192:195], v[208:211], v[48:51]
	v_mfma_f32_16x16x32_bf16 v[44:47], v[184:187], v[216:219], v[44:47]
	v_mfma_f32_16x16x32_bf16 v[40:43], v[192:195], v[216:219], v[40:43]
	v_mfma_f32_16x16x32_bf16 v[36:39], v[184:187], v[224:227], v[36:39]
	v_mfma_f32_16x16x32_bf16 v[32:35], v[192:195], v[224:227], v[32:35]
	s_setprio 0
	s_barrier
	v_readfirstlane_b32 s27, v163
	v_add_u32_e32 v179, 0x2000, v163
	v_lshl_add_u64 v[180:181], v[248:249], 0, s[16:17]
	s_mov_b32 m0, s27
	v_readfirstlane_b32 s27, v179
	global_load_lds_dwordx4 v[180:181], off
	v_lshl_add_u64 v[180:181], v[250:251], 0, s[16:17]
	s_mov_b32 m0, s27
	s_nop 0
	global_load_lds_dwordx4 v[180:181], off
	s_waitcnt vmcnt(6)
	s_barrier
	s_setprio 1
	v_mfma_f32_16x16x32_bf16 v[28:31], v[228:231], v[196:199], v[28:31]
	v_mfma_f32_16x16x32_bf16 v[24:27], v[236:239], v[196:199], v[24:27]
	v_mfma_f32_16x16x32_bf16 v[20:23], v[228:231], v[204:207], v[20:23]
	v_mfma_f32_16x16x32_bf16 v[16:19], v[236:239], v[204:207], v[16:19]
	v_mfma_f32_16x16x32_bf16 v[12:15], v[228:231], v[212:215], v[12:15]
	v_mfma_f32_16x16x32_bf16 v[8:11], v[236:239], v[212:215], v[8:11]
	v_mfma_f32_16x16x32_bf16 v[4:7], v[228:231], v[220:223], v[4:7]
	v_mfma_f32_16x16x32_bf16 v[0:3], v[236:239], v[220:223], v[0:3]
	v_mfma_f32_16x16x32_bf16 v[28:31], v[232:235], v[200:203], v[28:31]
	v_mfma_f32_16x16x32_bf16 v[24:27], v[240:243], v[200:203], v[24:27]
	v_mfma_f32_16x16x32_bf16 v[20:23], v[232:235], v[208:211], v[20:23]
	v_mfma_f32_16x16x32_bf16 v[16:19], v[240:243], v[208:211], v[16:19]
	v_mfma_f32_16x16x32_bf16 v[12:15], v[232:235], v[216:219], v[12:15]
	v_mfma_f32_16x16x32_bf16 v[8:11], v[240:243], v[216:219], v[8:11]
	v_mfma_f32_16x16x32_bf16 v[4:7], v[232:235], v[224:227], v[4:7]
	v_mfma_f32_16x16x32_bf16 v[0:3], v[240:243], v[224:227], v[0:3]
	s_setprio 0
	s_add_i32 s26, s26, 2
	v_lshl_add_u64 v[142:143], v[142:143], 0, s[18:19]
	v_lshl_add_u64 v[144:145], v[144:145], 0, s[18:19]
	v_lshl_add_u64 v[146:147], v[146:147], 0, s[18:19]
	s_cmp_lt_u32 s26, 28
	v_lshl_add_u64 v[148:149], v[148:149], 0, s[18:19]
	s_barrier
	s_cbranch_scc1 .LBB0_1938
	s_or_b32 s26, s22, 0x80
	s_ashr_i32 s27, s26, 31
	s_lshl_b64 s[26:27], s[26:27], 12
	s_add_u32 s26, s90, s26
	s_addc_u32 s27, s91, s27
	v_lshl_add_u64 v[216:217], v[134:135], 1, s[26:27]
	v_lshl_add_u64 v[138:139], v[138:139], 1, v[216:217]
	v_readfirstlane_b32 s23, v177
	v_lshl_add_u64 v[138:139], v[138:139], 0, s[20:21]
	s_mov_b32 m0, s23
	ds_read_b128 v[142:145], v165
	ds_read_b128 v[146:149], v165 offset:1024
	ds_read_b128 v[180:183], v165 offset:2048
	ds_read_b128 v[162:165], v165 offset:3072
	ds_read_b128 v[184:187], v155
	ds_read_b128 v[188:191], v155 offset:1024
	ds_read_b128 v[192:195], v173
	ds_read_b128 v[196:199], v173 offset:1024
	ds_read_b128 v[200:203], v174
	ds_read_b128 v[204:207], v174 offset:1024
	ds_read_b128 v[208:211], v175
	ds_read_b128 v[212:215], v175 offset:1024
	global_load_lds_dwordx4 v[138:139], off
	v_lshl_add_u64 v[138:139], v[136:137], 1, s[26:27]
	v_lshl_add_u64 v[138:139], v[140:141], 1, v[138:139]
	v_readfirstlane_b32 s23, v178
	v_lshl_add_u64 v[138:139], v[138:139], 0, s[20:21]
	s_mov_b32 m0, s23
	s_nop 0
	global_load_lds_dwordx4 v[138:139], off
	s_barrier
	s_waitcnt lgkmcnt(0)
	s_setprio 1
	v_mfma_f32_16x16x32_bf16 v[124:127], v[142:145], v[184:187], v[124:127]
	v_mfma_f32_16x16x32_bf16 v[120:123], v[180:183], v[184:187], v[120:123]
	v_mfma_f32_16x16x32_bf16 v[116:119], v[142:145], v[192:195], v[116:119]
	v_mfma_f32_16x16x32_bf16 v[112:115], v[180:183], v[192:195], v[112:115]
	v_mfma_f32_16x16x32_bf16 v[104:107], v[180:183], v[200:203], v[104:107]
	v_mfma_f32_16x16x32_bf16 v[96:99], v[180:183], v[208:211], v[96:99]
	v_mfma_f32_16x16x32_bf16 v[124:127], v[146:149], v[188:191], v[124:127]
	v_mfma_f32_16x16x32_bf16 v[120:123], v[162:165], v[188:191], v[120:123]
	v_mfma_f32_16x16x32_bf16 v[116:119], v[146:149], v[196:199], v[116:119]
	v_mfma_f32_16x16x32_bf16 v[112:115], v[162:165], v[196:199], v[112:115]
	v_mfma_f32_16x16x32_bf16 v[108:111], v[142:145], v[200:203], v[108:111]
	v_mfma_f32_16x16x32_bf16 v[104:107], v[162:165], v[204:207], v[104:107]
	v_mfma_f32_16x16x32_bf16 v[100:103], v[142:145], v[208:211], v[100:103]
	v_mfma_f32_16x16x32_bf16 v[96:99], v[162:165], v[212:215], v[96:99]
	v_mfma_f32_16x16x32_bf16 v[138:141], v[146:149], v[204:207], v[108:111]
	v_mfma_f32_16x16x32_bf16 v[216:219], v[146:149], v[212:215], v[100:103]
	s_setprio 0
	s_barrier
; #define LDA(dst,b,h) _Pragma("unroll") for(int m=0;m<4;++m) _Pragma("unroll") for(int k=0;k<2;++k) \
;     dst[m][k]=*reinterpret_cast<const bf16x8*>((char*)SA(b,h)+lds_byte(wr*64+m*16+fr,k*32+fq*8))
; #define LDB(dst,b,h) _Pragma("unroll") for(int n=0;n<2;++n) _Pragma("unroll") for(int k=0;k<2;++k) \
;     dst[n][k]=*reinterpret_cast<const bf16x8*>((char*)SB(b,h)+lds_byte(wc*32+n*16+fr,k*32+fq*8))
; #define MMA(ai,bj,At_,Bt_) do{__builtin_amdgcn_s_setprio(1); \
;     _Pragma("unroll") for(int m=0;m<4;++m) _Pragma("unroll") for(int n=0;n<2;++n) _Pragma("unroll") for(int k=0;k<2;++k) \
;       acc[ai][bj][m][n]=__builtin_amdgcn_mfma_f32_16x16x32_bf16(Bt_[n][k],At_[m][k],acc[ai][bj][m][n],0,0,0); \
;     __builtin_amdgcn_s_setprio(0);}while(0)
; #define WAIT_V(n) asm volatile("s_waitcnt vmcnt(" #n ")":::"memory")
; #define WAIT_L(n) asm volatile("s_waitcnt lgkmcnt(" #n ")":::"memory")
; #define BAR __builtin_amdgcn_s_barrier()
; DEVINL void gemm8_mainloop(const u16* A, long lda, const u16* Bt, long ldb, int K, int brow, int bcol, f32x4 (&acc)[2][2][4][2], char* smem, int tid) {
;     ...
;     BAR; WAIT_L(0); MMA(0,0,At,B0); BAR;
;     LDB(B1,0,1); BAR; WAIT_L(0); MMA(0,1,At,B1); BAR;
;     LDA(At,0,1); WAIT_V(4); BAR; WAIT_L(0); MMA(1,0,At,B0); MMA(1,1,At,B1); BAR; }
;   { LDB(B0,1,0); LDA(At,1,0); WAIT_V(2); BAR; WAIT_L(0); MMA(0,0,At,B0); BAR;
	s_nop 2
	ds_read_b128 v[100:103], v161
	ds_read_b128 v[108:111], v161 offset:1024
	ds_read_b128 v[220:223], v161 offset:2048
	ds_read_b128 v[224:227], v161 offset:3072
	s_barrier
	s_waitcnt lgkmcnt(0)
	s_setprio 1
	v_mfma_f32_16x16x32_bf16 v[88:91], v[220:223], v[184:187], v[88:91]
	v_mfma_f32_16x16x32_bf16 v[80:83], v[220:223], v[192:195], v[80:83]
	v_mfma_f32_16x16x32_bf16 v[72:75], v[220:223], v[200:203], v[72:75]
	v_mfma_f32_16x16x32_bf16 v[64:67], v[220:223], v[208:211], v[64:67]
	v_mfma_f32_16x16x32_bf16 v[92:95], v[100:103], v[184:187], v[92:95]
	v_mfma_f32_16x16x32_bf16 v[88:91], v[224:227], v[188:191], v[88:91]
	v_mfma_f32_16x16x32_bf16 v[84:87], v[100:103], v[192:195], v[84:87]
	v_mfma_f32_16x16x32_bf16 v[80:83], v[224:227], v[196:199], v[80:83]
	v_mfma_f32_16x16x32_bf16 v[76:79], v[100:103], v[200:203], v[76:79]
	v_mfma_f32_16x16x32_bf16 v[72:75], v[224:227], v[204:207], v[72:75]
	v_mfma_f32_16x16x32_bf16 v[68:71], v[100:103], v[208:211], v[68:71]
	v_mfma_f32_16x16x32_bf16 v[64:67], v[224:227], v[212:215], v[64:67]
	v_mfma_f32_16x16x32_bf16 v[228:231], v[108:111], v[188:191], v[92:95]
	v_mfma_f32_16x16x32_bf16 v[184:187], v[108:111], v[196:199], v[84:87]
	v_mfma_f32_16x16x32_bf16 v[188:191], v[108:111], v[204:207], v[76:79]
	v_mfma_f32_16x16x32_bf16 v[192:195], v[108:111], v[212:215], v[68:71]
	s_setprio 0
	s_barrier
	s_nop 0
	ds_read_b128 v[68:71], v155 offset:16384
	ds_read_b128 v[76:79], v155 offset:17408
	ds_read_b128 v[84:87], v173 offset:16384
	ds_read_b128 v[92:95], v173 offset:17408
	ds_read_b128 v[196:199], v174 offset:16384
	ds_read_b128 v[200:203], v174 offset:17408
	ds_read_b128 v[204:207], v175 offset:16384
	ds_read_b128 v[208:211], v175 offset:17408
	s_waitcnt vmcnt(4)
	s_barrier
	s_waitcnt lgkmcnt(0)
	s_setprio 1
	v_mfma_f32_16x16x32_bf16 v[60:63], v[142:145], v[68:71], v[60:63]
	v_mfma_f32_16x16x32_bf16 v[56:59], v[180:183], v[68:71], v[56:59]
	v_mfma_f32_16x16x32_bf16 v[48:51], v[180:183], v[84:87], v[48:51]
	v_mfma_f32_16x16x32_bf16 v[40:43], v[180:183], v[196:199], v[40:43]
	v_mfma_f32_16x16x32_bf16 v[32:35], v[180:183], v[204:207], v[32:35]
	v_mfma_f32_16x16x32_bf16 v[60:63], v[146:149], v[76:79], v[60:63]
	v_mfma_f32_16x16x32_bf16 v[56:59], v[162:165], v[76:79], v[56:59]
	v_mfma_f32_16x16x32_bf16 v[52:55], v[142:145], v[84:87], v[52:55]
	v_mfma_f32_16x16x32_bf16 v[48:51], v[162:165], v[92:95], v[48:51]
	v_mfma_f32_16x16x32_bf16 v[44:47], v[142:145], v[196:199], v[44:47]
	v_mfma_f32_16x16x32_bf16 v[40:43], v[162:165], v[200:203], v[40:43]
	v_mfma_f32_16x16x32_bf16 v[36:39], v[142:145], v[204:207], v[36:39]
	v_mfma_f32_16x16x32_bf16 v[32:35], v[162:165], v[208:211], v[32:35]
	v_mfma_f32_16x16x32_bf16 v[212:215], v[146:149], v[92:95], v[52:55]
	v_mfma_f32_16x16x32_bf16 v[232:235], v[146:149], v[200:203], v[44:47]
	v_mfma_f32_16x16x32_bf16 v[142:145], v[146:149], v[208:211], v[36:39]
	s_setprio 0
	s_setprio 1
	v_mfma_f32_16x16x32_bf16 v[24:27], v[220:223], v[68:71], v[24:27]
	v_mfma_f32_16x16x32_bf16 v[16:19], v[220:223], v[84:87], v[16:19]
	v_mfma_f32_16x16x32_bf16 v[4:7], v[100:103], v[204:207], v[4:7]
	v_mfma_f32_16x16x32_bf16 v[0:3], v[220:223], v[204:207], v[0:3]
	v_mfma_f32_16x16x32_bf16 v[28:31], v[100:103], v[68:71], v[28:31]
	v_mfma_f32_16x16x32_bf16 v[24:27], v[224:227], v[76:79], v[24:27]
	v_mfma_f32_16x16x32_bf16 v[20:23], v[100:103], v[84:87], v[20:23]
	v_mfma_f32_16x16x32_bf16 v[16:19], v[224:227], v[92:95], v[16:19]
	v_mfma_f32_16x16x32_bf16 v[12:15], v[100:103], v[196:199], v[12:15]
	v_mfma_f32_16x16x32_bf16 v[8:11], v[220:223], v[196:199], v[8:11]
	v_mfma_f32_16x16x32_bf16 v[4:7], v[108:111], v[208:211], v[4:7]
	v_mfma_f32_16x16x32_bf16 v[0:3], v[224:227], v[208:211], v[0:3]
	v_mfma_f32_16x16x32_bf16 v[146:149], v[108:111], v[76:79], v[28:31]
	v_mfma_f32_16x16x32_bf16 v[160:163], v[108:111], v[92:95], v[20:23]
	v_mfma_f32_16x16x32_bf16 v[178:181], v[108:111], v[200:203], v[12:15]
	v_mfma_f32_16x16x32_bf16 v[196:199], v[224:227], v[200:203], v[8:11]
	s_setprio 0
	s_barrier
	s_nop 0
	ds_read_b128 v[8:11], v158
	ds_read_b128 v[12:15], v158 offset:1024
	ds_read_b128 v[200:203], v158 offset:2048
	ds_read_b128 v[204:207], v158 offset:3072
	ds_read_b128 v[20:23], v155 offset:32768
	ds_read_b128 v[28:31], v155 offset:33792
	ds_read_b128 v[36:39], v173 offset:32768
	ds_read_b128 v[44:47], v173 offset:33792
	ds_read_b128 v[52:55], v174 offset:32768
	ds_read_b128 v[208:211], v174 offset:33792
	ds_read_b128 v[220:223], v175 offset:32768
	ds_read_b128 v[224:227], v175 offset:33792
	s_waitcnt vmcnt(2)
	s_barrier
; #define LDA(dst,b,h) _Pragma("unroll") for(int m=0;m<4;++m) _Pragma("unroll") for(int k=0;k<2;++k) \
;     dst[m][k]=*reinterpret_cast<const bf16x8*>((char*)SA(b,h)+lds_byte(wr*64+m*16+fr,k*32+fq*8))
; #define LDB(dst,b,h) _Pragma("unroll") for(int n=0;n<2;++n) _Pragma("unroll") for(int k=0;k<2;++k) \
;     dst[n][k]=*reinterpret_cast<const bf16x8*>((char*)SB(b,h)+lds_byte(wc*32+n*16+fr,k*32+fq*8))
; #define MMA(ai,bj,At_,Bt_) do{__builtin_amdgcn_s_setprio(1); \
;     _Pragma("unroll") for(int m=0;m<4;++m) _Pragma("unroll") for(int n=0;n<2;++n) _Pragma("unroll") for(int k=0;k<2;++k) \
;       acc[ai][bj][m][n]=__builtin_amdgcn_mfma_f32_16x16x32_bf16(Bt_[n][k],At_[m][k],acc[ai][bj][m][n],0,0,0); \
;     __builtin_amdgcn_s_setprio(0);}while(0)
; #define WAIT_V(n) asm volatile("s_waitcnt vmcnt(" #n ")":::"memory")
; #define WAIT_L(n) asm volatile("s_waitcnt lgkmcnt(" #n ")":::"memory")
; #define BAR __builtin_amdgcn_s_barrier()
; DEVINL void gemm8_mainloop(const u16* A, long lda, const u16* Bt, long ldb, int K, int brow, int bcol, f32x4 (&acc)[2][2][4][2], char* smem, int tid) {
;     ...
;     LDA(At,0,1); WAIT_V(4); BAR; WAIT_L(0); MMA(1,0,At,B0); MMA(1,1,At,B1); BAR; }
;   { LDB(B0,1,0); LDA(At,1,0); WAIT_V(2); BAR; WAIT_L(0); MMA(0,0,At,B0); BAR;
;     LDB(B1,1,1); WAIT_V(0); BAR; WAIT_L(0); MMA(0,1,At,B1); BAR;
;     LDA(At,1,1); BAR; WAIT_L(0); MMA(1,0,At,B0); MMA(1,1,At,B1); BAR; }
;   if(wr==0)BAR;
	s_waitcnt lgkmcnt(0)
	s_setprio 1
	v_mfma_f32_16x16x32_bf16 v[68:71], v[8:11], v[20:23], v[124:127]
	v_mfma_f32_16x16x32_bf16 v[124:127], v[12:15], v[28:31], v[68:71]
	v_mfma_f32_16x16x32_bf16 v[68:71], v[200:203], v[20:23], v[120:123]
	v_mfma_f32_16x16x32_bf16 v[120:123], v[204:207], v[28:31], v[68:71]
	v_mfma_f32_16x16x32_bf16 v[68:71], v[8:11], v[36:39], v[116:119]
	v_mfma_f32_16x16x32_bf16 v[108:111], v[12:15], v[44:47], v[68:71]
	v_mfma_f32_16x16x32_bf16 v[68:71], v[200:203], v[36:39], v[112:115]
	v_mfma_f32_16x16x32_bf16 v[100:103], v[204:207], v[44:47], v[68:71]
	v_mfma_f32_16x16x32_bf16 v[68:71], v[8:11], v[52:55], v[138:141]
	v_mfma_f32_16x16x32_bf16 v[92:95], v[12:15], v[208:211], v[68:71]
	v_mfma_f32_16x16x32_bf16 v[68:71], v[200:203], v[52:55], v[104:107]
	v_mfma_f32_16x16x32_bf16 v[84:87], v[204:207], v[208:211], v[68:71]
	v_mfma_f32_16x16x32_bf16 v[68:71], v[8:11], v[220:223], v[216:219]
	v_mfma_f32_16x16x32_bf16 v[76:79], v[12:15], v[224:227], v[68:71]
	v_mfma_f32_16x16x32_bf16 v[68:71], v[200:203], v[220:223], v[96:99]
	v_mfma_f32_16x16x32_bf16 v[68:71], v[204:207], v[224:227], v[68:71]
	s_setprio 0
	s_barrier
	ds_read_b128 v[138:141], v156
	ds_read_b128 v[216:219], v156 offset:1024
	ds_read_b128 v[236:239], v156 offset:2048
	ds_read_b128 v[156:159], v156 offset:3072
	s_waitcnt vmcnt(0)
	s_barrier
	s_waitcnt lgkmcnt(0)
	s_setprio 1
	v_mfma_f32_16x16x32_bf16 v[96:99], v[138:141], v[20:23], v[228:231]
	v_mfma_f32_16x16x32_bf16 v[20:23], v[236:239], v[20:23], v[88:91]
	v_mfma_f32_16x16x32_bf16 v[112:115], v[156:159], v[28:31], v[20:23]
	v_mfma_f32_16x16x32_bf16 v[20:23], v[138:141], v[36:39], v[184:187]
	v_mfma_f32_16x16x32_bf16 v[104:107], v[216:219], v[44:47], v[20:23]
	v_mfma_f32_16x16x32_bf16 v[20:23], v[236:239], v[36:39], v[80:83]
	v_mfma_f32_16x16x32_bf16 v[116:119], v[216:219], v[28:31], v[96:99]
	v_mfma_f32_16x16x32_bf16 v[96:99], v[156:159], v[44:47], v[20:23]
	v_mfma_f32_16x16x32_bf16 v[20:23], v[138:141], v[52:55], v[188:191]
	v_mfma_f32_16x16x32_bf16 v[88:91], v[216:219], v[208:211], v[20:23]
	v_mfma_f32_16x16x32_bf16 v[20:23], v[236:239], v[52:55], v[72:75]
	v_mfma_f32_16x16x32_bf16 v[80:83], v[156:159], v[208:211], v[20:23]
	v_mfma_f32_16x16x32_bf16 v[20:23], v[138:141], v[220:223], v[192:195]
	v_mfma_f32_16x16x32_bf16 v[72:75], v[216:219], v[224:227], v[20:23]
	v_mfma_f32_16x16x32_bf16 v[20:23], v[236:239], v[220:223], v[64:67]
	v_mfma_f32_16x16x32_bf16 v[64:67], v[156:159], v[224:227], v[20:23]
	s_setprio 0
	s_barrier
	ds_read_b128 v[182:185], v155 offset:49152
	ds_read_b128 v[186:189], v155 offset:50176
	ds_read_b128 v[190:193], v173 offset:49152
	ds_read_b128 v[208:211], v173 offset:50176
	ds_read_b128 v[220:223], v174 offset:49152
	ds_read_b128 v[224:227], v174 offset:50176
	ds_read_b128 v[228:231], v175 offset:49152
	ds_read_b128 v[240:243], v175 offset:50176
	s_barrier
	s_waitcnt lgkmcnt(0)
	s_setprio 1
	v_mfma_f32_16x16x32_bf16 v[20:23], v[8:11], v[182:185], v[60:63]
	v_mfma_f32_16x16x32_bf16 v[60:63], v[12:15], v[186:189], v[20:23]
	v_mfma_f32_16x16x32_bf16 v[20:23], v[200:203], v[182:185], v[56:59]
	v_mfma_f32_16x16x32_bf16 v[52:55], v[204:207], v[186:189], v[20:23]
	v_mfma_f32_16x16x32_bf16 v[20:23], v[8:11], v[190:193], v[212:215]
	v_mfma_f32_16x16x32_bf16 v[44:47], v[12:15], v[208:211], v[20:23]
	v_mfma_f32_16x16x32_bf16 v[20:23], v[200:203], v[190:193], v[48:51]
	v_mfma_f32_16x16x32_bf16 v[36:39], v[204:207], v[208:211], v[20:23]
	v_mfma_f32_16x16x32_bf16 v[20:23], v[8:11], v[220:223], v[232:235]
	v_mfma_f32_16x16x32_bf16 v[8:11], v[8:11], v[228:231], v[142:145]
	v_mfma_f32_16x16x32_bf16 v[28:31], v[12:15], v[224:227], v[20:23]
	v_mfma_f32_16x16x32_bf16 v[20:23], v[200:203], v[220:223], v[40:43]
	v_mfma_f32_16x16x32_bf16 v[12:15], v[12:15], v[240:243], v[8:11]
	v_mfma_f32_16x16x32_bf16 v[8:11], v[200:203], v[228:231], v[32:35]
	v_mfma_f32_16x16x32_bf16 v[20:23], v[204:207], v[224:227], v[20:23]
	v_mfma_f32_16x16x32_bf16 v[8:11], v[204:207], v[240:243], v[8:11]
	s_setprio 0
	s_setprio 1
	v_mfma_f32_16x16x32_bf16 v[32:35], v[138:141], v[182:185], v[146:149]
	v_mfma_f32_16x16x32_bf16 v[24:27], v[236:239], v[182:185], v[24:27]
	v_mfma_f32_16x16x32_bf16 v[16:19], v[236:239], v[190:193], v[16:19]
	v_mfma_f32_16x16x32_bf16 v[56:59], v[216:219], v[186:189], v[32:35]
	v_mfma_f32_16x16x32_bf16 v[48:51], v[156:159], v[186:189], v[24:27]
	v_mfma_f32_16x16x32_bf16 v[24:27], v[138:141], v[190:193], v[160:163]
	v_mfma_f32_16x16x32_bf16 v[32:35], v[156:159], v[208:211], v[16:19]
	v_mfma_f32_16x16x32_bf16 v[16:19], v[138:141], v[220:223], v[178:181]
	v_mfma_f32_16x16x32_bf16 v[40:43], v[216:219], v[208:211], v[24:27]
	v_mfma_f32_16x16x32_bf16 v[24:27], v[216:219], v[224:227], v[16:19]
	v_mfma_f32_16x16x32_bf16 v[16:19], v[236:239], v[220:223], v[196:199]
	v_mfma_f32_16x16x32_bf16 v[4:7], v[138:141], v[228:231], v[4:7]
	v_mfma_f32_16x16x32_bf16 v[0:3], v[236:239], v[228:231], v[0:3]
	v_mfma_f32_16x16x32_bf16 v[16:19], v[156:159], v[224:227], v[16:19]
	v_mfma_f32_16x16x32_bf16 v[4:7], v[216:219], v[240:243], v[4:7]
	v_mfma_f32_16x16x32_bf16 v[0:3], v[156:159], v[240:243], v[0:3]
	s_setprio 0
	s_cmpk_gt_u32 s37, 0xff
	s_barrier
	s_cbranch_scc1 .LBB0_1941
	s_barrier

; #define STAGE(P,BASE,LD,br,kt) do{long _g=(long)(br)*(LD)+(long)(kt)*BK; \
;     _Pragma("unroll") for(int _i=0;_i<2;++_i){int _b=tid*16+_i*8192;int _r,_c;stage_rc(_b,_r,_c); \
;       __builtin_amdgcn_global_load_lds((const unsigned*)((BASE)+_g+(long)_r*(LD)+_c), \
;         (unsigned*)((char*)(P)+_b),16,0,0);}}while(0)
; #define STAGE(P,BASE,LD,br,kt) do{long _g=(long)(br)*(LD)+(long)(kt)*BK; \
;     _Pragma("unroll") for(int _i=0;_i<2;++_i){int _b=tid*16+_i*8192;int _r,_c;stage_rc(_b,_r,_c); \
;       __builtin_amdgcn_global_load_lds((const unsigned*)((BASE)+_g+(long)_r*(LD)+_c), \
;         (unsigned*)((char*)(P)+_b),16,0,0);}}while(0)
; #define LDA(dst,b,h) _Pragma("unroll") for(int m=0;m<4;++m) _Pragma("unroll") for(int k=0;k<2;++k) \
;     dst[m][k]=*reinterpret_cast<const bf16x8*>((char*)SA(b,h)+lds_byte(wr*64+m*16+fr,k*32+fq*8))
; #define LDB(dst,b,h) _Pragma("unroll") for(int n=0;n<2;++n) _Pragma("unroll") for(int k=0;k<2;++k) \
;     dst[n][k]=*reinterpret_cast<const bf16x8*>((char*)SB(b,h)+lds_byte(wc*32+n*16+fr,k*32+fq*8))
; #define MMA(ai,bj,At_,Bt_) do{__builtin_amdgcn_s_setprio(1); \
;     _Pragma("unroll") for(int m=0;m<4;++m) _Pragma("unroll") for(int n=0;n<2;++n) _Pragma("unroll") for(int k=0;k<2;++k) \
;       acc[ai][bj][m][n]=__builtin_amdgcn_mfma_f32_16x16x32_bf16(Bt_[n][k],At_[m][k],acc[ai][bj][m][n],0,0,0); \
;     __builtin_amdgcn_s_setprio(0);}while(0)
; #define WAIT_L(n) asm volatile("s_waitcnt lgkmcnt(" #n ")":::"memory")
; #define BAR __builtin_amdgcn_s_barrier()
; #define SCHED __builtin_amdgcn_sched_barrier(0)
; DEVINL void gemm8_mainloop(const u16* A, long lda, const u16* Bt, long ldb, int K, int brow, int bcol, f32x4 (&acc)[2][2][4][2], char* smem, int tid) {
;     ...
;   for(int t=0;t<nt-2;t+=2){
;     LDB(B0,0,0); SCHED; LDA(At,0,0); STAGE(SA(1,1),A,lda,brow+HALF,t+1);
;     WAIT_L(8); BAR; WAIT_L(0); MMA(0,0,At,B0); BAR; SCHED;
;     LDB(B1,0,1); STAGE(SB(0,0),Bt,ldb,bcol,t+2);
;     BAR; WAIT_L(0); MMA(0,1,At,B1); BAR;
;     LDA(At,0,1); STAGE(SA(0,0),A,lda,brow,t+2);
;     BAR; WAIT_L(0); MMA(1,0,At,B0); BAR; SCHED;
;     STAGE(SB(0,1),Bt,ldb,bcol+HALF,t+2);
.LBB0_1987:
	ds_read_b128 v[178:181], v163
	ds_read_b128 v[182:185], v163 offset:1024
	ds_read_b128 v[186:189], v163 offset:2048
	ds_read_b128 v[190:193], v163 offset:3072
	v_add_u32_e32 v174, 0xc000, v152
	v_lshl_add_u64 v[242:243], s[94:95], 0, v[146:147]
	v_readfirstlane_b32 s25, v174
	v_add_u32_e32 v175, 0xe000, v152
	v_add_u32_e32 v171, s23, v162
	v_add_u32_e32 v172, s34, v162
	v_add_u32_e32 v173, s35, v162
	v_lshl_add_u64 v[164:165], v[242:243], 0, s[2:3]
	s_mov_b32 m0, s25
	v_lshl_add_u64 v[244:245], s[94:95], 0, v[148:149]
	v_readfirstlane_b32 s25, v175
	ds_read_b128 v[166:169], v153
	ds_read_b128 v[194:197], v153 offset:1024
	ds_read_b128 v[198:201], v171
	ds_read_b128 v[202:205], v171 offset:1024
	ds_read_b128 v[206:209], v172
	ds_read_b128 v[210:213], v172 offset:1024
	ds_read_b128 v[214:217], v173
	ds_read_b128 v[218:221], v173 offset:1024
	global_load_lds_dwordx4 v[164:165], off
	v_lshl_add_u64 v[164:165], v[244:245], 0, s[2:3]
	s_mov_b32 m0, s25
	s_nop 0
	global_load_lds_dwordx4 v[164:165], off
	s_waitcnt lgkmcnt(8)
	s_barrier
	s_waitcnt lgkmcnt(0)
	s_setprio 1
	v_mfma_f32_16x16x32_bf16 v[124:127], v[178:181], v[166:169], v[124:127]
	v_mfma_f32_16x16x32_bf16 v[120:123], v[186:189], v[166:169], v[120:123]
	v_mfma_f32_16x16x32_bf16 v[116:119], v[178:181], v[198:201], v[116:119]
	v_mfma_f32_16x16x32_bf16 v[112:115], v[186:189], v[198:201], v[112:115]
	v_mfma_f32_16x16x32_bf16 v[108:111], v[178:181], v[206:209], v[108:111]
	v_mfma_f32_16x16x32_bf16 v[104:107], v[186:189], v[206:209], v[104:107]
	v_mfma_f32_16x16x32_bf16 v[100:103], v[178:181], v[214:217], v[100:103]
	v_mfma_f32_16x16x32_bf16 v[96:99], v[186:189], v[214:217], v[96:99]
	v_mfma_f32_16x16x32_bf16 v[124:127], v[182:185], v[194:197], v[124:127]
	v_mfma_f32_16x16x32_bf16 v[120:123], v[190:193], v[194:197], v[120:123]
	v_mfma_f32_16x16x32_bf16 v[116:119], v[182:185], v[202:205], v[116:119]
	v_mfma_f32_16x16x32_bf16 v[112:115], v[190:193], v[202:205], v[112:115]
	v_mfma_f32_16x16x32_bf16 v[108:111], v[182:185], v[210:213], v[108:111]
	v_mfma_f32_16x16x32_bf16 v[104:107], v[190:193], v[210:213], v[104:107]
	v_mfma_f32_16x16x32_bf16 v[100:103], v[182:185], v[218:221], v[100:103]
	v_mfma_f32_16x16x32_bf16 v[96:99], v[190:193], v[218:221], v[96:99]
	s_setprio 0
	s_barrier
	v_add_u32_e32 v164, s28, v154
	v_lshl_add_u64 v[246:247], s[94:95], 0, v[142:143]
	v_readfirstlane_b32 s25, v164
	v_add_u32_e32 v165, 0x2000, v164
	v_lshl_add_u64 v[238:239], v[246:247], 0, s[4:5]
	s_mov_b32 m0, s25
	v_lshl_add_u64 v[248:249], s[94:95], 0, v[144:145]
	v_readfirstlane_b32 s25, v165
	ds_read_b128 v[222:225], v160
	ds_read_b128 v[226:229], v160 offset:1024
	ds_read_b128 v[230:233], v160 offset:2048
	ds_read_b128 v[234:237], v160 offset:3072
	global_load_lds_dwordx4 v[238:239], off
	v_lshl_add_u64 v[238:239], v[248:249], 0, s[4:5]
	s_mov_b32 m0, s25
	s_nop 0
	global_load_lds_dwordx4 v[238:239], off
	s_barrier
	s_waitcnt lgkmcnt(0)
	s_setprio 1
	v_mfma_f32_16x16x32_bf16 v[92:95], v[222:225], v[166:169], v[92:95]
	v_mfma_f32_16x16x32_bf16 v[88:91], v[230:233], v[166:169], v[88:91]
	v_mfma_f32_16x16x32_bf16 v[84:87], v[222:225], v[198:201], v[84:87]
	v_mfma_f32_16x16x32_bf16 v[80:83], v[230:233], v[198:201], v[80:83]
	v_mfma_f32_16x16x32_bf16 v[76:79], v[222:225], v[206:209], v[76:79]
	v_mfma_f32_16x16x32_bf16 v[72:75], v[230:233], v[206:209], v[72:75]
	v_mfma_f32_16x16x32_bf16 v[68:71], v[222:225], v[214:217], v[68:71]
	v_mfma_f32_16x16x32_bf16 v[64:67], v[230:233], v[214:217], v[64:67]
	v_mfma_f32_16x16x32_bf16 v[92:95], v[226:229], v[194:197], v[92:95]
	v_mfma_f32_16x16x32_bf16 v[88:91], v[234:237], v[194:197], v[88:91]
	v_mfma_f32_16x16x32_bf16 v[84:87], v[226:229], v[202:205], v[84:87]
	v_mfma_f32_16x16x32_bf16 v[80:83], v[234:237], v[202:205], v[80:83]
	v_mfma_f32_16x16x32_bf16 v[76:79], v[226:229], v[210:213], v[76:79]
	v_mfma_f32_16x16x32_bf16 v[72:75], v[234:237], v[210:213], v[72:75]
	v_mfma_f32_16x16x32_bf16 v[68:71], v[226:229], v[218:221], v[68:71]
	v_mfma_f32_16x16x32_bf16 v[64:67], v[234:237], v[218:221], v[64:67]
	s_setprio 0
	v_readfirstlane_b32 s25, v152
	v_lshl_add_u64 v[166:167], v[242:243], 0, s[6:7]
	s_mov_b32 m0, s25
	s_barrier
	ds_read_b128 v[194:197], v153 offset:16384
	ds_read_b128 v[198:201], v153 offset:17408
	ds_read_b128 v[202:205], v171 offset:16384
	ds_read_b128 v[206:209], v171 offset:17408
	ds_read_b128 v[210:213], v172 offset:16384
	ds_read_b128 v[214:217], v172 offset:17408
	ds_read_b128 v[218:221], v173 offset:16384
	ds_read_b128 v[238:241], v173 offset:17408
	global_load_lds_dwordx4 v[166:167], off
	v_add_u32_e32 v166, 0x2000, v152
	v_lshl_add_u64 v[168:169], v[244:245], 0, s[6:7]
	v_readfirstlane_b32 s25, v166
	s_mov_b32 m0, s25
	s_nop 0
	global_load_lds_dwordx4 v[168:169], off
	s_barrier
	s_waitcnt lgkmcnt(0)
	s_setprio 1
	v_mfma_f32_16x16x32_bf16 v[60:63], v[178:181], v[194:197], v[60:63]
	v_mfma_f32_16x16x32_bf16 v[56:59], v[186:189], v[194:197], v[56:59]
	v_mfma_f32_16x16x32_bf16 v[52:55], v[178:181], v[202:205], v[52:55]
	v_mfma_f32_16x16x32_bf16 v[48:51], v[186:189], v[202:205], v[48:51]
	v_mfma_f32_16x16x32_bf16 v[44:47], v[178:181], v[210:213], v[44:47]
	v_mfma_f32_16x16x32_bf16 v[40:43], v[186:189], v[210:213], v[40:43]
	v_mfma_f32_16x16x32_bf16 v[36:39], v[178:181], v[218:221], v[36:39]
	v_mfma_f32_16x16x32_bf16 v[32:35], v[186:189], v[218:221], v[32:35]
	v_mfma_f32_16x16x32_bf16 v[60:63], v[182:185], v[198:201], v[60:63]
	v_mfma_f32_16x16x32_bf16 v[56:59], v[190:193], v[198:201], v[56:59]
	v_mfma_f32_16x16x32_bf16 v[52:55], v[182:185], v[206:209], v[52:55]
	v_mfma_f32_16x16x32_bf16 v[48:51], v[190:193], v[206:209], v[48:51]
	v_mfma_f32_16x16x32_bf16 v[44:47], v[182:185], v[214:217], v[44:47]
	v_mfma_f32_16x16x32_bf16 v[40:43], v[190:193], v[214:217], v[40:43]
	v_mfma_f32_16x16x32_bf16 v[36:39], v[182:185], v[238:241], v[36:39]
	v_mfma_f32_16x16x32_bf16 v[32:35], v[190:193], v[238:241], v[32:35]
	s_setprio 0
	s_barrier
; #define STAGE(P,BASE,LD,br,kt) do{long _g=(long)(br)*(LD)+(long)(kt)*BK; \
;     _Pragma("unroll") for(int _i=0;_i<2;++_i){int _b=tid*16+_i*8192;int _r,_c;stage_rc(_b,_r,_c); \
;       __builtin_amdgcn_global_load_lds((const unsigned*)((BASE)+_g+(long)_r*(LD)+_c), \
;         (unsigned*)((char*)(P)+_b),16,0,0);}}while(0)
; #define STAGE(P,BASE,LD,br,kt) do{long _g=(long)(br)*(LD)+(long)(kt)*BK; \
;     _Pragma("unroll") for(int _i=0;_i<2;++_i){int _b=tid*16+_i*8192;int _r,_c;stage_rc(_b,_r,_c); \
;       __builtin_amdgcn_global_load_lds((const unsigned*)((BASE)+_g+(long)_r*(LD)+_c), \
;         (unsigned*)((char*)(P)+_b),16,0,0);}}while(0)
; #define LDA(dst,b,h) _Pragma("unroll") for(int m=0;m<4;++m) _Pragma("unroll") for(int k=0;k<2;++k) \
;     dst[m][k]=*reinterpret_cast<const bf16x8*>((char*)SA(b,h)+lds_byte(wr*64+m*16+fr,k*32+fq*8))
; #define LDB(dst,b,h) _Pragma("unroll") for(int n=0;n<2;++n) _Pragma("unroll") for(int k=0;k<2;++k) \
;     dst[n][k]=*reinterpret_cast<const bf16x8*>((char*)SB(b,h)+lds_byte(wc*32+n*16+fr,k*32+fq*8))
; #define MMA(ai,bj,At_,Bt_) do{__builtin_amdgcn_s_setprio(1); \
;     _Pragma("unroll") for(int m=0;m<4;++m) _Pragma("unroll") for(int n=0;n<2;++n) _Pragma("unroll") for(int k=0;k<2;++k) \
;       acc[ai][bj][m][n]=__builtin_amdgcn_mfma_f32_16x16x32_bf16(Bt_[n][k],At_[m][k],acc[ai][bj][m][n],0,0,0); \
;     __builtin_amdgcn_s_setprio(0);}while(0)
; #define WAIT_V(n) asm volatile("s_waitcnt vmcnt(" #n ")":::"memory")
; #define WAIT_L(n) asm volatile("s_waitcnt lgkmcnt(" #n ")":::"memory")
; #define BAR __builtin_amdgcn_s_barrier()
; #define SCHED __builtin_amdgcn_sched_barrier(0)
; DEVINL void gemm8_mainloop(const u16* A, long lda, const u16* Bt, long ldb, int K, int brow, int bcol, f32x4 (&acc)[2][2][4][2], char* smem, int tid) {
;     ...
;     STAGE(SB(0,1),Bt,ldb,bcol+HALF,t+2);
;     WAIT_V(6); BAR; MMA(1,1,At,B1); BAR;
;     LDB(B0,1,0); SCHED; LDA(At,1,0); STAGE(SA(0,1),A,lda,brow+HALF,t+2);
;     WAIT_L(8); BAR; WAIT_L(0); MMA(0,0,At,B0); BAR; SCHED;
;     LDB(B1,1,1); STAGE(SB(1,0),Bt,ldb,bcol,t+3);
;     BAR; WAIT_L(0); MMA(0,1,At,B1); BAR;
;     LDA(At,1,1); STAGE(SA(1,0),A,lda,brow,t+3);
	v_add_u32_e32 v167, s29, v154
	v_lshl_add_u64 v[168:169], v[246:247], 0, s[8:9]
	v_readfirstlane_b32 s25, v167
	s_mov_b32 m0, s25
	v_lshl_add_u64 v[178:179], v[248:249], 0, s[8:9]
	global_load_lds_dwordx4 v[168:169], off
	v_add_u32_e32 v168, 0x2000, v167
	s_nop 0
	v_readfirstlane_b32 s25, v168
	s_mov_b32 m0, s25
	s_nop 0
	global_load_lds_dwordx4 v[178:179], off
	s_waitcnt vmcnt(6)
	s_barrier
	s_setprio 1
	v_mfma_f32_16x16x32_bf16 v[28:31], v[222:225], v[194:197], v[28:31]
	v_mfma_f32_16x16x32_bf16 v[24:27], v[230:233], v[194:197], v[24:27]
	v_mfma_f32_16x16x32_bf16 v[20:23], v[222:225], v[202:205], v[20:23]
	v_mfma_f32_16x16x32_bf16 v[16:19], v[230:233], v[202:205], v[16:19]
	v_mfma_f32_16x16x32_bf16 v[12:15], v[222:225], v[210:213], v[12:15]
	v_mfma_f32_16x16x32_bf16 v[8:11], v[230:233], v[210:213], v[8:11]
	v_mfma_f32_16x16x32_bf16 v[4:7], v[222:225], v[218:221], v[4:7]
	v_mfma_f32_16x16x32_bf16 v[0:3], v[230:233], v[218:221], v[0:3]
	v_mfma_f32_16x16x32_bf16 v[28:31], v[226:229], v[198:201], v[28:31]
	v_mfma_f32_16x16x32_bf16 v[24:27], v[234:237], v[198:201], v[24:27]
	v_mfma_f32_16x16x32_bf16 v[20:23], v[226:229], v[206:209], v[20:23]
	v_mfma_f32_16x16x32_bf16 v[16:19], v[234:237], v[206:209], v[16:19]
	v_mfma_f32_16x16x32_bf16 v[12:15], v[226:229], v[214:217], v[12:15]
	v_mfma_f32_16x16x32_bf16 v[8:11], v[234:237], v[214:217], v[8:11]
	v_mfma_f32_16x16x32_bf16 v[4:7], v[226:229], v[238:241], v[4:7]
	v_mfma_f32_16x16x32_bf16 v[0:3], v[234:237], v[238:241], v[0:3]
	s_setprio 0
	s_barrier
	ds_read_b128 v[178:181], v156
	ds_read_b128 v[182:185], v156 offset:1024
	ds_read_b128 v[186:189], v156 offset:2048
	ds_read_b128 v[190:193], v156 offset:3072
	v_add_u32_e32 v169, 0x4000, v152
	v_add_u32_e32 v170, 0x6000, v152
	v_readfirstlane_b32 s25, v169
	v_lshl_add_u64 v[226:227], v[242:243], 0, s[10:11]
	s_mov_b32 m0, s25
	v_readfirstlane_b32 s25, v170
	ds_read_b128 v[194:197], v153 offset:32768
	ds_read_b128 v[198:201], v153 offset:33792
	ds_read_b128 v[202:205], v171 offset:32768
	ds_read_b128 v[206:209], v171 offset:33792
	ds_read_b128 v[210:213], v172 offset:32768
	ds_read_b128 v[214:217], v172 offset:33792
	ds_read_b128 v[218:221], v173 offset:32768
	ds_read_b128 v[222:225], v173 offset:33792
	global_load_lds_dwordx4 v[226:227], off
	v_lshl_add_u64 v[226:227], v[244:245], 0, s[10:11]
	s_mov_b32 m0, s25
	s_nop 0
	global_load_lds_dwordx4 v[226:227], off
	s_waitcnt lgkmcnt(8)
	s_barrier
	s_waitcnt lgkmcnt(0)
	s_setprio 1
	v_mfma_f32_16x16x32_bf16 v[124:127], v[178:181], v[194:197], v[124:127]
	v_mfma_f32_16x16x32_bf16 v[120:123], v[186:189], v[194:197], v[120:123]
	v_mfma_f32_16x16x32_bf16 v[116:119], v[178:181], v[202:205], v[116:119]
	v_mfma_f32_16x16x32_bf16 v[112:115], v[186:189], v[202:205], v[112:115]
	v_mfma_f32_16x16x32_bf16 v[108:111], v[178:181], v[210:213], v[108:111]
	v_mfma_f32_16x16x32_bf16 v[104:107], v[186:189], v[210:213], v[104:107]
	v_mfma_f32_16x16x32_bf16 v[100:103], v[178:181], v[218:221], v[100:103]
	v_mfma_f32_16x16x32_bf16 v[96:99], v[186:189], v[218:221], v[96:99]
	v_mfma_f32_16x16x32_bf16 v[124:127], v[182:185], v[198:201], v[124:127]
	v_mfma_f32_16x16x32_bf16 v[120:123], v[190:193], v[198:201], v[120:123]
	v_mfma_f32_16x16x32_bf16 v[116:119], v[182:185], v[206:209], v[116:119]
	v_mfma_f32_16x16x32_bf16 v[112:115], v[190:193], v[206:209], v[112:115]
	v_mfma_f32_16x16x32_bf16 v[108:111], v[182:185], v[214:217], v[108:111]
	v_mfma_f32_16x16x32_bf16 v[104:107], v[190:193], v[214:217], v[104:107]
	v_mfma_f32_16x16x32_bf16 v[100:103], v[182:185], v[222:225], v[100:103]
	v_mfma_f32_16x16x32_bf16 v[96:99], v[190:193], v[222:225], v[96:99]
	s_setprio 0
	s_barrier
	v_readfirstlane_b32 s25, v157
	v_add_u32_e32 v177, 0x2000, v157
	v_lshl_add_u64 v[250:251], v[246:247], 0, s[12:13]
	s_mov_b32 m0, s25
	v_readfirstlane_b32 s25, v177
	ds_read_b128 v[226:229], v155
	ds_read_b128 v[230:233], v155 offset:1024
	ds_read_b128 v[234:237], v155 offset:2048
	ds_read_b128 v[238:241], v155 offset:3072
	global_load_lds_dwordx4 v[250:251], off
	v_lshl_add_u64 v[250:251], v[248:249], 0, s[12:13]
	s_mov_b32 m0, s25
	s_nop 0
	global_load_lds_dwordx4 v[250:251], off
	s_barrier
	s_waitcnt lgkmcnt(0)
	s_setprio 1
	v_mfma_f32_16x16x32_bf16 v[92:95], v[226:229], v[194:197], v[92:95]
	v_mfma_f32_16x16x32_bf16 v[88:91], v[234:237], v[194:197], v[88:91]
	v_mfma_f32_16x16x32_bf16 v[84:87], v[226:229], v[202:205], v[84:87]
	v_mfma_f32_16x16x32_bf16 v[80:83], v[234:237], v[202:205], v[80:83]
	v_mfma_f32_16x16x32_bf16 v[76:79], v[226:229], v[210:213], v[76:79]
	v_mfma_f32_16x16x32_bf16 v[72:75], v[234:237], v[210:213], v[72:75]
	v_mfma_f32_16x16x32_bf16 v[68:71], v[226:229], v[218:221], v[68:71]
	v_mfma_f32_16x16x32_bf16 v[64:67], v[234:237], v[218:221], v[64:67]
	v_mfma_f32_16x16x32_bf16 v[92:95], v[230:233], v[198:201], v[92:95]
	v_mfma_f32_16x16x32_bf16 v[88:91], v[238:241], v[198:201], v[88:91]
	v_mfma_f32_16x16x32_bf16 v[84:87], v[230:233], v[206:209], v[84:87]
	v_mfma_f32_16x16x32_bf16 v[80:83], v[238:241], v[206:209], v[80:83]
	v_mfma_f32_16x16x32_bf16 v[76:79], v[230:233], v[214:217], v[76:79]
	v_mfma_f32_16x16x32_bf16 v[72:75], v[238:241], v[214:217], v[72:75]
	v_mfma_f32_16x16x32_bf16 v[68:71], v[230:233], v[222:225], v[68:71]
	v_mfma_f32_16x16x32_bf16 v[64:67], v[238:241], v[222:225], v[64:67]
	s_setprio 0
	v_readfirstlane_b32 s25, v158
	v_lshl_add_u64 v[242:243], v[242:243], 0, s[14:15]
	s_mov_b32 m0, s25
	v_readfirstlane_b32 s25, v159
	s_barrier
; #define STAGE(P,BASE,LD,br,kt) do{long _g=(long)(br)*(LD)+(long)(kt)*BK; \
;     _Pragma("unroll") for(int _i=0;_i<2;++_i){int _b=tid*16+_i*8192;int _r,_c;stage_rc(_b,_r,_c); \
;       __builtin_amdgcn_global_load_lds((const unsigned*)((BASE)+_g+(long)_r*(LD)+_c), \
;         (unsigned*)((char*)(P)+_b),16,0,0);}}while(0)
; #define STAGE(P,BASE,LD,br,kt) do{long _g=(long)(br)*(LD)+(long)(kt)*BK; \
;     _Pragma("unroll") for(int _i=0;_i<2;++_i){int _b=tid*16+_i*8192;int _r,_c;stage_rc(_b,_r,_c); \
;       __builtin_amdgcn_global_load_lds((const unsigned*)((BASE)+_g+(long)_r*(LD)+_c), \
;         (unsigned*)((char*)(P)+_b),16,0,0);}}while(0)
; #define LDA(dst,b,h) _Pragma("unroll") for(int m=0;m<4;++m) _Pragma("unroll") for(int k=0;k<2;++k) \
;     dst[m][k]=*reinterpret_cast<const bf16x8*>((char*)SA(b,h)+lds_byte(wr*64+m*16+fr,k*32+fq*8))
; #define LDB(dst,b,h) _Pragma("unroll") for(int n=0;n<2;++n) _Pragma("unroll") for(int k=0;k<2;++k) \
;     dst[n][k]=*reinterpret_cast<const bf16x8*>((char*)SB(b,h)+lds_byte(wc*32+n*16+fr,k*32+fq*8))
; #define MMA(ai,bj,At_,Bt_) do{__builtin_amdgcn_s_setprio(1); \
;     _Pragma("unroll") for(int m=0;m<4;++m) _Pragma("unroll") for(int n=0;n<2;++n) _Pragma("unroll") for(int k=0;k<2;++k) \
;       acc[ai][bj][m][n]=__builtin_amdgcn_mfma_f32_16x16x32_bf16(Bt_[n][k],At_[m][k],acc[ai][bj][m][n],0,0,0); \
;     __builtin_amdgcn_s_setprio(0);}while(0)
; #define WAIT_V(n) asm volatile("s_waitcnt vmcnt(" #n ")":::"memory")
; #define WAIT_L(n) asm volatile("s_waitcnt lgkmcnt(" #n ")":::"memory")
; #define BAR __builtin_amdgcn_s_barrier()
; #define SCHED __builtin_amdgcn_sched_barrier(0)
; DEVINL void gemm8_mainloop(const u16* A, long lda, const u16* Bt, long ldb, int K, int brow, int bcol, f32x4 (&acc)[2][2][4][2], char* smem, int tid) {
;     ...
;     LDA(At,1,1); STAGE(SA(1,0),A,lda,brow,t+3);
;     BAR; WAIT_L(0); MMA(1,0,At,B0); BAR; SCHED;
;     STAGE(SB(1,1),Bt,ldb,bcol+HALF,t+3);
;     WAIT_V(6); BAR; MMA(1,1,At,B1); BAR;
;   }
;   { LDB(B0,0,0); LDA(At,0,0); STAGE(SA(1,1),A,lda,brow+HALF,nt-1);
;     BAR; WAIT_L(0); MMA(0,0,At,B0); BAR;
	ds_read_b128 v[194:197], v153 offset:49152
	ds_read_b128 v[198:201], v153 offset:50176
	ds_read_b128 v[202:205], v171 offset:49152
	ds_read_b128 v[206:209], v171 offset:50176
	ds_read_b128 v[210:213], v172 offset:49152
	ds_read_b128 v[214:217], v172 offset:50176
	ds_read_b128 v[218:221], v173 offset:49152
	ds_read_b128 v[222:225], v173 offset:50176
	global_load_lds_dwordx4 v[242:243], off
	v_lshl_add_u64 v[242:243], v[244:245], 0, s[14:15]
	s_mov_b32 m0, s25
	s_nop 0
	global_load_lds_dwordx4 v[242:243], off
	s_barrier
	s_waitcnt lgkmcnt(0)
	s_setprio 1
	v_mfma_f32_16x16x32_bf16 v[60:63], v[178:181], v[194:197], v[60:63]
	v_mfma_f32_16x16x32_bf16 v[56:59], v[186:189], v[194:197], v[56:59]
	v_mfma_f32_16x16x32_bf16 v[52:55], v[178:181], v[202:205], v[52:55]
	v_mfma_f32_16x16x32_bf16 v[48:51], v[186:189], v[202:205], v[48:51]
	v_mfma_f32_16x16x32_bf16 v[44:47], v[178:181], v[210:213], v[44:47]
	v_mfma_f32_16x16x32_bf16 v[40:43], v[186:189], v[210:213], v[40:43]
	v_mfma_f32_16x16x32_bf16 v[36:39], v[178:181], v[218:221], v[36:39]
	v_mfma_f32_16x16x32_bf16 v[32:35], v[186:189], v[218:221], v[32:35]
	v_mfma_f32_16x16x32_bf16 v[60:63], v[182:185], v[198:201], v[60:63]
	v_mfma_f32_16x16x32_bf16 v[56:59], v[190:193], v[198:201], v[56:59]
	v_mfma_f32_16x16x32_bf16 v[52:55], v[182:185], v[206:209], v[52:55]
	v_mfma_f32_16x16x32_bf16 v[48:51], v[190:193], v[206:209], v[48:51]
	v_mfma_f32_16x16x32_bf16 v[44:47], v[182:185], v[214:217], v[44:47]
	v_mfma_f32_16x16x32_bf16 v[40:43], v[190:193], v[214:217], v[40:43]
	v_mfma_f32_16x16x32_bf16 v[36:39], v[182:185], v[222:225], v[36:39]
	v_mfma_f32_16x16x32_bf16 v[32:35], v[190:193], v[222:225], v[32:35]
	s_setprio 0
	s_barrier
	v_readfirstlane_b32 s25, v161
	v_add_u32_e32 v177, 0x2000, v161
	v_lshl_add_u64 v[178:179], v[246:247], 0, s[16:17]
	s_mov_b32 m0, s25
	v_readfirstlane_b32 s25, v177
	global_load_lds_dwordx4 v[178:179], off
	v_lshl_add_u64 v[178:179], v[248:249], 0, s[16:17]
	s_mov_b32 m0, s25
	s_nop 0
	global_load_lds_dwordx4 v[178:179], off
	s_waitcnt vmcnt(6)
	s_barrier
	s_setprio 1
	v_mfma_f32_16x16x32_bf16 v[28:31], v[226:229], v[194:197], v[28:31]
	v_mfma_f32_16x16x32_bf16 v[24:27], v[234:237], v[194:197], v[24:27]
	v_mfma_f32_16x16x32_bf16 v[20:23], v[226:229], v[202:205], v[20:23]
	v_mfma_f32_16x16x32_bf16 v[16:19], v[234:237], v[202:205], v[16:19]
	v_mfma_f32_16x16x32_bf16 v[12:15], v[226:229], v[210:213], v[12:15]
	v_mfma_f32_16x16x32_bf16 v[8:11], v[234:237], v[210:213], v[8:11]
	v_mfma_f32_16x16x32_bf16 v[4:7], v[226:229], v[218:221], v[4:7]
	v_mfma_f32_16x16x32_bf16 v[0:3], v[234:237], v[218:221], v[0:3]
	v_mfma_f32_16x16x32_bf16 v[28:31], v[230:233], v[198:201], v[28:31]
	v_mfma_f32_16x16x32_bf16 v[24:27], v[238:241], v[198:201], v[24:27]
	v_mfma_f32_16x16x32_bf16 v[20:23], v[230:233], v[206:209], v[20:23]
	v_mfma_f32_16x16x32_bf16 v[16:19], v[238:241], v[206:209], v[16:19]
	v_mfma_f32_16x16x32_bf16 v[12:15], v[230:233], v[214:217], v[12:15]
	v_mfma_f32_16x16x32_bf16 v[8:11], v[238:241], v[214:217], v[8:11]
	v_mfma_f32_16x16x32_bf16 v[4:7], v[230:233], v[222:225], v[4:7]
	v_mfma_f32_16x16x32_bf16 v[0:3], v[238:241], v[222:225], v[0:3]
	s_setprio 0
	s_add_i32 s24, s24, 2
	v_lshl_add_u64 v[142:143], v[142:143], 0, s[18:19]
	v_lshl_add_u64 v[144:145], v[144:145], 0, s[18:19]
	v_lshl_add_u64 v[146:147], v[146:147], 0, s[18:19]
	s_cmpk_lt_u32 s24, 0x7c
	v_lshl_add_u64 v[148:149], v[148:149], 0, s[18:19]
	s_barrier
	s_cbranch_scc1 .LBB0_1987
	s_or_b32 s24, s22, 0x80
	s_ashr_i32 s25, s24, 31
	s_lshl_b64 s[24:25], s[24:25], 14
	s_add_u32 s23, s62, s24
	s_addc_u32 s25, s63, s25
	s_add_u32 s24, s23, 0x3f80
	s_addc_u32 s25, s25, 0
	v_lshl_add_u64 v[158:159], v[134:135], 1, s[24:25]
	v_readfirstlane_b32 s23, v174
	v_lshl_add_u64 v[138:139], v[138:139], 1, v[158:159]
	s_mov_b32 m0, s23
	ds_read_b128 v[142:145], v163
	ds_read_b128 v[146:149], v163 offset:1024
	ds_read_b128 v[178:181], v163 offset:2048
	ds_read_b128 v[182:185], v163 offset:3072
	ds_read_b128 v[186:189], v153
	ds_read_b128 v[190:193], v153 offset:1024
	ds_read_b128 v[194:197], v171
	ds_read_b128 v[198:201], v171 offset:1024
	ds_read_b128 v[202:205], v172
	ds_read_b128 v[206:209], v172 offset:1024
	ds_read_b128 v[210:213], v173
	ds_read_b128 v[214:217], v173 offset:1024
	global_load_lds_dwordx4 v[138:139], off
	v_lshl_add_u64 v[138:139], v[136:137], 1, s[24:25]
	v_readfirstlane_b32 s23, v175
	v_lshl_add_u64 v[138:139], v[140:141], 1, v[138:139]
	s_mov_b32 m0, s23
	s_nop 0
	global_load_lds_dwordx4 v[138:139], off
	s_barrier
	s_waitcnt lgkmcnt(0)
	s_setprio 1
	v_mfma_f32_16x16x32_bf16 v[124:127], v[142:145], v[186:189], v[124:127]
	v_mfma_f32_16x16x32_bf16 v[120:123], v[178:181], v[186:189], v[120:123]
	v_mfma_f32_16x16x32_bf16 v[116:119], v[142:145], v[194:197], v[116:119]
	v_mfma_f32_16x16x32_bf16 v[112:115], v[178:181], v[194:197], v[112:115]
	v_mfma_f32_16x16x32_bf16 v[100:103], v[142:145], v[210:213], v[100:103]
	v_mfma_f32_16x16x32_bf16 v[96:99], v[178:181], v[210:213], v[96:99]
	v_mfma_f32_16x16x32_bf16 v[124:127], v[146:149], v[190:193], v[124:127]
	v_mfma_f32_16x16x32_bf16 v[120:123], v[182:185], v[190:193], v[120:123]
	v_mfma_f32_16x16x32_bf16 v[116:119], v[146:149], v[198:201], v[116:119]
	v_mfma_f32_16x16x32_bf16 v[112:115], v[182:185], v[198:201], v[112:115]
	v_mfma_f32_16x16x32_bf16 v[108:111], v[142:145], v[202:205], v[108:111]
	v_mfma_f32_16x16x32_bf16 v[104:107], v[178:181], v[202:205], v[104:107]
	v_mfma_f32_16x16x32_bf16 v[100:103], v[146:149], v[214:217], v[100:103]
	v_mfma_f32_16x16x32_bf16 v[96:99], v[182:185], v[214:217], v[96:99]
	v_mfma_f32_16x16x32_bf16 v[138:141], v[146:149], v[206:209], v[108:111]
	v_mfma_f32_16x16x32_bf16 v[218:221], v[182:185], v[206:209], v[104:107]
	s_setprio 0
	s_barrier
; #define LDA(dst,b,h) _Pragma("unroll") for(int m=0;m<4;++m) _Pragma("unroll") for(int k=0;k<2;++k) \
;     dst[m][k]=*reinterpret_cast<const bf16x8*>((char*)SA(b,h)+lds_byte(wr*64+m*16+fr,k*32+fq*8))
; #define LDB(dst,b,h) _Pragma("unroll") for(int n=0;n<2;++n) _Pragma("unroll") for(int k=0;k<2;++k) \
;     dst[n][k]=*reinterpret_cast<const bf16x8*>((char*)SB(b,h)+lds_byte(wc*32+n*16+fr,k*32+fq*8))
; #define MMA(ai,bj,At_,Bt_) do{__builtin_amdgcn_s_setprio(1); \
;     _Pragma("unroll") for(int m=0;m<4;++m) _Pragma("unroll") for(int n=0;n<2;++n) _Pragma("unroll") for(int k=0;k<2;++k) \
;       acc[ai][bj][m][n]=__builtin_amdgcn_mfma_f32_16x16x32_bf16(Bt_[n][k],At_[m][k],acc[ai][bj][m][n],0,0,0); \
;     __builtin_amdgcn_s_setprio(0);}while(0)
; #define WAIT_V(n) asm volatile("s_waitcnt vmcnt(" #n ")":::"memory")
; #define WAIT_L(n) asm volatile("s_waitcnt lgkmcnt(" #n ")":::"memory")
; #define BAR __builtin_amdgcn_s_barrier()
; DEVINL void gemm8_mainloop(const u16* A, long lda, const u16* Bt, long ldb, int K, int brow, int bcol, f32x4 (&acc)[2][2][4][2], char* smem, int tid) {
;     ...
;     BAR; WAIT_L(0); MMA(0,0,At,B0); BAR;
;     LDB(B1,0,1); BAR; WAIT_L(0); MMA(0,1,At,B1); BAR;
;     LDA(At,0,1); WAIT_V(4); BAR; WAIT_L(0); MMA(1,0,At,B0); MMA(1,1,At,B1); BAR; }
;   { LDB(B0,1,0); LDA(At,1,0); WAIT_V(2); BAR; WAIT_L(0); MMA(0,0,At,B0); BAR;
	s_nop 1
	ds_read_b128 v[104:107], v160
	ds_read_b128 v[108:111], v160 offset:1024
	ds_read_b128 v[222:225], v160 offset:2048
	ds_read_b128 v[158:161], v160 offset:3072
	s_barrier
	s_waitcnt lgkmcnt(0)
	s_setprio 1
	v_mfma_f32_16x16x32_bf16 v[84:87], v[104:107], v[194:197], v[84:87]
	v_mfma_f32_16x16x32_bf16 v[80:83], v[222:225], v[194:197], v[80:83]
	v_mfma_f32_16x16x32_bf16 v[68:71], v[104:107], v[210:213], v[68:71]
	v_mfma_f32_16x16x32_bf16 v[92:95], v[104:107], v[186:189], v[92:95]
	v_mfma_f32_16x16x32_bf16 v[88:91], v[222:225], v[186:189], v[88:91]
	v_mfma_f32_16x16x32_bf16 v[84:87], v[108:111], v[198:201], v[84:87]
	v_mfma_f32_16x16x32_bf16 v[80:83], v[158:161], v[198:201], v[80:83]
	v_mfma_f32_16x16x32_bf16 v[76:79], v[104:107], v[202:205], v[76:79]
	v_mfma_f32_16x16x32_bf16 v[72:75], v[222:225], v[202:205], v[72:75]
	v_mfma_f32_16x16x32_bf16 v[68:71], v[108:111], v[214:217], v[68:71]
	v_mfma_f32_16x16x32_bf16 v[64:67], v[222:225], v[210:213], v[64:67]
	v_mfma_f32_16x16x32_bf16 v[226:229], v[108:111], v[190:193], v[92:95]
	v_mfma_f32_16x16x32_bf16 v[186:189], v[158:161], v[190:193], v[88:91]
	v_mfma_f32_16x16x32_bf16 v[190:193], v[108:111], v[206:209], v[76:79]
	v_mfma_f32_16x16x32_bf16 v[194:197], v[158:161], v[206:209], v[72:75]
	v_mfma_f32_16x16x32_bf16 v[198:201], v[158:161], v[214:217], v[64:67]
	s_setprio 0
	s_barrier
	s_nop 0
	ds_read_b128 v[64:67], v153 offset:16384
	ds_read_b128 v[72:75], v153 offset:17408
	ds_read_b128 v[76:79], v171 offset:16384
	ds_read_b128 v[88:91], v171 offset:17408
	ds_read_b128 v[92:95], v172 offset:16384
	ds_read_b128 v[202:205], v172 offset:17408
	ds_read_b128 v[206:209], v173 offset:16384
	ds_read_b128 v[210:213], v173 offset:17408
	s_waitcnt vmcnt(4)
	s_barrier
	s_waitcnt lgkmcnt(0)
	s_setprio 1
	v_mfma_f32_16x16x32_bf16 v[60:63], v[142:145], v[64:67], v[60:63]
	v_mfma_f32_16x16x32_bf16 v[56:59], v[178:181], v[64:67], v[56:59]
	v_mfma_f32_16x16x32_bf16 v[52:55], v[142:145], v[76:79], v[52:55]
	v_mfma_f32_16x16x32_bf16 v[48:51], v[178:181], v[76:79], v[48:51]
	v_mfma_f32_16x16x32_bf16 v[36:39], v[142:145], v[206:209], v[36:39]
	v_mfma_f32_16x16x32_bf16 v[32:35], v[178:181], v[206:209], v[32:35]
	v_mfma_f32_16x16x32_bf16 v[60:63], v[146:149], v[72:75], v[60:63]
	v_mfma_f32_16x16x32_bf16 v[56:59], v[182:185], v[72:75], v[56:59]
	v_mfma_f32_16x16x32_bf16 v[52:55], v[146:149], v[88:91], v[52:55]
	v_mfma_f32_16x16x32_bf16 v[48:51], v[182:185], v[88:91], v[48:51]
	v_mfma_f32_16x16x32_bf16 v[44:47], v[142:145], v[92:95], v[44:47]
	v_mfma_f32_16x16x32_bf16 v[40:43], v[178:181], v[92:95], v[40:43]
	v_mfma_f32_16x16x32_bf16 v[36:39], v[146:149], v[210:213], v[36:39]
	v_mfma_f32_16x16x32_bf16 v[32:35], v[182:185], v[210:213], v[32:35]
	v_mfma_f32_16x16x32_bf16 v[214:217], v[146:149], v[202:205], v[44:47]
	v_mfma_f32_16x16x32_bf16 v[230:233], v[182:185], v[202:205], v[40:43]
	s_setprio 0
	s_setprio 1
	v_mfma_f32_16x16x32_bf16 v[20:23], v[104:107], v[76:79], v[20:23]
	v_mfma_f32_16x16x32_bf16 v[16:19], v[222:225], v[76:79], v[16:19]
	v_mfma_f32_16x16x32_bf16 v[4:7], v[104:107], v[206:209], v[4:7]
	v_mfma_f32_16x16x32_bf16 v[28:31], v[104:107], v[64:67], v[28:31]
	v_mfma_f32_16x16x32_bf16 v[24:27], v[222:225], v[64:67], v[24:27]
	v_mfma_f32_16x16x32_bf16 v[20:23], v[108:111], v[88:91], v[20:23]
	v_mfma_f32_16x16x32_bf16 v[16:19], v[158:161], v[88:91], v[16:19]
	v_mfma_f32_16x16x32_bf16 v[12:15], v[104:107], v[92:95], v[12:15]
	v_mfma_f32_16x16x32_bf16 v[8:11], v[222:225], v[92:95], v[8:11]
	v_mfma_f32_16x16x32_bf16 v[4:7], v[108:111], v[210:213], v[4:7]
	v_mfma_f32_16x16x32_bf16 v[0:3], v[222:225], v[206:209], v[0:3]
	v_mfma_f32_16x16x32_bf16 v[142:145], v[108:111], v[72:75], v[28:31]
	v_mfma_f32_16x16x32_bf16 v[146:149], v[158:161], v[72:75], v[24:27]
	v_mfma_f32_16x16x32_bf16 v[178:181], v[108:111], v[202:205], v[12:15]
	v_mfma_f32_16x16x32_bf16 v[182:185], v[158:161], v[202:205], v[8:11]
	v_mfma_f32_16x16x32_bf16 v[158:161], v[158:161], v[210:213], v[0:3]
	s_setprio 0
	s_barrier
	s_nop 0
	ds_read_b128 v[0:3], v156
	ds_read_b128 v[8:11], v156 offset:1024
	ds_read_b128 v[202:205], v156 offset:2048
	ds_read_b128 v[206:209], v156 offset:3072
	ds_read_b128 v[12:15], v153 offset:32768
	ds_read_b128 v[24:27], v153 offset:33792
	ds_read_b128 v[28:31], v171 offset:32768
	ds_read_b128 v[40:43], v171 offset:33792
	ds_read_b128 v[44:47], v172 offset:32768
	ds_read_b128 v[64:67], v172 offset:33792
	ds_read_b128 v[210:213], v173 offset:32768
	ds_read_b128 v[222:225], v173 offset:33792
	s_waitcnt vmcnt(2)
	s_barrier
; #define LDA(dst,b,h) _Pragma("unroll") for(int m=0;m<4;++m) _Pragma("unroll") for(int k=0;k<2;++k) \
;     dst[m][k]=*reinterpret_cast<const bf16x8*>((char*)SA(b,h)+lds_byte(wr*64+m*16+fr,k*32+fq*8))
; #define LDB(dst,b,h) _Pragma("unroll") for(int n=0;n<2;++n) _Pragma("unroll") for(int k=0;k<2;++k) \
;     dst[n][k]=*reinterpret_cast<const bf16x8*>((char*)SB(b,h)+lds_byte(wc*32+n*16+fr,k*32+fq*8))
; #define MMA(ai,bj,At_,Bt_) do{__builtin_amdgcn_s_setprio(1); \
;     _Pragma("unroll") for(int m=0;m<4;++m) _Pragma("unroll") for(int n=0;n<2;++n) _Pragma("unroll") for(int k=0;k<2;++k) \
;       acc[ai][bj][m][n]=__builtin_amdgcn_mfma_f32_16x16x32_bf16(Bt_[n][k],At_[m][k],acc[ai][bj][m][n],0,0,0); \
;     __builtin_amdgcn_s_setprio(0);}while(0)
; #define WAIT_V(n) asm volatile("s_waitcnt vmcnt(" #n ")":::"memory")
; #define WAIT_L(n) asm volatile("s_waitcnt lgkmcnt(" #n ")":::"memory")
; #define BAR __builtin_amdgcn_s_barrier()
; DEVINL void gemm8_mainloop(const u16* A, long lda, const u16* Bt, long ldb, int K, int brow, int bcol, f32x4 (&acc)[2][2][4][2], char* smem, int tid) {
;     ...
;     LDA(At,0,1); WAIT_V(4); BAR; WAIT_L(0); MMA(1,0,At,B0); MMA(1,1,At,B1); BAR; }
;   { LDB(B0,1,0); LDA(At,1,0); WAIT_V(2); BAR; WAIT_L(0); MMA(0,0,At,B0); BAR;
;     LDB(B1,1,1); WAIT_V(0); BAR; WAIT_L(0); MMA(0,1,At,B1); BAR;
;     LDA(At,1,1); BAR; WAIT_L(0); MMA(1,0,At,B0); MMA(1,1,At,B1); BAR; }
;   if(wr==0)BAR;
	s_waitcnt lgkmcnt(0)
	s_setprio 1
	v_mfma_f32_16x16x32_bf16 v[72:75], v[0:3], v[12:15], v[124:127]
	v_mfma_f32_16x16x32_bf16 v[124:127], v[8:11], v[24:27], v[72:75]
	v_mfma_f32_16x16x32_bf16 v[72:75], v[202:205], v[12:15], v[120:123]
	v_mfma_f32_16x16x32_bf16 v[120:123], v[206:209], v[24:27], v[72:75]
	v_mfma_f32_16x16x32_bf16 v[72:75], v[0:3], v[28:31], v[116:119]
	v_mfma_f32_16x16x32_bf16 v[108:111], v[8:11], v[40:43], v[72:75]
	v_mfma_f32_16x16x32_bf16 v[72:75], v[202:205], v[28:31], v[112:115]
	v_mfma_f32_16x16x32_bf16 v[104:107], v[206:209], v[40:43], v[72:75]
	v_mfma_f32_16x16x32_bf16 v[72:75], v[0:3], v[44:47], v[138:141]
	v_mfma_f32_16x16x32_bf16 v[92:95], v[8:11], v[64:67], v[72:75]
	v_mfma_f32_16x16x32_bf16 v[72:75], v[202:205], v[44:47], v[218:221]
	v_mfma_f32_16x16x32_bf16 v[88:91], v[206:209], v[64:67], v[72:75]
	v_mfma_f32_16x16x32_bf16 v[72:75], v[0:3], v[210:213], v[100:103]
	v_mfma_f32_16x16x32_bf16 v[76:79], v[8:11], v[222:225], v[72:75]
	v_mfma_f32_16x16x32_bf16 v[72:75], v[202:205], v[210:213], v[96:99]
	v_mfma_f32_16x16x32_bf16 v[72:75], v[206:209], v[222:225], v[72:75]
	s_setprio 0
	s_barrier
	ds_read_b128 v[138:141], v155
	ds_read_b128 v[218:221], v155 offset:1024
	ds_read_b128 v[234:237], v155 offset:2048
	ds_read_b128 v[154:157], v155 offset:3072
	s_waitcnt vmcnt(0)
	s_barrier
	s_waitcnt lgkmcnt(0)
	s_setprio 1
	v_mfma_f32_16x16x32_bf16 v[96:99], v[138:141], v[12:15], v[226:229]
	v_mfma_f32_16x16x32_bf16 v[12:15], v[234:237], v[12:15], v[186:189]
	v_mfma_f32_16x16x32_bf16 v[116:119], v[154:157], v[24:27], v[12:15]
	v_mfma_f32_16x16x32_bf16 v[12:15], v[138:141], v[28:31], v[84:87]
	v_mfma_f32_16x16x32_bf16 v[112:115], v[218:221], v[24:27], v[96:99]
	v_mfma_f32_16x16x32_bf16 v[96:99], v[218:221], v[40:43], v[12:15]
	v_mfma_f32_16x16x32_bf16 v[12:15], v[234:237], v[28:31], v[80:83]
	v_mfma_f32_16x16x32_bf16 v[100:103], v[154:157], v[40:43], v[12:15]
	v_mfma_f32_16x16x32_bf16 v[12:15], v[138:141], v[44:47], v[190:193]
	v_mfma_f32_16x16x32_bf16 v[80:83], v[218:221], v[64:67], v[12:15]
	v_mfma_f32_16x16x32_bf16 v[12:15], v[234:237], v[44:47], v[194:197]
	v_mfma_f32_16x16x32_bf16 v[84:87], v[154:157], v[64:67], v[12:15]
	v_mfma_f32_16x16x32_bf16 v[12:15], v[138:141], v[210:213], v[68:71]
	v_mfma_f32_16x16x32_bf16 v[64:67], v[218:221], v[222:225], v[12:15]
	v_mfma_f32_16x16x32_bf16 v[12:15], v[234:237], v[210:213], v[198:201]
	v_mfma_f32_16x16x32_bf16 v[68:71], v[154:157], v[222:225], v[12:15]
	s_setprio 0
	s_barrier
	ds_read_b128 v[186:189], v153 offset:49152
	ds_read_b128 v[190:193], v153 offset:50176
	ds_read_b128 v[194:197], v171 offset:49152
	ds_read_b128 v[198:201], v171 offset:50176
	ds_read_b128 v[210:213], v172 offset:49152
	ds_read_b128 v[222:225], v172 offset:50176
	ds_read_b128 v[226:229], v173 offset:49152
	ds_read_b128 v[172:175], v173 offset:50176
	s_barrier
	s_waitcnt lgkmcnt(0)
	s_setprio 1
	v_mfma_f32_16x16x32_bf16 v[12:15], v[0:3], v[186:189], v[60:63]
	v_mfma_f32_16x16x32_bf16 v[60:63], v[8:11], v[190:193], v[12:15]
	v_mfma_f32_16x16x32_bf16 v[12:15], v[202:205], v[186:189], v[56:59]
	v_mfma_f32_16x16x32_bf16 v[56:59], v[206:209], v[190:193], v[12:15]
	v_mfma_f32_16x16x32_bf16 v[12:15], v[0:3], v[194:197], v[52:55]
	v_mfma_f32_16x16x32_bf16 v[44:47], v[8:11], v[198:201], v[12:15]
	v_mfma_f32_16x16x32_bf16 v[12:15], v[202:205], v[194:197], v[48:51]
	v_mfma_f32_16x16x32_bf16 v[40:43], v[206:209], v[198:201], v[12:15]
	v_mfma_f32_16x16x32_bf16 v[12:15], v[0:3], v[210:213], v[214:217]
	v_mfma_f32_16x16x32_bf16 v[28:31], v[8:11], v[222:225], v[12:15]
	v_mfma_f32_16x16x32_bf16 v[12:15], v[202:205], v[210:213], v[230:233]
	v_mfma_f32_16x16x32_bf16 v[0:3], v[0:3], v[226:229], v[36:39]
	v_mfma_f32_16x16x32_bf16 v[24:27], v[206:209], v[222:225], v[12:15]
	v_mfma_f32_16x16x32_bf16 v[12:15], v[8:11], v[172:175], v[0:3]
	v_mfma_f32_16x16x32_bf16 v[0:3], v[202:205], v[226:229], v[32:35]
	v_mfma_f32_16x16x32_bf16 v[8:11], v[206:209], v[172:175], v[0:3]
	s_setprio 0
	s_setprio 1
	v_mfma_f32_16x16x32_bf16 v[0:3], v[138:141], v[186:189], v[142:145]
	v_mfma_f32_16x16x32_bf16 v[48:51], v[218:221], v[190:193], v[0:3]
	v_mfma_f32_16x16x32_bf16 v[0:3], v[234:237], v[186:189], v[146:149]
	v_mfma_f32_16x16x32_bf16 v[52:55], v[154:157], v[190:193], v[0:3]
	v_mfma_f32_16x16x32_bf16 v[0:3], v[138:141], v[194:197], v[20:23]
	v_mfma_f32_16x16x32_bf16 v[32:35], v[218:221], v[198:201], v[0:3]
	v_mfma_f32_16x16x32_bf16 v[0:3], v[234:237], v[194:197], v[16:19]
	v_mfma_f32_16x16x32_bf16 v[36:39], v[154:157], v[198:201], v[0:3]
	v_mfma_f32_16x16x32_bf16 v[0:3], v[138:141], v[210:213], v[178:181]
	v_mfma_f32_16x16x32_bf16 v[16:19], v[218:221], v[222:225], v[0:3]
	v_mfma_f32_16x16x32_bf16 v[0:3], v[234:237], v[210:213], v[182:185]
	v_mfma_f32_16x16x32_bf16 v[20:23], v[154:157], v[222:225], v[0:3]
	v_mfma_f32_16x16x32_bf16 v[0:3], v[138:141], v[226:229], v[4:7]
	v_mfma_f32_16x16x32_bf16 v[4:7], v[234:237], v[226:229], v[158:161]
	v_mfma_f32_16x16x32_bf16 v[0:3], v[218:221], v[172:175], v[0:3]
	v_mfma_f32_16x16x32_bf16 v[4:7], v[154:157], v[172:175], v[4:7]
	s_setprio 0
	s_cmpk_gt_u32 s27, 0xff
	s_barrier
	s_cbranch_scc1 .LBB0_1990
	s_barrier
